# hand-rewrote prompt mLSTM scan: gate scalars via lane broadcast, batched prefetch of chunk states (no per-step load wait)
# speedup vs baseline: 1.0051x; 1.0051x over previous
;     __device__ __forceinline__ bf16* DC() const { return (bf16*)(ws + WS_XN); }
;     __device__ __forceinline__ float* DN() const { return (float*)(ws + WS_DN); }
; __device__ __forceinline__ void phase_scan(Ctx& C, int l, const bool st, LAS unsigned char* lds) {
;     const int gt = C.bid * 512 + C.tid, NT = C.G * 512;
;     for (int e = gt; e < 16 * 8192; e += NT) {
;         const int chain = e >> 13, p = e & 8191, b = chain >> 2, h = chain & 3;
;         const bool hn = p < 128;
;         unsigned* base = (unsigned*)C.DC() + p;
;         float* dnb = C.DN() + (hn ? p : 0);
;         float c0 = 0.f, c1 = 0.f, m = 0.f, nn = 0.f;
;         unsigned buf[16], nb[16]; float fb[16], fnb[16];
; #pragma unroll
;         for (int j = 0; j < 16; ++j) { buf[j] = base[(size_t)((b * NPC + j) * 4 + h) * 8192]; fb[j] = hn ? dnb[(size_t)((b * NPC + j) * 4 + h) * 128] : 0.f; }
.LBB0_690:
	s_or_b64 exec, exec, s[2:3]
	s_waitcnt lgkmcnt(0)
	s_barrier
	s_mov_b64 s[2:3], exec
	v_readfirstlane_b32 s12, v202
	v_and_b32_e32 v37, 63, v202
	s_lshl_b32 s18, s76, 9
	s_lshl_b32 s19, s26, 9
	v_lshlrev_b32_e32 v124, 4, v37
	v_lshlrev_b32_e32 v180, 10, v37
	v_mov_b32_e32 v123, 0
	s_add_u32 s12, s12, s18
.Lscan_outer:
	s_cmp_lt_u32 s12, 0x20000
	s_cbranch_scc0 .LBB0_813
	s_lshr_b32 s46, s12, 15
	s_bfe_u32 s47, s12, 0x2000d
	s_and_b32 s41, s12, 0x1fff
	v_add_u32_e32 v36, s41, v37
	s_lshl_b32 s48, s46, 9
	v_lshlrev_b32_e32 v36, 2, v36
	s_add_u32 s48, s48, s47
	s_lshl_b32 s49, s48, 2
	s_add_u32 s42, s90, s49
	s_addc_u32 s43, s91, 0
	s_add_u32 s42, s42, 0x1f730000
	s_addc_u32 s43, s43, 0
	s_add_u32 s44, s42, 0x2200
	s_addc_u32 s45, s43, 0
	s_add_u32 s50, s42, 0x4400
	s_addc_u32 s51, s43, 0
	global_load_dword v174, v124, s[44:45]
	global_load_dword v176, v124, s[42:43]
	global_load_dword v175, v124, s[44:45] offset:1024
	global_load_dword v177, v124, s[42:43] offset:1024
	s_lshl_b32 s49, s48, 15
	s_add_u32 s4, s90, s49
	s_addc_u32 s5, s91, 0
	s_add_u32 s4, s4, 0x18c00000
	s_addc_u32 s5, s5, 0
	s_mov_b64 s[6:7], s[4:5]
	s_lshl_b32 s49, s48, 9
	s_add_u32 s8, s90, s49
	s_addc_u32 s9, s91, 0
	s_add_u32 s8, s8, 0x1f620000
	s_addc_u32 s9, s9, 0
	s_mov_b64 s[10:11], s[8:9]
	v_mov_b32_e32 v38, 0
	v_mov_b32_e32 v118, 0
	v_mov_b32_e32 v119, 0
	v_mov_b32_e32 v120, 0
	s_cmp_lt_u32 s41, 0x80
	s_cselect_b32 s52, 1, 0
	s_cmp_eq_u32 s41, 0
	s_cselect_b32 s53, 1, 0
	s_cmp_eq_u32 s52, 1
	s_cbranch_scc1 .Lscan_hn
	global_load_dword v126, v36, s[4:5]
	s_add_u32 s4, s4, 0x20000
	s_addc_u32 s5, s5, 0
	global_load_dword v127, v36, s[4:5]
	s_add_u32 s4, s4, 0x20000
	s_addc_u32 s5, s5, 0
	global_load_dword v128, v36, s[4:5]
	s_add_u32 s4, s4, 0x20000
	s_addc_u32 s5, s5, 0
	global_load_dword v129, v36, s[4:5]
	s_add_u32 s4, s4, 0x20000
	s_addc_u32 s5, s5, 0
	global_load_dword v130, v36, s[4:5]
	s_add_u32 s4, s4, 0x20000
	s_addc_u32 s5, s5, 0
	global_load_dword v131, v36, s[4:5]
	s_add_u32 s4, s4, 0x20000
	s_addc_u32 s5, s5, 0
	global_load_dword v132, v36, s[4:5]
	s_add_u32 s4, s4, 0x20000
	s_addc_u32 s5, s5, 0
	global_load_dword v133, v36, s[4:5]
	s_add_u32 s4, s4, 0x20000
	s_addc_u32 s5, s5, 0
	global_load_dword v134, v36, s[4:5]
	s_add_u32 s4, s4, 0x20000
	s_addc_u32 s5, s5, 0
	global_load_dword v135, v36, s[4:5]
	s_add_u32 s4, s4, 0x20000
	s_addc_u32 s5, s5, 0
	global_load_dword v136, v36, s[4:5]
	s_add_u32 s4, s4, 0x20000
	s_addc_u32 s5, s5, 0
	global_load_dword v137, v36, s[4:5]
	s_add_u32 s4, s4, 0x20000
	s_addc_u32 s5, s5, 0
	global_load_dword v138, v36, s[4:5]
	s_add_u32 s4, s4, 0x20000
	s_addc_u32 s5, s5, 0
	global_load_dword v139, v36, s[4:5]
	s_add_u32 s4, s4, 0x20000
	s_addc_u32 s5, s5, 0
	global_load_dword v140, v36, s[4:5]
	s_add_u32 s4, s4, 0x20000
	s_addc_u32 s5, s5, 0
	global_load_dword v141, v36, s[4:5]
	s_add_u32 s4, s4, 0x20000
	s_addc_u32 s5, s5, 0
	global_load_dword v142, v36, s[4:5]
	s_add_u32 s4, s4, 0x20000
	s_addc_u32 s5, s5, 0
	global_load_dword v143, v36, s[4:5]
	s_add_u32 s4, s4, 0x20000
	s_addc_u32 s5, s5, 0
	global_load_dword v144, v36, s[4:5]
	s_add_u32 s4, s4, 0x20000
	s_addc_u32 s5, s5, 0
	global_load_dword v145, v36, s[4:5]
	s_add_u32 s4, s4, 0x20000
	s_addc_u32 s5, s5, 0
	global_load_dword v146, v36, s[4:5]
	s_add_u32 s4, s4, 0x20000
	s_addc_u32 s5, s5, 0
	global_load_dword v147, v36, s[4:5]
	s_add_u32 s4, s4, 0x20000
	s_addc_u32 s5, s5, 0
	global_load_dword v148, v36, s[4:5]
	s_add_u32 s4, s4, 0x20000
	s_addc_u32 s5, s5, 0
	global_load_dword v149, v36, s[4:5]
	s_add_u32 s4, s4, 0x20000
	s_addc_u32 s5, s5, 0
	global_load_dword v150, v36, s[4:5]
	s_add_u32 s4, s4, 0x20000
	s_addc_u32 s5, s5, 0
	global_load_dword v151, v36, s[4:5]
	s_add_u32 s4, s4, 0x20000
	s_addc_u32 s5, s5, 0
	global_load_dword v152, v36, s[4:5]
	s_add_u32 s4, s4, 0x20000
	s_addc_u32 s5, s5, 0
	global_load_dword v153, v36, s[4:5]
	s_add_u32 s4, s4, 0x20000
	s_addc_u32 s5, s5, 0
	global_load_dword v154, v36, s[4:5]
	s_add_u32 s4, s4, 0x20000
	s_addc_u32 s5, s5, 0
	global_load_dword v155, v36, s[4:5]
	s_add_u32 s4, s4, 0x20000
	s_addc_u32 s5, s5, 0
	global_load_dword v156, v36, s[4:5]
	s_add_u32 s4, s4, 0x20000
	s_addc_u32 s5, s5, 0
	global_load_dword v157, v36, s[4:5]
	s_add_u32 s4, s4, 0x20000
	s_addc_u32 s5, s5, 0
; __device__ __forceinline__ unsigned pk2(float lo, float hi) { f32x2_t v = {lo, hi}; bf16x2_t b = __builtin_convertvector(v, bf16x2_t); return __builtin_bit_cast(unsigned, b); }
; __device__ __forceinline__ float bflo(unsigned w) { return __uint_as_float(w << 16); }
; __device__ __forceinline__ float bfhi(unsigned w) { return __uint_as_float(w & 0xffff0000u); }
; __device__ __forceinline__ float fexp(float x) { return __builtin_amdgcn_exp2f(x * LOG2E); }
;     __device__ __forceinline__ float* MBM() const { return (float*)(ws + WS_MB); }
;     __device__ __forceinline__ float* MBB() const { return (float*)(ws + WS_MB) + (NSLOT_P + NSLOT_S); }
;     __device__ __forceinline__ float* MST() const { return (float*)(ws + WS_MB) + 2 * (NSLOT_P + NSLOT_S); }
; __device__ __forceinline__ void phase_scan(Ctx& C, int l, const bool st, LAS unsigned char* lds) {
;     ...
;         for (int cg0 = 0; cg0 < NPC; cg0 += 16) {
;             if (cg0 + 16 < NPC) {
; #pragma unroll
;                 for (int j = 0; j < 16; ++j) { nb[j] = base[(size_t)((b * NPC + cg0 + 16 + j) * 4 + h) * 8192]; fnb[j] = hn ? dnb[(size_t)((b * NPC + cg0 + 16 + j) * 4 + h) * 128] : 0.f; }
;             }
; #pragma unroll
;             for (int j = 0; j < 16; ++j) { const int slot = (b * NPC + cg0 + j) * 4 + h;
;                 const float Bc = C.MBB()[slot], Mc = C.MBM()[slot];
;                 const float mn = fmaxf(Bc + m, Mc), g = fexp(Bc + m - mn), f = fexp(Mc - mn);
;                 if (st) { base[(size_t)slot * 8192] = pk2(c0, c1); if (hn) { dnb[(size_t)slot * 128] = nn; if (p == 0) C.MST()[slot] = m; } }
;                 c0 = g * c0 + f * bflo(buf[j]); c1 = g * c1 + f * bfhi(buf[j]); nn = g * nn + f * fb[j]; m = mn; }
.Lscan_nh_b0:
	s_waitcnt vmcnt(16)
	global_load_dword v158, v36, s[4:5]
	s_add_u32 s4, s4, 0x20000
	s_addc_u32 s5, s5, 0
	global_load_dword v159, v36, s[4:5]
	s_add_u32 s4, s4, 0x20000
	s_addc_u32 s5, s5, 0
	global_load_dword v160, v36, s[4:5]
	s_add_u32 s4, s4, 0x20000
	s_addc_u32 s5, s5, 0
	global_load_dword v161, v36, s[4:5]
	s_add_u32 s4, s4, 0x20000
	s_addc_u32 s5, s5, 0
	global_load_dword v162, v36, s[4:5]
	s_add_u32 s4, s4, 0x20000
	s_addc_u32 s5, s5, 0
	global_load_dword v163, v36, s[4:5]
	s_add_u32 s4, s4, 0x20000
	s_addc_u32 s5, s5, 0
	global_load_dword v164, v36, s[4:5]
	s_add_u32 s4, s4, 0x20000
	s_addc_u32 s5, s5, 0
	global_load_dword v165, v36, s[4:5]
	s_add_u32 s4, s4, 0x20000
	s_addc_u32 s5, s5, 0
	global_load_dword v166, v36, s[4:5]
	s_add_u32 s4, s4, 0x20000
	s_addc_u32 s5, s5, 0
	global_load_dword v167, v36, s[4:5]
	s_add_u32 s4, s4, 0x20000
	s_addc_u32 s5, s5, 0
	global_load_dword v168, v36, s[4:5]
	s_add_u32 s4, s4, 0x20000
	s_addc_u32 s5, s5, 0
	global_load_dword v169, v36, s[4:5]
	s_add_u32 s4, s4, 0x20000
	s_addc_u32 s5, s5, 0
	global_load_dword v170, v36, s[4:5]
	s_add_u32 s4, s4, 0x20000
	s_addc_u32 s5, s5, 0
	global_load_dword v171, v36, s[4:5]
	s_add_u32 s4, s4, 0x20000
	s_addc_u32 s5, s5, 0
	global_load_dword v172, v36, s[4:5]
	s_add_u32 s4, s4, 0x20000
	s_addc_u32 s5, s5, 0
	global_load_dword v173, v36, s[4:5]
	s_add_u32 s4, s4, 0x20000
	s_addc_u32 s5, s5, 0
	v_readlane_b32 s22, v174, 0
	v_readlane_b32 s32, v176, 0
	s_nop 1
	v_add_f32_e32 v39, s22, v38
	v_readlane_b32 s34, v174, 1
	v_max_f32_e32 v40, s32, v39
	v_readlane_b32 s40, v176, 1
	v_sub_f32_e32 v58, v39, v40
	v_sub_f32_e32 v59, s32, v40
	v_mul_f32_e32 v58, 0x3fb8aa3b, v58
	v_mul_f32_e32 v59, 0x3fb8aa3b, v59
	v_exp_f32_e32 v60, v58
	v_exp_f32_e32 v62, v59
	v_cvt_pk_bf16_f32 v122, v118, v119
	global_store_dword v36, v122, s[6:7]
	s_add_u32 s6, s6, 0x20000
	s_addc_u32 s7, s7, 0
	v_lshlrev_b32_e32 v108, 16, v126
	v_and_b32_e32 v109, 0xffff0000, v126
	v_pk_mul_f32 v[108:109], v[62:63], v[108:109] op_sel_hi:[0,1]
	v_pk_fma_f32 v[118:119], v[118:119], v[60:61], v[108:109] op_sel_hi:[1,0,1]
	v_add_f32_e32 v39, s34, v40
	v_readlane_b32 s22, v174, 2
	v_max_f32_e32 v38, s40, v39
	v_readlane_b32 s32, v176, 2
	v_sub_f32_e32 v58, v39, v38
	v_sub_f32_e32 v59, s40, v38
	v_mul_f32_e32 v58, 0x3fb8aa3b, v58
	v_mul_f32_e32 v59, 0x3fb8aa3b, v59
	v_exp_f32_e32 v60, v58
	v_exp_f32_e32 v62, v59
	v_cvt_pk_bf16_f32 v122, v118, v119
	global_store_dword v36, v122, s[6:7]
	s_add_u32 s6, s6, 0x20000
	s_addc_u32 s7, s7, 0
	v_lshlrev_b32_e32 v108, 16, v127
	v_and_b32_e32 v109, 0xffff0000, v127
	v_pk_mul_f32 v[108:109], v[62:63], v[108:109] op_sel_hi:[0,1]
	v_pk_fma_f32 v[118:119], v[118:119], v[60:61], v[108:109] op_sel_hi:[1,0,1]
	v_add_f32_e32 v39, s22, v38
	v_readlane_b32 s34, v174, 3
	v_max_f32_e32 v40, s32, v39
	v_readlane_b32 s40, v176, 3
	v_sub_f32_e32 v58, v39, v40
	v_sub_f32_e32 v59, s32, v40
	v_mul_f32_e32 v58, 0x3fb8aa3b, v58
	v_mul_f32_e32 v59, 0x3fb8aa3b, v59
	v_exp_f32_e32 v60, v58
	v_exp_f32_e32 v62, v59
	v_cvt_pk_bf16_f32 v122, v118, v119
	global_store_dword v36, v122, s[6:7]
	s_add_u32 s6, s6, 0x20000
	s_addc_u32 s7, s7, 0
	v_lshlrev_b32_e32 v108, 16, v128
	v_and_b32_e32 v109, 0xffff0000, v128
	v_pk_mul_f32 v[108:109], v[62:63], v[108:109] op_sel_hi:[0,1]
	v_pk_fma_f32 v[118:119], v[118:119], v[60:61], v[108:109] op_sel_hi:[1,0,1]
	v_add_f32_e32 v39, s34, v40
	v_readlane_b32 s22, v174, 4
	v_max_f32_e32 v38, s40, v39
	v_readlane_b32 s32, v176, 4
	v_sub_f32_e32 v58, v39, v38
	v_sub_f32_e32 v59, s40, v38
	v_mul_f32_e32 v58, 0x3fb8aa3b, v58
	v_mul_f32_e32 v59, 0x3fb8aa3b, v59
	v_exp_f32_e32 v60, v58
	v_exp_f32_e32 v62, v59
	v_cvt_pk_bf16_f32 v122, v118, v119
	global_store_dword v36, v122, s[6:7]
	s_add_u32 s6, s6, 0x20000
	s_addc_u32 s7, s7, 0
	v_lshlrev_b32_e32 v108, 16, v129
	v_and_b32_e32 v109, 0xffff0000, v129
	v_pk_mul_f32 v[108:109], v[62:63], v[108:109] op_sel_hi:[0,1]
	v_pk_fma_f32 v[118:119], v[118:119], v[60:61], v[108:109] op_sel_hi:[1,0,1]
	v_add_f32_e32 v39, s22, v38
	v_readlane_b32 s34, v174, 5
	v_max_f32_e32 v40, s32, v39
	v_readlane_b32 s40, v176, 5
	v_sub_f32_e32 v58, v39, v40
	v_sub_f32_e32 v59, s32, v40
	v_mul_f32_e32 v58, 0x3fb8aa3b, v58
	v_mul_f32_e32 v59, 0x3fb8aa3b, v59
	v_exp_f32_e32 v60, v58
	v_exp_f32_e32 v62, v59
	v_cvt_pk_bf16_f32 v122, v118, v119
	global_store_dword v36, v122, s[6:7]
	s_add_u32 s6, s6, 0x20000
	s_addc_u32 s7, s7, 0
	v_lshlrev_b32_e32 v108, 16, v130
	v_and_b32_e32 v109, 0xffff0000, v130
	v_pk_mul_f32 v[108:109], v[62:63], v[108:109] op_sel_hi:[0,1]
	v_pk_fma_f32 v[118:119], v[118:119], v[60:61], v[108:109] op_sel_hi:[1,0,1]
	v_add_f32_e32 v39, s34, v40
	v_readlane_b32 s22, v174, 6
	v_max_f32_e32 v38, s40, v39
	v_readlane_b32 s32, v176, 6
	v_sub_f32_e32 v58, v39, v38
	v_sub_f32_e32 v59, s40, v38
	v_mul_f32_e32 v58, 0x3fb8aa3b, v58
	v_mul_f32_e32 v59, 0x3fb8aa3b, v59
	v_exp_f32_e32 v60, v58
	v_exp_f32_e32 v62, v59
	v_cvt_pk_bf16_f32 v122, v118, v119
	global_store_dword v36, v122, s[6:7]
	s_add_u32 s6, s6, 0x20000
	s_addc_u32 s7, s7, 0
	v_lshlrev_b32_e32 v108, 16, v131
	v_and_b32_e32 v109, 0xffff0000, v131
	v_pk_mul_f32 v[108:109], v[62:63], v[108:109] op_sel_hi:[0,1]
	v_pk_fma_f32 v[118:119], v[118:119], v[60:61], v[108:109] op_sel_hi:[1,0,1]
	v_add_f32_e32 v39, s22, v38
	v_readlane_b32 s34, v174, 7
	v_max_f32_e32 v40, s32, v39
	v_readlane_b32 s40, v176, 7
	v_sub_f32_e32 v58, v39, v40
	v_sub_f32_e32 v59, s32, v40
	v_mul_f32_e32 v58, 0x3fb8aa3b, v58
	v_mul_f32_e32 v59, 0x3fb8aa3b, v59
	v_exp_f32_e32 v60, v58
	v_exp_f32_e32 v62, v59
	v_cvt_pk_bf16_f32 v122, v118, v119
	global_store_dword v36, v122, s[6:7]
	s_add_u32 s6, s6, 0x20000
; __device__ __forceinline__ unsigned pk2(float lo, float hi) { f32x2_t v = {lo, hi}; bf16x2_t b = __builtin_convertvector(v, bf16x2_t); return __builtin_bit_cast(unsigned, b); }
; __device__ __forceinline__ float bflo(unsigned w) { return __uint_as_float(w << 16); }
; __device__ __forceinline__ float bfhi(unsigned w) { return __uint_as_float(w & 0xffff0000u); }
; __device__ __forceinline__ float fexp(float x) { return __builtin_amdgcn_exp2f(x * LOG2E); }
;     __device__ __forceinline__ float* MBM() const { return (float*)(ws + WS_MB); }
;     __device__ __forceinline__ float* MBB() const { return (float*)(ws + WS_MB) + (NSLOT_P + NSLOT_S); }
;     __device__ __forceinline__ float* MST() const { return (float*)(ws + WS_MB) + 2 * (NSLOT_P + NSLOT_S); }
; __device__ __forceinline__ void phase_scan(Ctx& C, int l, const bool st, LAS unsigned char* lds) {
;     ...
;             for (int j = 0; j < 16; ++j) { const int slot = (b * NPC + cg0 + j) * 4 + h;
;                 const float Bc = C.MBB()[slot], Mc = C.MBM()[slot];
;                 const float mn = fmaxf(Bc + m, Mc), g = fexp(Bc + m - mn), f = fexp(Mc - mn);
;                 if (st) { base[(size_t)slot * 8192] = pk2(c0, c1); if (hn) { dnb[(size_t)slot * 128] = nn; if (p == 0) C.MST()[slot] = m; } }
;                 c0 = g * c0 + f * bflo(buf[j]); c1 = g * c1 + f * bfhi(buf[j]); nn = g * nn + f * fb[j]; m = mn; }
	s_addc_u32 s7, s7, 0
	v_lshlrev_b32_e32 v108, 16, v132
	v_and_b32_e32 v109, 0xffff0000, v132
	v_pk_mul_f32 v[108:109], v[62:63], v[108:109] op_sel_hi:[0,1]
	v_pk_fma_f32 v[118:119], v[118:119], v[60:61], v[108:109] op_sel_hi:[1,0,1]
	v_add_f32_e32 v39, s34, v40
	v_readlane_b32 s22, v174, 8
	v_max_f32_e32 v38, s40, v39
	v_readlane_b32 s32, v176, 8
	v_sub_f32_e32 v58, v39, v38
	v_sub_f32_e32 v59, s40, v38
	v_mul_f32_e32 v58, 0x3fb8aa3b, v58
	v_mul_f32_e32 v59, 0x3fb8aa3b, v59
	v_exp_f32_e32 v60, v58
	v_exp_f32_e32 v62, v59
	v_cvt_pk_bf16_f32 v122, v118, v119
	global_store_dword v36, v122, s[6:7]
	s_add_u32 s6, s6, 0x20000
	s_addc_u32 s7, s7, 0
	v_lshlrev_b32_e32 v108, 16, v133
	v_and_b32_e32 v109, 0xffff0000, v133
	v_pk_mul_f32 v[108:109], v[62:63], v[108:109] op_sel_hi:[0,1]
	v_pk_fma_f32 v[118:119], v[118:119], v[60:61], v[108:109] op_sel_hi:[1,0,1]
	v_add_f32_e32 v39, s22, v38
	v_readlane_b32 s34, v174, 9
	v_max_f32_e32 v40, s32, v39
	v_readlane_b32 s40, v176, 9
	v_sub_f32_e32 v58, v39, v40
	v_sub_f32_e32 v59, s32, v40
	v_mul_f32_e32 v58, 0x3fb8aa3b, v58
	v_mul_f32_e32 v59, 0x3fb8aa3b, v59
	v_exp_f32_e32 v60, v58
	v_exp_f32_e32 v62, v59
	v_cvt_pk_bf16_f32 v122, v118, v119
	global_store_dword v36, v122, s[6:7]
	s_add_u32 s6, s6, 0x20000
	s_addc_u32 s7, s7, 0
	v_lshlrev_b32_e32 v108, 16, v134
	v_and_b32_e32 v109, 0xffff0000, v134
	v_pk_mul_f32 v[108:109], v[62:63], v[108:109] op_sel_hi:[0,1]
	v_pk_fma_f32 v[118:119], v[118:119], v[60:61], v[108:109] op_sel_hi:[1,0,1]
	v_add_f32_e32 v39, s34, v40
	v_readlane_b32 s22, v174, 10
	v_max_f32_e32 v38, s40, v39
	v_readlane_b32 s32, v176, 10
	v_sub_f32_e32 v58, v39, v38
	v_sub_f32_e32 v59, s40, v38
	v_mul_f32_e32 v58, 0x3fb8aa3b, v58
	v_mul_f32_e32 v59, 0x3fb8aa3b, v59
	v_exp_f32_e32 v60, v58
	v_exp_f32_e32 v62, v59
	v_cvt_pk_bf16_f32 v122, v118, v119
	global_store_dword v36, v122, s[6:7]
	s_add_u32 s6, s6, 0x20000
	s_addc_u32 s7, s7, 0
	v_lshlrev_b32_e32 v108, 16, v135
	v_and_b32_e32 v109, 0xffff0000, v135
	v_pk_mul_f32 v[108:109], v[62:63], v[108:109] op_sel_hi:[0,1]
	v_pk_fma_f32 v[118:119], v[118:119], v[60:61], v[108:109] op_sel_hi:[1,0,1]
	v_add_f32_e32 v39, s22, v38
	v_readlane_b32 s34, v174, 11
	v_max_f32_e32 v40, s32, v39
	v_readlane_b32 s40, v176, 11
	v_sub_f32_e32 v58, v39, v40
	v_sub_f32_e32 v59, s32, v40
	v_mul_f32_e32 v58, 0x3fb8aa3b, v58
	v_mul_f32_e32 v59, 0x3fb8aa3b, v59
	v_exp_f32_e32 v60, v58
	v_exp_f32_e32 v62, v59
	v_cvt_pk_bf16_f32 v122, v118, v119
	global_store_dword v36, v122, s[6:7]
	s_add_u32 s6, s6, 0x20000
	s_addc_u32 s7, s7, 0
	v_lshlrev_b32_e32 v108, 16, v136
	v_and_b32_e32 v109, 0xffff0000, v136
	v_pk_mul_f32 v[108:109], v[62:63], v[108:109] op_sel_hi:[0,1]
	v_pk_fma_f32 v[118:119], v[118:119], v[60:61], v[108:109] op_sel_hi:[1,0,1]
	v_add_f32_e32 v39, s34, v40
	v_readlane_b32 s22, v174, 12
	v_max_f32_e32 v38, s40, v39
	v_readlane_b32 s32, v176, 12
	v_sub_f32_e32 v58, v39, v38
	v_sub_f32_e32 v59, s40, v38
	v_mul_f32_e32 v58, 0x3fb8aa3b, v58
	v_mul_f32_e32 v59, 0x3fb8aa3b, v59
	v_exp_f32_e32 v60, v58
	v_exp_f32_e32 v62, v59
	v_cvt_pk_bf16_f32 v122, v118, v119
	global_store_dword v36, v122, s[6:7]
	s_add_u32 s6, s6, 0x20000
	s_addc_u32 s7, s7, 0
	v_lshlrev_b32_e32 v108, 16, v137
	v_and_b32_e32 v109, 0xffff0000, v137
	v_pk_mul_f32 v[108:109], v[62:63], v[108:109] op_sel_hi:[0,1]
	v_pk_fma_f32 v[118:119], v[118:119], v[60:61], v[108:109] op_sel_hi:[1,0,1]
	v_add_f32_e32 v39, s22, v38
	v_readlane_b32 s34, v174, 13
	v_max_f32_e32 v40, s32, v39
	v_readlane_b32 s40, v176, 13
	v_sub_f32_e32 v58, v39, v40
	v_sub_f32_e32 v59, s32, v40
	v_mul_f32_e32 v58, 0x3fb8aa3b, v58
	v_mul_f32_e32 v59, 0x3fb8aa3b, v59
	v_exp_f32_e32 v60, v58
	v_exp_f32_e32 v62, v59
	v_cvt_pk_bf16_f32 v122, v118, v119
	global_store_dword v36, v122, s[6:7]
	s_add_u32 s6, s6, 0x20000
	s_addc_u32 s7, s7, 0
	v_lshlrev_b32_e32 v108, 16, v138
	v_and_b32_e32 v109, 0xffff0000, v138
	v_pk_mul_f32 v[108:109], v[62:63], v[108:109] op_sel_hi:[0,1]
	v_pk_fma_f32 v[118:119], v[118:119], v[60:61], v[108:109] op_sel_hi:[1,0,1]
	v_add_f32_e32 v39, s34, v40
	v_readlane_b32 s22, v174, 14
	v_max_f32_e32 v38, s40, v39
	v_readlane_b32 s32, v176, 14
	v_sub_f32_e32 v58, v39, v38
	v_sub_f32_e32 v59, s40, v38
	v_mul_f32_e32 v58, 0x3fb8aa3b, v58
	v_mul_f32_e32 v59, 0x3fb8aa3b, v59
	v_exp_f32_e32 v60, v58
	v_exp_f32_e32 v62, v59
	v_cvt_pk_bf16_f32 v122, v118, v119
	global_store_dword v36, v122, s[6:7]
	s_add_u32 s6, s6, 0x20000
	s_addc_u32 s7, s7, 0
	v_lshlrev_b32_e32 v108, 16, v139
	v_and_b32_e32 v109, 0xffff0000, v139
	v_pk_mul_f32 v[108:109], v[62:63], v[108:109] op_sel_hi:[0,1]
	v_pk_fma_f32 v[118:119], v[118:119], v[60:61], v[108:109] op_sel_hi:[1,0,1]
	v_add_f32_e32 v39, s22, v38
	v_readlane_b32 s34, v174, 15
	v_max_f32_e32 v40, s32, v39
	v_readlane_b32 s40, v176, 15
	v_sub_f32_e32 v58, v39, v40
	v_sub_f32_e32 v59, s32, v40
	v_mul_f32_e32 v58, 0x3fb8aa3b, v58
	v_mul_f32_e32 v59, 0x3fb8aa3b, v59
	v_exp_f32_e32 v60, v58
	v_exp_f32_e32 v62, v59
	v_cvt_pk_bf16_f32 v122, v118, v119
	global_store_dword v36, v122, s[6:7]
	s_add_u32 s6, s6, 0x20000
	s_addc_u32 s7, s7, 0
	v_lshlrev_b32_e32 v108, 16, v140
	v_and_b32_e32 v109, 0xffff0000, v140
	v_pk_mul_f32 v[108:109], v[62:63], v[108:109] op_sel_hi:[0,1]
	v_pk_fma_f32 v[118:119], v[118:119], v[60:61], v[108:109] op_sel_hi:[1,0,1]
	v_add_f32_e32 v39, s34, v40
	v_readlane_b32 s22, v174, 16
	v_max_f32_e32 v38, s40, v39
	v_readlane_b32 s32, v176, 16
	v_sub_f32_e32 v58, v39, v38
	v_sub_f32_e32 v59, s40, v38
	v_mul_f32_e32 v58, 0x3fb8aa3b, v58
	v_mul_f32_e32 v59, 0x3fb8aa3b, v59
	v_exp_f32_e32 v60, v58
	v_exp_f32_e32 v62, v59
	v_cvt_pk_bf16_f32 v122, v118, v119
	global_store_dword v36, v122, s[6:7]
	s_add_u32 s6, s6, 0x20000
	s_addc_u32 s7, s7, 0
	v_lshlrev_b32_e32 v108, 16, v141
	v_and_b32_e32 v109, 0xffff0000, v141
	v_pk_mul_f32 v[108:109], v[62:63], v[108:109] op_sel_hi:[0,1]
	v_pk_fma_f32 v[118:119], v[118:119], v[60:61], v[108:109] op_sel_hi:[1,0,1]
; __device__ __forceinline__ unsigned pk2(float lo, float hi) { f32x2_t v = {lo, hi}; bf16x2_t b = __builtin_convertvector(v, bf16x2_t); return __builtin_bit_cast(unsigned, b); }
; __device__ __forceinline__ float bflo(unsigned w) { return __uint_as_float(w << 16); }
; __device__ __forceinline__ float bfhi(unsigned w) { return __uint_as_float(w & 0xffff0000u); }
; __device__ __forceinline__ float fexp(float x) { return __builtin_amdgcn_exp2f(x * LOG2E); }
;     __device__ __forceinline__ float* MBM() const { return (float*)(ws + WS_MB); }
;     __device__ __forceinline__ float* MBB() const { return (float*)(ws + WS_MB) + (NSLOT_P + NSLOT_S); }
;     __device__ __forceinline__ float* MST() const { return (float*)(ws + WS_MB) + 2 * (NSLOT_P + NSLOT_S); }
; __device__ __forceinline__ void phase_scan(Ctx& C, int l, const bool st, LAS unsigned char* lds) {
;     ...
;         for (int cg0 = 0; cg0 < NPC; cg0 += 16) {
;             if (cg0 + 16 < NPC) {
; #pragma unroll
;                 for (int j = 0; j < 16; ++j) { nb[j] = base[(size_t)((b * NPC + cg0 + 16 + j) * 4 + h) * 8192]; fnb[j] = hn ? dnb[(size_t)((b * NPC + cg0 + 16 + j) * 4 + h) * 128] : 0.f; }
;             }
; #pragma unroll
;             for (int j = 0; j < 16; ++j) { const int slot = (b * NPC + cg0 + j) * 4 + h;
;                 const float Bc = C.MBB()[slot], Mc = C.MBM()[slot];
;                 const float mn = fmaxf(Bc + m, Mc), g = fexp(Bc + m - mn), f = fexp(Mc - mn);
;                 if (st) { base[(size_t)slot * 8192] = pk2(c0, c1); if (hn) { dnb[(size_t)slot * 128] = nn; if (p == 0) C.MST()[slot] = m; } }
;                 c0 = g * c0 + f * bflo(buf[j]); c1 = g * c1 + f * bfhi(buf[j]); nn = g * nn + f * fb[j]; m = mn; }
.Lscan_nh_b1:
	s_waitcnt vmcnt(32)
	global_load_dword v126, v36, s[4:5]
	s_add_u32 s4, s4, 0x20000
	s_addc_u32 s5, s5, 0
	global_load_dword v127, v36, s[4:5]
	s_add_u32 s4, s4, 0x20000
	s_addc_u32 s5, s5, 0
	global_load_dword v128, v36, s[4:5]
	s_add_u32 s4, s4, 0x20000
	s_addc_u32 s5, s5, 0
	global_load_dword v129, v36, s[4:5]
	s_add_u32 s4, s4, 0x20000
	s_addc_u32 s5, s5, 0
	global_load_dword v130, v36, s[4:5]
	s_add_u32 s4, s4, 0x20000
	s_addc_u32 s5, s5, 0
	global_load_dword v131, v36, s[4:5]
	s_add_u32 s4, s4, 0x20000
	s_addc_u32 s5, s5, 0
	global_load_dword v132, v36, s[4:5]
	s_add_u32 s4, s4, 0x20000
	s_addc_u32 s5, s5, 0
	global_load_dword v133, v36, s[4:5]
	s_add_u32 s4, s4, 0x20000
	s_addc_u32 s5, s5, 0
	global_load_dword v134, v36, s[4:5]
	s_add_u32 s4, s4, 0x20000
	s_addc_u32 s5, s5, 0
	global_load_dword v135, v36, s[4:5]
	s_add_u32 s4, s4, 0x20000
	s_addc_u32 s5, s5, 0
	global_load_dword v136, v36, s[4:5]
	s_add_u32 s4, s4, 0x20000
	s_addc_u32 s5, s5, 0
	global_load_dword v137, v36, s[4:5]
	s_add_u32 s4, s4, 0x20000
	s_addc_u32 s5, s5, 0
	global_load_dword v138, v36, s[4:5]
	s_add_u32 s4, s4, 0x20000
	s_addc_u32 s5, s5, 0
	global_load_dword v139, v36, s[4:5]
	s_add_u32 s4, s4, 0x20000
	s_addc_u32 s5, s5, 0
	global_load_dword v140, v36, s[4:5]
	s_add_u32 s4, s4, 0x20000
	s_addc_u32 s5, s5, 0
	global_load_dword v141, v36, s[4:5]
	s_add_u32 s4, s4, 0x20000
	s_addc_u32 s5, s5, 0
	v_add_f32_e32 v39, s22, v38
	v_readlane_b32 s34, v174, 17
	v_max_f32_e32 v40, s32, v39
	v_readlane_b32 s40, v176, 17
	v_sub_f32_e32 v58, v39, v40
	v_sub_f32_e32 v59, s32, v40
	v_mul_f32_e32 v58, 0x3fb8aa3b, v58
	v_mul_f32_e32 v59, 0x3fb8aa3b, v59
	v_exp_f32_e32 v60, v58
	v_exp_f32_e32 v62, v59
	v_cvt_pk_bf16_f32 v122, v118, v119
	global_store_dword v36, v122, s[6:7]
	s_add_u32 s6, s6, 0x20000
	s_addc_u32 s7, s7, 0
	v_lshlrev_b32_e32 v108, 16, v142
	v_and_b32_e32 v109, 0xffff0000, v142
	v_pk_mul_f32 v[108:109], v[62:63], v[108:109] op_sel_hi:[0,1]
	v_pk_fma_f32 v[118:119], v[118:119], v[60:61], v[108:109] op_sel_hi:[1,0,1]
	v_add_f32_e32 v39, s34, v40
	v_readlane_b32 s22, v174, 18
	v_max_f32_e32 v38, s40, v39
	v_readlane_b32 s32, v176, 18
	v_sub_f32_e32 v58, v39, v38
	v_sub_f32_e32 v59, s40, v38
	v_mul_f32_e32 v58, 0x3fb8aa3b, v58
	v_mul_f32_e32 v59, 0x3fb8aa3b, v59
	v_exp_f32_e32 v60, v58
	v_exp_f32_e32 v62, v59
	v_cvt_pk_bf16_f32 v122, v118, v119
	global_store_dword v36, v122, s[6:7]
	s_add_u32 s6, s6, 0x20000
	s_addc_u32 s7, s7, 0
	v_lshlrev_b32_e32 v108, 16, v143
	v_and_b32_e32 v109, 0xffff0000, v143
	v_pk_mul_f32 v[108:109], v[62:63], v[108:109] op_sel_hi:[0,1]
	v_pk_fma_f32 v[118:119], v[118:119], v[60:61], v[108:109] op_sel_hi:[1,0,1]
	v_add_f32_e32 v39, s22, v38
	v_readlane_b32 s34, v174, 19
	v_max_f32_e32 v40, s32, v39
	v_readlane_b32 s40, v176, 19
	v_sub_f32_e32 v58, v39, v40
	v_sub_f32_e32 v59, s32, v40
	v_mul_f32_e32 v58, 0x3fb8aa3b, v58
	v_mul_f32_e32 v59, 0x3fb8aa3b, v59
	v_exp_f32_e32 v60, v58
	v_exp_f32_e32 v62, v59
	v_cvt_pk_bf16_f32 v122, v118, v119
	global_store_dword v36, v122, s[6:7]
	s_add_u32 s6, s6, 0x20000
	s_addc_u32 s7, s7, 0
	v_lshlrev_b32_e32 v108, 16, v144
	v_and_b32_e32 v109, 0xffff0000, v144
	v_pk_mul_f32 v[108:109], v[62:63], v[108:109] op_sel_hi:[0,1]
	v_pk_fma_f32 v[118:119], v[118:119], v[60:61], v[108:109] op_sel_hi:[1,0,1]
	v_add_f32_e32 v39, s34, v40
	v_readlane_b32 s22, v174, 20
	v_max_f32_e32 v38, s40, v39
	v_readlane_b32 s32, v176, 20
	v_sub_f32_e32 v58, v39, v38
	v_sub_f32_e32 v59, s40, v38
	v_mul_f32_e32 v58, 0x3fb8aa3b, v58
	v_mul_f32_e32 v59, 0x3fb8aa3b, v59
	v_exp_f32_e32 v60, v58
	v_exp_f32_e32 v62, v59
	v_cvt_pk_bf16_f32 v122, v118, v119
	global_store_dword v36, v122, s[6:7]
	s_add_u32 s6, s6, 0x20000
	s_addc_u32 s7, s7, 0
	v_lshlrev_b32_e32 v108, 16, v145
	v_and_b32_e32 v109, 0xffff0000, v145
	v_pk_mul_f32 v[108:109], v[62:63], v[108:109] op_sel_hi:[0,1]
	v_pk_fma_f32 v[118:119], v[118:119], v[60:61], v[108:109] op_sel_hi:[1,0,1]
	v_add_f32_e32 v39, s22, v38
	v_readlane_b32 s34, v174, 21
	v_max_f32_e32 v40, s32, v39
	v_readlane_b32 s40, v176, 21
	v_sub_f32_e32 v58, v39, v40
	v_sub_f32_e32 v59, s32, v40
	v_mul_f32_e32 v58, 0x3fb8aa3b, v58
	v_mul_f32_e32 v59, 0x3fb8aa3b, v59
	v_exp_f32_e32 v60, v58
	v_exp_f32_e32 v62, v59
	v_cvt_pk_bf16_f32 v122, v118, v119
	global_store_dword v36, v122, s[6:7]
	s_add_u32 s6, s6, 0x20000
	s_addc_u32 s7, s7, 0
	v_lshlrev_b32_e32 v108, 16, v146
	v_and_b32_e32 v109, 0xffff0000, v146
	v_pk_mul_f32 v[108:109], v[62:63], v[108:109] op_sel_hi:[0,1]
	v_pk_fma_f32 v[118:119], v[118:119], v[60:61], v[108:109] op_sel_hi:[1,0,1]
	v_add_f32_e32 v39, s34, v40
	v_readlane_b32 s22, v174, 22
	v_max_f32_e32 v38, s40, v39
	v_readlane_b32 s32, v176, 22
	v_sub_f32_e32 v58, v39, v38
	v_sub_f32_e32 v59, s40, v38
	v_mul_f32_e32 v58, 0x3fb8aa3b, v58
	v_mul_f32_e32 v59, 0x3fb8aa3b, v59
	v_exp_f32_e32 v60, v58
	v_exp_f32_e32 v62, v59
	v_cvt_pk_bf16_f32 v122, v118, v119
	global_store_dword v36, v122, s[6:7]
	s_add_u32 s6, s6, 0x20000
	s_addc_u32 s7, s7, 0
	v_lshlrev_b32_e32 v108, 16, v147
	v_and_b32_e32 v109, 0xffff0000, v147
	v_pk_mul_f32 v[108:109], v[62:63], v[108:109] op_sel_hi:[0,1]
	v_pk_fma_f32 v[118:119], v[118:119], v[60:61], v[108:109] op_sel_hi:[1,0,1]
	v_add_f32_e32 v39, s22, v38
	v_readlane_b32 s34, v174, 23
	v_max_f32_e32 v40, s32, v39
	v_readlane_b32 s40, v176, 23
	v_sub_f32_e32 v58, v39, v40
	v_sub_f32_e32 v59, s32, v40
	v_mul_f32_e32 v58, 0x3fb8aa3b, v58
	v_mul_f32_e32 v59, 0x3fb8aa3b, v59
	v_exp_f32_e32 v60, v58
	v_exp_f32_e32 v62, v59
	v_cvt_pk_bf16_f32 v122, v118, v119
	global_store_dword v36, v122, s[6:7]
	s_add_u32 s6, s6, 0x20000
	s_addc_u32 s7, s7, 0
	v_lshlrev_b32_e32 v108, 16, v148
; __device__ __forceinline__ unsigned pk2(float lo, float hi) { f32x2_t v = {lo, hi}; bf16x2_t b = __builtin_convertvector(v, bf16x2_t); return __builtin_bit_cast(unsigned, b); }
; __device__ __forceinline__ float bflo(unsigned w) { return __uint_as_float(w << 16); }
; __device__ __forceinline__ float bfhi(unsigned w) { return __uint_as_float(w & 0xffff0000u); }
; __device__ __forceinline__ float fexp(float x) { return __builtin_amdgcn_exp2f(x * LOG2E); }
;     __device__ __forceinline__ float* MBM() const { return (float*)(ws + WS_MB); }
;     __device__ __forceinline__ float* MBB() const { return (float*)(ws + WS_MB) + (NSLOT_P + NSLOT_S); }
;     __device__ __forceinline__ float* MST() const { return (float*)(ws + WS_MB) + 2 * (NSLOT_P + NSLOT_S); }
; __device__ __forceinline__ void phase_scan(Ctx& C, int l, const bool st, LAS unsigned char* lds) {
;     ...
;             for (int j = 0; j < 16; ++j) { const int slot = (b * NPC + cg0 + j) * 4 + h;
;                 const float Bc = C.MBB()[slot], Mc = C.MBM()[slot];
;                 const float mn = fmaxf(Bc + m, Mc), g = fexp(Bc + m - mn), f = fexp(Mc - mn);
;                 if (st) { base[(size_t)slot * 8192] = pk2(c0, c1); if (hn) { dnb[(size_t)slot * 128] = nn; if (p == 0) C.MST()[slot] = m; } }
;                 c0 = g * c0 + f * bflo(buf[j]); c1 = g * c1 + f * bfhi(buf[j]); nn = g * nn + f * fb[j]; m = mn; }
	v_and_b32_e32 v109, 0xffff0000, v148
	v_pk_mul_f32 v[108:109], v[62:63], v[108:109] op_sel_hi:[0,1]
	v_pk_fma_f32 v[118:119], v[118:119], v[60:61], v[108:109] op_sel_hi:[1,0,1]
	v_add_f32_e32 v39, s34, v40
	v_readlane_b32 s22, v174, 24
	v_max_f32_e32 v38, s40, v39
	v_readlane_b32 s32, v176, 24
	v_sub_f32_e32 v58, v39, v38
	v_sub_f32_e32 v59, s40, v38
	v_mul_f32_e32 v58, 0x3fb8aa3b, v58
	v_mul_f32_e32 v59, 0x3fb8aa3b, v59
	v_exp_f32_e32 v60, v58
	v_exp_f32_e32 v62, v59
	v_cvt_pk_bf16_f32 v122, v118, v119
	global_store_dword v36, v122, s[6:7]
	s_add_u32 s6, s6, 0x20000
	s_addc_u32 s7, s7, 0
	v_lshlrev_b32_e32 v108, 16, v149
	v_and_b32_e32 v109, 0xffff0000, v149
	v_pk_mul_f32 v[108:109], v[62:63], v[108:109] op_sel_hi:[0,1]
	v_pk_fma_f32 v[118:119], v[118:119], v[60:61], v[108:109] op_sel_hi:[1,0,1]
	v_add_f32_e32 v39, s22, v38
	v_readlane_b32 s34, v174, 25
	v_max_f32_e32 v40, s32, v39
	v_readlane_b32 s40, v176, 25
	v_sub_f32_e32 v58, v39, v40
	v_sub_f32_e32 v59, s32, v40
	v_mul_f32_e32 v58, 0x3fb8aa3b, v58
	v_mul_f32_e32 v59, 0x3fb8aa3b, v59
	v_exp_f32_e32 v60, v58
	v_exp_f32_e32 v62, v59
	v_cvt_pk_bf16_f32 v122, v118, v119
	global_store_dword v36, v122, s[6:7]
	s_add_u32 s6, s6, 0x20000
	s_addc_u32 s7, s7, 0
	v_lshlrev_b32_e32 v108, 16, v150
	v_and_b32_e32 v109, 0xffff0000, v150
	v_pk_mul_f32 v[108:109], v[62:63], v[108:109] op_sel_hi:[0,1]
	v_pk_fma_f32 v[118:119], v[118:119], v[60:61], v[108:109] op_sel_hi:[1,0,1]
	v_add_f32_e32 v39, s34, v40
	v_readlane_b32 s22, v174, 26
	v_max_f32_e32 v38, s40, v39
	v_readlane_b32 s32, v176, 26
	v_sub_f32_e32 v58, v39, v38
	v_sub_f32_e32 v59, s40, v38
	v_mul_f32_e32 v58, 0x3fb8aa3b, v58
	v_mul_f32_e32 v59, 0x3fb8aa3b, v59
	v_exp_f32_e32 v60, v58
	v_exp_f32_e32 v62, v59
	v_cvt_pk_bf16_f32 v122, v118, v119
	global_store_dword v36, v122, s[6:7]
	s_add_u32 s6, s6, 0x20000
	s_addc_u32 s7, s7, 0
	v_lshlrev_b32_e32 v108, 16, v151
	v_and_b32_e32 v109, 0xffff0000, v151
	v_pk_mul_f32 v[108:109], v[62:63], v[108:109] op_sel_hi:[0,1]
	v_pk_fma_f32 v[118:119], v[118:119], v[60:61], v[108:109] op_sel_hi:[1,0,1]
	v_add_f32_e32 v39, s22, v38
	v_readlane_b32 s34, v174, 27
	v_max_f32_e32 v40, s32, v39
	v_readlane_b32 s40, v176, 27
	v_sub_f32_e32 v58, v39, v40
	v_sub_f32_e32 v59, s32, v40
	v_mul_f32_e32 v58, 0x3fb8aa3b, v58
	v_mul_f32_e32 v59, 0x3fb8aa3b, v59
	v_exp_f32_e32 v60, v58
	v_exp_f32_e32 v62, v59
	v_cvt_pk_bf16_f32 v122, v118, v119
	global_store_dword v36, v122, s[6:7]
	s_add_u32 s6, s6, 0x20000
	s_addc_u32 s7, s7, 0
	v_lshlrev_b32_e32 v108, 16, v152
	v_and_b32_e32 v109, 0xffff0000, v152
	v_pk_mul_f32 v[108:109], v[62:63], v[108:109] op_sel_hi:[0,1]
	v_pk_fma_f32 v[118:119], v[118:119], v[60:61], v[108:109] op_sel_hi:[1,0,1]
	v_add_f32_e32 v39, s34, v40
	v_readlane_b32 s22, v174, 28
	v_max_f32_e32 v38, s40, v39
	v_readlane_b32 s32, v176, 28
	v_sub_f32_e32 v58, v39, v38
	v_sub_f32_e32 v59, s40, v38
	v_mul_f32_e32 v58, 0x3fb8aa3b, v58
	v_mul_f32_e32 v59, 0x3fb8aa3b, v59
	v_exp_f32_e32 v60, v58
	v_exp_f32_e32 v62, v59
	v_cvt_pk_bf16_f32 v122, v118, v119
	global_store_dword v36, v122, s[6:7]
	s_add_u32 s6, s6, 0x20000
	s_addc_u32 s7, s7, 0
	v_lshlrev_b32_e32 v108, 16, v153
	v_and_b32_e32 v109, 0xffff0000, v153
	v_pk_mul_f32 v[108:109], v[62:63], v[108:109] op_sel_hi:[0,1]
	v_pk_fma_f32 v[118:119], v[118:119], v[60:61], v[108:109] op_sel_hi:[1,0,1]
	v_add_f32_e32 v39, s22, v38
	v_readlane_b32 s34, v174, 29
	v_max_f32_e32 v40, s32, v39
	v_readlane_b32 s40, v176, 29
	v_sub_f32_e32 v58, v39, v40
	v_sub_f32_e32 v59, s32, v40
	v_mul_f32_e32 v58, 0x3fb8aa3b, v58
	v_mul_f32_e32 v59, 0x3fb8aa3b, v59
	v_exp_f32_e32 v60, v58
	v_exp_f32_e32 v62, v59
	v_cvt_pk_bf16_f32 v122, v118, v119
	global_store_dword v36, v122, s[6:7]
	s_add_u32 s6, s6, 0x20000
	s_addc_u32 s7, s7, 0
	v_lshlrev_b32_e32 v108, 16, v154
	v_and_b32_e32 v109, 0xffff0000, v154
	v_pk_mul_f32 v[108:109], v[62:63], v[108:109] op_sel_hi:[0,1]
	v_pk_fma_f32 v[118:119], v[118:119], v[60:61], v[108:109] op_sel_hi:[1,0,1]
	v_add_f32_e32 v39, s34, v40
	v_readlane_b32 s22, v174, 30
	v_max_f32_e32 v38, s40, v39
	v_readlane_b32 s32, v176, 30
	v_sub_f32_e32 v58, v39, v38
	v_sub_f32_e32 v59, s40, v38
	v_mul_f32_e32 v58, 0x3fb8aa3b, v58
	v_mul_f32_e32 v59, 0x3fb8aa3b, v59
	v_exp_f32_e32 v60, v58
	v_exp_f32_e32 v62, v59
	v_cvt_pk_bf16_f32 v122, v118, v119
	global_store_dword v36, v122, s[6:7]
	s_add_u32 s6, s6, 0x20000
	s_addc_u32 s7, s7, 0
	v_lshlrev_b32_e32 v108, 16, v155
	v_and_b32_e32 v109, 0xffff0000, v155
	v_pk_mul_f32 v[108:109], v[62:63], v[108:109] op_sel_hi:[0,1]
	v_pk_fma_f32 v[118:119], v[118:119], v[60:61], v[108:109] op_sel_hi:[1,0,1]
	v_add_f32_e32 v39, s22, v38
	v_readlane_b32 s34, v174, 31
	v_max_f32_e32 v40, s32, v39
	v_readlane_b32 s40, v176, 31
	v_sub_f32_e32 v58, v39, v40
	v_sub_f32_e32 v59, s32, v40
	v_mul_f32_e32 v58, 0x3fb8aa3b, v58
	v_mul_f32_e32 v59, 0x3fb8aa3b, v59
	v_exp_f32_e32 v60, v58
	v_exp_f32_e32 v62, v59
	v_cvt_pk_bf16_f32 v122, v118, v119
	global_store_dword v36, v122, s[6:7]
	s_add_u32 s6, s6, 0x20000
	s_addc_u32 s7, s7, 0
	v_lshlrev_b32_e32 v108, 16, v156
	v_and_b32_e32 v109, 0xffff0000, v156
	v_pk_mul_f32 v[108:109], v[62:63], v[108:109] op_sel_hi:[0,1]
	v_pk_fma_f32 v[118:119], v[118:119], v[60:61], v[108:109] op_sel_hi:[1,0,1]
	v_add_f32_e32 v39, s34, v40
	v_readlane_b32 s22, v174, 32
	v_max_f32_e32 v38, s40, v39
	v_readlane_b32 s32, v176, 32
	v_sub_f32_e32 v58, v39, v38
	v_sub_f32_e32 v59, s40, v38
	v_mul_f32_e32 v58, 0x3fb8aa3b, v58
	v_mul_f32_e32 v59, 0x3fb8aa3b, v59
	v_exp_f32_e32 v60, v58
	v_exp_f32_e32 v62, v59
	v_cvt_pk_bf16_f32 v122, v118, v119
	global_store_dword v36, v122, s[6:7]
	s_add_u32 s6, s6, 0x20000
	s_addc_u32 s7, s7, 0
	v_lshlrev_b32_e32 v108, 16, v157
	v_and_b32_e32 v109, 0xffff0000, v157
	v_pk_mul_f32 v[108:109], v[62:63], v[108:109] op_sel_hi:[0,1]
	v_pk_fma_f32 v[118:119], v[118:119], v[60:61], v[108:109] op_sel_hi:[1,0,1]
; __device__ __forceinline__ unsigned pk2(float lo, float hi) { f32x2_t v = {lo, hi}; bf16x2_t b = __builtin_convertvector(v, bf16x2_t); return __builtin_bit_cast(unsigned, b); }
; __device__ __forceinline__ float bflo(unsigned w) { return __uint_as_float(w << 16); }
; __device__ __forceinline__ float bfhi(unsigned w) { return __uint_as_float(w & 0xffff0000u); }
; __device__ __forceinline__ float fexp(float x) { return __builtin_amdgcn_exp2f(x * LOG2E); }
;     __device__ __forceinline__ float* MBM() const { return (float*)(ws + WS_MB); }
;     __device__ __forceinline__ float* MBB() const { return (float*)(ws + WS_MB) + (NSLOT_P + NSLOT_S); }
;     __device__ __forceinline__ float* MST() const { return (float*)(ws + WS_MB) + 2 * (NSLOT_P + NSLOT_S); }
; __device__ __forceinline__ void phase_scan(Ctx& C, int l, const bool st, LAS unsigned char* lds) {
;     ...
;         for (int cg0 = 0; cg0 < NPC; cg0 += 16) {
;             if (cg0 + 16 < NPC) {
; #pragma unroll
;                 for (int j = 0; j < 16; ++j) { nb[j] = base[(size_t)((b * NPC + cg0 + 16 + j) * 4 + h) * 8192]; fnb[j] = hn ? dnb[(size_t)((b * NPC + cg0 + 16 + j) * 4 + h) * 128] : 0.f; }
;             }
; #pragma unroll
;             for (int j = 0; j < 16; ++j) { const int slot = (b * NPC + cg0 + j) * 4 + h;
;                 const float Bc = C.MBB()[slot], Mc = C.MBM()[slot];
;                 const float mn = fmaxf(Bc + m, Mc), g = fexp(Bc + m - mn), f = fexp(Mc - mn);
;                 if (st) { base[(size_t)slot * 8192] = pk2(c0, c1); if (hn) { dnb[(size_t)slot * 128] = nn; if (p == 0) C.MST()[slot] = m; } }
;                 c0 = g * c0 + f * bflo(buf[j]); c1 = g * c1 + f * bfhi(buf[j]); nn = g * nn + f * fb[j]; m = mn; }
.Lscan_nh_b2:
	s_waitcnt vmcnt(32)
	global_load_dword v142, v36, s[4:5]
	s_add_u32 s4, s4, 0x20000
	s_addc_u32 s5, s5, 0
	global_load_dword v143, v36, s[4:5]
	s_add_u32 s4, s4, 0x20000
	s_addc_u32 s5, s5, 0
	global_load_dword v144, v36, s[4:5]
	s_add_u32 s4, s4, 0x20000
	s_addc_u32 s5, s5, 0
	global_load_dword v145, v36, s[4:5]
	s_add_u32 s4, s4, 0x20000
	s_addc_u32 s5, s5, 0
	global_load_dword v146, v36, s[4:5]
	s_add_u32 s4, s4, 0x20000
	s_addc_u32 s5, s5, 0
	global_load_dword v147, v36, s[4:5]
	s_add_u32 s4, s4, 0x20000
	s_addc_u32 s5, s5, 0
	global_load_dword v148, v36, s[4:5]
	s_add_u32 s4, s4, 0x20000
	s_addc_u32 s5, s5, 0
	global_load_dword v149, v36, s[4:5]
	s_add_u32 s4, s4, 0x20000
	s_addc_u32 s5, s5, 0
	global_load_dword v150, v36, s[4:5]
	s_add_u32 s4, s4, 0x20000
	s_addc_u32 s5, s5, 0
	global_load_dword v151, v36, s[4:5]
	s_add_u32 s4, s4, 0x20000
	s_addc_u32 s5, s5, 0
	global_load_dword v152, v36, s[4:5]
	s_add_u32 s4, s4, 0x20000
	s_addc_u32 s5, s5, 0
	global_load_dword v153, v36, s[4:5]
	s_add_u32 s4, s4, 0x20000
	s_addc_u32 s5, s5, 0
	global_load_dword v154, v36, s[4:5]
	s_add_u32 s4, s4, 0x20000
	s_addc_u32 s5, s5, 0
	global_load_dword v155, v36, s[4:5]
	s_add_u32 s4, s4, 0x20000
	s_addc_u32 s5, s5, 0
	global_load_dword v156, v36, s[4:5]
	s_add_u32 s4, s4, 0x20000
	s_addc_u32 s5, s5, 0
	global_load_dword v157, v36, s[4:5]
	s_add_u32 s4, s4, 0x20000
	s_addc_u32 s5, s5, 0
	v_add_f32_e32 v39, s22, v38
	v_readlane_b32 s34, v174, 33
	v_max_f32_e32 v40, s32, v39
	v_readlane_b32 s40, v176, 33
	v_sub_f32_e32 v58, v39, v40
	v_sub_f32_e32 v59, s32, v40
	v_mul_f32_e32 v58, 0x3fb8aa3b, v58
	v_mul_f32_e32 v59, 0x3fb8aa3b, v59
	v_exp_f32_e32 v60, v58
	v_exp_f32_e32 v62, v59
	v_cvt_pk_bf16_f32 v122, v118, v119
	global_store_dword v36, v122, s[6:7]
	s_add_u32 s6, s6, 0x20000
	s_addc_u32 s7, s7, 0
	v_lshlrev_b32_e32 v108, 16, v158
	v_and_b32_e32 v109, 0xffff0000, v158
	v_pk_mul_f32 v[108:109], v[62:63], v[108:109] op_sel_hi:[0,1]
	v_pk_fma_f32 v[118:119], v[118:119], v[60:61], v[108:109] op_sel_hi:[1,0,1]
	v_add_f32_e32 v39, s34, v40
	v_readlane_b32 s22, v174, 34
	v_max_f32_e32 v38, s40, v39
	v_readlane_b32 s32, v176, 34
	v_sub_f32_e32 v58, v39, v38
	v_sub_f32_e32 v59, s40, v38
	v_mul_f32_e32 v58, 0x3fb8aa3b, v58
	v_mul_f32_e32 v59, 0x3fb8aa3b, v59
	v_exp_f32_e32 v60, v58
	v_exp_f32_e32 v62, v59
	v_cvt_pk_bf16_f32 v122, v118, v119
	global_store_dword v36, v122, s[6:7]
	s_add_u32 s6, s6, 0x20000
	s_addc_u32 s7, s7, 0
	v_lshlrev_b32_e32 v108, 16, v159
	v_and_b32_e32 v109, 0xffff0000, v159
	v_pk_mul_f32 v[108:109], v[62:63], v[108:109] op_sel_hi:[0,1]
	v_pk_fma_f32 v[118:119], v[118:119], v[60:61], v[108:109] op_sel_hi:[1,0,1]
	v_add_f32_e32 v39, s22, v38
	v_readlane_b32 s34, v174, 35
	v_max_f32_e32 v40, s32, v39
	v_readlane_b32 s40, v176, 35
	v_sub_f32_e32 v58, v39, v40
	v_sub_f32_e32 v59, s32, v40
	v_mul_f32_e32 v58, 0x3fb8aa3b, v58
	v_mul_f32_e32 v59, 0x3fb8aa3b, v59
	v_exp_f32_e32 v60, v58
	v_exp_f32_e32 v62, v59
	v_cvt_pk_bf16_f32 v122, v118, v119
	global_store_dword v36, v122, s[6:7]
	s_add_u32 s6, s6, 0x20000
	s_addc_u32 s7, s7, 0
	v_lshlrev_b32_e32 v108, 16, v160
	v_and_b32_e32 v109, 0xffff0000, v160
	v_pk_mul_f32 v[108:109], v[62:63], v[108:109] op_sel_hi:[0,1]
	v_pk_fma_f32 v[118:119], v[118:119], v[60:61], v[108:109] op_sel_hi:[1,0,1]
	v_add_f32_e32 v39, s34, v40
	v_readlane_b32 s22, v174, 36
	v_max_f32_e32 v38, s40, v39
	v_readlane_b32 s32, v176, 36
	v_sub_f32_e32 v58, v39, v38
	v_sub_f32_e32 v59, s40, v38
	v_mul_f32_e32 v58, 0x3fb8aa3b, v58
	v_mul_f32_e32 v59, 0x3fb8aa3b, v59
	v_exp_f32_e32 v60, v58
	v_exp_f32_e32 v62, v59
	v_cvt_pk_bf16_f32 v122, v118, v119
	global_store_dword v36, v122, s[6:7]
	s_add_u32 s6, s6, 0x20000
	s_addc_u32 s7, s7, 0
	v_lshlrev_b32_e32 v108, 16, v161
	v_and_b32_e32 v109, 0xffff0000, v161
	v_pk_mul_f32 v[108:109], v[62:63], v[108:109] op_sel_hi:[0,1]
	v_pk_fma_f32 v[118:119], v[118:119], v[60:61], v[108:109] op_sel_hi:[1,0,1]
	v_add_f32_e32 v39, s22, v38
	v_readlane_b32 s34, v174, 37
	v_max_f32_e32 v40, s32, v39
	v_readlane_b32 s40, v176, 37
	v_sub_f32_e32 v58, v39, v40
	v_sub_f32_e32 v59, s32, v40
	v_mul_f32_e32 v58, 0x3fb8aa3b, v58
	v_mul_f32_e32 v59, 0x3fb8aa3b, v59
	v_exp_f32_e32 v60, v58
	v_exp_f32_e32 v62, v59
	v_cvt_pk_bf16_f32 v122, v118, v119
	global_store_dword v36, v122, s[6:7]
	s_add_u32 s6, s6, 0x20000
	s_addc_u32 s7, s7, 0
	v_lshlrev_b32_e32 v108, 16, v162
	v_and_b32_e32 v109, 0xffff0000, v162
	v_pk_mul_f32 v[108:109], v[62:63], v[108:109] op_sel_hi:[0,1]
	v_pk_fma_f32 v[118:119], v[118:119], v[60:61], v[108:109] op_sel_hi:[1,0,1]
	v_add_f32_e32 v39, s34, v40
	v_readlane_b32 s22, v174, 38
	v_max_f32_e32 v38, s40, v39
	v_readlane_b32 s32, v176, 38
	v_sub_f32_e32 v58, v39, v38
	v_sub_f32_e32 v59, s40, v38
	v_mul_f32_e32 v58, 0x3fb8aa3b, v58
	v_mul_f32_e32 v59, 0x3fb8aa3b, v59
	v_exp_f32_e32 v60, v58
	v_exp_f32_e32 v62, v59
	v_cvt_pk_bf16_f32 v122, v118, v119
	global_store_dword v36, v122, s[6:7]
	s_add_u32 s6, s6, 0x20000
	s_addc_u32 s7, s7, 0
	v_lshlrev_b32_e32 v108, 16, v163
	v_and_b32_e32 v109, 0xffff0000, v163
	v_pk_mul_f32 v[108:109], v[62:63], v[108:109] op_sel_hi:[0,1]
	v_pk_fma_f32 v[118:119], v[118:119], v[60:61], v[108:109] op_sel_hi:[1,0,1]
	v_add_f32_e32 v39, s22, v38
	v_readlane_b32 s34, v174, 39
	v_max_f32_e32 v40, s32, v39
	v_readlane_b32 s40, v176, 39
	v_sub_f32_e32 v58, v39, v40
	v_sub_f32_e32 v59, s32, v40
	v_mul_f32_e32 v58, 0x3fb8aa3b, v58
	v_mul_f32_e32 v59, 0x3fb8aa3b, v59
	v_exp_f32_e32 v60, v58
	v_exp_f32_e32 v62, v59
	v_cvt_pk_bf16_f32 v122, v118, v119
	global_store_dword v36, v122, s[6:7]
	s_add_u32 s6, s6, 0x20000
	s_addc_u32 s7, s7, 0
	v_lshlrev_b32_e32 v108, 16, v164
; __device__ __forceinline__ unsigned pk2(float lo, float hi) { f32x2_t v = {lo, hi}; bf16x2_t b = __builtin_convertvector(v, bf16x2_t); return __builtin_bit_cast(unsigned, b); }
; __device__ __forceinline__ float bflo(unsigned w) { return __uint_as_float(w << 16); }
; __device__ __forceinline__ float bfhi(unsigned w) { return __uint_as_float(w & 0xffff0000u); }
; __device__ __forceinline__ float fexp(float x) { return __builtin_amdgcn_exp2f(x * LOG2E); }
;     __device__ __forceinline__ float* MBM() const { return (float*)(ws + WS_MB); }
;     __device__ __forceinline__ float* MBB() const { return (float*)(ws + WS_MB) + (NSLOT_P + NSLOT_S); }
;     __device__ __forceinline__ float* MST() const { return (float*)(ws + WS_MB) + 2 * (NSLOT_P + NSLOT_S); }
; __device__ __forceinline__ void phase_scan(Ctx& C, int l, const bool st, LAS unsigned char* lds) {
;     ...
;             for (int j = 0; j < 16; ++j) { const int slot = (b * NPC + cg0 + j) * 4 + h;
;                 const float Bc = C.MBB()[slot], Mc = C.MBM()[slot];
;                 const float mn = fmaxf(Bc + m, Mc), g = fexp(Bc + m - mn), f = fexp(Mc - mn);
;                 if (st) { base[(size_t)slot * 8192] = pk2(c0, c1); if (hn) { dnb[(size_t)slot * 128] = nn; if (p == 0) C.MST()[slot] = m; } }
;                 c0 = g * c0 + f * bflo(buf[j]); c1 = g * c1 + f * bfhi(buf[j]); nn = g * nn + f * fb[j]; m = mn; }
	v_and_b32_e32 v109, 0xffff0000, v164
	v_pk_mul_f32 v[108:109], v[62:63], v[108:109] op_sel_hi:[0,1]
	v_pk_fma_f32 v[118:119], v[118:119], v[60:61], v[108:109] op_sel_hi:[1,0,1]
	v_add_f32_e32 v39, s34, v40
	v_readlane_b32 s22, v174, 40
	v_max_f32_e32 v38, s40, v39
	v_readlane_b32 s32, v176, 40
	v_sub_f32_e32 v58, v39, v38
	v_sub_f32_e32 v59, s40, v38
	v_mul_f32_e32 v58, 0x3fb8aa3b, v58
	v_mul_f32_e32 v59, 0x3fb8aa3b, v59
	v_exp_f32_e32 v60, v58
	v_exp_f32_e32 v62, v59
	v_cvt_pk_bf16_f32 v122, v118, v119
	global_store_dword v36, v122, s[6:7]
	s_add_u32 s6, s6, 0x20000
	s_addc_u32 s7, s7, 0
	v_lshlrev_b32_e32 v108, 16, v165
	v_and_b32_e32 v109, 0xffff0000, v165
	v_pk_mul_f32 v[108:109], v[62:63], v[108:109] op_sel_hi:[0,1]
	v_pk_fma_f32 v[118:119], v[118:119], v[60:61], v[108:109] op_sel_hi:[1,0,1]
	v_add_f32_e32 v39, s22, v38
	v_readlane_b32 s34, v174, 41
	v_max_f32_e32 v40, s32, v39
	v_readlane_b32 s40, v176, 41
	v_sub_f32_e32 v58, v39, v40
	v_sub_f32_e32 v59, s32, v40
	v_mul_f32_e32 v58, 0x3fb8aa3b, v58
	v_mul_f32_e32 v59, 0x3fb8aa3b, v59
	v_exp_f32_e32 v60, v58
	v_exp_f32_e32 v62, v59
	v_cvt_pk_bf16_f32 v122, v118, v119
	global_store_dword v36, v122, s[6:7]
	s_add_u32 s6, s6, 0x20000
	s_addc_u32 s7, s7, 0
	v_lshlrev_b32_e32 v108, 16, v166
	v_and_b32_e32 v109, 0xffff0000, v166
	v_pk_mul_f32 v[108:109], v[62:63], v[108:109] op_sel_hi:[0,1]
	v_pk_fma_f32 v[118:119], v[118:119], v[60:61], v[108:109] op_sel_hi:[1,0,1]
	v_add_f32_e32 v39, s34, v40
	v_readlane_b32 s22, v174, 42
	v_max_f32_e32 v38, s40, v39
	v_readlane_b32 s32, v176, 42
	v_sub_f32_e32 v58, v39, v38
	v_sub_f32_e32 v59, s40, v38
	v_mul_f32_e32 v58, 0x3fb8aa3b, v58
	v_mul_f32_e32 v59, 0x3fb8aa3b, v59
	v_exp_f32_e32 v60, v58
	v_exp_f32_e32 v62, v59
	v_cvt_pk_bf16_f32 v122, v118, v119
	global_store_dword v36, v122, s[6:7]
	s_add_u32 s6, s6, 0x20000
	s_addc_u32 s7, s7, 0
	v_lshlrev_b32_e32 v108, 16, v167
	v_and_b32_e32 v109, 0xffff0000, v167
	v_pk_mul_f32 v[108:109], v[62:63], v[108:109] op_sel_hi:[0,1]
	v_pk_fma_f32 v[118:119], v[118:119], v[60:61], v[108:109] op_sel_hi:[1,0,1]
	v_add_f32_e32 v39, s22, v38
	v_readlane_b32 s34, v174, 43
	v_max_f32_e32 v40, s32, v39
	v_readlane_b32 s40, v176, 43
	v_sub_f32_e32 v58, v39, v40
	v_sub_f32_e32 v59, s32, v40
	v_mul_f32_e32 v58, 0x3fb8aa3b, v58
	v_mul_f32_e32 v59, 0x3fb8aa3b, v59
	v_exp_f32_e32 v60, v58
	v_exp_f32_e32 v62, v59
	v_cvt_pk_bf16_f32 v122, v118, v119
	global_store_dword v36, v122, s[6:7]
	s_add_u32 s6, s6, 0x20000
	s_addc_u32 s7, s7, 0
	v_lshlrev_b32_e32 v108, 16, v168
	v_and_b32_e32 v109, 0xffff0000, v168
	v_pk_mul_f32 v[108:109], v[62:63], v[108:109] op_sel_hi:[0,1]
	v_pk_fma_f32 v[118:119], v[118:119], v[60:61], v[108:109] op_sel_hi:[1,0,1]
	v_add_f32_e32 v39, s34, v40
	v_readlane_b32 s22, v174, 44
	v_max_f32_e32 v38, s40, v39
	v_readlane_b32 s32, v176, 44
	v_sub_f32_e32 v58, v39, v38
	v_sub_f32_e32 v59, s40, v38
	v_mul_f32_e32 v58, 0x3fb8aa3b, v58
	v_mul_f32_e32 v59, 0x3fb8aa3b, v59
	v_exp_f32_e32 v60, v58
	v_exp_f32_e32 v62, v59
	v_cvt_pk_bf16_f32 v122, v118, v119
	global_store_dword v36, v122, s[6:7]
	s_add_u32 s6, s6, 0x20000
	s_addc_u32 s7, s7, 0
	v_lshlrev_b32_e32 v108, 16, v169
	v_and_b32_e32 v109, 0xffff0000, v169
	v_pk_mul_f32 v[108:109], v[62:63], v[108:109] op_sel_hi:[0,1]
	v_pk_fma_f32 v[118:119], v[118:119], v[60:61], v[108:109] op_sel_hi:[1,0,1]
	v_add_f32_e32 v39, s22, v38
	v_readlane_b32 s34, v174, 45
	v_max_f32_e32 v40, s32, v39
	v_readlane_b32 s40, v176, 45
	v_sub_f32_e32 v58, v39, v40
	v_sub_f32_e32 v59, s32, v40
	v_mul_f32_e32 v58, 0x3fb8aa3b, v58
	v_mul_f32_e32 v59, 0x3fb8aa3b, v59
	v_exp_f32_e32 v60, v58
	v_exp_f32_e32 v62, v59
	v_cvt_pk_bf16_f32 v122, v118, v119
	global_store_dword v36, v122, s[6:7]
	s_add_u32 s6, s6, 0x20000
	s_addc_u32 s7, s7, 0
	v_lshlrev_b32_e32 v108, 16, v170
	v_and_b32_e32 v109, 0xffff0000, v170
	v_pk_mul_f32 v[108:109], v[62:63], v[108:109] op_sel_hi:[0,1]
	v_pk_fma_f32 v[118:119], v[118:119], v[60:61], v[108:109] op_sel_hi:[1,0,1]
	v_add_f32_e32 v39, s34, v40
	v_readlane_b32 s22, v174, 46
	v_max_f32_e32 v38, s40, v39
	v_readlane_b32 s32, v176, 46
	v_sub_f32_e32 v58, v39, v38
	v_sub_f32_e32 v59, s40, v38
	v_mul_f32_e32 v58, 0x3fb8aa3b, v58
	v_mul_f32_e32 v59, 0x3fb8aa3b, v59
	v_exp_f32_e32 v60, v58
	v_exp_f32_e32 v62, v59
	v_cvt_pk_bf16_f32 v122, v118, v119
	global_store_dword v36, v122, s[6:7]
	s_add_u32 s6, s6, 0x20000
	s_addc_u32 s7, s7, 0
	v_lshlrev_b32_e32 v108, 16, v171
	v_and_b32_e32 v109, 0xffff0000, v171
	v_pk_mul_f32 v[108:109], v[62:63], v[108:109] op_sel_hi:[0,1]
	v_pk_fma_f32 v[118:119], v[118:119], v[60:61], v[108:109] op_sel_hi:[1,0,1]
	v_add_f32_e32 v39, s22, v38
	v_readlane_b32 s34, v174, 47
	v_max_f32_e32 v40, s32, v39
	v_readlane_b32 s40, v176, 47
	v_sub_f32_e32 v58, v39, v40
	v_sub_f32_e32 v59, s32, v40
	v_mul_f32_e32 v58, 0x3fb8aa3b, v58
	v_mul_f32_e32 v59, 0x3fb8aa3b, v59
	v_exp_f32_e32 v60, v58
	v_exp_f32_e32 v62, v59
	v_cvt_pk_bf16_f32 v122, v118, v119
	global_store_dword v36, v122, s[6:7]
	s_add_u32 s6, s6, 0x20000
	s_addc_u32 s7, s7, 0
	v_lshlrev_b32_e32 v108, 16, v172
	v_and_b32_e32 v109, 0xffff0000, v172
	v_pk_mul_f32 v[108:109], v[62:63], v[108:109] op_sel_hi:[0,1]
	v_pk_fma_f32 v[118:119], v[118:119], v[60:61], v[108:109] op_sel_hi:[1,0,1]
	v_add_f32_e32 v39, s34, v40
	v_readlane_b32 s22, v174, 48
	v_max_f32_e32 v38, s40, v39
	v_readlane_b32 s32, v176, 48
	v_sub_f32_e32 v58, v39, v38
	v_sub_f32_e32 v59, s40, v38
	v_mul_f32_e32 v58, 0x3fb8aa3b, v58
	v_mul_f32_e32 v59, 0x3fb8aa3b, v59
	v_exp_f32_e32 v60, v58
	v_exp_f32_e32 v62, v59
	v_cvt_pk_bf16_f32 v122, v118, v119
	global_store_dword v36, v122, s[6:7]
	s_add_u32 s6, s6, 0x20000
	s_addc_u32 s7, s7, 0
	v_lshlrev_b32_e32 v108, 16, v173
	v_and_b32_e32 v109, 0xffff0000, v173
	v_pk_mul_f32 v[108:109], v[62:63], v[108:109] op_sel_hi:[0,1]
	v_pk_fma_f32 v[118:119], v[118:119], v[60:61], v[108:109] op_sel_hi:[1,0,1]
; __device__ __forceinline__ unsigned pk2(float lo, float hi) { f32x2_t v = {lo, hi}; bf16x2_t b = __builtin_convertvector(v, bf16x2_t); return __builtin_bit_cast(unsigned, b); }
; __device__ __forceinline__ float bflo(unsigned w) { return __uint_as_float(w << 16); }
; __device__ __forceinline__ float bfhi(unsigned w) { return __uint_as_float(w & 0xffff0000u); }
; __device__ __forceinline__ float fexp(float x) { return __builtin_amdgcn_exp2f(x * LOG2E); }
;     __device__ __forceinline__ float* MBM() const { return (float*)(ws + WS_MB); }
;     __device__ __forceinline__ float* MBB() const { return (float*)(ws + WS_MB) + (NSLOT_P + NSLOT_S); }
;     __device__ __forceinline__ float* MST() const { return (float*)(ws + WS_MB) + 2 * (NSLOT_P + NSLOT_S); }
; __device__ __forceinline__ void phase_scan(Ctx& C, int l, const bool st, LAS unsigned char* lds) {
;     ...
;         for (int cg0 = 0; cg0 < NPC; cg0 += 16) {
;             if (cg0 + 16 < NPC) {
; #pragma unroll
;                 for (int j = 0; j < 16; ++j) { nb[j] = base[(size_t)((b * NPC + cg0 + 16 + j) * 4 + h) * 8192]; fnb[j] = hn ? dnb[(size_t)((b * NPC + cg0 + 16 + j) * 4 + h) * 128] : 0.f; }
;             }
; #pragma unroll
;             for (int j = 0; j < 16; ++j) { const int slot = (b * NPC + cg0 + j) * 4 + h;
;                 const float Bc = C.MBB()[slot], Mc = C.MBM()[slot];
;                 const float mn = fmaxf(Bc + m, Mc), g = fexp(Bc + m - mn), f = fexp(Mc - mn);
;                 if (st) { base[(size_t)slot * 8192] = pk2(c0, c1); if (hn) { dnb[(size_t)slot * 128] = nn; if (p == 0) C.MST()[slot] = m; } }
;                 c0 = g * c0 + f * bflo(buf[j]); c1 = g * c1 + f * bfhi(buf[j]); nn = g * nn + f * fb[j]; m = mn; }
.Lscan_nh_b3:
	s_waitcnt vmcnt(32)
	global_load_dword v158, v36, s[4:5]
	s_add_u32 s4, s4, 0x20000
	s_addc_u32 s5, s5, 0
	global_load_dword v159, v36, s[4:5]
	s_add_u32 s4, s4, 0x20000
	s_addc_u32 s5, s5, 0
	global_load_dword v160, v36, s[4:5]
	s_add_u32 s4, s4, 0x20000
	s_addc_u32 s5, s5, 0
	global_load_dword v161, v36, s[4:5]
	s_add_u32 s4, s4, 0x20000
	s_addc_u32 s5, s5, 0
	global_load_dword v162, v36, s[4:5]
	s_add_u32 s4, s4, 0x20000
	s_addc_u32 s5, s5, 0
	global_load_dword v163, v36, s[4:5]
	s_add_u32 s4, s4, 0x20000
	s_addc_u32 s5, s5, 0
	global_load_dword v164, v36, s[4:5]
	s_add_u32 s4, s4, 0x20000
	s_addc_u32 s5, s5, 0
	global_load_dword v165, v36, s[4:5]
	s_add_u32 s4, s4, 0x20000
	s_addc_u32 s5, s5, 0
	global_load_dword v166, v36, s[4:5]
	s_add_u32 s4, s4, 0x20000
	s_addc_u32 s5, s5, 0
	global_load_dword v167, v36, s[4:5]
	s_add_u32 s4, s4, 0x20000
	s_addc_u32 s5, s5, 0
	global_load_dword v168, v36, s[4:5]
	s_add_u32 s4, s4, 0x20000
	s_addc_u32 s5, s5, 0
	global_load_dword v169, v36, s[4:5]
	s_add_u32 s4, s4, 0x20000
	s_addc_u32 s5, s5, 0
	global_load_dword v170, v36, s[4:5]
	s_add_u32 s4, s4, 0x20000
	s_addc_u32 s5, s5, 0
	global_load_dword v171, v36, s[4:5]
	s_add_u32 s4, s4, 0x20000
	s_addc_u32 s5, s5, 0
	global_load_dword v172, v36, s[4:5]
	s_add_u32 s4, s4, 0x20000
	s_addc_u32 s5, s5, 0
	global_load_dword v173, v36, s[4:5]
	s_add_u32 s4, s4, 0x20000
	s_addc_u32 s5, s5, 0
	v_add_f32_e32 v39, s22, v38
	v_readlane_b32 s34, v174, 49
	v_max_f32_e32 v40, s32, v39
	v_readlane_b32 s40, v176, 49
	v_sub_f32_e32 v58, v39, v40
	v_sub_f32_e32 v59, s32, v40
	v_mul_f32_e32 v58, 0x3fb8aa3b, v58
	v_mul_f32_e32 v59, 0x3fb8aa3b, v59
	v_exp_f32_e32 v60, v58
	v_exp_f32_e32 v62, v59
	v_cvt_pk_bf16_f32 v122, v118, v119
	global_store_dword v36, v122, s[6:7]
	s_add_u32 s6, s6, 0x20000
	s_addc_u32 s7, s7, 0
	v_lshlrev_b32_e32 v108, 16, v126
	v_and_b32_e32 v109, 0xffff0000, v126
	v_pk_mul_f32 v[108:109], v[62:63], v[108:109] op_sel_hi:[0,1]
	v_pk_fma_f32 v[118:119], v[118:119], v[60:61], v[108:109] op_sel_hi:[1,0,1]
	v_add_f32_e32 v39, s34, v40
	v_readlane_b32 s22, v174, 50
	v_max_f32_e32 v38, s40, v39
	v_readlane_b32 s32, v176, 50
	v_sub_f32_e32 v58, v39, v38
	v_sub_f32_e32 v59, s40, v38
	v_mul_f32_e32 v58, 0x3fb8aa3b, v58
	v_mul_f32_e32 v59, 0x3fb8aa3b, v59
	v_exp_f32_e32 v60, v58
	v_exp_f32_e32 v62, v59
	v_cvt_pk_bf16_f32 v122, v118, v119
	global_store_dword v36, v122, s[6:7]
	s_add_u32 s6, s6, 0x20000
	s_addc_u32 s7, s7, 0
	v_lshlrev_b32_e32 v108, 16, v127
	v_and_b32_e32 v109, 0xffff0000, v127
	v_pk_mul_f32 v[108:109], v[62:63], v[108:109] op_sel_hi:[0,1]
	v_pk_fma_f32 v[118:119], v[118:119], v[60:61], v[108:109] op_sel_hi:[1,0,1]
	v_add_f32_e32 v39, s22, v38
	v_readlane_b32 s34, v174, 51
	v_max_f32_e32 v40, s32, v39
	v_readlane_b32 s40, v176, 51
	v_sub_f32_e32 v58, v39, v40
	v_sub_f32_e32 v59, s32, v40
	v_mul_f32_e32 v58, 0x3fb8aa3b, v58
	v_mul_f32_e32 v59, 0x3fb8aa3b, v59
	v_exp_f32_e32 v60, v58
	v_exp_f32_e32 v62, v59
	v_cvt_pk_bf16_f32 v122, v118, v119
	global_store_dword v36, v122, s[6:7]
	s_add_u32 s6, s6, 0x20000
	s_addc_u32 s7, s7, 0
	v_lshlrev_b32_e32 v108, 16, v128
	v_and_b32_e32 v109, 0xffff0000, v128
	v_pk_mul_f32 v[108:109], v[62:63], v[108:109] op_sel_hi:[0,1]
	v_pk_fma_f32 v[118:119], v[118:119], v[60:61], v[108:109] op_sel_hi:[1,0,1]
	v_add_f32_e32 v39, s34, v40
	v_readlane_b32 s22, v174, 52
	v_max_f32_e32 v38, s40, v39
	v_readlane_b32 s32, v176, 52
	v_sub_f32_e32 v58, v39, v38
	v_sub_f32_e32 v59, s40, v38
	v_mul_f32_e32 v58, 0x3fb8aa3b, v58
	v_mul_f32_e32 v59, 0x3fb8aa3b, v59
	v_exp_f32_e32 v60, v58
	v_exp_f32_e32 v62, v59
	v_cvt_pk_bf16_f32 v122, v118, v119
	global_store_dword v36, v122, s[6:7]
	s_add_u32 s6, s6, 0x20000
	s_addc_u32 s7, s7, 0
	v_lshlrev_b32_e32 v108, 16, v129
	v_and_b32_e32 v109, 0xffff0000, v129
	v_pk_mul_f32 v[108:109], v[62:63], v[108:109] op_sel_hi:[0,1]
	v_pk_fma_f32 v[118:119], v[118:119], v[60:61], v[108:109] op_sel_hi:[1,0,1]
	v_add_f32_e32 v39, s22, v38
	v_readlane_b32 s34, v174, 53
	v_max_f32_e32 v40, s32, v39
	v_readlane_b32 s40, v176, 53
	v_sub_f32_e32 v58, v39, v40
	v_sub_f32_e32 v59, s32, v40
	v_mul_f32_e32 v58, 0x3fb8aa3b, v58
	v_mul_f32_e32 v59, 0x3fb8aa3b, v59
	v_exp_f32_e32 v60, v58
	v_exp_f32_e32 v62, v59
	v_cvt_pk_bf16_f32 v122, v118, v119
	global_store_dword v36, v122, s[6:7]
	s_add_u32 s6, s6, 0x20000
	s_addc_u32 s7, s7, 0
	v_lshlrev_b32_e32 v108, 16, v130
	v_and_b32_e32 v109, 0xffff0000, v130
	v_pk_mul_f32 v[108:109], v[62:63], v[108:109] op_sel_hi:[0,1]
	v_pk_fma_f32 v[118:119], v[118:119], v[60:61], v[108:109] op_sel_hi:[1,0,1]
	v_add_f32_e32 v39, s34, v40
	v_readlane_b32 s22, v174, 54
	v_max_f32_e32 v38, s40, v39
	v_readlane_b32 s32, v176, 54
	v_sub_f32_e32 v58, v39, v38
	v_sub_f32_e32 v59, s40, v38
	v_mul_f32_e32 v58, 0x3fb8aa3b, v58
	v_mul_f32_e32 v59, 0x3fb8aa3b, v59
	v_exp_f32_e32 v60, v58
	v_exp_f32_e32 v62, v59
	v_cvt_pk_bf16_f32 v122, v118, v119
	global_store_dword v36, v122, s[6:7]
	s_add_u32 s6, s6, 0x20000
	s_addc_u32 s7, s7, 0
	v_lshlrev_b32_e32 v108, 16, v131
	v_and_b32_e32 v109, 0xffff0000, v131
	v_pk_mul_f32 v[108:109], v[62:63], v[108:109] op_sel_hi:[0,1]
	v_pk_fma_f32 v[118:119], v[118:119], v[60:61], v[108:109] op_sel_hi:[1,0,1]
	v_add_f32_e32 v39, s22, v38
	v_readlane_b32 s34, v174, 55
	v_max_f32_e32 v40, s32, v39
	v_readlane_b32 s40, v176, 55
	v_sub_f32_e32 v58, v39, v40
	v_sub_f32_e32 v59, s32, v40
	v_mul_f32_e32 v58, 0x3fb8aa3b, v58
	v_mul_f32_e32 v59, 0x3fb8aa3b, v59
	v_exp_f32_e32 v60, v58
	v_exp_f32_e32 v62, v59
	v_cvt_pk_bf16_f32 v122, v118, v119
	global_store_dword v36, v122, s[6:7]
	s_add_u32 s6, s6, 0x20000
	s_addc_u32 s7, s7, 0
	v_lshlrev_b32_e32 v108, 16, v132
; __device__ __forceinline__ unsigned pk2(float lo, float hi) { f32x2_t v = {lo, hi}; bf16x2_t b = __builtin_convertvector(v, bf16x2_t); return __builtin_bit_cast(unsigned, b); }
; __device__ __forceinline__ float bflo(unsigned w) { return __uint_as_float(w << 16); }
; __device__ __forceinline__ float bfhi(unsigned w) { return __uint_as_float(w & 0xffff0000u); }
; __device__ __forceinline__ float fexp(float x) { return __builtin_amdgcn_exp2f(x * LOG2E); }
;     __device__ __forceinline__ float* MBM() const { return (float*)(ws + WS_MB); }
;     __device__ __forceinline__ float* MBB() const { return (float*)(ws + WS_MB) + (NSLOT_P + NSLOT_S); }
;     __device__ __forceinline__ float* MST() const { return (float*)(ws + WS_MB) + 2 * (NSLOT_P + NSLOT_S); }
; __device__ __forceinline__ void phase_scan(Ctx& C, int l, const bool st, LAS unsigned char* lds) {
;     ...
;             for (int j = 0; j < 16; ++j) { const int slot = (b * NPC + cg0 + j) * 4 + h;
;                 const float Bc = C.MBB()[slot], Mc = C.MBM()[slot];
;                 const float mn = fmaxf(Bc + m, Mc), g = fexp(Bc + m - mn), f = fexp(Mc - mn);
;                 if (st) { base[(size_t)slot * 8192] = pk2(c0, c1); if (hn) { dnb[(size_t)slot * 128] = nn; if (p == 0) C.MST()[slot] = m; } }
;                 c0 = g * c0 + f * bflo(buf[j]); c1 = g * c1 + f * bfhi(buf[j]); nn = g * nn + f * fb[j]; m = mn; }
	v_and_b32_e32 v109, 0xffff0000, v132
	v_pk_mul_f32 v[108:109], v[62:63], v[108:109] op_sel_hi:[0,1]
	v_pk_fma_f32 v[118:119], v[118:119], v[60:61], v[108:109] op_sel_hi:[1,0,1]
	v_add_f32_e32 v39, s34, v40
	v_readlane_b32 s22, v174, 56
	v_max_f32_e32 v38, s40, v39
	v_readlane_b32 s32, v176, 56
	v_sub_f32_e32 v58, v39, v38
	v_sub_f32_e32 v59, s40, v38
	v_mul_f32_e32 v58, 0x3fb8aa3b, v58
	v_mul_f32_e32 v59, 0x3fb8aa3b, v59
	v_exp_f32_e32 v60, v58
	v_exp_f32_e32 v62, v59
	v_cvt_pk_bf16_f32 v122, v118, v119
	global_store_dword v36, v122, s[6:7]
	s_add_u32 s6, s6, 0x20000
	s_addc_u32 s7, s7, 0
	v_lshlrev_b32_e32 v108, 16, v133
	v_and_b32_e32 v109, 0xffff0000, v133
	v_pk_mul_f32 v[108:109], v[62:63], v[108:109] op_sel_hi:[0,1]
	v_pk_fma_f32 v[118:119], v[118:119], v[60:61], v[108:109] op_sel_hi:[1,0,1]
	v_add_f32_e32 v39, s22, v38
	v_readlane_b32 s34, v174, 57
	v_max_f32_e32 v40, s32, v39
	v_readlane_b32 s40, v176, 57
	v_sub_f32_e32 v58, v39, v40
	v_sub_f32_e32 v59, s32, v40
	v_mul_f32_e32 v58, 0x3fb8aa3b, v58
	v_mul_f32_e32 v59, 0x3fb8aa3b, v59
	v_exp_f32_e32 v60, v58
	v_exp_f32_e32 v62, v59
	v_cvt_pk_bf16_f32 v122, v118, v119
	global_store_dword v36, v122, s[6:7]
	s_add_u32 s6, s6, 0x20000
	s_addc_u32 s7, s7, 0
	v_lshlrev_b32_e32 v108, 16, v134
	v_and_b32_e32 v109, 0xffff0000, v134
	v_pk_mul_f32 v[108:109], v[62:63], v[108:109] op_sel_hi:[0,1]
	v_pk_fma_f32 v[118:119], v[118:119], v[60:61], v[108:109] op_sel_hi:[1,0,1]
	v_add_f32_e32 v39, s34, v40
	v_readlane_b32 s22, v174, 58
	v_max_f32_e32 v38, s40, v39
	v_readlane_b32 s32, v176, 58
	v_sub_f32_e32 v58, v39, v38
	v_sub_f32_e32 v59, s40, v38
	v_mul_f32_e32 v58, 0x3fb8aa3b, v58
	v_mul_f32_e32 v59, 0x3fb8aa3b, v59
	v_exp_f32_e32 v60, v58
	v_exp_f32_e32 v62, v59
	v_cvt_pk_bf16_f32 v122, v118, v119
	global_store_dword v36, v122, s[6:7]
	s_add_u32 s6, s6, 0x20000
	s_addc_u32 s7, s7, 0
	v_lshlrev_b32_e32 v108, 16, v135
	v_and_b32_e32 v109, 0xffff0000, v135
	v_pk_mul_f32 v[108:109], v[62:63], v[108:109] op_sel_hi:[0,1]
	v_pk_fma_f32 v[118:119], v[118:119], v[60:61], v[108:109] op_sel_hi:[1,0,1]
	v_add_f32_e32 v39, s22, v38
	v_readlane_b32 s34, v174, 59
	v_max_f32_e32 v40, s32, v39
	v_readlane_b32 s40, v176, 59
	v_sub_f32_e32 v58, v39, v40
	v_sub_f32_e32 v59, s32, v40
	v_mul_f32_e32 v58, 0x3fb8aa3b, v58
	v_mul_f32_e32 v59, 0x3fb8aa3b, v59
	v_exp_f32_e32 v60, v58
	v_exp_f32_e32 v62, v59
	v_cvt_pk_bf16_f32 v122, v118, v119
	global_store_dword v36, v122, s[6:7]
	s_add_u32 s6, s6, 0x20000
	s_addc_u32 s7, s7, 0
	v_lshlrev_b32_e32 v108, 16, v136
	v_and_b32_e32 v109, 0xffff0000, v136
	v_pk_mul_f32 v[108:109], v[62:63], v[108:109] op_sel_hi:[0,1]
	v_pk_fma_f32 v[118:119], v[118:119], v[60:61], v[108:109] op_sel_hi:[1,0,1]
	v_add_f32_e32 v39, s34, v40
	v_readlane_b32 s22, v174, 60
	v_max_f32_e32 v38, s40, v39
	v_readlane_b32 s32, v176, 60
	v_sub_f32_e32 v58, v39, v38
	v_sub_f32_e32 v59, s40, v38
	v_mul_f32_e32 v58, 0x3fb8aa3b, v58
	v_mul_f32_e32 v59, 0x3fb8aa3b, v59
	v_exp_f32_e32 v60, v58
	v_exp_f32_e32 v62, v59
	v_cvt_pk_bf16_f32 v122, v118, v119
	global_store_dword v36, v122, s[6:7]
	s_add_u32 s6, s6, 0x20000
	s_addc_u32 s7, s7, 0
	v_lshlrev_b32_e32 v108, 16, v137
	v_and_b32_e32 v109, 0xffff0000, v137
	v_pk_mul_f32 v[108:109], v[62:63], v[108:109] op_sel_hi:[0,1]
	v_pk_fma_f32 v[118:119], v[118:119], v[60:61], v[108:109] op_sel_hi:[1,0,1]
	v_add_f32_e32 v39, s22, v38
	v_readlane_b32 s34, v174, 61
	v_max_f32_e32 v40, s32, v39
	v_readlane_b32 s40, v176, 61
	v_sub_f32_e32 v58, v39, v40
	v_sub_f32_e32 v59, s32, v40
	v_mul_f32_e32 v58, 0x3fb8aa3b, v58
	v_mul_f32_e32 v59, 0x3fb8aa3b, v59
	v_exp_f32_e32 v60, v58
	v_exp_f32_e32 v62, v59
	v_cvt_pk_bf16_f32 v122, v118, v119
	global_store_dword v36, v122, s[6:7]
	s_add_u32 s6, s6, 0x20000
	s_addc_u32 s7, s7, 0
	v_lshlrev_b32_e32 v108, 16, v138
	v_and_b32_e32 v109, 0xffff0000, v138
	v_pk_mul_f32 v[108:109], v[62:63], v[108:109] op_sel_hi:[0,1]
	v_pk_fma_f32 v[118:119], v[118:119], v[60:61], v[108:109] op_sel_hi:[1,0,1]
	v_add_f32_e32 v39, s34, v40
	v_readlane_b32 s22, v174, 62
	v_max_f32_e32 v38, s40, v39
	v_readlane_b32 s32, v176, 62
	v_sub_f32_e32 v58, v39, v38
	v_sub_f32_e32 v59, s40, v38
	v_mul_f32_e32 v58, 0x3fb8aa3b, v58
	v_mul_f32_e32 v59, 0x3fb8aa3b, v59
	v_exp_f32_e32 v60, v58
	v_exp_f32_e32 v62, v59
	v_cvt_pk_bf16_f32 v122, v118, v119
	global_store_dword v36, v122, s[6:7]
	s_add_u32 s6, s6, 0x20000
	s_addc_u32 s7, s7, 0
	v_lshlrev_b32_e32 v108, 16, v139
	v_and_b32_e32 v109, 0xffff0000, v139
	v_pk_mul_f32 v[108:109], v[62:63], v[108:109] op_sel_hi:[0,1]
	v_pk_fma_f32 v[118:119], v[118:119], v[60:61], v[108:109] op_sel_hi:[1,0,1]
	v_add_f32_e32 v39, s22, v38
	v_readlane_b32 s34, v174, 63
	v_max_f32_e32 v40, s32, v39
	v_readlane_b32 s40, v176, 63
	v_sub_f32_e32 v58, v39, v40
	v_sub_f32_e32 v59, s32, v40
	v_mul_f32_e32 v58, 0x3fb8aa3b, v58
	v_mul_f32_e32 v59, 0x3fb8aa3b, v59
	v_exp_f32_e32 v60, v58
	v_exp_f32_e32 v62, v59
	v_cvt_pk_bf16_f32 v122, v118, v119
	global_store_dword v36, v122, s[6:7]
	s_add_u32 s6, s6, 0x20000
	s_addc_u32 s7, s7, 0
	v_lshlrev_b32_e32 v108, 16, v140
	v_and_b32_e32 v109, 0xffff0000, v140
	v_pk_mul_f32 v[108:109], v[62:63], v[108:109] op_sel_hi:[0,1]
	v_pk_fma_f32 v[118:119], v[118:119], v[60:61], v[108:109] op_sel_hi:[1,0,1]
	v_add_f32_e32 v39, s34, v40
	v_readlane_b32 s22, v175, 0
	v_max_f32_e32 v38, s40, v39
	v_readlane_b32 s32, v177, 0
	v_sub_f32_e32 v58, v39, v38
	v_sub_f32_e32 v59, s40, v38
	v_mul_f32_e32 v58, 0x3fb8aa3b, v58
	v_mul_f32_e32 v59, 0x3fb8aa3b, v59
	v_exp_f32_e32 v60, v58
	v_exp_f32_e32 v62, v59
	v_cvt_pk_bf16_f32 v122, v118, v119
	global_store_dword v36, v122, s[6:7]
	s_add_u32 s6, s6, 0x20000
	s_addc_u32 s7, s7, 0
	v_lshlrev_b32_e32 v108, 16, v141
	v_and_b32_e32 v109, 0xffff0000, v141
	v_pk_mul_f32 v[108:109], v[62:63], v[108:109] op_sel_hi:[0,1]
	v_pk_fma_f32 v[118:119], v[118:119], v[60:61], v[108:109] op_sel_hi:[1,0,1]
; __device__ __forceinline__ unsigned pk2(float lo, float hi) { f32x2_t v = {lo, hi}; bf16x2_t b = __builtin_convertvector(v, bf16x2_t); return __builtin_bit_cast(unsigned, b); }
; __device__ __forceinline__ float bflo(unsigned w) { return __uint_as_float(w << 16); }
; __device__ __forceinline__ float bfhi(unsigned w) { return __uint_as_float(w & 0xffff0000u); }
; __device__ __forceinline__ float fexp(float x) { return __builtin_amdgcn_exp2f(x * LOG2E); }
;     __device__ __forceinline__ float* MBM() const { return (float*)(ws + WS_MB); }
;     __device__ __forceinline__ float* MBB() const { return (float*)(ws + WS_MB) + (NSLOT_P + NSLOT_S); }
;     __device__ __forceinline__ float* MST() const { return (float*)(ws + WS_MB) + 2 * (NSLOT_P + NSLOT_S); }
; __device__ __forceinline__ void phase_scan(Ctx& C, int l, const bool st, LAS unsigned char* lds) {
;     ...
;         for (int cg0 = 0; cg0 < NPC; cg0 += 16) {
;             if (cg0 + 16 < NPC) {
; #pragma unroll
;                 for (int j = 0; j < 16; ++j) { nb[j] = base[(size_t)((b * NPC + cg0 + 16 + j) * 4 + h) * 8192]; fnb[j] = hn ? dnb[(size_t)((b * NPC + cg0 + 16 + j) * 4 + h) * 128] : 0.f; }
;             }
; #pragma unroll
;             for (int j = 0; j < 16; ++j) { const int slot = (b * NPC + cg0 + j) * 4 + h;
;                 const float Bc = C.MBB()[slot], Mc = C.MBM()[slot];
;                 const float mn = fmaxf(Bc + m, Mc), g = fexp(Bc + m - mn), f = fexp(Mc - mn);
;                 if (st) { base[(size_t)slot * 8192] = pk2(c0, c1); if (hn) { dnb[(size_t)slot * 128] = nn; if (p == 0) C.MST()[slot] = m; } }
;                 c0 = g * c0 + f * bflo(buf[j]); c1 = g * c1 + f * bfhi(buf[j]); nn = g * nn + f * fb[j]; m = mn; }
.Lscan_nh_b4:
	s_waitcnt vmcnt(32)
	global_load_dword v126, v36, s[4:5]
	s_add_u32 s4, s4, 0x20000
	s_addc_u32 s5, s5, 0
	global_load_dword v127, v36, s[4:5]
	s_add_u32 s4, s4, 0x20000
	s_addc_u32 s5, s5, 0
	global_load_dword v128, v36, s[4:5]
	s_add_u32 s4, s4, 0x20000
	s_addc_u32 s5, s5, 0
	global_load_dword v129, v36, s[4:5]
	s_add_u32 s4, s4, 0x20000
	s_addc_u32 s5, s5, 0
	global_load_dword v130, v36, s[4:5]
	s_add_u32 s4, s4, 0x20000
	s_addc_u32 s5, s5, 0
	global_load_dword v131, v36, s[4:5]
	s_add_u32 s4, s4, 0x20000
	s_addc_u32 s5, s5, 0
	global_load_dword v132, v36, s[4:5]
	s_add_u32 s4, s4, 0x20000
	s_addc_u32 s5, s5, 0
	global_load_dword v133, v36, s[4:5]
	s_add_u32 s4, s4, 0x20000
	s_addc_u32 s5, s5, 0
	global_load_dword v134, v36, s[4:5]
	s_add_u32 s4, s4, 0x20000
	s_addc_u32 s5, s5, 0
	global_load_dword v135, v36, s[4:5]
	s_add_u32 s4, s4, 0x20000
	s_addc_u32 s5, s5, 0
	global_load_dword v136, v36, s[4:5]
	s_add_u32 s4, s4, 0x20000
	s_addc_u32 s5, s5, 0
	global_load_dword v137, v36, s[4:5]
	s_add_u32 s4, s4, 0x20000
	s_addc_u32 s5, s5, 0
	global_load_dword v138, v36, s[4:5]
	s_add_u32 s4, s4, 0x20000
	s_addc_u32 s5, s5, 0
	global_load_dword v139, v36, s[4:5]
	s_add_u32 s4, s4, 0x20000
	s_addc_u32 s5, s5, 0
	global_load_dword v140, v36, s[4:5]
	s_add_u32 s4, s4, 0x20000
	s_addc_u32 s5, s5, 0
	global_load_dword v141, v36, s[4:5]
	s_add_u32 s4, s4, 0x20000
	s_addc_u32 s5, s5, 0
	v_add_f32_e32 v39, s22, v38
	v_readlane_b32 s34, v175, 1
	v_max_f32_e32 v40, s32, v39
	v_readlane_b32 s40, v177, 1
	v_sub_f32_e32 v58, v39, v40
	v_sub_f32_e32 v59, s32, v40
	v_mul_f32_e32 v58, 0x3fb8aa3b, v58
	v_mul_f32_e32 v59, 0x3fb8aa3b, v59
	v_exp_f32_e32 v60, v58
	v_exp_f32_e32 v62, v59
	v_cvt_pk_bf16_f32 v122, v118, v119
	global_store_dword v36, v122, s[6:7]
	s_add_u32 s6, s6, 0x20000
	s_addc_u32 s7, s7, 0
	v_lshlrev_b32_e32 v108, 16, v142
	v_and_b32_e32 v109, 0xffff0000, v142
	v_pk_mul_f32 v[108:109], v[62:63], v[108:109] op_sel_hi:[0,1]
	v_pk_fma_f32 v[118:119], v[118:119], v[60:61], v[108:109] op_sel_hi:[1,0,1]
	v_add_f32_e32 v39, s34, v40
	v_readlane_b32 s22, v175, 2
	v_max_f32_e32 v38, s40, v39
	v_readlane_b32 s32, v177, 2
	v_sub_f32_e32 v58, v39, v38
	v_sub_f32_e32 v59, s40, v38
	v_mul_f32_e32 v58, 0x3fb8aa3b, v58
	v_mul_f32_e32 v59, 0x3fb8aa3b, v59
	v_exp_f32_e32 v60, v58
	v_exp_f32_e32 v62, v59
	v_cvt_pk_bf16_f32 v122, v118, v119
	global_store_dword v36, v122, s[6:7]
	s_add_u32 s6, s6, 0x20000
	s_addc_u32 s7, s7, 0
	v_lshlrev_b32_e32 v108, 16, v143
	v_and_b32_e32 v109, 0xffff0000, v143
	v_pk_mul_f32 v[108:109], v[62:63], v[108:109] op_sel_hi:[0,1]
	v_pk_fma_f32 v[118:119], v[118:119], v[60:61], v[108:109] op_sel_hi:[1,0,1]
	v_add_f32_e32 v39, s22, v38
	v_readlane_b32 s34, v175, 3
	v_max_f32_e32 v40, s32, v39
	v_readlane_b32 s40, v177, 3
	v_sub_f32_e32 v58, v39, v40
	v_sub_f32_e32 v59, s32, v40
	v_mul_f32_e32 v58, 0x3fb8aa3b, v58
	v_mul_f32_e32 v59, 0x3fb8aa3b, v59
	v_exp_f32_e32 v60, v58
	v_exp_f32_e32 v62, v59
	v_cvt_pk_bf16_f32 v122, v118, v119
	global_store_dword v36, v122, s[6:7]
	s_add_u32 s6, s6, 0x20000
	s_addc_u32 s7, s7, 0
	v_lshlrev_b32_e32 v108, 16, v144
	v_and_b32_e32 v109, 0xffff0000, v144
	v_pk_mul_f32 v[108:109], v[62:63], v[108:109] op_sel_hi:[0,1]
	v_pk_fma_f32 v[118:119], v[118:119], v[60:61], v[108:109] op_sel_hi:[1,0,1]
	v_add_f32_e32 v39, s34, v40
	v_readlane_b32 s22, v175, 4
	v_max_f32_e32 v38, s40, v39
	v_readlane_b32 s32, v177, 4
	v_sub_f32_e32 v58, v39, v38
	v_sub_f32_e32 v59, s40, v38
	v_mul_f32_e32 v58, 0x3fb8aa3b, v58
	v_mul_f32_e32 v59, 0x3fb8aa3b, v59
	v_exp_f32_e32 v60, v58
	v_exp_f32_e32 v62, v59
	v_cvt_pk_bf16_f32 v122, v118, v119
	global_store_dword v36, v122, s[6:7]
	s_add_u32 s6, s6, 0x20000
	s_addc_u32 s7, s7, 0
	v_lshlrev_b32_e32 v108, 16, v145
	v_and_b32_e32 v109, 0xffff0000, v145
	v_pk_mul_f32 v[108:109], v[62:63], v[108:109] op_sel_hi:[0,1]
	v_pk_fma_f32 v[118:119], v[118:119], v[60:61], v[108:109] op_sel_hi:[1,0,1]
	v_add_f32_e32 v39, s22, v38
	v_readlane_b32 s34, v175, 5
	v_max_f32_e32 v40, s32, v39
	v_readlane_b32 s40, v177, 5
	v_sub_f32_e32 v58, v39, v40
	v_sub_f32_e32 v59, s32, v40
	v_mul_f32_e32 v58, 0x3fb8aa3b, v58
	v_mul_f32_e32 v59, 0x3fb8aa3b, v59
	v_exp_f32_e32 v60, v58
	v_exp_f32_e32 v62, v59
	v_cvt_pk_bf16_f32 v122, v118, v119
	global_store_dword v36, v122, s[6:7]
	s_add_u32 s6, s6, 0x20000
	s_addc_u32 s7, s7, 0
	v_lshlrev_b32_e32 v108, 16, v146
	v_and_b32_e32 v109, 0xffff0000, v146
	v_pk_mul_f32 v[108:109], v[62:63], v[108:109] op_sel_hi:[0,1]
	v_pk_fma_f32 v[118:119], v[118:119], v[60:61], v[108:109] op_sel_hi:[1,0,1]
	v_add_f32_e32 v39, s34, v40
	v_readlane_b32 s22, v175, 6
	v_max_f32_e32 v38, s40, v39
	v_readlane_b32 s32, v177, 6
	v_sub_f32_e32 v58, v39, v38
	v_sub_f32_e32 v59, s40, v38
	v_mul_f32_e32 v58, 0x3fb8aa3b, v58
	v_mul_f32_e32 v59, 0x3fb8aa3b, v59
	v_exp_f32_e32 v60, v58
	v_exp_f32_e32 v62, v59
	v_cvt_pk_bf16_f32 v122, v118, v119
	global_store_dword v36, v122, s[6:7]
	s_add_u32 s6, s6, 0x20000
	s_addc_u32 s7, s7, 0
	v_lshlrev_b32_e32 v108, 16, v147
	v_and_b32_e32 v109, 0xffff0000, v147
	v_pk_mul_f32 v[108:109], v[62:63], v[108:109] op_sel_hi:[0,1]
	v_pk_fma_f32 v[118:119], v[118:119], v[60:61], v[108:109] op_sel_hi:[1,0,1]
	v_add_f32_e32 v39, s22, v38
	v_readlane_b32 s34, v175, 7
	v_max_f32_e32 v40, s32, v39
	v_readlane_b32 s40, v177, 7
	v_sub_f32_e32 v58, v39, v40
	v_sub_f32_e32 v59, s32, v40
	v_mul_f32_e32 v58, 0x3fb8aa3b, v58
	v_mul_f32_e32 v59, 0x3fb8aa3b, v59
	v_exp_f32_e32 v60, v58
	v_exp_f32_e32 v62, v59
	v_cvt_pk_bf16_f32 v122, v118, v119
	global_store_dword v36, v122, s[6:7]
	s_add_u32 s6, s6, 0x20000
	s_addc_u32 s7, s7, 0
	v_lshlrev_b32_e32 v108, 16, v148
; __device__ __forceinline__ unsigned pk2(float lo, float hi) { f32x2_t v = {lo, hi}; bf16x2_t b = __builtin_convertvector(v, bf16x2_t); return __builtin_bit_cast(unsigned, b); }
; __device__ __forceinline__ float bflo(unsigned w) { return __uint_as_float(w << 16); }
; __device__ __forceinline__ float bfhi(unsigned w) { return __uint_as_float(w & 0xffff0000u); }
; __device__ __forceinline__ float fexp(float x) { return __builtin_amdgcn_exp2f(x * LOG2E); }
;     __device__ __forceinline__ float* MBM() const { return (float*)(ws + WS_MB); }
;     __device__ __forceinline__ float* MBB() const { return (float*)(ws + WS_MB) + (NSLOT_P + NSLOT_S); }
;     __device__ __forceinline__ float* MST() const { return (float*)(ws + WS_MB) + 2 * (NSLOT_P + NSLOT_S); }
; __device__ __forceinline__ void phase_scan(Ctx& C, int l, const bool st, LAS unsigned char* lds) {
;     ...
;             for (int j = 0; j < 16; ++j) { const int slot = (b * NPC + cg0 + j) * 4 + h;
;                 const float Bc = C.MBB()[slot], Mc = C.MBM()[slot];
;                 const float mn = fmaxf(Bc + m, Mc), g = fexp(Bc + m - mn), f = fexp(Mc - mn);
;                 if (st) { base[(size_t)slot * 8192] = pk2(c0, c1); if (hn) { dnb[(size_t)slot * 128] = nn; if (p == 0) C.MST()[slot] = m; } }
;                 c0 = g * c0 + f * bflo(buf[j]); c1 = g * c1 + f * bfhi(buf[j]); nn = g * nn + f * fb[j]; m = mn; }
	v_and_b32_e32 v109, 0xffff0000, v148
	v_pk_mul_f32 v[108:109], v[62:63], v[108:109] op_sel_hi:[0,1]
	v_pk_fma_f32 v[118:119], v[118:119], v[60:61], v[108:109] op_sel_hi:[1,0,1]
	v_add_f32_e32 v39, s34, v40
	v_readlane_b32 s22, v175, 8
	v_max_f32_e32 v38, s40, v39
	v_readlane_b32 s32, v177, 8
	v_sub_f32_e32 v58, v39, v38
	v_sub_f32_e32 v59, s40, v38
	v_mul_f32_e32 v58, 0x3fb8aa3b, v58
	v_mul_f32_e32 v59, 0x3fb8aa3b, v59
	v_exp_f32_e32 v60, v58
	v_exp_f32_e32 v62, v59
	v_cvt_pk_bf16_f32 v122, v118, v119
	global_store_dword v36, v122, s[6:7]
	s_add_u32 s6, s6, 0x20000
	s_addc_u32 s7, s7, 0
	v_lshlrev_b32_e32 v108, 16, v149
	v_and_b32_e32 v109, 0xffff0000, v149
	v_pk_mul_f32 v[108:109], v[62:63], v[108:109] op_sel_hi:[0,1]
	v_pk_fma_f32 v[118:119], v[118:119], v[60:61], v[108:109] op_sel_hi:[1,0,1]
	v_add_f32_e32 v39, s22, v38
	v_readlane_b32 s34, v175, 9
	v_max_f32_e32 v40, s32, v39
	v_readlane_b32 s40, v177, 9
	v_sub_f32_e32 v58, v39, v40
	v_sub_f32_e32 v59, s32, v40
	v_mul_f32_e32 v58, 0x3fb8aa3b, v58
	v_mul_f32_e32 v59, 0x3fb8aa3b, v59
	v_exp_f32_e32 v60, v58
	v_exp_f32_e32 v62, v59
	v_cvt_pk_bf16_f32 v122, v118, v119
	global_store_dword v36, v122, s[6:7]
	s_add_u32 s6, s6, 0x20000
	s_addc_u32 s7, s7, 0
	v_lshlrev_b32_e32 v108, 16, v150
	v_and_b32_e32 v109, 0xffff0000, v150
	v_pk_mul_f32 v[108:109], v[62:63], v[108:109] op_sel_hi:[0,1]
	v_pk_fma_f32 v[118:119], v[118:119], v[60:61], v[108:109] op_sel_hi:[1,0,1]
	v_add_f32_e32 v39, s34, v40
	v_readlane_b32 s22, v175, 10
	v_max_f32_e32 v38, s40, v39
	v_readlane_b32 s32, v177, 10
	v_sub_f32_e32 v58, v39, v38
	v_sub_f32_e32 v59, s40, v38
	v_mul_f32_e32 v58, 0x3fb8aa3b, v58
	v_mul_f32_e32 v59, 0x3fb8aa3b, v59
	v_exp_f32_e32 v60, v58
	v_exp_f32_e32 v62, v59
	v_cvt_pk_bf16_f32 v122, v118, v119
	global_store_dword v36, v122, s[6:7]
	s_add_u32 s6, s6, 0x20000
	s_addc_u32 s7, s7, 0
	v_lshlrev_b32_e32 v108, 16, v151
	v_and_b32_e32 v109, 0xffff0000, v151
	v_pk_mul_f32 v[108:109], v[62:63], v[108:109] op_sel_hi:[0,1]
	v_pk_fma_f32 v[118:119], v[118:119], v[60:61], v[108:109] op_sel_hi:[1,0,1]
	v_add_f32_e32 v39, s22, v38
	v_readlane_b32 s34, v175, 11
	v_max_f32_e32 v40, s32, v39
	v_readlane_b32 s40, v177, 11
	v_sub_f32_e32 v58, v39, v40
	v_sub_f32_e32 v59, s32, v40
	v_mul_f32_e32 v58, 0x3fb8aa3b, v58
	v_mul_f32_e32 v59, 0x3fb8aa3b, v59
	v_exp_f32_e32 v60, v58
	v_exp_f32_e32 v62, v59
	v_cvt_pk_bf16_f32 v122, v118, v119
	global_store_dword v36, v122, s[6:7]
	s_add_u32 s6, s6, 0x20000
	s_addc_u32 s7, s7, 0
	v_lshlrev_b32_e32 v108, 16, v152
	v_and_b32_e32 v109, 0xffff0000, v152
	v_pk_mul_f32 v[108:109], v[62:63], v[108:109] op_sel_hi:[0,1]
	v_pk_fma_f32 v[118:119], v[118:119], v[60:61], v[108:109] op_sel_hi:[1,0,1]
	v_add_f32_e32 v39, s34, v40
	v_readlane_b32 s22, v175, 12
	v_max_f32_e32 v38, s40, v39
	v_readlane_b32 s32, v177, 12
	v_sub_f32_e32 v58, v39, v38
	v_sub_f32_e32 v59, s40, v38
	v_mul_f32_e32 v58, 0x3fb8aa3b, v58
	v_mul_f32_e32 v59, 0x3fb8aa3b, v59
	v_exp_f32_e32 v60, v58
	v_exp_f32_e32 v62, v59
	v_cvt_pk_bf16_f32 v122, v118, v119
	global_store_dword v36, v122, s[6:7]
	s_add_u32 s6, s6, 0x20000
	s_addc_u32 s7, s7, 0
	v_lshlrev_b32_e32 v108, 16, v153
	v_and_b32_e32 v109, 0xffff0000, v153
	v_pk_mul_f32 v[108:109], v[62:63], v[108:109] op_sel_hi:[0,1]
	v_pk_fma_f32 v[118:119], v[118:119], v[60:61], v[108:109] op_sel_hi:[1,0,1]
	v_add_f32_e32 v39, s22, v38
	v_readlane_b32 s34, v175, 13
	v_max_f32_e32 v40, s32, v39
	v_readlane_b32 s40, v177, 13
	v_sub_f32_e32 v58, v39, v40
	v_sub_f32_e32 v59, s32, v40
	v_mul_f32_e32 v58, 0x3fb8aa3b, v58
	v_mul_f32_e32 v59, 0x3fb8aa3b, v59
	v_exp_f32_e32 v60, v58
	v_exp_f32_e32 v62, v59
	v_cvt_pk_bf16_f32 v122, v118, v119
	global_store_dword v36, v122, s[6:7]
	s_add_u32 s6, s6, 0x20000
	s_addc_u32 s7, s7, 0
	v_lshlrev_b32_e32 v108, 16, v154
	v_and_b32_e32 v109, 0xffff0000, v154
	v_pk_mul_f32 v[108:109], v[62:63], v[108:109] op_sel_hi:[0,1]
	v_pk_fma_f32 v[118:119], v[118:119], v[60:61], v[108:109] op_sel_hi:[1,0,1]
	v_add_f32_e32 v39, s34, v40
	v_readlane_b32 s22, v175, 14
	v_max_f32_e32 v38, s40, v39
	v_readlane_b32 s32, v177, 14
	v_sub_f32_e32 v58, v39, v38
	v_sub_f32_e32 v59, s40, v38
	v_mul_f32_e32 v58, 0x3fb8aa3b, v58
	v_mul_f32_e32 v59, 0x3fb8aa3b, v59
	v_exp_f32_e32 v60, v58
	v_exp_f32_e32 v62, v59
	v_cvt_pk_bf16_f32 v122, v118, v119
	global_store_dword v36, v122, s[6:7]
	s_add_u32 s6, s6, 0x20000
	s_addc_u32 s7, s7, 0
	v_lshlrev_b32_e32 v108, 16, v155
	v_and_b32_e32 v109, 0xffff0000, v155
	v_pk_mul_f32 v[108:109], v[62:63], v[108:109] op_sel_hi:[0,1]
	v_pk_fma_f32 v[118:119], v[118:119], v[60:61], v[108:109] op_sel_hi:[1,0,1]
	v_add_f32_e32 v39, s22, v38
	v_readlane_b32 s34, v175, 15
	v_max_f32_e32 v40, s32, v39
	v_readlane_b32 s40, v177, 15
	v_sub_f32_e32 v58, v39, v40
	v_sub_f32_e32 v59, s32, v40
	v_mul_f32_e32 v58, 0x3fb8aa3b, v58
	v_mul_f32_e32 v59, 0x3fb8aa3b, v59
	v_exp_f32_e32 v60, v58
	v_exp_f32_e32 v62, v59
	v_cvt_pk_bf16_f32 v122, v118, v119
	global_store_dword v36, v122, s[6:7]
	s_add_u32 s6, s6, 0x20000
	s_addc_u32 s7, s7, 0
	v_lshlrev_b32_e32 v108, 16, v156
	v_and_b32_e32 v109, 0xffff0000, v156
	v_pk_mul_f32 v[108:109], v[62:63], v[108:109] op_sel_hi:[0,1]
	v_pk_fma_f32 v[118:119], v[118:119], v[60:61], v[108:109] op_sel_hi:[1,0,1]
	v_add_f32_e32 v39, s34, v40
	v_readlane_b32 s22, v175, 16
	v_max_f32_e32 v38, s40, v39
	v_readlane_b32 s32, v177, 16
	v_sub_f32_e32 v58, v39, v38
	v_sub_f32_e32 v59, s40, v38
	v_mul_f32_e32 v58, 0x3fb8aa3b, v58
	v_mul_f32_e32 v59, 0x3fb8aa3b, v59
	v_exp_f32_e32 v60, v58
	v_exp_f32_e32 v62, v59
	v_cvt_pk_bf16_f32 v122, v118, v119
	global_store_dword v36, v122, s[6:7]
	s_add_u32 s6, s6, 0x20000
	s_addc_u32 s7, s7, 0
	v_lshlrev_b32_e32 v108, 16, v157
	v_and_b32_e32 v109, 0xffff0000, v157
	v_pk_mul_f32 v[108:109], v[62:63], v[108:109] op_sel_hi:[0,1]
	v_pk_fma_f32 v[118:119], v[118:119], v[60:61], v[108:109] op_sel_hi:[1,0,1]
; __device__ __forceinline__ unsigned pk2(float lo, float hi) { f32x2_t v = {lo, hi}; bf16x2_t b = __builtin_convertvector(v, bf16x2_t); return __builtin_bit_cast(unsigned, b); }
; __device__ __forceinline__ float bflo(unsigned w) { return __uint_as_float(w << 16); }
; __device__ __forceinline__ float bfhi(unsigned w) { return __uint_as_float(w & 0xffff0000u); }
; __device__ __forceinline__ float fexp(float x) { return __builtin_amdgcn_exp2f(x * LOG2E); }
;     __device__ __forceinline__ float* MBM() const { return (float*)(ws + WS_MB); }
;     __device__ __forceinline__ float* MBB() const { return (float*)(ws + WS_MB) + (NSLOT_P + NSLOT_S); }
;     __device__ __forceinline__ float* MST() const { return (float*)(ws + WS_MB) + 2 * (NSLOT_P + NSLOT_S); }
; __device__ __forceinline__ void phase_scan(Ctx& C, int l, const bool st, LAS unsigned char* lds) {
;     ...
;         for (int cg0 = 0; cg0 < NPC; cg0 += 16) {
;             if (cg0 + 16 < NPC) {
; #pragma unroll
;                 for (int j = 0; j < 16; ++j) { nb[j] = base[(size_t)((b * NPC + cg0 + 16 + j) * 4 + h) * 8192]; fnb[j] = hn ? dnb[(size_t)((b * NPC + cg0 + 16 + j) * 4 + h) * 128] : 0.f; }
;             }
; #pragma unroll
;             for (int j = 0; j < 16; ++j) { const int slot = (b * NPC + cg0 + j) * 4 + h;
;                 const float Bc = C.MBB()[slot], Mc = C.MBM()[slot];
;                 const float mn = fmaxf(Bc + m, Mc), g = fexp(Bc + m - mn), f = fexp(Mc - mn);
;                 if (st) { base[(size_t)slot * 8192] = pk2(c0, c1); if (hn) { dnb[(size_t)slot * 128] = nn; if (p == 0) C.MST()[slot] = m; } }
;                 c0 = g * c0 + f * bflo(buf[j]); c1 = g * c1 + f * bfhi(buf[j]); nn = g * nn + f * fb[j]; m = mn; }
.Lscan_nh_b5:
	s_waitcnt vmcnt(32)
	global_load_dword v142, v36, s[4:5]
	s_add_u32 s4, s4, 0x20000
	s_addc_u32 s5, s5, 0
	global_load_dword v143, v36, s[4:5]
	s_add_u32 s4, s4, 0x20000
	s_addc_u32 s5, s5, 0
	global_load_dword v144, v36, s[4:5]
	s_add_u32 s4, s4, 0x20000
	s_addc_u32 s5, s5, 0
	global_load_dword v145, v36, s[4:5]
	s_add_u32 s4, s4, 0x20000
	s_addc_u32 s5, s5, 0
	global_load_dword v146, v36, s[4:5]
	s_add_u32 s4, s4, 0x20000
	s_addc_u32 s5, s5, 0
	global_load_dword v147, v36, s[4:5]
	s_add_u32 s4, s4, 0x20000
	s_addc_u32 s5, s5, 0
	global_load_dword v148, v36, s[4:5]
	s_add_u32 s4, s4, 0x20000
	s_addc_u32 s5, s5, 0
	global_load_dword v149, v36, s[4:5]
	s_add_u32 s4, s4, 0x20000
	s_addc_u32 s5, s5, 0
	global_load_dword v150, v36, s[4:5]
	s_add_u32 s4, s4, 0x20000
	s_addc_u32 s5, s5, 0
	global_load_dword v151, v36, s[4:5]
	s_add_u32 s4, s4, 0x20000
	s_addc_u32 s5, s5, 0
	global_load_dword v152, v36, s[4:5]
	s_add_u32 s4, s4, 0x20000
	s_addc_u32 s5, s5, 0
	global_load_dword v153, v36, s[4:5]
	s_add_u32 s4, s4, 0x20000
	s_addc_u32 s5, s5, 0
	global_load_dword v154, v36, s[4:5]
	s_add_u32 s4, s4, 0x20000
	s_addc_u32 s5, s5, 0
	global_load_dword v155, v36, s[4:5]
	s_add_u32 s4, s4, 0x20000
	s_addc_u32 s5, s5, 0
	global_load_dword v156, v36, s[4:5]
	s_add_u32 s4, s4, 0x20000
	s_addc_u32 s5, s5, 0
	global_load_dword v157, v36, s[4:5]
	s_add_u32 s4, s4, 0x20000
	s_addc_u32 s5, s5, 0
	v_add_f32_e32 v39, s22, v38
	v_readlane_b32 s34, v175, 17
	v_max_f32_e32 v40, s32, v39
	v_readlane_b32 s40, v177, 17
	v_sub_f32_e32 v58, v39, v40
	v_sub_f32_e32 v59, s32, v40
	v_mul_f32_e32 v58, 0x3fb8aa3b, v58
	v_mul_f32_e32 v59, 0x3fb8aa3b, v59
	v_exp_f32_e32 v60, v58
	v_exp_f32_e32 v62, v59
	v_cvt_pk_bf16_f32 v122, v118, v119
	global_store_dword v36, v122, s[6:7]
	s_add_u32 s6, s6, 0x20000
	s_addc_u32 s7, s7, 0
	v_lshlrev_b32_e32 v108, 16, v158
	v_and_b32_e32 v109, 0xffff0000, v158
	v_pk_mul_f32 v[108:109], v[62:63], v[108:109] op_sel_hi:[0,1]
	v_pk_fma_f32 v[118:119], v[118:119], v[60:61], v[108:109] op_sel_hi:[1,0,1]
	v_add_f32_e32 v39, s34, v40
	v_readlane_b32 s22, v175, 18
	v_max_f32_e32 v38, s40, v39
	v_readlane_b32 s32, v177, 18
	v_sub_f32_e32 v58, v39, v38
	v_sub_f32_e32 v59, s40, v38
	v_mul_f32_e32 v58, 0x3fb8aa3b, v58
	v_mul_f32_e32 v59, 0x3fb8aa3b, v59
	v_exp_f32_e32 v60, v58
	v_exp_f32_e32 v62, v59
	v_cvt_pk_bf16_f32 v122, v118, v119
	global_store_dword v36, v122, s[6:7]
	s_add_u32 s6, s6, 0x20000
	s_addc_u32 s7, s7, 0
	v_lshlrev_b32_e32 v108, 16, v159
	v_and_b32_e32 v109, 0xffff0000, v159
	v_pk_mul_f32 v[108:109], v[62:63], v[108:109] op_sel_hi:[0,1]
	v_pk_fma_f32 v[118:119], v[118:119], v[60:61], v[108:109] op_sel_hi:[1,0,1]
	v_add_f32_e32 v39, s22, v38
	v_readlane_b32 s34, v175, 19
	v_max_f32_e32 v40, s32, v39
	v_readlane_b32 s40, v177, 19
	v_sub_f32_e32 v58, v39, v40
	v_sub_f32_e32 v59, s32, v40
	v_mul_f32_e32 v58, 0x3fb8aa3b, v58
	v_mul_f32_e32 v59, 0x3fb8aa3b, v59
	v_exp_f32_e32 v60, v58
	v_exp_f32_e32 v62, v59
	v_cvt_pk_bf16_f32 v122, v118, v119
	global_store_dword v36, v122, s[6:7]
	s_add_u32 s6, s6, 0x20000
	s_addc_u32 s7, s7, 0
	v_lshlrev_b32_e32 v108, 16, v160
	v_and_b32_e32 v109, 0xffff0000, v160
	v_pk_mul_f32 v[108:109], v[62:63], v[108:109] op_sel_hi:[0,1]
	v_pk_fma_f32 v[118:119], v[118:119], v[60:61], v[108:109] op_sel_hi:[1,0,1]
	v_add_f32_e32 v39, s34, v40
	v_readlane_b32 s22, v175, 20
	v_max_f32_e32 v38, s40, v39
	v_readlane_b32 s32, v177, 20
	v_sub_f32_e32 v58, v39, v38
	v_sub_f32_e32 v59, s40, v38
	v_mul_f32_e32 v58, 0x3fb8aa3b, v58
	v_mul_f32_e32 v59, 0x3fb8aa3b, v59
	v_exp_f32_e32 v60, v58
	v_exp_f32_e32 v62, v59
	v_cvt_pk_bf16_f32 v122, v118, v119
	global_store_dword v36, v122, s[6:7]
	s_add_u32 s6, s6, 0x20000
	s_addc_u32 s7, s7, 0
	v_lshlrev_b32_e32 v108, 16, v161
	v_and_b32_e32 v109, 0xffff0000, v161
	v_pk_mul_f32 v[108:109], v[62:63], v[108:109] op_sel_hi:[0,1]
	v_pk_fma_f32 v[118:119], v[118:119], v[60:61], v[108:109] op_sel_hi:[1,0,1]
	v_add_f32_e32 v39, s22, v38
	v_readlane_b32 s34, v175, 21
	v_max_f32_e32 v40, s32, v39
	v_readlane_b32 s40, v177, 21
	v_sub_f32_e32 v58, v39, v40
	v_sub_f32_e32 v59, s32, v40
	v_mul_f32_e32 v58, 0x3fb8aa3b, v58
	v_mul_f32_e32 v59, 0x3fb8aa3b, v59
	v_exp_f32_e32 v60, v58
	v_exp_f32_e32 v62, v59
	v_cvt_pk_bf16_f32 v122, v118, v119
	global_store_dword v36, v122, s[6:7]
	s_add_u32 s6, s6, 0x20000
	s_addc_u32 s7, s7, 0
	v_lshlrev_b32_e32 v108, 16, v162
	v_and_b32_e32 v109, 0xffff0000, v162
	v_pk_mul_f32 v[108:109], v[62:63], v[108:109] op_sel_hi:[0,1]
	v_pk_fma_f32 v[118:119], v[118:119], v[60:61], v[108:109] op_sel_hi:[1,0,1]
	v_add_f32_e32 v39, s34, v40
	v_readlane_b32 s22, v175, 22
	v_max_f32_e32 v38, s40, v39
	v_readlane_b32 s32, v177, 22
	v_sub_f32_e32 v58, v39, v38
	v_sub_f32_e32 v59, s40, v38
	v_mul_f32_e32 v58, 0x3fb8aa3b, v58
	v_mul_f32_e32 v59, 0x3fb8aa3b, v59
	v_exp_f32_e32 v60, v58
	v_exp_f32_e32 v62, v59
	v_cvt_pk_bf16_f32 v122, v118, v119
	global_store_dword v36, v122, s[6:7]
	s_add_u32 s6, s6, 0x20000
	s_addc_u32 s7, s7, 0
	v_lshlrev_b32_e32 v108, 16, v163
	v_and_b32_e32 v109, 0xffff0000, v163
	v_pk_mul_f32 v[108:109], v[62:63], v[108:109] op_sel_hi:[0,1]
	v_pk_fma_f32 v[118:119], v[118:119], v[60:61], v[108:109] op_sel_hi:[1,0,1]
	v_add_f32_e32 v39, s22, v38
	v_readlane_b32 s34, v175, 23
	v_max_f32_e32 v40, s32, v39
	v_readlane_b32 s40, v177, 23
	v_sub_f32_e32 v58, v39, v40
	v_sub_f32_e32 v59, s32, v40
	v_mul_f32_e32 v58, 0x3fb8aa3b, v58
	v_mul_f32_e32 v59, 0x3fb8aa3b, v59
	v_exp_f32_e32 v60, v58
	v_exp_f32_e32 v62, v59
	v_cvt_pk_bf16_f32 v122, v118, v119
	global_store_dword v36, v122, s[6:7]
	s_add_u32 s6, s6, 0x20000
	s_addc_u32 s7, s7, 0
	v_lshlrev_b32_e32 v108, 16, v164
; __device__ __forceinline__ unsigned pk2(float lo, float hi) { f32x2_t v = {lo, hi}; bf16x2_t b = __builtin_convertvector(v, bf16x2_t); return __builtin_bit_cast(unsigned, b); }
; __device__ __forceinline__ float bflo(unsigned w) { return __uint_as_float(w << 16); }
; __device__ __forceinline__ float bfhi(unsigned w) { return __uint_as_float(w & 0xffff0000u); }
; __device__ __forceinline__ float fexp(float x) { return __builtin_amdgcn_exp2f(x * LOG2E); }
;     __device__ __forceinline__ float* MBM() const { return (float*)(ws + WS_MB); }
;     __device__ __forceinline__ float* MBB() const { return (float*)(ws + WS_MB) + (NSLOT_P + NSLOT_S); }
;     __device__ __forceinline__ float* MST() const { return (float*)(ws + WS_MB) + 2 * (NSLOT_P + NSLOT_S); }
; __device__ __forceinline__ void phase_scan(Ctx& C, int l, const bool st, LAS unsigned char* lds) {
;     ...
;             for (int j = 0; j < 16; ++j) { const int slot = (b * NPC + cg0 + j) * 4 + h;
;                 const float Bc = C.MBB()[slot], Mc = C.MBM()[slot];
;                 const float mn = fmaxf(Bc + m, Mc), g = fexp(Bc + m - mn), f = fexp(Mc - mn);
;                 if (st) { base[(size_t)slot * 8192] = pk2(c0, c1); if (hn) { dnb[(size_t)slot * 128] = nn; if (p == 0) C.MST()[slot] = m; } }
;                 c0 = g * c0 + f * bflo(buf[j]); c1 = g * c1 + f * bfhi(buf[j]); nn = g * nn + f * fb[j]; m = mn; }
	v_and_b32_e32 v109, 0xffff0000, v164
	v_pk_mul_f32 v[108:109], v[62:63], v[108:109] op_sel_hi:[0,1]
	v_pk_fma_f32 v[118:119], v[118:119], v[60:61], v[108:109] op_sel_hi:[1,0,1]
	v_add_f32_e32 v39, s34, v40
	v_readlane_b32 s22, v175, 24
	v_max_f32_e32 v38, s40, v39
	v_readlane_b32 s32, v177, 24
	v_sub_f32_e32 v58, v39, v38
	v_sub_f32_e32 v59, s40, v38
	v_mul_f32_e32 v58, 0x3fb8aa3b, v58
	v_mul_f32_e32 v59, 0x3fb8aa3b, v59
	v_exp_f32_e32 v60, v58
	v_exp_f32_e32 v62, v59
	v_cvt_pk_bf16_f32 v122, v118, v119
	global_store_dword v36, v122, s[6:7]
	s_add_u32 s6, s6, 0x20000
	s_addc_u32 s7, s7, 0
	v_lshlrev_b32_e32 v108, 16, v165
	v_and_b32_e32 v109, 0xffff0000, v165
	v_pk_mul_f32 v[108:109], v[62:63], v[108:109] op_sel_hi:[0,1]
	v_pk_fma_f32 v[118:119], v[118:119], v[60:61], v[108:109] op_sel_hi:[1,0,1]
	v_add_f32_e32 v39, s22, v38
	v_readlane_b32 s34, v175, 25
	v_max_f32_e32 v40, s32, v39
	v_readlane_b32 s40, v177, 25
	v_sub_f32_e32 v58, v39, v40
	v_sub_f32_e32 v59, s32, v40
	v_mul_f32_e32 v58, 0x3fb8aa3b, v58
	v_mul_f32_e32 v59, 0x3fb8aa3b, v59
	v_exp_f32_e32 v60, v58
	v_exp_f32_e32 v62, v59
	v_cvt_pk_bf16_f32 v122, v118, v119
	global_store_dword v36, v122, s[6:7]
	s_add_u32 s6, s6, 0x20000
	s_addc_u32 s7, s7, 0
	v_lshlrev_b32_e32 v108, 16, v166
	v_and_b32_e32 v109, 0xffff0000, v166
	v_pk_mul_f32 v[108:109], v[62:63], v[108:109] op_sel_hi:[0,1]
	v_pk_fma_f32 v[118:119], v[118:119], v[60:61], v[108:109] op_sel_hi:[1,0,1]
	v_add_f32_e32 v39, s34, v40
	v_readlane_b32 s22, v175, 26
	v_max_f32_e32 v38, s40, v39
	v_readlane_b32 s32, v177, 26
	v_sub_f32_e32 v58, v39, v38
	v_sub_f32_e32 v59, s40, v38
	v_mul_f32_e32 v58, 0x3fb8aa3b, v58
	v_mul_f32_e32 v59, 0x3fb8aa3b, v59
	v_exp_f32_e32 v60, v58
	v_exp_f32_e32 v62, v59
	v_cvt_pk_bf16_f32 v122, v118, v119
	global_store_dword v36, v122, s[6:7]
	s_add_u32 s6, s6, 0x20000
	s_addc_u32 s7, s7, 0
	v_lshlrev_b32_e32 v108, 16, v167
	v_and_b32_e32 v109, 0xffff0000, v167
	v_pk_mul_f32 v[108:109], v[62:63], v[108:109] op_sel_hi:[0,1]
	v_pk_fma_f32 v[118:119], v[118:119], v[60:61], v[108:109] op_sel_hi:[1,0,1]
	v_add_f32_e32 v39, s22, v38
	v_readlane_b32 s34, v175, 27
	v_max_f32_e32 v40, s32, v39
	v_readlane_b32 s40, v177, 27
	v_sub_f32_e32 v58, v39, v40
	v_sub_f32_e32 v59, s32, v40
	v_mul_f32_e32 v58, 0x3fb8aa3b, v58
	v_mul_f32_e32 v59, 0x3fb8aa3b, v59
	v_exp_f32_e32 v60, v58
	v_exp_f32_e32 v62, v59
	v_cvt_pk_bf16_f32 v122, v118, v119
	global_store_dword v36, v122, s[6:7]
	s_add_u32 s6, s6, 0x20000
	s_addc_u32 s7, s7, 0
	v_lshlrev_b32_e32 v108, 16, v168
	v_and_b32_e32 v109, 0xffff0000, v168
	v_pk_mul_f32 v[108:109], v[62:63], v[108:109] op_sel_hi:[0,1]
	v_pk_fma_f32 v[118:119], v[118:119], v[60:61], v[108:109] op_sel_hi:[1,0,1]
	v_add_f32_e32 v39, s34, v40
	v_readlane_b32 s22, v175, 28
	v_max_f32_e32 v38, s40, v39
	v_readlane_b32 s32, v177, 28
	v_sub_f32_e32 v58, v39, v38
	v_sub_f32_e32 v59, s40, v38
	v_mul_f32_e32 v58, 0x3fb8aa3b, v58
	v_mul_f32_e32 v59, 0x3fb8aa3b, v59
	v_exp_f32_e32 v60, v58
	v_exp_f32_e32 v62, v59
	v_cvt_pk_bf16_f32 v122, v118, v119
	global_store_dword v36, v122, s[6:7]
	s_add_u32 s6, s6, 0x20000
	s_addc_u32 s7, s7, 0
	v_lshlrev_b32_e32 v108, 16, v169
	v_and_b32_e32 v109, 0xffff0000, v169
	v_pk_mul_f32 v[108:109], v[62:63], v[108:109] op_sel_hi:[0,1]
	v_pk_fma_f32 v[118:119], v[118:119], v[60:61], v[108:109] op_sel_hi:[1,0,1]
	v_add_f32_e32 v39, s22, v38
	v_readlane_b32 s34, v175, 29
	v_max_f32_e32 v40, s32, v39
	v_readlane_b32 s40, v177, 29
	v_sub_f32_e32 v58, v39, v40
	v_sub_f32_e32 v59, s32, v40
	v_mul_f32_e32 v58, 0x3fb8aa3b, v58
	v_mul_f32_e32 v59, 0x3fb8aa3b, v59
	v_exp_f32_e32 v60, v58
	v_exp_f32_e32 v62, v59
	v_cvt_pk_bf16_f32 v122, v118, v119
	global_store_dword v36, v122, s[6:7]
	s_add_u32 s6, s6, 0x20000
	s_addc_u32 s7, s7, 0
	v_lshlrev_b32_e32 v108, 16, v170
	v_and_b32_e32 v109, 0xffff0000, v170
	v_pk_mul_f32 v[108:109], v[62:63], v[108:109] op_sel_hi:[0,1]
	v_pk_fma_f32 v[118:119], v[118:119], v[60:61], v[108:109] op_sel_hi:[1,0,1]
	v_add_f32_e32 v39, s34, v40
	v_readlane_b32 s22, v175, 30
	v_max_f32_e32 v38, s40, v39
	v_readlane_b32 s32, v177, 30
	v_sub_f32_e32 v58, v39, v38
	v_sub_f32_e32 v59, s40, v38
	v_mul_f32_e32 v58, 0x3fb8aa3b, v58
	v_mul_f32_e32 v59, 0x3fb8aa3b, v59
	v_exp_f32_e32 v60, v58
	v_exp_f32_e32 v62, v59
	v_cvt_pk_bf16_f32 v122, v118, v119
	global_store_dword v36, v122, s[6:7]
	s_add_u32 s6, s6, 0x20000
	s_addc_u32 s7, s7, 0
	v_lshlrev_b32_e32 v108, 16, v171
	v_and_b32_e32 v109, 0xffff0000, v171
	v_pk_mul_f32 v[108:109], v[62:63], v[108:109] op_sel_hi:[0,1]
	v_pk_fma_f32 v[118:119], v[118:119], v[60:61], v[108:109] op_sel_hi:[1,0,1]
	v_add_f32_e32 v39, s22, v38
	v_readlane_b32 s34, v175, 31
	v_max_f32_e32 v40, s32, v39
	v_readlane_b32 s40, v177, 31
	v_sub_f32_e32 v58, v39, v40
	v_sub_f32_e32 v59, s32, v40
	v_mul_f32_e32 v58, 0x3fb8aa3b, v58
	v_mul_f32_e32 v59, 0x3fb8aa3b, v59
	v_exp_f32_e32 v60, v58
	v_exp_f32_e32 v62, v59
	v_cvt_pk_bf16_f32 v122, v118, v119
	global_store_dword v36, v122, s[6:7]
	s_add_u32 s6, s6, 0x20000
	s_addc_u32 s7, s7, 0
	v_lshlrev_b32_e32 v108, 16, v172
	v_and_b32_e32 v109, 0xffff0000, v172
	v_pk_mul_f32 v[108:109], v[62:63], v[108:109] op_sel_hi:[0,1]
	v_pk_fma_f32 v[118:119], v[118:119], v[60:61], v[108:109] op_sel_hi:[1,0,1]
	v_add_f32_e32 v39, s34, v40
	v_readlane_b32 s22, v175, 32
	v_max_f32_e32 v38, s40, v39
	v_readlane_b32 s32, v177, 32
	v_sub_f32_e32 v58, v39, v38
	v_sub_f32_e32 v59, s40, v38
	v_mul_f32_e32 v58, 0x3fb8aa3b, v58
	v_mul_f32_e32 v59, 0x3fb8aa3b, v59
	v_exp_f32_e32 v60, v58
	v_exp_f32_e32 v62, v59
	v_cvt_pk_bf16_f32 v122, v118, v119
	global_store_dword v36, v122, s[6:7]
	s_add_u32 s6, s6, 0x20000
	s_addc_u32 s7, s7, 0
	v_lshlrev_b32_e32 v108, 16, v173
	v_and_b32_e32 v109, 0xffff0000, v173
	v_pk_mul_f32 v[108:109], v[62:63], v[108:109] op_sel_hi:[0,1]
	v_pk_fma_f32 v[118:119], v[118:119], v[60:61], v[108:109] op_sel_hi:[1,0,1]
; __device__ __forceinline__ unsigned pk2(float lo, float hi) { f32x2_t v = {lo, hi}; bf16x2_t b = __builtin_convertvector(v, bf16x2_t); return __builtin_bit_cast(unsigned, b); }
; __device__ __forceinline__ float bflo(unsigned w) { return __uint_as_float(w << 16); }
; __device__ __forceinline__ float bfhi(unsigned w) { return __uint_as_float(w & 0xffff0000u); }
; __device__ __forceinline__ float fexp(float x) { return __builtin_amdgcn_exp2f(x * LOG2E); }
;     __device__ __forceinline__ float* MBM() const { return (float*)(ws + WS_MB); }
;     __device__ __forceinline__ float* MBB() const { return (float*)(ws + WS_MB) + (NSLOT_P + NSLOT_S); }
;     __device__ __forceinline__ float* MST() const { return (float*)(ws + WS_MB) + 2 * (NSLOT_P + NSLOT_S); }
; __device__ __forceinline__ void phase_scan(Ctx& C, int l, const bool st, LAS unsigned char* lds) {
;     ...
;             for (int j = 0; j < 16; ++j) { const int slot = (b * NPC + cg0 + j) * 4 + h;
;                 const float Bc = C.MBB()[slot], Mc = C.MBM()[slot];
;                 const float mn = fmaxf(Bc + m, Mc), g = fexp(Bc + m - mn), f = fexp(Mc - mn);
;                 if (st) { base[(size_t)slot * 8192] = pk2(c0, c1); if (hn) { dnb[(size_t)slot * 128] = nn; if (p == 0) C.MST()[slot] = m; } }
;                 c0 = g * c0 + f * bflo(buf[j]); c1 = g * c1 + f * bfhi(buf[j]); nn = g * nn + f * fb[j]; m = mn; }
.Lscan_nh_b6:
	s_waitcnt vmcnt(32)
	v_add_f32_e32 v39, s22, v38
	v_readlane_b32 s34, v175, 33
	v_max_f32_e32 v40, s32, v39
	v_readlane_b32 s40, v177, 33
	v_sub_f32_e32 v58, v39, v40
	v_sub_f32_e32 v59, s32, v40
	v_mul_f32_e32 v58, 0x3fb8aa3b, v58
	v_mul_f32_e32 v59, 0x3fb8aa3b, v59
	v_exp_f32_e32 v60, v58
	v_exp_f32_e32 v62, v59
	v_cvt_pk_bf16_f32 v122, v118, v119
	global_store_dword v36, v122, s[6:7]
	s_add_u32 s6, s6, 0x20000
	s_addc_u32 s7, s7, 0
	v_lshlrev_b32_e32 v108, 16, v126
	v_and_b32_e32 v109, 0xffff0000, v126
	v_pk_mul_f32 v[108:109], v[62:63], v[108:109] op_sel_hi:[0,1]
	v_pk_fma_f32 v[118:119], v[118:119], v[60:61], v[108:109] op_sel_hi:[1,0,1]
	v_add_f32_e32 v39, s34, v40
	v_readlane_b32 s22, v175, 34
	v_max_f32_e32 v38, s40, v39
	v_readlane_b32 s32, v177, 34
	v_sub_f32_e32 v58, v39, v38
	v_sub_f32_e32 v59, s40, v38
	v_mul_f32_e32 v58, 0x3fb8aa3b, v58
	v_mul_f32_e32 v59, 0x3fb8aa3b, v59
	v_exp_f32_e32 v60, v58
	v_exp_f32_e32 v62, v59
	v_cvt_pk_bf16_f32 v122, v118, v119
	global_store_dword v36, v122, s[6:7]
	s_add_u32 s6, s6, 0x20000
	s_addc_u32 s7, s7, 0
	v_lshlrev_b32_e32 v108, 16, v127
	v_and_b32_e32 v109, 0xffff0000, v127
	v_pk_mul_f32 v[108:109], v[62:63], v[108:109] op_sel_hi:[0,1]
	v_pk_fma_f32 v[118:119], v[118:119], v[60:61], v[108:109] op_sel_hi:[1,0,1]
	v_add_f32_e32 v39, s22, v38
	v_readlane_b32 s34, v175, 35
	v_max_f32_e32 v40, s32, v39
	v_readlane_b32 s40, v177, 35
	v_sub_f32_e32 v58, v39, v40
	v_sub_f32_e32 v59, s32, v40
	v_mul_f32_e32 v58, 0x3fb8aa3b, v58
	v_mul_f32_e32 v59, 0x3fb8aa3b, v59
	v_exp_f32_e32 v60, v58
	v_exp_f32_e32 v62, v59
	v_cvt_pk_bf16_f32 v122, v118, v119
	global_store_dword v36, v122, s[6:7]
	s_add_u32 s6, s6, 0x20000
	s_addc_u32 s7, s7, 0
	v_lshlrev_b32_e32 v108, 16, v128
	v_and_b32_e32 v109, 0xffff0000, v128
	v_pk_mul_f32 v[108:109], v[62:63], v[108:109] op_sel_hi:[0,1]
	v_pk_fma_f32 v[118:119], v[118:119], v[60:61], v[108:109] op_sel_hi:[1,0,1]
	v_add_f32_e32 v39, s34, v40
	v_readlane_b32 s22, v175, 36
	v_max_f32_e32 v38, s40, v39
	v_readlane_b32 s32, v177, 36
	v_sub_f32_e32 v58, v39, v38
	v_sub_f32_e32 v59, s40, v38
	v_mul_f32_e32 v58, 0x3fb8aa3b, v58
	v_mul_f32_e32 v59, 0x3fb8aa3b, v59
	v_exp_f32_e32 v60, v58
	v_exp_f32_e32 v62, v59
	v_cvt_pk_bf16_f32 v122, v118, v119
	global_store_dword v36, v122, s[6:7]
	s_add_u32 s6, s6, 0x20000
	s_addc_u32 s7, s7, 0
	v_lshlrev_b32_e32 v108, 16, v129
	v_and_b32_e32 v109, 0xffff0000, v129
	v_pk_mul_f32 v[108:109], v[62:63], v[108:109] op_sel_hi:[0,1]
	v_pk_fma_f32 v[118:119], v[118:119], v[60:61], v[108:109] op_sel_hi:[1,0,1]
	v_add_f32_e32 v39, s22, v38
	v_readlane_b32 s34, v175, 37
	v_max_f32_e32 v40, s32, v39
	v_readlane_b32 s40, v177, 37
	v_sub_f32_e32 v58, v39, v40
	v_sub_f32_e32 v59, s32, v40
	v_mul_f32_e32 v58, 0x3fb8aa3b, v58
	v_mul_f32_e32 v59, 0x3fb8aa3b, v59
	v_exp_f32_e32 v60, v58
	v_exp_f32_e32 v62, v59
	v_cvt_pk_bf16_f32 v122, v118, v119
	global_store_dword v36, v122, s[6:7]
	s_add_u32 s6, s6, 0x20000
	s_addc_u32 s7, s7, 0
	v_lshlrev_b32_e32 v108, 16, v130
	v_and_b32_e32 v109, 0xffff0000, v130
	v_pk_mul_f32 v[108:109], v[62:63], v[108:109] op_sel_hi:[0,1]
	v_pk_fma_f32 v[118:119], v[118:119], v[60:61], v[108:109] op_sel_hi:[1,0,1]
	v_add_f32_e32 v39, s34, v40
	v_readlane_b32 s22, v175, 38
	v_max_f32_e32 v38, s40, v39
	v_readlane_b32 s32, v177, 38
	v_sub_f32_e32 v58, v39, v38
	v_sub_f32_e32 v59, s40, v38
	v_mul_f32_e32 v58, 0x3fb8aa3b, v58
	v_mul_f32_e32 v59, 0x3fb8aa3b, v59
	v_exp_f32_e32 v60, v58
	v_exp_f32_e32 v62, v59
	v_cvt_pk_bf16_f32 v122, v118, v119
	global_store_dword v36, v122, s[6:7]
	s_add_u32 s6, s6, 0x20000
	s_addc_u32 s7, s7, 0
	v_lshlrev_b32_e32 v108, 16, v131
	v_and_b32_e32 v109, 0xffff0000, v131
	v_pk_mul_f32 v[108:109], v[62:63], v[108:109] op_sel_hi:[0,1]
	v_pk_fma_f32 v[118:119], v[118:119], v[60:61], v[108:109] op_sel_hi:[1,0,1]
	v_add_f32_e32 v39, s22, v38
	v_readlane_b32 s34, v175, 39
	v_max_f32_e32 v40, s32, v39
	v_readlane_b32 s40, v177, 39
	v_sub_f32_e32 v58, v39, v40
	v_sub_f32_e32 v59, s32, v40
	v_mul_f32_e32 v58, 0x3fb8aa3b, v58
	v_mul_f32_e32 v59, 0x3fb8aa3b, v59
	v_exp_f32_e32 v60, v58
	v_exp_f32_e32 v62, v59
	v_cvt_pk_bf16_f32 v122, v118, v119
	global_store_dword v36, v122, s[6:7]
	s_add_u32 s6, s6, 0x20000
	s_addc_u32 s7, s7, 0
	v_lshlrev_b32_e32 v108, 16, v132
	v_and_b32_e32 v109, 0xffff0000, v132
	v_pk_mul_f32 v[108:109], v[62:63], v[108:109] op_sel_hi:[0,1]
	v_pk_fma_f32 v[118:119], v[118:119], v[60:61], v[108:109] op_sel_hi:[1,0,1]
	v_add_f32_e32 v39, s34, v40
	v_readlane_b32 s22, v175, 40
	v_max_f32_e32 v38, s40, v39
	v_readlane_b32 s32, v177, 40
	v_sub_f32_e32 v58, v39, v38
	v_sub_f32_e32 v59, s40, v38
	v_mul_f32_e32 v58, 0x3fb8aa3b, v58
	v_mul_f32_e32 v59, 0x3fb8aa3b, v59
	v_exp_f32_e32 v60, v58
	v_exp_f32_e32 v62, v59
	v_cvt_pk_bf16_f32 v122, v118, v119
	global_store_dword v36, v122, s[6:7]
	s_add_u32 s6, s6, 0x20000
	s_addc_u32 s7, s7, 0
	v_lshlrev_b32_e32 v108, 16, v133
	v_and_b32_e32 v109, 0xffff0000, v133
	v_pk_mul_f32 v[108:109], v[62:63], v[108:109] op_sel_hi:[0,1]
	v_pk_fma_f32 v[118:119], v[118:119], v[60:61], v[108:109] op_sel_hi:[1,0,1]
	v_add_f32_e32 v39, s22, v38
	v_readlane_b32 s34, v175, 41
	v_max_f32_e32 v40, s32, v39
	v_readlane_b32 s40, v177, 41
	v_sub_f32_e32 v58, v39, v40
	v_sub_f32_e32 v59, s32, v40
	v_mul_f32_e32 v58, 0x3fb8aa3b, v58
	v_mul_f32_e32 v59, 0x3fb8aa3b, v59
	v_exp_f32_e32 v60, v58
	v_exp_f32_e32 v62, v59
	v_cvt_pk_bf16_f32 v122, v118, v119
	global_store_dword v36, v122, s[6:7]
	s_add_u32 s6, s6, 0x20000
	s_addc_u32 s7, s7, 0
	v_lshlrev_b32_e32 v108, 16, v134
	v_and_b32_e32 v109, 0xffff0000, v134
	v_pk_mul_f32 v[108:109], v[62:63], v[108:109] op_sel_hi:[0,1]
; __device__ __forceinline__ unsigned pk2(float lo, float hi) { f32x2_t v = {lo, hi}; bf16x2_t b = __builtin_convertvector(v, bf16x2_t); return __builtin_bit_cast(unsigned, b); }
; __device__ __forceinline__ float bflo(unsigned w) { return __uint_as_float(w << 16); }
; __device__ __forceinline__ float bfhi(unsigned w) { return __uint_as_float(w & 0xffff0000u); }
; __device__ __forceinline__ float fexp(float x) { return __builtin_amdgcn_exp2f(x * LOG2E); }
;     __device__ __forceinline__ float* MBM() const { return (float*)(ws + WS_MB); }
;     __device__ __forceinline__ float* MBB() const { return (float*)(ws + WS_MB) + (NSLOT_P + NSLOT_S); }
;     __device__ __forceinline__ float* MST() const { return (float*)(ws + WS_MB) + 2 * (NSLOT_P + NSLOT_S); }
; __device__ __forceinline__ void phase_scan(Ctx& C, int l, const bool st, LAS unsigned char* lds) {
;     ...
;             for (int j = 0; j < 16; ++j) { const int slot = (b * NPC + cg0 + j) * 4 + h;
;                 const float Bc = C.MBB()[slot], Mc = C.MBM()[slot];
;                 const float mn = fmaxf(Bc + m, Mc), g = fexp(Bc + m - mn), f = fexp(Mc - mn);
;                 if (st) { base[(size_t)slot * 8192] = pk2(c0, c1); if (hn) { dnb[(size_t)slot * 128] = nn; if (p == 0) C.MST()[slot] = m; } }
;                 c0 = g * c0 + f * bflo(buf[j]); c1 = g * c1 + f * bfhi(buf[j]); nn = g * nn + f * fb[j]; m = mn; }
	v_pk_fma_f32 v[118:119], v[118:119], v[60:61], v[108:109] op_sel_hi:[1,0,1]
	v_add_f32_e32 v39, s34, v40
	v_readlane_b32 s22, v175, 42
	v_max_f32_e32 v38, s40, v39
	v_readlane_b32 s32, v177, 42
	v_sub_f32_e32 v58, v39, v38
	v_sub_f32_e32 v59, s40, v38
	v_mul_f32_e32 v58, 0x3fb8aa3b, v58
	v_mul_f32_e32 v59, 0x3fb8aa3b, v59
	v_exp_f32_e32 v60, v58
	v_exp_f32_e32 v62, v59
	v_cvt_pk_bf16_f32 v122, v118, v119
	global_store_dword v36, v122, s[6:7]
	s_add_u32 s6, s6, 0x20000
	s_addc_u32 s7, s7, 0
	v_lshlrev_b32_e32 v108, 16, v135
	v_and_b32_e32 v109, 0xffff0000, v135
	v_pk_mul_f32 v[108:109], v[62:63], v[108:109] op_sel_hi:[0,1]
	v_pk_fma_f32 v[118:119], v[118:119], v[60:61], v[108:109] op_sel_hi:[1,0,1]
	v_add_f32_e32 v39, s22, v38
	v_readlane_b32 s34, v175, 43
	v_max_f32_e32 v40, s32, v39
	v_readlane_b32 s40, v177, 43
	v_sub_f32_e32 v58, v39, v40
	v_sub_f32_e32 v59, s32, v40
	v_mul_f32_e32 v58, 0x3fb8aa3b, v58
	v_mul_f32_e32 v59, 0x3fb8aa3b, v59
	v_exp_f32_e32 v60, v58
	v_exp_f32_e32 v62, v59
	v_cvt_pk_bf16_f32 v122, v118, v119
	global_store_dword v36, v122, s[6:7]
	s_add_u32 s6, s6, 0x20000
	s_addc_u32 s7, s7, 0
	v_lshlrev_b32_e32 v108, 16, v136
	v_and_b32_e32 v109, 0xffff0000, v136
	v_pk_mul_f32 v[108:109], v[62:63], v[108:109] op_sel_hi:[0,1]
	v_pk_fma_f32 v[118:119], v[118:119], v[60:61], v[108:109] op_sel_hi:[1,0,1]
	v_add_f32_e32 v39, s34, v40
	v_readlane_b32 s22, v175, 44
	v_max_f32_e32 v38, s40, v39
	v_readlane_b32 s32, v177, 44
	v_sub_f32_e32 v58, v39, v38
	v_sub_f32_e32 v59, s40, v38
	v_mul_f32_e32 v58, 0x3fb8aa3b, v58
	v_mul_f32_e32 v59, 0x3fb8aa3b, v59
	v_exp_f32_e32 v60, v58
	v_exp_f32_e32 v62, v59
	v_cvt_pk_bf16_f32 v122, v118, v119
	global_store_dword v36, v122, s[6:7]
	s_add_u32 s6, s6, 0x20000
	s_addc_u32 s7, s7, 0
	v_lshlrev_b32_e32 v108, 16, v137
	v_and_b32_e32 v109, 0xffff0000, v137
	v_pk_mul_f32 v[108:109], v[62:63], v[108:109] op_sel_hi:[0,1]
	v_pk_fma_f32 v[118:119], v[118:119], v[60:61], v[108:109] op_sel_hi:[1,0,1]
	v_add_f32_e32 v39, s22, v38
	v_readlane_b32 s34, v175, 45
	v_max_f32_e32 v40, s32, v39
	v_readlane_b32 s40, v177, 45
	v_sub_f32_e32 v58, v39, v40
	v_sub_f32_e32 v59, s32, v40
	v_mul_f32_e32 v58, 0x3fb8aa3b, v58
	v_mul_f32_e32 v59, 0x3fb8aa3b, v59
	v_exp_f32_e32 v60, v58
	v_exp_f32_e32 v62, v59
	v_cvt_pk_bf16_f32 v122, v118, v119
	global_store_dword v36, v122, s[6:7]
	s_add_u32 s6, s6, 0x20000
	s_addc_u32 s7, s7, 0
	v_lshlrev_b32_e32 v108, 16, v138
	v_and_b32_e32 v109, 0xffff0000, v138
	v_pk_mul_f32 v[108:109], v[62:63], v[108:109] op_sel_hi:[0,1]
	v_pk_fma_f32 v[118:119], v[118:119], v[60:61], v[108:109] op_sel_hi:[1,0,1]
	v_add_f32_e32 v39, s34, v40
	v_readlane_b32 s22, v175, 46
	v_max_f32_e32 v38, s40, v39
	v_readlane_b32 s32, v177, 46
	v_sub_f32_e32 v58, v39, v38
	v_sub_f32_e32 v59, s40, v38
	v_mul_f32_e32 v58, 0x3fb8aa3b, v58
	v_mul_f32_e32 v59, 0x3fb8aa3b, v59
	v_exp_f32_e32 v60, v58
	v_exp_f32_e32 v62, v59
	v_cvt_pk_bf16_f32 v122, v118, v119
	global_store_dword v36, v122, s[6:7]
	s_add_u32 s6, s6, 0x20000
	s_addc_u32 s7, s7, 0
	v_lshlrev_b32_e32 v108, 16, v139
	v_and_b32_e32 v109, 0xffff0000, v139
	v_pk_mul_f32 v[108:109], v[62:63], v[108:109] op_sel_hi:[0,1]
	v_pk_fma_f32 v[118:119], v[118:119], v[60:61], v[108:109] op_sel_hi:[1,0,1]
	v_add_f32_e32 v39, s22, v38
	v_readlane_b32 s34, v175, 47
	v_max_f32_e32 v40, s32, v39
	v_readlane_b32 s40, v177, 47
	v_sub_f32_e32 v58, v39, v40
	v_sub_f32_e32 v59, s32, v40
	v_mul_f32_e32 v58, 0x3fb8aa3b, v58
	v_mul_f32_e32 v59, 0x3fb8aa3b, v59
	v_exp_f32_e32 v60, v58
	v_exp_f32_e32 v62, v59
	v_cvt_pk_bf16_f32 v122, v118, v119
	global_store_dword v36, v122, s[6:7]
	s_add_u32 s6, s6, 0x20000
	s_addc_u32 s7, s7, 0
	v_lshlrev_b32_e32 v108, 16, v140
	v_and_b32_e32 v109, 0xffff0000, v140
	v_pk_mul_f32 v[108:109], v[62:63], v[108:109] op_sel_hi:[0,1]
	v_pk_fma_f32 v[118:119], v[118:119], v[60:61], v[108:109] op_sel_hi:[1,0,1]
	v_add_f32_e32 v39, s34, v40
	v_readlane_b32 s22, v175, 48
	v_max_f32_e32 v38, s40, v39
	v_readlane_b32 s32, v177, 48
	v_sub_f32_e32 v58, v39, v38
	v_sub_f32_e32 v59, s40, v38
	v_mul_f32_e32 v58, 0x3fb8aa3b, v58
	v_mul_f32_e32 v59, 0x3fb8aa3b, v59
	v_exp_f32_e32 v60, v58
	v_exp_f32_e32 v62, v59
	v_cvt_pk_bf16_f32 v122, v118, v119
	global_store_dword v36, v122, s[6:7]
	s_add_u32 s6, s6, 0x20000
	s_addc_u32 s7, s7, 0
	v_lshlrev_b32_e32 v108, 16, v141
	v_and_b32_e32 v109, 0xffff0000, v141
	v_pk_mul_f32 v[108:109], v[62:63], v[108:109] op_sel_hi:[0,1]
	v_pk_fma_f32 v[118:119], v[118:119], v[60:61], v[108:109] op_sel_hi:[1,0,1]
; __device__ __forceinline__ unsigned pk2(float lo, float hi) { f32x2_t v = {lo, hi}; bf16x2_t b = __builtin_convertvector(v, bf16x2_t); return __builtin_bit_cast(unsigned, b); }
; __device__ __forceinline__ float bflo(unsigned w) { return __uint_as_float(w << 16); }
; __device__ __forceinline__ float bfhi(unsigned w) { return __uint_as_float(w & 0xffff0000u); }
; __device__ __forceinline__ float fexp(float x) { return __builtin_amdgcn_exp2f(x * LOG2E); }
;     __device__ __forceinline__ float* MBM() const { return (float*)(ws + WS_MB); }
;     __device__ __forceinline__ float* MBB() const { return (float*)(ws + WS_MB) + (NSLOT_P + NSLOT_S); }
;     __device__ __forceinline__ float* MST() const { return (float*)(ws + WS_MB) + 2 * (NSLOT_P + NSLOT_S); }
; __device__ __forceinline__ void phase_scan(Ctx& C, int l, const bool st, LAS unsigned char* lds) {
;     ...
;             for (int j = 0; j < 16; ++j) { const int slot = (b * NPC + cg0 + j) * 4 + h;
;                 const float Bc = C.MBB()[slot], Mc = C.MBM()[slot];
;                 const float mn = fmaxf(Bc + m, Mc), g = fexp(Bc + m - mn), f = fexp(Mc - mn);
;                 if (st) { base[(size_t)slot * 8192] = pk2(c0, c1); if (hn) { dnb[(size_t)slot * 128] = nn; if (p == 0) C.MST()[slot] = m; } }
;                 c0 = g * c0 + f * bflo(buf[j]); c1 = g * c1 + f * bfhi(buf[j]); nn = g * nn + f * fb[j]; m = mn; }
.Lscan_nh_b7:
	s_waitcnt vmcnt(32)
	v_add_f32_e32 v39, s22, v38
	v_readlane_b32 s34, v175, 49
	v_max_f32_e32 v40, s32, v39
	v_readlane_b32 s40, v177, 49
	v_sub_f32_e32 v58, v39, v40
	v_sub_f32_e32 v59, s32, v40
	v_mul_f32_e32 v58, 0x3fb8aa3b, v58
	v_mul_f32_e32 v59, 0x3fb8aa3b, v59
	v_exp_f32_e32 v60, v58
	v_exp_f32_e32 v62, v59
	v_cvt_pk_bf16_f32 v122, v118, v119
	global_store_dword v36, v122, s[6:7]
	s_add_u32 s6, s6, 0x20000
	s_addc_u32 s7, s7, 0
	v_lshlrev_b32_e32 v108, 16, v142
	v_and_b32_e32 v109, 0xffff0000, v142
	v_pk_mul_f32 v[108:109], v[62:63], v[108:109] op_sel_hi:[0,1]
	v_pk_fma_f32 v[118:119], v[118:119], v[60:61], v[108:109] op_sel_hi:[1,0,1]
	v_add_f32_e32 v39, s34, v40
	v_readlane_b32 s22, v175, 50
	v_max_f32_e32 v38, s40, v39
	v_readlane_b32 s32, v177, 50
	v_sub_f32_e32 v58, v39, v38
	v_sub_f32_e32 v59, s40, v38
	v_mul_f32_e32 v58, 0x3fb8aa3b, v58
	v_mul_f32_e32 v59, 0x3fb8aa3b, v59
	v_exp_f32_e32 v60, v58
	v_exp_f32_e32 v62, v59
	v_cvt_pk_bf16_f32 v122, v118, v119
	global_store_dword v36, v122, s[6:7]
	s_add_u32 s6, s6, 0x20000
	s_addc_u32 s7, s7, 0
	v_lshlrev_b32_e32 v108, 16, v143
	v_and_b32_e32 v109, 0xffff0000, v143
	v_pk_mul_f32 v[108:109], v[62:63], v[108:109] op_sel_hi:[0,1]
	v_pk_fma_f32 v[118:119], v[118:119], v[60:61], v[108:109] op_sel_hi:[1,0,1]
	v_add_f32_e32 v39, s22, v38
	v_readlane_b32 s34, v175, 51
	v_max_f32_e32 v40, s32, v39
	v_readlane_b32 s40, v177, 51
	v_sub_f32_e32 v58, v39, v40
	v_sub_f32_e32 v59, s32, v40
	v_mul_f32_e32 v58, 0x3fb8aa3b, v58
	v_mul_f32_e32 v59, 0x3fb8aa3b, v59
	v_exp_f32_e32 v60, v58
	v_exp_f32_e32 v62, v59
	v_cvt_pk_bf16_f32 v122, v118, v119
	global_store_dword v36, v122, s[6:7]
	s_add_u32 s6, s6, 0x20000
	s_addc_u32 s7, s7, 0
	v_lshlrev_b32_e32 v108, 16, v144
	v_and_b32_e32 v109, 0xffff0000, v144
	v_pk_mul_f32 v[108:109], v[62:63], v[108:109] op_sel_hi:[0,1]
	v_pk_fma_f32 v[118:119], v[118:119], v[60:61], v[108:109] op_sel_hi:[1,0,1]
	v_add_f32_e32 v39, s34, v40
	v_readlane_b32 s22, v175, 52
	v_max_f32_e32 v38, s40, v39
	v_readlane_b32 s32, v177, 52
	v_sub_f32_e32 v58, v39, v38
	v_sub_f32_e32 v59, s40, v38
	v_mul_f32_e32 v58, 0x3fb8aa3b, v58
	v_mul_f32_e32 v59, 0x3fb8aa3b, v59
	v_exp_f32_e32 v60, v58
	v_exp_f32_e32 v62, v59
	v_cvt_pk_bf16_f32 v122, v118, v119
	global_store_dword v36, v122, s[6:7]
	s_add_u32 s6, s6, 0x20000
	s_addc_u32 s7, s7, 0
	v_lshlrev_b32_e32 v108, 16, v145
	v_and_b32_e32 v109, 0xffff0000, v145
	v_pk_mul_f32 v[108:109], v[62:63], v[108:109] op_sel_hi:[0,1]
	v_pk_fma_f32 v[118:119], v[118:119], v[60:61], v[108:109] op_sel_hi:[1,0,1]
	v_add_f32_e32 v39, s22, v38
	v_readlane_b32 s34, v175, 53
	v_max_f32_e32 v40, s32, v39
	v_readlane_b32 s40, v177, 53
	v_sub_f32_e32 v58, v39, v40
	v_sub_f32_e32 v59, s32, v40
	v_mul_f32_e32 v58, 0x3fb8aa3b, v58
	v_mul_f32_e32 v59, 0x3fb8aa3b, v59
	v_exp_f32_e32 v60, v58
	v_exp_f32_e32 v62, v59
	v_cvt_pk_bf16_f32 v122, v118, v119
	global_store_dword v36, v122, s[6:7]
	s_add_u32 s6, s6, 0x20000
	s_addc_u32 s7, s7, 0
	v_lshlrev_b32_e32 v108, 16, v146
	v_and_b32_e32 v109, 0xffff0000, v146
	v_pk_mul_f32 v[108:109], v[62:63], v[108:109] op_sel_hi:[0,1]
	v_pk_fma_f32 v[118:119], v[118:119], v[60:61], v[108:109] op_sel_hi:[1,0,1]
	v_add_f32_e32 v39, s34, v40
	v_readlane_b32 s22, v175, 54
	v_max_f32_e32 v38, s40, v39
	v_readlane_b32 s32, v177, 54
	v_sub_f32_e32 v58, v39, v38
	v_sub_f32_e32 v59, s40, v38
	v_mul_f32_e32 v58, 0x3fb8aa3b, v58
	v_mul_f32_e32 v59, 0x3fb8aa3b, v59
	v_exp_f32_e32 v60, v58
	v_exp_f32_e32 v62, v59
	v_cvt_pk_bf16_f32 v122, v118, v119
	global_store_dword v36, v122, s[6:7]
	s_add_u32 s6, s6, 0x20000
	s_addc_u32 s7, s7, 0
	v_lshlrev_b32_e32 v108, 16, v147
	v_and_b32_e32 v109, 0xffff0000, v147
	v_pk_mul_f32 v[108:109], v[62:63], v[108:109] op_sel_hi:[0,1]
	v_pk_fma_f32 v[118:119], v[118:119], v[60:61], v[108:109] op_sel_hi:[1,0,1]
	v_add_f32_e32 v39, s22, v38
	v_readlane_b32 s34, v175, 55
	v_max_f32_e32 v40, s32, v39
	v_readlane_b32 s40, v177, 55
	v_sub_f32_e32 v58, v39, v40
	v_sub_f32_e32 v59, s32, v40
	v_mul_f32_e32 v58, 0x3fb8aa3b, v58
	v_mul_f32_e32 v59, 0x3fb8aa3b, v59
	v_exp_f32_e32 v60, v58
	v_exp_f32_e32 v62, v59
	v_cvt_pk_bf16_f32 v122, v118, v119
	global_store_dword v36, v122, s[6:7]
	s_add_u32 s6, s6, 0x20000
	s_addc_u32 s7, s7, 0
	v_lshlrev_b32_e32 v108, 16, v148
	v_and_b32_e32 v109, 0xffff0000, v148
	v_pk_mul_f32 v[108:109], v[62:63], v[108:109] op_sel_hi:[0,1]
	v_pk_fma_f32 v[118:119], v[118:119], v[60:61], v[108:109] op_sel_hi:[1,0,1]
	v_add_f32_e32 v39, s34, v40
	v_readlane_b32 s22, v175, 56
	v_max_f32_e32 v38, s40, v39
	v_readlane_b32 s32, v177, 56
	v_sub_f32_e32 v58, v39, v38
	v_sub_f32_e32 v59, s40, v38
	v_mul_f32_e32 v58, 0x3fb8aa3b, v58
	v_mul_f32_e32 v59, 0x3fb8aa3b, v59
	v_exp_f32_e32 v60, v58
	v_exp_f32_e32 v62, v59
	v_cvt_pk_bf16_f32 v122, v118, v119
	global_store_dword v36, v122, s[6:7]
	s_add_u32 s6, s6, 0x20000
	s_addc_u32 s7, s7, 0
	v_lshlrev_b32_e32 v108, 16, v149
	v_and_b32_e32 v109, 0xffff0000, v149
	v_pk_mul_f32 v[108:109], v[62:63], v[108:109] op_sel_hi:[0,1]
	v_pk_fma_f32 v[118:119], v[118:119], v[60:61], v[108:109] op_sel_hi:[1,0,1]
	v_add_f32_e32 v39, s22, v38
	v_readlane_b32 s34, v175, 57
	v_max_f32_e32 v40, s32, v39
	v_readlane_b32 s40, v177, 57
	v_sub_f32_e32 v58, v39, v40
	v_sub_f32_e32 v59, s32, v40
	v_mul_f32_e32 v58, 0x3fb8aa3b, v58
	v_mul_f32_e32 v59, 0x3fb8aa3b, v59
	v_exp_f32_e32 v60, v58
	v_exp_f32_e32 v62, v59
	v_cvt_pk_bf16_f32 v122, v118, v119
	global_store_dword v36, v122, s[6:7]
	s_add_u32 s6, s6, 0x20000
	s_addc_u32 s7, s7, 0
	v_lshlrev_b32_e32 v108, 16, v150
	v_and_b32_e32 v109, 0xffff0000, v150
	v_pk_mul_f32 v[108:109], v[62:63], v[108:109] op_sel_hi:[0,1]
; __device__ __forceinline__ unsigned pk2(float lo, float hi) { f32x2_t v = {lo, hi}; bf16x2_t b = __builtin_convertvector(v, bf16x2_t); return __builtin_bit_cast(unsigned, b); }
; __device__ __forceinline__ float bflo(unsigned w) { return __uint_as_float(w << 16); }
; __device__ __forceinline__ float bfhi(unsigned w) { return __uint_as_float(w & 0xffff0000u); }
; __device__ __forceinline__ float fexp(float x) { return __builtin_amdgcn_exp2f(x * LOG2E); }
;     __device__ __forceinline__ float* MBM() const { return (float*)(ws + WS_MB); }
;     __device__ __forceinline__ float* MBB() const { return (float*)(ws + WS_MB) + (NSLOT_P + NSLOT_S); }
;     __device__ __forceinline__ float* MST() const { return (float*)(ws + WS_MB) + 2 * (NSLOT_P + NSLOT_S); }
; __device__ __forceinline__ void phase_scan(Ctx& C, int l, const bool st, LAS unsigned char* lds) {
;     ...
;             for (int j = 0; j < 16; ++j) { const int slot = (b * NPC + cg0 + j) * 4 + h;
;                 const float Bc = C.MBB()[slot], Mc = C.MBM()[slot];
;                 const float mn = fmaxf(Bc + m, Mc), g = fexp(Bc + m - mn), f = fexp(Mc - mn);
;                 if (st) { base[(size_t)slot * 8192] = pk2(c0, c1); if (hn) { dnb[(size_t)slot * 128] = nn; if (p == 0) C.MST()[slot] = m; } }
;                 c0 = g * c0 + f * bflo(buf[j]); c1 = g * c1 + f * bfhi(buf[j]); nn = g * nn + f * fb[j]; m = mn; }
; #pragma unroll
;             for (int j = 0; j < 16; ++j) { buf[j] = nb[j]; fb[j] = fnb[j]; }
;         }
	v_pk_fma_f32 v[118:119], v[118:119], v[60:61], v[108:109] op_sel_hi:[1,0,1]
	v_add_f32_e32 v39, s34, v40
	v_readlane_b32 s22, v175, 58
	v_max_f32_e32 v38, s40, v39
	v_readlane_b32 s32, v177, 58
	v_sub_f32_e32 v58, v39, v38
	v_sub_f32_e32 v59, s40, v38
	v_mul_f32_e32 v58, 0x3fb8aa3b, v58
	v_mul_f32_e32 v59, 0x3fb8aa3b, v59
	v_exp_f32_e32 v60, v58
	v_exp_f32_e32 v62, v59
	v_cvt_pk_bf16_f32 v122, v118, v119
	global_store_dword v36, v122, s[6:7]
	s_add_u32 s6, s6, 0x20000
	s_addc_u32 s7, s7, 0
	v_lshlrev_b32_e32 v108, 16, v151
	v_and_b32_e32 v109, 0xffff0000, v151
	v_pk_mul_f32 v[108:109], v[62:63], v[108:109] op_sel_hi:[0,1]
	v_pk_fma_f32 v[118:119], v[118:119], v[60:61], v[108:109] op_sel_hi:[1,0,1]
	v_add_f32_e32 v39, s22, v38
	v_readlane_b32 s34, v175, 59
	v_max_f32_e32 v40, s32, v39
	v_readlane_b32 s40, v177, 59
	v_sub_f32_e32 v58, v39, v40
	v_sub_f32_e32 v59, s32, v40
	v_mul_f32_e32 v58, 0x3fb8aa3b, v58
	v_mul_f32_e32 v59, 0x3fb8aa3b, v59
	v_exp_f32_e32 v60, v58
	v_exp_f32_e32 v62, v59
	v_cvt_pk_bf16_f32 v122, v118, v119
	global_store_dword v36, v122, s[6:7]
	s_add_u32 s6, s6, 0x20000
	s_addc_u32 s7, s7, 0
	v_lshlrev_b32_e32 v108, 16, v152
	v_and_b32_e32 v109, 0xffff0000, v152
	v_pk_mul_f32 v[108:109], v[62:63], v[108:109] op_sel_hi:[0,1]
	v_pk_fma_f32 v[118:119], v[118:119], v[60:61], v[108:109] op_sel_hi:[1,0,1]
	v_add_f32_e32 v39, s34, v40
	v_readlane_b32 s22, v175, 60
	v_max_f32_e32 v38, s40, v39
	v_readlane_b32 s32, v177, 60
	v_sub_f32_e32 v58, v39, v38
	v_sub_f32_e32 v59, s40, v38
	v_mul_f32_e32 v58, 0x3fb8aa3b, v58
	v_mul_f32_e32 v59, 0x3fb8aa3b, v59
	v_exp_f32_e32 v60, v58
	v_exp_f32_e32 v62, v59
	v_cvt_pk_bf16_f32 v122, v118, v119
	global_store_dword v36, v122, s[6:7]
	s_add_u32 s6, s6, 0x20000
	s_addc_u32 s7, s7, 0
	v_lshlrev_b32_e32 v108, 16, v153
	v_and_b32_e32 v109, 0xffff0000, v153
	v_pk_mul_f32 v[108:109], v[62:63], v[108:109] op_sel_hi:[0,1]
	v_pk_fma_f32 v[118:119], v[118:119], v[60:61], v[108:109] op_sel_hi:[1,0,1]
	v_add_f32_e32 v39, s22, v38
	v_readlane_b32 s34, v175, 61
	v_max_f32_e32 v40, s32, v39
	v_readlane_b32 s40, v177, 61
	v_sub_f32_e32 v58, v39, v40
	v_sub_f32_e32 v59, s32, v40
	v_mul_f32_e32 v58, 0x3fb8aa3b, v58
	v_mul_f32_e32 v59, 0x3fb8aa3b, v59
	v_exp_f32_e32 v60, v58
	v_exp_f32_e32 v62, v59
	v_cvt_pk_bf16_f32 v122, v118, v119
	global_store_dword v36, v122, s[6:7]
	s_add_u32 s6, s6, 0x20000
	s_addc_u32 s7, s7, 0
	v_lshlrev_b32_e32 v108, 16, v154
	v_and_b32_e32 v109, 0xffff0000, v154
	v_pk_mul_f32 v[108:109], v[62:63], v[108:109] op_sel_hi:[0,1]
	v_pk_fma_f32 v[118:119], v[118:119], v[60:61], v[108:109] op_sel_hi:[1,0,1]
	v_add_f32_e32 v39, s34, v40
	v_readlane_b32 s22, v175, 62
	v_max_f32_e32 v38, s40, v39
	v_readlane_b32 s32, v177, 62
	v_sub_f32_e32 v58, v39, v38
	v_sub_f32_e32 v59, s40, v38
	v_mul_f32_e32 v58, 0x3fb8aa3b, v58
	v_mul_f32_e32 v59, 0x3fb8aa3b, v59
	v_exp_f32_e32 v60, v58
	v_exp_f32_e32 v62, v59
	v_cvt_pk_bf16_f32 v122, v118, v119
	global_store_dword v36, v122, s[6:7]
	s_add_u32 s6, s6, 0x20000
	s_addc_u32 s7, s7, 0
	v_lshlrev_b32_e32 v108, 16, v155
	v_and_b32_e32 v109, 0xffff0000, v155
	v_pk_mul_f32 v[108:109], v[62:63], v[108:109] op_sel_hi:[0,1]
	v_pk_fma_f32 v[118:119], v[118:119], v[60:61], v[108:109] op_sel_hi:[1,0,1]
	v_add_f32_e32 v39, s22, v38
	v_readlane_b32 s34, v175, 63
	v_max_f32_e32 v40, s32, v39
	v_readlane_b32 s40, v177, 63
	v_sub_f32_e32 v58, v39, v40
	v_sub_f32_e32 v59, s32, v40
	v_mul_f32_e32 v58, 0x3fb8aa3b, v58
	v_mul_f32_e32 v59, 0x3fb8aa3b, v59
	v_exp_f32_e32 v60, v58
	v_exp_f32_e32 v62, v59
	v_cvt_pk_bf16_f32 v122, v118, v119
	global_store_dword v36, v122, s[6:7]
	s_add_u32 s6, s6, 0x20000
	s_addc_u32 s7, s7, 0
	v_lshlrev_b32_e32 v108, 16, v156
	v_and_b32_e32 v109, 0xffff0000, v156
	v_pk_mul_f32 v[108:109], v[62:63], v[108:109] op_sel_hi:[0,1]
	v_pk_fma_f32 v[118:119], v[118:119], v[60:61], v[108:109] op_sel_hi:[1,0,1]
	v_add_f32_e32 v39, s34, v40
	v_max_f32_e32 v38, s40, v39
	v_sub_f32_e32 v58, v39, v38
	v_sub_f32_e32 v59, s40, v38
	v_mul_f32_e32 v58, 0x3fb8aa3b, v58
	v_mul_f32_e32 v59, 0x3fb8aa3b, v59
	v_exp_f32_e32 v60, v58
	v_exp_f32_e32 v62, v59
	v_cvt_pk_bf16_f32 v122, v118, v119
	global_store_dword v36, v122, s[6:7]
	s_add_u32 s6, s6, 0x20000
	s_addc_u32 s7, s7, 0
	v_lshlrev_b32_e32 v108, 16, v157
	v_and_b32_e32 v109, 0xffff0000, v157
	v_pk_mul_f32 v[108:109], v[62:63], v[108:109] op_sel_hi:[0,1]
	v_pk_fma_f32 v[118:119], v[118:119], v[60:61], v[108:109] op_sel_hi:[1,0,1]
	s_branch .Lscan_fin
;     __device__ __forceinline__ bf16* DC() const { return (bf16*)(ws + WS_XN); }
;     __device__ __forceinline__ float* DN() const { return (float*)(ws + WS_DN); }
; __device__ __forceinline__ void phase_scan(Ctx& C, int l, const bool st, LAS unsigned char* lds) {
;     ...
;         const bool hn = p < 128;
;         unsigned* base = (unsigned*)C.DC() + p;
;         float* dnb = C.DN() + (hn ? p : 0);
;         float c0 = 0.f, c1 = 0.f, m = 0.f, nn = 0.f;
;         unsigned buf[16], nb[16]; float fb[16], fnb[16];
; #pragma unroll
;         for (int j = 0; j < 16; ++j) { buf[j] = base[(size_t)((b * NPC + j) * 4 + h) * 8192]; fb[j] = hn ? dnb[(size_t)((b * NPC + j) * 4 + h) * 128] : 0.f; }
;         for (int cg0 = 0; cg0 < NPC; cg0 += 16) {
;             if (cg0 + 16 < NPC) {
; #pragma unroll
;                 for (int j = 0; j < 16; ++j) { nb[j] = base[(size_t)((b * NPC + cg0 + 16 + j) * 4 + h) * 8192]; fnb[j] = hn ? dnb[(size_t)((b * NPC + cg0 + 16 + j) * 4 + h) * 128] : 0.f; }
.Lscan_hn:
	global_load_dword v126, v36, s[4:5]
	s_add_u32 s4, s4, 0x20000
	s_addc_u32 s5, s5, 0
	global_load_dword v127, v36, s[4:5]
	s_add_u32 s4, s4, 0x20000
	s_addc_u32 s5, s5, 0
	global_load_dword v128, v36, s[4:5]
	s_add_u32 s4, s4, 0x20000
	s_addc_u32 s5, s5, 0
	global_load_dword v129, v36, s[4:5]
	s_add_u32 s4, s4, 0x20000
	s_addc_u32 s5, s5, 0
	global_load_dword v130, v36, s[4:5]
	s_add_u32 s4, s4, 0x20000
	s_addc_u32 s5, s5, 0
	global_load_dword v131, v36, s[4:5]
	s_add_u32 s4, s4, 0x20000
	s_addc_u32 s5, s5, 0
	global_load_dword v132, v36, s[4:5]
	s_add_u32 s4, s4, 0x20000
	s_addc_u32 s5, s5, 0
	global_load_dword v133, v36, s[4:5]
	s_add_u32 s4, s4, 0x20000
	s_addc_u32 s5, s5, 0
	global_load_dword v134, v36, s[4:5]
	s_add_u32 s4, s4, 0x20000
	s_addc_u32 s5, s5, 0
	global_load_dword v135, v36, s[4:5]
	s_add_u32 s4, s4, 0x20000
	s_addc_u32 s5, s5, 0
	global_load_dword v136, v36, s[4:5]
	s_add_u32 s4, s4, 0x20000
	s_addc_u32 s5, s5, 0
	global_load_dword v137, v36, s[4:5]
	s_add_u32 s4, s4, 0x20000
	s_addc_u32 s5, s5, 0
	global_load_dword v138, v36, s[4:5]
	s_add_u32 s4, s4, 0x20000
	s_addc_u32 s5, s5, 0
	global_load_dword v139, v36, s[4:5]
	s_add_u32 s4, s4, 0x20000
	s_addc_u32 s5, s5, 0
	global_load_dword v140, v36, s[4:5]
	s_add_u32 s4, s4, 0x20000
	s_addc_u32 s5, s5, 0
	global_load_dword v141, v36, s[4:5]
	s_add_u32 s4, s4, 0x20000
	s_addc_u32 s5, s5, 0
	global_load_dword v16, v36, s[8:9]
	s_add_u32 s8, s8, 0x800
	s_addc_u32 s9, s9, 0
	global_load_dword v17, v36, s[8:9]
	s_add_u32 s8, s8, 0x800
	s_addc_u32 s9, s9, 0
	global_load_dword v18, v36, s[8:9]
	s_add_u32 s8, s8, 0x800
	s_addc_u32 s9, s9, 0
	global_load_dword v19, v36, s[8:9]
	s_add_u32 s8, s8, 0x800
	s_addc_u32 s9, s9, 0
	global_load_dword v20, v36, s[8:9]
	s_add_u32 s8, s8, 0x800
	s_addc_u32 s9, s9, 0
	global_load_dword v21, v36, s[8:9]
	s_add_u32 s8, s8, 0x800
	s_addc_u32 s9, s9, 0
	global_load_dword v22, v36, s[8:9]
	s_add_u32 s8, s8, 0x800
	s_addc_u32 s9, s9, 0
	global_load_dword v23, v36, s[8:9]
	s_add_u32 s8, s8, 0x800
	s_addc_u32 s9, s9, 0
	global_load_dword v24, v36, s[8:9]
	s_add_u32 s8, s8, 0x800
	s_addc_u32 s9, s9, 0
	global_load_dword v25, v36, s[8:9]
	s_add_u32 s8, s8, 0x800
	s_addc_u32 s9, s9, 0
	global_load_dword v26, v36, s[8:9]
	s_add_u32 s8, s8, 0x800
	s_addc_u32 s9, s9, 0
	global_load_dword v27, v36, s[8:9]
	s_add_u32 s8, s8, 0x800
	s_addc_u32 s9, s9, 0
	global_load_dword v28, v36, s[8:9]
	s_add_u32 s8, s8, 0x800
	s_addc_u32 s9, s9, 0
	global_load_dword v29, v36, s[8:9]
	s_add_u32 s8, s8, 0x800
	s_addc_u32 s9, s9, 0
	global_load_dword v30, v36, s[8:9]
	s_add_u32 s8, s8, 0x800
	s_addc_u32 s9, s9, 0
	global_load_dword v31, v36, s[8:9]
	s_add_u32 s8, s8, 0x800
	s_addc_u32 s9, s9, 0
.Lscan_hn_b0:
	s_waitcnt vmcnt(0)
	global_load_dword v142, v36, s[4:5]
	s_add_u32 s4, s4, 0x20000
	s_addc_u32 s5, s5, 0
	global_load_dword v143, v36, s[4:5]
	s_add_u32 s4, s4, 0x20000
	s_addc_u32 s5, s5, 0
	global_load_dword v144, v36, s[4:5]
	s_add_u32 s4, s4, 0x20000
	s_addc_u32 s5, s5, 0
	global_load_dword v145, v36, s[4:5]
	s_add_u32 s4, s4, 0x20000
	s_addc_u32 s5, s5, 0
	global_load_dword v146, v36, s[4:5]
	s_add_u32 s4, s4, 0x20000
	s_addc_u32 s5, s5, 0
	global_load_dword v147, v36, s[4:5]
	s_add_u32 s4, s4, 0x20000
	s_addc_u32 s5, s5, 0
	global_load_dword v148, v36, s[4:5]
	s_add_u32 s4, s4, 0x20000
	s_addc_u32 s5, s5, 0
	global_load_dword v149, v36, s[4:5]
	s_add_u32 s4, s4, 0x20000
	s_addc_u32 s5, s5, 0
	global_load_dword v150, v36, s[4:5]
	s_add_u32 s4, s4, 0x20000
	s_addc_u32 s5, s5, 0
	global_load_dword v151, v36, s[4:5]
	s_add_u32 s4, s4, 0x20000
	s_addc_u32 s5, s5, 0
	global_load_dword v152, v36, s[4:5]
	s_add_u32 s4, s4, 0x20000
	s_addc_u32 s5, s5, 0
	global_load_dword v153, v36, s[4:5]
	s_add_u32 s4, s4, 0x20000
	s_addc_u32 s5, s5, 0
	global_load_dword v154, v36, s[4:5]
	s_add_u32 s4, s4, 0x20000
	s_addc_u32 s5, s5, 0
	global_load_dword v155, v36, s[4:5]
	s_add_u32 s4, s4, 0x20000
	s_addc_u32 s5, s5, 0
	global_load_dword v156, v36, s[4:5]
	s_add_u32 s4, s4, 0x20000
	s_addc_u32 s5, s5, 0
	global_load_dword v157, v36, s[4:5]
	s_add_u32 s4, s4, 0x20000
	s_addc_u32 s5, s5, 0
	global_load_dword v42, v36, s[8:9]
	s_add_u32 s8, s8, 0x800
	s_addc_u32 s9, s9, 0
	global_load_dword v43, v36, s[8:9]
	s_add_u32 s8, s8, 0x800
	s_addc_u32 s9, s9, 0
	global_load_dword v44, v36, s[8:9]
	s_add_u32 s8, s8, 0x800
	s_addc_u32 s9, s9, 0
	global_load_dword v45, v36, s[8:9]
	s_add_u32 s8, s8, 0x800
	s_addc_u32 s9, s9, 0
	global_load_dword v46, v36, s[8:9]
	s_add_u32 s8, s8, 0x800
	s_addc_u32 s9, s9, 0
	global_load_dword v47, v36, s[8:9]
	s_add_u32 s8, s8, 0x800
	s_addc_u32 s9, s9, 0
	global_load_dword v48, v36, s[8:9]
	s_add_u32 s8, s8, 0x800
	s_addc_u32 s9, s9, 0
	global_load_dword v49, v36, s[8:9]
	s_add_u32 s8, s8, 0x800
	s_addc_u32 s9, s9, 0
	global_load_dword v50, v36, s[8:9]
	s_add_u32 s8, s8, 0x800
	s_addc_u32 s9, s9, 0
	global_load_dword v51, v36, s[8:9]
	s_add_u32 s8, s8, 0x800
	s_addc_u32 s9, s9, 0
	global_load_dword v52, v36, s[8:9]
	s_add_u32 s8, s8, 0x800
	s_addc_u32 s9, s9, 0
	global_load_dword v53, v36, s[8:9]
	s_add_u32 s8, s8, 0x800
	s_addc_u32 s9, s9, 0
	global_load_dword v54, v36, s[8:9]
	s_add_u32 s8, s8, 0x800
	s_addc_u32 s9, s9, 0
	global_load_dword v55, v36, s[8:9]
	s_add_u32 s8, s8, 0x800
	s_addc_u32 s9, s9, 0
	global_load_dword v56, v36, s[8:9]
	s_add_u32 s8, s8, 0x800
	s_addc_u32 s9, s9, 0
	global_load_dword v57, v36, s[8:9]
	s_add_u32 s8, s8, 0x800
	s_addc_u32 s9, s9, 0
	v_readlane_b32 s22, v174, 0
	v_readlane_b32 s32, v176, 0
	s_nop 1
	v_readfirstlane_b32 s54, v38
	v_add_f32_e32 v39, s22, v38
	v_readlane_b32 s34, v174, 1
	v_max_f32_e32 v40, s32, v39
; __device__ __forceinline__ unsigned pk2(float lo, float hi) { f32x2_t v = {lo, hi}; bf16x2_t b = __builtin_convertvector(v, bf16x2_t); return __builtin_bit_cast(unsigned, b); }
; __device__ __forceinline__ float bflo(unsigned w) { return __uint_as_float(w << 16); }
; __device__ __forceinline__ float bfhi(unsigned w) { return __uint_as_float(w & 0xffff0000u); }
; __device__ __forceinline__ float fexp(float x) { return __builtin_amdgcn_exp2f(x * LOG2E); }
;     __device__ __forceinline__ float* MBM() const { return (float*)(ws + WS_MB); }
;     __device__ __forceinline__ float* MBB() const { return (float*)(ws + WS_MB) + (NSLOT_P + NSLOT_S); }
;     __device__ __forceinline__ float* MST() const { return (float*)(ws + WS_MB) + 2 * (NSLOT_P + NSLOT_S); }
; __device__ __forceinline__ void phase_scan(Ctx& C, int l, const bool st, LAS unsigned char* lds) {
;     ...
;             for (int j = 0; j < 16; ++j) { const int slot = (b * NPC + cg0 + j) * 4 + h;
;                 const float Bc = C.MBB()[slot], Mc = C.MBM()[slot];
;                 const float mn = fmaxf(Bc + m, Mc), g = fexp(Bc + m - mn), f = fexp(Mc - mn);
;                 if (st) { base[(size_t)slot * 8192] = pk2(c0, c1); if (hn) { dnb[(size_t)slot * 128] = nn; if (p == 0) C.MST()[slot] = m; } }
;                 c0 = g * c0 + f * bflo(buf[j]); c1 = g * c1 + f * bfhi(buf[j]); nn = g * nn + f * fb[j]; m = mn; }
	v_readlane_b32 s40, v176, 1
	v_sub_f32_e32 v58, v39, v40
	v_sub_f32_e32 v59, s32, v40
	v_mul_f32_e32 v58, 0x3fb8aa3b, v58
	v_mul_f32_e32 v59, 0x3fb8aa3b, v59
	v_exp_f32_e32 v60, v58
	v_exp_f32_e32 v62, v59
	v_cvt_pk_bf16_f32 v122, v118, v119
	v_writelane_b32 v178, s54, 0
	global_store_dword v36, v122, s[6:7]
	s_add_u32 s6, s6, 0x20000
	s_addc_u32 s7, s7, 0
	global_store_dword v36, v120, s[10:11]
	s_add_u32 s10, s10, 0x800
	s_addc_u32 s11, s11, 0
	v_lshlrev_b32_e32 v108, 16, v126
	v_and_b32_e32 v109, 0xffff0000, v126
	v_pk_mul_f32 v[108:109], v[62:63], v[108:109] op_sel_hi:[0,1]
	v_mul_f32_e32 v121, v16, v62
	v_pk_fma_f32 v[118:119], v[118:119], v[60:61], v[108:109] op_sel_hi:[1,0,1]
	v_fma_f32 v120, v120, v60, v121
	v_readfirstlane_b32 s54, v40
	v_add_f32_e32 v39, s34, v40
	v_readlane_b32 s22, v174, 2
	v_max_f32_e32 v38, s40, v39
	v_readlane_b32 s32, v176, 2
	v_sub_f32_e32 v58, v39, v38
	v_sub_f32_e32 v59, s40, v38
	v_mul_f32_e32 v58, 0x3fb8aa3b, v58
	v_mul_f32_e32 v59, 0x3fb8aa3b, v59
	v_exp_f32_e32 v60, v58
	v_exp_f32_e32 v62, v59
	v_cvt_pk_bf16_f32 v122, v118, v119
	v_writelane_b32 v178, s54, 1
	global_store_dword v36, v122, s[6:7]
	s_add_u32 s6, s6, 0x20000
	s_addc_u32 s7, s7, 0
	global_store_dword v36, v120, s[10:11]
	s_add_u32 s10, s10, 0x800
	s_addc_u32 s11, s11, 0
	v_lshlrev_b32_e32 v108, 16, v127
	v_and_b32_e32 v109, 0xffff0000, v127
	v_pk_mul_f32 v[108:109], v[62:63], v[108:109] op_sel_hi:[0,1]
	v_mul_f32_e32 v121, v17, v62
	v_pk_fma_f32 v[118:119], v[118:119], v[60:61], v[108:109] op_sel_hi:[1,0,1]
	v_fma_f32 v120, v120, v60, v121
	v_readfirstlane_b32 s54, v38
	v_add_f32_e32 v39, s22, v38
	v_readlane_b32 s34, v174, 3
	v_max_f32_e32 v40, s32, v39
	v_readlane_b32 s40, v176, 3
	v_sub_f32_e32 v58, v39, v40
	v_sub_f32_e32 v59, s32, v40
	v_mul_f32_e32 v58, 0x3fb8aa3b, v58
	v_mul_f32_e32 v59, 0x3fb8aa3b, v59
	v_exp_f32_e32 v60, v58
	v_exp_f32_e32 v62, v59
	v_cvt_pk_bf16_f32 v122, v118, v119
	v_writelane_b32 v178, s54, 2
	global_store_dword v36, v122, s[6:7]
	s_add_u32 s6, s6, 0x20000
	s_addc_u32 s7, s7, 0
	global_store_dword v36, v120, s[10:11]
	s_add_u32 s10, s10, 0x800
	s_addc_u32 s11, s11, 0
	v_lshlrev_b32_e32 v108, 16, v128
	v_and_b32_e32 v109, 0xffff0000, v128
	v_pk_mul_f32 v[108:109], v[62:63], v[108:109] op_sel_hi:[0,1]
	v_mul_f32_e32 v121, v18, v62
	v_pk_fma_f32 v[118:119], v[118:119], v[60:61], v[108:109] op_sel_hi:[1,0,1]
	v_fma_f32 v120, v120, v60, v121
	v_readfirstlane_b32 s54, v40
	v_add_f32_e32 v39, s34, v40
	v_readlane_b32 s22, v174, 4
	v_max_f32_e32 v38, s40, v39
	v_readlane_b32 s32, v176, 4
	v_sub_f32_e32 v58, v39, v38
	v_sub_f32_e32 v59, s40, v38
	v_mul_f32_e32 v58, 0x3fb8aa3b, v58
	v_mul_f32_e32 v59, 0x3fb8aa3b, v59
	v_exp_f32_e32 v60, v58
	v_exp_f32_e32 v62, v59
	v_cvt_pk_bf16_f32 v122, v118, v119
	v_writelane_b32 v178, s54, 3
	global_store_dword v36, v122, s[6:7]
	s_add_u32 s6, s6, 0x20000
	s_addc_u32 s7, s7, 0
	global_store_dword v36, v120, s[10:11]
	s_add_u32 s10, s10, 0x800
	s_addc_u32 s11, s11, 0
	v_lshlrev_b32_e32 v108, 16, v129
	v_and_b32_e32 v109, 0xffff0000, v129
	v_pk_mul_f32 v[108:109], v[62:63], v[108:109] op_sel_hi:[0,1]
	v_mul_f32_e32 v121, v19, v62
	v_pk_fma_f32 v[118:119], v[118:119], v[60:61], v[108:109] op_sel_hi:[1,0,1]
	v_fma_f32 v120, v120, v60, v121
	v_readfirstlane_b32 s54, v38
	v_add_f32_e32 v39, s22, v38
	v_readlane_b32 s34, v174, 5
	v_max_f32_e32 v40, s32, v39
	v_readlane_b32 s40, v176, 5
	v_sub_f32_e32 v58, v39, v40
	v_sub_f32_e32 v59, s32, v40
	v_mul_f32_e32 v58, 0x3fb8aa3b, v58
	v_mul_f32_e32 v59, 0x3fb8aa3b, v59
	v_exp_f32_e32 v60, v58
	v_exp_f32_e32 v62, v59
	v_cvt_pk_bf16_f32 v122, v118, v119
	v_writelane_b32 v178, s54, 4
	global_store_dword v36, v122, s[6:7]
	s_add_u32 s6, s6, 0x20000
	s_addc_u32 s7, s7, 0
	global_store_dword v36, v120, s[10:11]
	s_add_u32 s10, s10, 0x800
	s_addc_u32 s11, s11, 0
	v_lshlrev_b32_e32 v108, 16, v130
	v_and_b32_e32 v109, 0xffff0000, v130
	v_pk_mul_f32 v[108:109], v[62:63], v[108:109] op_sel_hi:[0,1]
	v_mul_f32_e32 v121, v20, v62
	v_pk_fma_f32 v[118:119], v[118:119], v[60:61], v[108:109] op_sel_hi:[1,0,1]
	v_fma_f32 v120, v120, v60, v121
	v_readfirstlane_b32 s54, v40
	v_add_f32_e32 v39, s34, v40
	v_readlane_b32 s22, v174, 6
	v_max_f32_e32 v38, s40, v39
	v_readlane_b32 s32, v176, 6
	v_sub_f32_e32 v58, v39, v38
	v_sub_f32_e32 v59, s40, v38
	v_mul_f32_e32 v58, 0x3fb8aa3b, v58
	v_mul_f32_e32 v59, 0x3fb8aa3b, v59
	v_exp_f32_e32 v60, v58
	v_exp_f32_e32 v62, v59
	v_cvt_pk_bf16_f32 v122, v118, v119
	v_writelane_b32 v178, s54, 5
	global_store_dword v36, v122, s[6:7]
	s_add_u32 s6, s6, 0x20000
	s_addc_u32 s7, s7, 0
	global_store_dword v36, v120, s[10:11]
	s_add_u32 s10, s10, 0x800
	s_addc_u32 s11, s11, 0
	v_lshlrev_b32_e32 v108, 16, v131
	v_and_b32_e32 v109, 0xffff0000, v131
	v_pk_mul_f32 v[108:109], v[62:63], v[108:109] op_sel_hi:[0,1]
	v_mul_f32_e32 v121, v21, v62
	v_pk_fma_f32 v[118:119], v[118:119], v[60:61], v[108:109] op_sel_hi:[1,0,1]
	v_fma_f32 v120, v120, v60, v121
	v_readfirstlane_b32 s54, v38
	v_add_f32_e32 v39, s22, v38
	v_readlane_b32 s34, v174, 7
	v_max_f32_e32 v40, s32, v39
	v_readlane_b32 s40, v176, 7
	v_sub_f32_e32 v58, v39, v40
	v_sub_f32_e32 v59, s32, v40
	v_mul_f32_e32 v58, 0x3fb8aa3b, v58
	v_mul_f32_e32 v59, 0x3fb8aa3b, v59
	v_exp_f32_e32 v60, v58
	v_exp_f32_e32 v62, v59
	v_cvt_pk_bf16_f32 v122, v118, v119
	v_writelane_b32 v178, s54, 6
	global_store_dword v36, v122, s[6:7]
	s_add_u32 s6, s6, 0x20000
	s_addc_u32 s7, s7, 0
	global_store_dword v36, v120, s[10:11]
	s_add_u32 s10, s10, 0x800
	s_addc_u32 s11, s11, 0
	v_lshlrev_b32_e32 v108, 16, v132
	v_and_b32_e32 v109, 0xffff0000, v132
	v_pk_mul_f32 v[108:109], v[62:63], v[108:109] op_sel_hi:[0,1]
; __device__ __forceinline__ unsigned pk2(float lo, float hi) { f32x2_t v = {lo, hi}; bf16x2_t b = __builtin_convertvector(v, bf16x2_t); return __builtin_bit_cast(unsigned, b); }
; __device__ __forceinline__ float bflo(unsigned w) { return __uint_as_float(w << 16); }
; __device__ __forceinline__ float bfhi(unsigned w) { return __uint_as_float(w & 0xffff0000u); }
; __device__ __forceinline__ float fexp(float x) { return __builtin_amdgcn_exp2f(x * LOG2E); }
;     __device__ __forceinline__ float* MBM() const { return (float*)(ws + WS_MB); }
;     __device__ __forceinline__ float* MBB() const { return (float*)(ws + WS_MB) + (NSLOT_P + NSLOT_S); }
;     __device__ __forceinline__ float* MST() const { return (float*)(ws + WS_MB) + 2 * (NSLOT_P + NSLOT_S); }
; __device__ __forceinline__ void phase_scan(Ctx& C, int l, const bool st, LAS unsigned char* lds) {
;     ...
;             for (int j = 0; j < 16; ++j) { const int slot = (b * NPC + cg0 + j) * 4 + h;
;                 const float Bc = C.MBB()[slot], Mc = C.MBM()[slot];
;                 const float mn = fmaxf(Bc + m, Mc), g = fexp(Bc + m - mn), f = fexp(Mc - mn);
;                 if (st) { base[(size_t)slot * 8192] = pk2(c0, c1); if (hn) { dnb[(size_t)slot * 128] = nn; if (p == 0) C.MST()[slot] = m; } }
;                 c0 = g * c0 + f * bflo(buf[j]); c1 = g * c1 + f * bfhi(buf[j]); nn = g * nn + f * fb[j]; m = mn; }
	v_mul_f32_e32 v121, v22, v62
	v_pk_fma_f32 v[118:119], v[118:119], v[60:61], v[108:109] op_sel_hi:[1,0,1]
	v_fma_f32 v120, v120, v60, v121
	v_readfirstlane_b32 s54, v40
	v_add_f32_e32 v39, s34, v40
	v_readlane_b32 s22, v174, 8
	v_max_f32_e32 v38, s40, v39
	v_readlane_b32 s32, v176, 8
	v_sub_f32_e32 v58, v39, v38
	v_sub_f32_e32 v59, s40, v38
	v_mul_f32_e32 v58, 0x3fb8aa3b, v58
	v_mul_f32_e32 v59, 0x3fb8aa3b, v59
	v_exp_f32_e32 v60, v58
	v_exp_f32_e32 v62, v59
	v_cvt_pk_bf16_f32 v122, v118, v119
	v_writelane_b32 v178, s54, 7
	global_store_dword v36, v122, s[6:7]
	s_add_u32 s6, s6, 0x20000
	s_addc_u32 s7, s7, 0
	global_store_dword v36, v120, s[10:11]
	s_add_u32 s10, s10, 0x800
	s_addc_u32 s11, s11, 0
	v_lshlrev_b32_e32 v108, 16, v133
	v_and_b32_e32 v109, 0xffff0000, v133
	v_pk_mul_f32 v[108:109], v[62:63], v[108:109] op_sel_hi:[0,1]
	v_mul_f32_e32 v121, v23, v62
	v_pk_fma_f32 v[118:119], v[118:119], v[60:61], v[108:109] op_sel_hi:[1,0,1]
	v_fma_f32 v120, v120, v60, v121
	v_readfirstlane_b32 s54, v38
	v_add_f32_e32 v39, s22, v38
	v_readlane_b32 s34, v174, 9
	v_max_f32_e32 v40, s32, v39
	v_readlane_b32 s40, v176, 9
	v_sub_f32_e32 v58, v39, v40
	v_sub_f32_e32 v59, s32, v40
	v_mul_f32_e32 v58, 0x3fb8aa3b, v58
	v_mul_f32_e32 v59, 0x3fb8aa3b, v59
	v_exp_f32_e32 v60, v58
	v_exp_f32_e32 v62, v59
	v_cvt_pk_bf16_f32 v122, v118, v119
	v_writelane_b32 v178, s54, 8
	global_store_dword v36, v122, s[6:7]
	s_add_u32 s6, s6, 0x20000
	s_addc_u32 s7, s7, 0
	global_store_dword v36, v120, s[10:11]
	s_add_u32 s10, s10, 0x800
	s_addc_u32 s11, s11, 0
	v_lshlrev_b32_e32 v108, 16, v134
	v_and_b32_e32 v109, 0xffff0000, v134
	v_pk_mul_f32 v[108:109], v[62:63], v[108:109] op_sel_hi:[0,1]
	v_mul_f32_e32 v121, v24, v62
	v_pk_fma_f32 v[118:119], v[118:119], v[60:61], v[108:109] op_sel_hi:[1,0,1]
	v_fma_f32 v120, v120, v60, v121
	v_readfirstlane_b32 s54, v40
	v_add_f32_e32 v39, s34, v40
	v_readlane_b32 s22, v174, 10
	v_max_f32_e32 v38, s40, v39
	v_readlane_b32 s32, v176, 10
	v_sub_f32_e32 v58, v39, v38
	v_sub_f32_e32 v59, s40, v38
	v_mul_f32_e32 v58, 0x3fb8aa3b, v58
	v_mul_f32_e32 v59, 0x3fb8aa3b, v59
	v_exp_f32_e32 v60, v58
	v_exp_f32_e32 v62, v59
	v_cvt_pk_bf16_f32 v122, v118, v119
	v_writelane_b32 v178, s54, 9
	global_store_dword v36, v122, s[6:7]
	s_add_u32 s6, s6, 0x20000
	s_addc_u32 s7, s7, 0
	global_store_dword v36, v120, s[10:11]
	s_add_u32 s10, s10, 0x800
	s_addc_u32 s11, s11, 0
	v_lshlrev_b32_e32 v108, 16, v135
	v_and_b32_e32 v109, 0xffff0000, v135
	v_pk_mul_f32 v[108:109], v[62:63], v[108:109] op_sel_hi:[0,1]
	v_mul_f32_e32 v121, v25, v62
	v_pk_fma_f32 v[118:119], v[118:119], v[60:61], v[108:109] op_sel_hi:[1,0,1]
	v_fma_f32 v120, v120, v60, v121
	v_readfirstlane_b32 s54, v38
	v_add_f32_e32 v39, s22, v38
	v_readlane_b32 s34, v174, 11
	v_max_f32_e32 v40, s32, v39
	v_readlane_b32 s40, v176, 11
	v_sub_f32_e32 v58, v39, v40
	v_sub_f32_e32 v59, s32, v40
	v_mul_f32_e32 v58, 0x3fb8aa3b, v58
	v_mul_f32_e32 v59, 0x3fb8aa3b, v59
	v_exp_f32_e32 v60, v58
	v_exp_f32_e32 v62, v59
	v_cvt_pk_bf16_f32 v122, v118, v119
	v_writelane_b32 v178, s54, 10
	global_store_dword v36, v122, s[6:7]
	s_add_u32 s6, s6, 0x20000
	s_addc_u32 s7, s7, 0
	global_store_dword v36, v120, s[10:11]
	s_add_u32 s10, s10, 0x800
	s_addc_u32 s11, s11, 0
	v_lshlrev_b32_e32 v108, 16, v136
	v_and_b32_e32 v109, 0xffff0000, v136
	v_pk_mul_f32 v[108:109], v[62:63], v[108:109] op_sel_hi:[0,1]
	v_mul_f32_e32 v121, v26, v62
	v_pk_fma_f32 v[118:119], v[118:119], v[60:61], v[108:109] op_sel_hi:[1,0,1]
	v_fma_f32 v120, v120, v60, v121
	v_readfirstlane_b32 s54, v40
	v_add_f32_e32 v39, s34, v40
	v_readlane_b32 s22, v174, 12
	v_max_f32_e32 v38, s40, v39
	v_readlane_b32 s32, v176, 12
	v_sub_f32_e32 v58, v39, v38
	v_sub_f32_e32 v59, s40, v38
	v_mul_f32_e32 v58, 0x3fb8aa3b, v58
	v_mul_f32_e32 v59, 0x3fb8aa3b, v59
	v_exp_f32_e32 v60, v58
	v_exp_f32_e32 v62, v59
	v_cvt_pk_bf16_f32 v122, v118, v119
	v_writelane_b32 v178, s54, 11
	global_store_dword v36, v122, s[6:7]
	s_add_u32 s6, s6, 0x20000
	s_addc_u32 s7, s7, 0
	global_store_dword v36, v120, s[10:11]
	s_add_u32 s10, s10, 0x800
	s_addc_u32 s11, s11, 0
	v_lshlrev_b32_e32 v108, 16, v137
	v_and_b32_e32 v109, 0xffff0000, v137
	v_pk_mul_f32 v[108:109], v[62:63], v[108:109] op_sel_hi:[0,1]
	v_mul_f32_e32 v121, v27, v62
	v_pk_fma_f32 v[118:119], v[118:119], v[60:61], v[108:109] op_sel_hi:[1,0,1]
	v_fma_f32 v120, v120, v60, v121
	v_readfirstlane_b32 s54, v38
	v_add_f32_e32 v39, s22, v38
	v_readlane_b32 s34, v174, 13
	v_max_f32_e32 v40, s32, v39
	v_readlane_b32 s40, v176, 13
	v_sub_f32_e32 v58, v39, v40
	v_sub_f32_e32 v59, s32, v40
	v_mul_f32_e32 v58, 0x3fb8aa3b, v58
	v_mul_f32_e32 v59, 0x3fb8aa3b, v59
	v_exp_f32_e32 v60, v58
	v_exp_f32_e32 v62, v59
	v_cvt_pk_bf16_f32 v122, v118, v119
	v_writelane_b32 v178, s54, 12
	global_store_dword v36, v122, s[6:7]
	s_add_u32 s6, s6, 0x20000
	s_addc_u32 s7, s7, 0
	global_store_dword v36, v120, s[10:11]
	s_add_u32 s10, s10, 0x800
	s_addc_u32 s11, s11, 0
	v_lshlrev_b32_e32 v108, 16, v138
	v_and_b32_e32 v109, 0xffff0000, v138
	v_pk_mul_f32 v[108:109], v[62:63], v[108:109] op_sel_hi:[0,1]
	v_mul_f32_e32 v121, v28, v62
	v_pk_fma_f32 v[118:119], v[118:119], v[60:61], v[108:109] op_sel_hi:[1,0,1]
	v_fma_f32 v120, v120, v60, v121
	v_readfirstlane_b32 s54, v40
	v_add_f32_e32 v39, s34, v40
	v_readlane_b32 s22, v174, 14
	v_max_f32_e32 v38, s40, v39
	v_readlane_b32 s32, v176, 14
	v_sub_f32_e32 v58, v39, v38
	v_sub_f32_e32 v59, s40, v38
	v_mul_f32_e32 v58, 0x3fb8aa3b, v58
	v_mul_f32_e32 v59, 0x3fb8aa3b, v59
	v_exp_f32_e32 v60, v58
	v_exp_f32_e32 v62, v59
	v_cvt_pk_bf16_f32 v122, v118, v119
	v_writelane_b32 v178, s54, 13
	global_store_dword v36, v122, s[6:7]
; __device__ __forceinline__ unsigned pk2(float lo, float hi) { f32x2_t v = {lo, hi}; bf16x2_t b = __builtin_convertvector(v, bf16x2_t); return __builtin_bit_cast(unsigned, b); }
; __device__ __forceinline__ float bflo(unsigned w) { return __uint_as_float(w << 16); }
; __device__ __forceinline__ float bfhi(unsigned w) { return __uint_as_float(w & 0xffff0000u); }
; __device__ __forceinline__ float fexp(float x) { return __builtin_amdgcn_exp2f(x * LOG2E); }
;     __device__ __forceinline__ float* MBM() const { return (float*)(ws + WS_MB); }
;     __device__ __forceinline__ float* MBB() const { return (float*)(ws + WS_MB) + (NSLOT_P + NSLOT_S); }
;     __device__ __forceinline__ float* MST() const { return (float*)(ws + WS_MB) + 2 * (NSLOT_P + NSLOT_S); }
; __device__ __forceinline__ void phase_scan(Ctx& C, int l, const bool st, LAS unsigned char* lds) {
;     ...
;         for (int cg0 = 0; cg0 < NPC; cg0 += 16) {
;             if (cg0 + 16 < NPC) {
; #pragma unroll
;                 for (int j = 0; j < 16; ++j) { nb[j] = base[(size_t)((b * NPC + cg0 + 16 + j) * 4 + h) * 8192]; fnb[j] = hn ? dnb[(size_t)((b * NPC + cg0 + 16 + j) * 4 + h) * 128] : 0.f; }
;             }
; #pragma unroll
;             for (int j = 0; j < 16; ++j) { const int slot = (b * NPC + cg0 + j) * 4 + h;
;                 const float Bc = C.MBB()[slot], Mc = C.MBM()[slot];
;                 const float mn = fmaxf(Bc + m, Mc), g = fexp(Bc + m - mn), f = fexp(Mc - mn);
;                 if (st) { base[(size_t)slot * 8192] = pk2(c0, c1); if (hn) { dnb[(size_t)slot * 128] = nn; if (p == 0) C.MST()[slot] = m; } }
;                 c0 = g * c0 + f * bflo(buf[j]); c1 = g * c1 + f * bfhi(buf[j]); nn = g * nn + f * fb[j]; m = mn; }
	s_add_u32 s6, s6, 0x20000
	s_addc_u32 s7, s7, 0
	global_store_dword v36, v120, s[10:11]
	s_add_u32 s10, s10, 0x800
	s_addc_u32 s11, s11, 0
	v_lshlrev_b32_e32 v108, 16, v139
	v_and_b32_e32 v109, 0xffff0000, v139
	v_pk_mul_f32 v[108:109], v[62:63], v[108:109] op_sel_hi:[0,1]
	v_mul_f32_e32 v121, v29, v62
	v_pk_fma_f32 v[118:119], v[118:119], v[60:61], v[108:109] op_sel_hi:[1,0,1]
	v_fma_f32 v120, v120, v60, v121
	v_readfirstlane_b32 s54, v38
	v_add_f32_e32 v39, s22, v38
	v_readlane_b32 s34, v174, 15
	v_max_f32_e32 v40, s32, v39
	v_readlane_b32 s40, v176, 15
	v_sub_f32_e32 v58, v39, v40
	v_sub_f32_e32 v59, s32, v40
	v_mul_f32_e32 v58, 0x3fb8aa3b, v58
	v_mul_f32_e32 v59, 0x3fb8aa3b, v59
	v_exp_f32_e32 v60, v58
	v_exp_f32_e32 v62, v59
	v_cvt_pk_bf16_f32 v122, v118, v119
	v_writelane_b32 v178, s54, 14
	global_store_dword v36, v122, s[6:7]
	s_add_u32 s6, s6, 0x20000
	s_addc_u32 s7, s7, 0
	global_store_dword v36, v120, s[10:11]
	s_add_u32 s10, s10, 0x800
	s_addc_u32 s11, s11, 0
	v_lshlrev_b32_e32 v108, 16, v140
	v_and_b32_e32 v109, 0xffff0000, v140
	v_pk_mul_f32 v[108:109], v[62:63], v[108:109] op_sel_hi:[0,1]
	v_mul_f32_e32 v121, v30, v62
	v_pk_fma_f32 v[118:119], v[118:119], v[60:61], v[108:109] op_sel_hi:[1,0,1]
	v_fma_f32 v120, v120, v60, v121
	v_readfirstlane_b32 s54, v40
	v_add_f32_e32 v39, s34, v40
	v_readlane_b32 s22, v174, 16
	v_max_f32_e32 v38, s40, v39
	v_readlane_b32 s32, v176, 16
	v_sub_f32_e32 v58, v39, v38
	v_sub_f32_e32 v59, s40, v38
	v_mul_f32_e32 v58, 0x3fb8aa3b, v58
	v_mul_f32_e32 v59, 0x3fb8aa3b, v59
	v_exp_f32_e32 v60, v58
	v_exp_f32_e32 v62, v59
	v_cvt_pk_bf16_f32 v122, v118, v119
	v_writelane_b32 v178, s54, 15
	global_store_dword v36, v122, s[6:7]
	s_add_u32 s6, s6, 0x20000
	s_addc_u32 s7, s7, 0
	global_store_dword v36, v120, s[10:11]
	s_add_u32 s10, s10, 0x800
	s_addc_u32 s11, s11, 0
	v_lshlrev_b32_e32 v108, 16, v141
	v_and_b32_e32 v109, 0xffff0000, v141
	v_pk_mul_f32 v[108:109], v[62:63], v[108:109] op_sel_hi:[0,1]
	v_mul_f32_e32 v121, v31, v62
	v_pk_fma_f32 v[118:119], v[118:119], v[60:61], v[108:109] op_sel_hi:[1,0,1]
	v_fma_f32 v120, v120, v60, v121
.Lscan_hn_b1:
	s_waitcnt vmcnt(32)
	global_load_dword v158, v36, s[4:5]
	s_add_u32 s4, s4, 0x20000
	s_addc_u32 s5, s5, 0
	global_load_dword v159, v36, s[4:5]
	s_add_u32 s4, s4, 0x20000
	s_addc_u32 s5, s5, 0
	global_load_dword v160, v36, s[4:5]
	s_add_u32 s4, s4, 0x20000
	s_addc_u32 s5, s5, 0
	global_load_dword v161, v36, s[4:5]
	s_add_u32 s4, s4, 0x20000
	s_addc_u32 s5, s5, 0
	global_load_dword v162, v36, s[4:5]
	s_add_u32 s4, s4, 0x20000
	s_addc_u32 s5, s5, 0
	global_load_dword v163, v36, s[4:5]
	s_add_u32 s4, s4, 0x20000
	s_addc_u32 s5, s5, 0
	global_load_dword v164, v36, s[4:5]
	s_add_u32 s4, s4, 0x20000
	s_addc_u32 s5, s5, 0
	global_load_dword v165, v36, s[4:5]
	s_add_u32 s4, s4, 0x20000
	s_addc_u32 s5, s5, 0
	global_load_dword v166, v36, s[4:5]
	s_add_u32 s4, s4, 0x20000
	s_addc_u32 s5, s5, 0
	global_load_dword v167, v36, s[4:5]
	s_add_u32 s4, s4, 0x20000
	s_addc_u32 s5, s5, 0
	global_load_dword v168, v36, s[4:5]
	s_add_u32 s4, s4, 0x20000
	s_addc_u32 s5, s5, 0
	global_load_dword v169, v36, s[4:5]
	s_add_u32 s4, s4, 0x20000
	s_addc_u32 s5, s5, 0
	global_load_dword v170, v36, s[4:5]
	s_add_u32 s4, s4, 0x20000
	s_addc_u32 s5, s5, 0
	global_load_dword v171, v36, s[4:5]
	s_add_u32 s4, s4, 0x20000
	s_addc_u32 s5, s5, 0
	global_load_dword v172, v36, s[4:5]
	s_add_u32 s4, s4, 0x20000
	s_addc_u32 s5, s5, 0
	global_load_dword v173, v36, s[4:5]
	s_add_u32 s4, s4, 0x20000
	s_addc_u32 s5, s5, 0
	global_load_dword v92, v36, s[8:9]
	s_add_u32 s8, s8, 0x800
	s_addc_u32 s9, s9, 0
	global_load_dword v93, v36, s[8:9]
	s_add_u32 s8, s8, 0x800
	s_addc_u32 s9, s9, 0
	global_load_dword v94, v36, s[8:9]
	s_add_u32 s8, s8, 0x800
	s_addc_u32 s9, s9, 0
	global_load_dword v95, v36, s[8:9]
	s_add_u32 s8, s8, 0x800
	s_addc_u32 s9, s9, 0
	global_load_dword v96, v36, s[8:9]
	s_add_u32 s8, s8, 0x800
	s_addc_u32 s9, s9, 0
	global_load_dword v97, v36, s[8:9]
	s_add_u32 s8, s8, 0x800
	s_addc_u32 s9, s9, 0
	global_load_dword v98, v36, s[8:9]
	s_add_u32 s8, s8, 0x800
	s_addc_u32 s9, s9, 0
	global_load_dword v99, v36, s[8:9]
	s_add_u32 s8, s8, 0x800
	s_addc_u32 s9, s9, 0
	global_load_dword v100, v36, s[8:9]
	s_add_u32 s8, s8, 0x800
	s_addc_u32 s9, s9, 0
	global_load_dword v101, v36, s[8:9]
	s_add_u32 s8, s8, 0x800
	s_addc_u32 s9, s9, 0
	global_load_dword v102, v36, s[8:9]
	s_add_u32 s8, s8, 0x800
	s_addc_u32 s9, s9, 0
	global_load_dword v103, v36, s[8:9]
	s_add_u32 s8, s8, 0x800
	s_addc_u32 s9, s9, 0
	global_load_dword v104, v36, s[8:9]
	s_add_u32 s8, s8, 0x800
	s_addc_u32 s9, s9, 0
	global_load_dword v105, v36, s[8:9]
	s_add_u32 s8, s8, 0x800
	s_addc_u32 s9, s9, 0
	global_load_dword v106, v36, s[8:9]
	s_add_u32 s8, s8, 0x800
	s_addc_u32 s9, s9, 0
	global_load_dword v107, v36, s[8:9]
	s_add_u32 s8, s8, 0x800
	s_addc_u32 s9, s9, 0
	v_readfirstlane_b32 s54, v38
	v_add_f32_e32 v39, s22, v38
	v_readlane_b32 s34, v174, 17
	v_max_f32_e32 v40, s32, v39
	v_readlane_b32 s40, v176, 17
	v_sub_f32_e32 v58, v39, v40
	v_sub_f32_e32 v59, s32, v40
	v_mul_f32_e32 v58, 0x3fb8aa3b, v58
	v_mul_f32_e32 v59, 0x3fb8aa3b, v59
	v_exp_f32_e32 v60, v58
	v_exp_f32_e32 v62, v59
	v_cvt_pk_bf16_f32 v122, v118, v119
	v_writelane_b32 v178, s54, 16
	global_store_dword v36, v122, s[6:7]
	s_add_u32 s6, s6, 0x20000
	s_addc_u32 s7, s7, 0
	global_store_dword v36, v120, s[10:11]
	s_add_u32 s10, s10, 0x800
	s_addc_u32 s11, s11, 0
	v_lshlrev_b32_e32 v108, 16, v142
	v_and_b32_e32 v109, 0xffff0000, v142
	v_pk_mul_f32 v[108:109], v[62:63], v[108:109] op_sel_hi:[0,1]
	v_mul_f32_e32 v121, v42, v62
	v_pk_fma_f32 v[118:119], v[118:119], v[60:61], v[108:109] op_sel_hi:[1,0,1]
; __device__ __forceinline__ unsigned pk2(float lo, float hi) { f32x2_t v = {lo, hi}; bf16x2_t b = __builtin_convertvector(v, bf16x2_t); return __builtin_bit_cast(unsigned, b); }
; __device__ __forceinline__ float bflo(unsigned w) { return __uint_as_float(w << 16); }
; __device__ __forceinline__ float bfhi(unsigned w) { return __uint_as_float(w & 0xffff0000u); }
; __device__ __forceinline__ float fexp(float x) { return __builtin_amdgcn_exp2f(x * LOG2E); }
;     __device__ __forceinline__ float* MBM() const { return (float*)(ws + WS_MB); }
;     __device__ __forceinline__ float* MBB() const { return (float*)(ws + WS_MB) + (NSLOT_P + NSLOT_S); }
;     __device__ __forceinline__ float* MST() const { return (float*)(ws + WS_MB) + 2 * (NSLOT_P + NSLOT_S); }
; __device__ __forceinline__ void phase_scan(Ctx& C, int l, const bool st, LAS unsigned char* lds) {
;     ...
;         for (int cg0 = 0; cg0 < NPC; cg0 += 16) {
;             if (cg0 + 16 < NPC) {
; #pragma unroll
;                 for (int j = 0; j < 16; ++j) { nb[j] = base[(size_t)((b * NPC + cg0 + 16 + j) * 4 + h) * 8192]; fnb[j] = hn ? dnb[(size_t)((b * NPC + cg0 + 16 + j) * 4 + h) * 128] : 0.f; }
;             }
; #pragma unroll
;             for (int j = 0; j < 16; ++j) { const int slot = (b * NPC + cg0 + j) * 4 + h;
;                 const float Bc = C.MBB()[slot], Mc = C.MBM()[slot];
;                 const float mn = fmaxf(Bc + m, Mc), g = fexp(Bc + m - mn), f = fexp(Mc - mn);
;                 if (st) { base[(size_t)slot * 8192] = pk2(c0, c1); if (hn) { dnb[(size_t)slot * 128] = nn; if (p == 0) C.MST()[slot] = m; } }
;                 c0 = g * c0 + f * bflo(buf[j]); c1 = g * c1 + f * bfhi(buf[j]); nn = g * nn + f * fb[j]; m = mn; }
; #pragma unroll
;             for (int j = 0; j < 16; ++j) { buf[j] = nb[j]; fb[j] = fnb[j]; }
	v_fma_f32 v120, v120, v60, v121
	v_readfirstlane_b32 s54, v40
	v_add_f32_e32 v39, s34, v40
	v_readlane_b32 s22, v174, 18
	v_max_f32_e32 v38, s40, v39
	v_readlane_b32 s32, v176, 18
	v_sub_f32_e32 v58, v39, v38
	v_sub_f32_e32 v59, s40, v38
	v_mul_f32_e32 v58, 0x3fb8aa3b, v58
	v_mul_f32_e32 v59, 0x3fb8aa3b, v59
	v_exp_f32_e32 v60, v58
	v_exp_f32_e32 v62, v59
	v_cvt_pk_bf16_f32 v122, v118, v119
	v_writelane_b32 v178, s54, 17
	global_store_dword v36, v122, s[6:7]
	s_add_u32 s6, s6, 0x20000
	s_addc_u32 s7, s7, 0
	global_store_dword v36, v120, s[10:11]
	s_add_u32 s10, s10, 0x800
	s_addc_u32 s11, s11, 0
	v_lshlrev_b32_e32 v108, 16, v143
	v_and_b32_e32 v109, 0xffff0000, v143
	v_pk_mul_f32 v[108:109], v[62:63], v[108:109] op_sel_hi:[0,1]
	v_mul_f32_e32 v121, v43, v62
	v_pk_fma_f32 v[118:119], v[118:119], v[60:61], v[108:109] op_sel_hi:[1,0,1]
	v_fma_f32 v120, v120, v60, v121
	v_readfirstlane_b32 s54, v38
	v_add_f32_e32 v39, s22, v38
	v_readlane_b32 s34, v174, 19
	v_max_f32_e32 v40, s32, v39
	v_readlane_b32 s40, v176, 19
	v_sub_f32_e32 v58, v39, v40
	v_sub_f32_e32 v59, s32, v40
	v_mul_f32_e32 v58, 0x3fb8aa3b, v58
	v_mul_f32_e32 v59, 0x3fb8aa3b, v59
	v_exp_f32_e32 v60, v58
	v_exp_f32_e32 v62, v59
	v_cvt_pk_bf16_f32 v122, v118, v119
	v_writelane_b32 v178, s54, 18
	global_store_dword v36, v122, s[6:7]
	s_add_u32 s6, s6, 0x20000
	s_addc_u32 s7, s7, 0
	global_store_dword v36, v120, s[10:11]
	s_add_u32 s10, s10, 0x800
	s_addc_u32 s11, s11, 0
	v_lshlrev_b32_e32 v108, 16, v144
	v_and_b32_e32 v109, 0xffff0000, v144
	v_pk_mul_f32 v[108:109], v[62:63], v[108:109] op_sel_hi:[0,1]
	v_mul_f32_e32 v121, v44, v62
	v_pk_fma_f32 v[118:119], v[118:119], v[60:61], v[108:109] op_sel_hi:[1,0,1]
	v_fma_f32 v120, v120, v60, v121
	v_readfirstlane_b32 s54, v40
	v_add_f32_e32 v39, s34, v40
	v_readlane_b32 s22, v174, 20
	v_max_f32_e32 v38, s40, v39
	v_readlane_b32 s32, v176, 20
	v_sub_f32_e32 v58, v39, v38
	v_sub_f32_e32 v59, s40, v38
	v_mul_f32_e32 v58, 0x3fb8aa3b, v58
	v_mul_f32_e32 v59, 0x3fb8aa3b, v59
	v_exp_f32_e32 v60, v58
	v_exp_f32_e32 v62, v59
	v_cvt_pk_bf16_f32 v122, v118, v119
	v_writelane_b32 v178, s54, 19
	global_store_dword v36, v122, s[6:7]
	s_add_u32 s6, s6, 0x20000
	s_addc_u32 s7, s7, 0
	global_store_dword v36, v120, s[10:11]
	s_add_u32 s10, s10, 0x800
	s_addc_u32 s11, s11, 0
	v_lshlrev_b32_e32 v108, 16, v145
	v_and_b32_e32 v109, 0xffff0000, v145
	v_pk_mul_f32 v[108:109], v[62:63], v[108:109] op_sel_hi:[0,1]
	v_mul_f32_e32 v121, v45, v62
	v_pk_fma_f32 v[118:119], v[118:119], v[60:61], v[108:109] op_sel_hi:[1,0,1]
	v_fma_f32 v120, v120, v60, v121
	v_readfirstlane_b32 s54, v38
	v_add_f32_e32 v39, s22, v38
	v_readlane_b32 s34, v174, 21
	v_max_f32_e32 v40, s32, v39
	v_readlane_b32 s40, v176, 21
	v_sub_f32_e32 v58, v39, v40
	v_sub_f32_e32 v59, s32, v40
	v_mul_f32_e32 v58, 0x3fb8aa3b, v58
	v_mul_f32_e32 v59, 0x3fb8aa3b, v59
	v_exp_f32_e32 v60, v58
	v_exp_f32_e32 v62, v59
	v_cvt_pk_bf16_f32 v122, v118, v119
	v_writelane_b32 v178, s54, 20
	global_store_dword v36, v122, s[6:7]
	s_add_u32 s6, s6, 0x20000
	s_addc_u32 s7, s7, 0
	global_store_dword v36, v120, s[10:11]
	s_add_u32 s10, s10, 0x800
	s_addc_u32 s11, s11, 0
	v_lshlrev_b32_e32 v108, 16, v146
	v_and_b32_e32 v109, 0xffff0000, v146
	v_pk_mul_f32 v[108:109], v[62:63], v[108:109] op_sel_hi:[0,1]
	v_mul_f32_e32 v121, v46, v62
	v_pk_fma_f32 v[118:119], v[118:119], v[60:61], v[108:109] op_sel_hi:[1,0,1]
	v_fma_f32 v120, v120, v60, v121
	v_readfirstlane_b32 s54, v40
	v_add_f32_e32 v39, s34, v40
	v_readlane_b32 s22, v174, 22
	v_max_f32_e32 v38, s40, v39
	v_readlane_b32 s32, v176, 22
	v_sub_f32_e32 v58, v39, v38
	v_sub_f32_e32 v59, s40, v38
	v_mul_f32_e32 v58, 0x3fb8aa3b, v58
	v_mul_f32_e32 v59, 0x3fb8aa3b, v59
	v_exp_f32_e32 v60, v58
	v_exp_f32_e32 v62, v59
	v_cvt_pk_bf16_f32 v122, v118, v119
	v_writelane_b32 v178, s54, 21
	global_store_dword v36, v122, s[6:7]
	s_add_u32 s6, s6, 0x20000
	s_addc_u32 s7, s7, 0
	global_store_dword v36, v120, s[10:11]
	s_add_u32 s10, s10, 0x800
	s_addc_u32 s11, s11, 0
	v_lshlrev_b32_e32 v108, 16, v147
	v_and_b32_e32 v109, 0xffff0000, v147
	v_pk_mul_f32 v[108:109], v[62:63], v[108:109] op_sel_hi:[0,1]
	v_mul_f32_e32 v121, v47, v62
	v_pk_fma_f32 v[118:119], v[118:119], v[60:61], v[108:109] op_sel_hi:[1,0,1]
	v_fma_f32 v120, v120, v60, v121
	v_readfirstlane_b32 s54, v38
	v_add_f32_e32 v39, s22, v38
	v_readlane_b32 s34, v174, 23
	v_max_f32_e32 v40, s32, v39
	v_readlane_b32 s40, v176, 23
	v_sub_f32_e32 v58, v39, v40
	v_sub_f32_e32 v59, s32, v40
	v_mul_f32_e32 v58, 0x3fb8aa3b, v58
	v_mul_f32_e32 v59, 0x3fb8aa3b, v59
	v_exp_f32_e32 v60, v58
	v_exp_f32_e32 v62, v59
	v_cvt_pk_bf16_f32 v122, v118, v119
	v_writelane_b32 v178, s54, 22
	global_store_dword v36, v122, s[6:7]
	s_add_u32 s6, s6, 0x20000
	s_addc_u32 s7, s7, 0
	global_store_dword v36, v120, s[10:11]
	s_add_u32 s10, s10, 0x800
	s_addc_u32 s11, s11, 0
	v_lshlrev_b32_e32 v108, 16, v148
	v_and_b32_e32 v109, 0xffff0000, v148
	v_pk_mul_f32 v[108:109], v[62:63], v[108:109] op_sel_hi:[0,1]
	v_mul_f32_e32 v121, v48, v62
	v_pk_fma_f32 v[118:119], v[118:119], v[60:61], v[108:109] op_sel_hi:[1,0,1]
	v_fma_f32 v120, v120, v60, v121
	v_readfirstlane_b32 s54, v40
	v_add_f32_e32 v39, s34, v40
	v_readlane_b32 s22, v174, 24
	v_max_f32_e32 v38, s40, v39
	v_readlane_b32 s32, v176, 24
	v_sub_f32_e32 v58, v39, v38
	v_sub_f32_e32 v59, s40, v38
	v_mul_f32_e32 v58, 0x3fb8aa3b, v58
	v_mul_f32_e32 v59, 0x3fb8aa3b, v59
	v_exp_f32_e32 v60, v58
	v_exp_f32_e32 v62, v59
	v_cvt_pk_bf16_f32 v122, v118, v119
	v_writelane_b32 v178, s54, 23
	global_store_dword v36, v122, s[6:7]
	s_add_u32 s6, s6, 0x20000
	s_addc_u32 s7, s7, 0
	global_store_dword v36, v120, s[10:11]
; __device__ __forceinline__ unsigned pk2(float lo, float hi) { f32x2_t v = {lo, hi}; bf16x2_t b = __builtin_convertvector(v, bf16x2_t); return __builtin_bit_cast(unsigned, b); }
; __device__ __forceinline__ float bflo(unsigned w) { return __uint_as_float(w << 16); }
; __device__ __forceinline__ float bfhi(unsigned w) { return __uint_as_float(w & 0xffff0000u); }
; __device__ __forceinline__ float fexp(float x) { return __builtin_amdgcn_exp2f(x * LOG2E); }
;     __device__ __forceinline__ float* MBM() const { return (float*)(ws + WS_MB); }
;     __device__ __forceinline__ float* MBB() const { return (float*)(ws + WS_MB) + (NSLOT_P + NSLOT_S); }
;     __device__ __forceinline__ float* MST() const { return (float*)(ws + WS_MB) + 2 * (NSLOT_P + NSLOT_S); }
; __device__ __forceinline__ void phase_scan(Ctx& C, int l, const bool st, LAS unsigned char* lds) {
;     ...
;         for (int cg0 = 0; cg0 < NPC; cg0 += 16) {
;             if (cg0 + 16 < NPC) {
; #pragma unroll
;                 for (int j = 0; j < 16; ++j) { nb[j] = base[(size_t)((b * NPC + cg0 + 16 + j) * 4 + h) * 8192]; fnb[j] = hn ? dnb[(size_t)((b * NPC + cg0 + 16 + j) * 4 + h) * 128] : 0.f; }
;             }
; #pragma unroll
;             for (int j = 0; j < 16; ++j) { const int slot = (b * NPC + cg0 + j) * 4 + h;
;                 const float Bc = C.MBB()[slot], Mc = C.MBM()[slot];
;                 const float mn = fmaxf(Bc + m, Mc), g = fexp(Bc + m - mn), f = fexp(Mc - mn);
;                 if (st) { base[(size_t)slot * 8192] = pk2(c0, c1); if (hn) { dnb[(size_t)slot * 128] = nn; if (p == 0) C.MST()[slot] = m; } }
;                 c0 = g * c0 + f * bflo(buf[j]); c1 = g * c1 + f * bfhi(buf[j]); nn = g * nn + f * fb[j]; m = mn; }
; #pragma unroll
;             for (int j = 0; j < 16; ++j) { buf[j] = nb[j]; fb[j] = fnb[j]; }
	s_add_u32 s10, s10, 0x800
	s_addc_u32 s11, s11, 0
	v_lshlrev_b32_e32 v108, 16, v149
	v_and_b32_e32 v109, 0xffff0000, v149
	v_pk_mul_f32 v[108:109], v[62:63], v[108:109] op_sel_hi:[0,1]
	v_mul_f32_e32 v121, v49, v62
	v_pk_fma_f32 v[118:119], v[118:119], v[60:61], v[108:109] op_sel_hi:[1,0,1]
	v_fma_f32 v120, v120, v60, v121
	v_readfirstlane_b32 s54, v38
	v_add_f32_e32 v39, s22, v38
	v_readlane_b32 s34, v174, 25
	v_max_f32_e32 v40, s32, v39
	v_readlane_b32 s40, v176, 25
	v_sub_f32_e32 v58, v39, v40
	v_sub_f32_e32 v59, s32, v40
	v_mul_f32_e32 v58, 0x3fb8aa3b, v58
	v_mul_f32_e32 v59, 0x3fb8aa3b, v59
	v_exp_f32_e32 v60, v58
	v_exp_f32_e32 v62, v59
	v_cvt_pk_bf16_f32 v122, v118, v119
	v_writelane_b32 v178, s54, 24
	global_store_dword v36, v122, s[6:7]
	s_add_u32 s6, s6, 0x20000
	s_addc_u32 s7, s7, 0
	global_store_dword v36, v120, s[10:11]
	s_add_u32 s10, s10, 0x800
	s_addc_u32 s11, s11, 0
	v_lshlrev_b32_e32 v108, 16, v150
	v_and_b32_e32 v109, 0xffff0000, v150
	v_pk_mul_f32 v[108:109], v[62:63], v[108:109] op_sel_hi:[0,1]
	v_mul_f32_e32 v121, v50, v62
	v_pk_fma_f32 v[118:119], v[118:119], v[60:61], v[108:109] op_sel_hi:[1,0,1]
	v_fma_f32 v120, v120, v60, v121
	v_readfirstlane_b32 s54, v40
	v_add_f32_e32 v39, s34, v40
	v_readlane_b32 s22, v174, 26
	v_max_f32_e32 v38, s40, v39
	v_readlane_b32 s32, v176, 26
	v_sub_f32_e32 v58, v39, v38
	v_sub_f32_e32 v59, s40, v38
	v_mul_f32_e32 v58, 0x3fb8aa3b, v58
	v_mul_f32_e32 v59, 0x3fb8aa3b, v59
	v_exp_f32_e32 v60, v58
	v_exp_f32_e32 v62, v59
	v_cvt_pk_bf16_f32 v122, v118, v119
	v_writelane_b32 v178, s54, 25
	global_store_dword v36, v122, s[6:7]
	s_add_u32 s6, s6, 0x20000
	s_addc_u32 s7, s7, 0
	global_store_dword v36, v120, s[10:11]
	s_add_u32 s10, s10, 0x800
	s_addc_u32 s11, s11, 0
	v_lshlrev_b32_e32 v108, 16, v151
	v_and_b32_e32 v109, 0xffff0000, v151
	v_pk_mul_f32 v[108:109], v[62:63], v[108:109] op_sel_hi:[0,1]
	v_mul_f32_e32 v121, v51, v62
	v_pk_fma_f32 v[118:119], v[118:119], v[60:61], v[108:109] op_sel_hi:[1,0,1]
	v_fma_f32 v120, v120, v60, v121
	v_readfirstlane_b32 s54, v38
	v_add_f32_e32 v39, s22, v38
	v_readlane_b32 s34, v174, 27
	v_max_f32_e32 v40, s32, v39
	v_readlane_b32 s40, v176, 27
	v_sub_f32_e32 v58, v39, v40
	v_sub_f32_e32 v59, s32, v40
	v_mul_f32_e32 v58, 0x3fb8aa3b, v58
	v_mul_f32_e32 v59, 0x3fb8aa3b, v59
	v_exp_f32_e32 v60, v58
	v_exp_f32_e32 v62, v59
	v_cvt_pk_bf16_f32 v122, v118, v119
	v_writelane_b32 v178, s54, 26
	global_store_dword v36, v122, s[6:7]
	s_add_u32 s6, s6, 0x20000
	s_addc_u32 s7, s7, 0
	global_store_dword v36, v120, s[10:11]
	s_add_u32 s10, s10, 0x800
	s_addc_u32 s11, s11, 0
	v_lshlrev_b32_e32 v108, 16, v152
	v_and_b32_e32 v109, 0xffff0000, v152
	v_pk_mul_f32 v[108:109], v[62:63], v[108:109] op_sel_hi:[0,1]
	v_mul_f32_e32 v121, v52, v62
	v_pk_fma_f32 v[118:119], v[118:119], v[60:61], v[108:109] op_sel_hi:[1,0,1]
	v_fma_f32 v120, v120, v60, v121
	v_readfirstlane_b32 s54, v40
	v_add_f32_e32 v39, s34, v40
	v_readlane_b32 s22, v174, 28
	v_max_f32_e32 v38, s40, v39
	v_readlane_b32 s32, v176, 28
	v_sub_f32_e32 v58, v39, v38
	v_sub_f32_e32 v59, s40, v38
	v_mul_f32_e32 v58, 0x3fb8aa3b, v58
	v_mul_f32_e32 v59, 0x3fb8aa3b, v59
	v_exp_f32_e32 v60, v58
	v_exp_f32_e32 v62, v59
	v_cvt_pk_bf16_f32 v122, v118, v119
	v_writelane_b32 v178, s54, 27
	global_store_dword v36, v122, s[6:7]
	s_add_u32 s6, s6, 0x20000
	s_addc_u32 s7, s7, 0
	global_store_dword v36, v120, s[10:11]
	s_add_u32 s10, s10, 0x800
	s_addc_u32 s11, s11, 0
	v_lshlrev_b32_e32 v108, 16, v153
	v_and_b32_e32 v109, 0xffff0000, v153
	v_pk_mul_f32 v[108:109], v[62:63], v[108:109] op_sel_hi:[0,1]
	v_mul_f32_e32 v121, v53, v62
	v_pk_fma_f32 v[118:119], v[118:119], v[60:61], v[108:109] op_sel_hi:[1,0,1]
	v_fma_f32 v120, v120, v60, v121
	v_readfirstlane_b32 s54, v38
	v_add_f32_e32 v39, s22, v38
	v_readlane_b32 s34, v174, 29
	v_max_f32_e32 v40, s32, v39
	v_readlane_b32 s40, v176, 29
	v_sub_f32_e32 v58, v39, v40
	v_sub_f32_e32 v59, s32, v40
	v_mul_f32_e32 v58, 0x3fb8aa3b, v58
	v_mul_f32_e32 v59, 0x3fb8aa3b, v59
	v_exp_f32_e32 v60, v58
	v_exp_f32_e32 v62, v59
	v_cvt_pk_bf16_f32 v122, v118, v119
	v_writelane_b32 v178, s54, 28
	global_store_dword v36, v122, s[6:7]
	s_add_u32 s6, s6, 0x20000
	s_addc_u32 s7, s7, 0
	global_store_dword v36, v120, s[10:11]
	s_add_u32 s10, s10, 0x800
	s_addc_u32 s11, s11, 0
	v_lshlrev_b32_e32 v108, 16, v154
	v_and_b32_e32 v109, 0xffff0000, v154
	v_pk_mul_f32 v[108:109], v[62:63], v[108:109] op_sel_hi:[0,1]
	v_mul_f32_e32 v121, v54, v62
	v_pk_fma_f32 v[118:119], v[118:119], v[60:61], v[108:109] op_sel_hi:[1,0,1]
	v_fma_f32 v120, v120, v60, v121
	v_readfirstlane_b32 s54, v40
	v_add_f32_e32 v39, s34, v40
	v_readlane_b32 s22, v174, 30
	v_max_f32_e32 v38, s40, v39
	v_readlane_b32 s32, v176, 30
	v_sub_f32_e32 v58, v39, v38
	v_sub_f32_e32 v59, s40, v38
	v_mul_f32_e32 v58, 0x3fb8aa3b, v58
	v_mul_f32_e32 v59, 0x3fb8aa3b, v59
	v_exp_f32_e32 v60, v58
	v_exp_f32_e32 v62, v59
	v_cvt_pk_bf16_f32 v122, v118, v119
	v_writelane_b32 v178, s54, 29
	global_store_dword v36, v122, s[6:7]
	s_add_u32 s6, s6, 0x20000
	s_addc_u32 s7, s7, 0
	global_store_dword v36, v120, s[10:11]
	s_add_u32 s10, s10, 0x800
	s_addc_u32 s11, s11, 0
	v_lshlrev_b32_e32 v108, 16, v155
	v_and_b32_e32 v109, 0xffff0000, v155
	v_pk_mul_f32 v[108:109], v[62:63], v[108:109] op_sel_hi:[0,1]
	v_mul_f32_e32 v121, v55, v62
	v_pk_fma_f32 v[118:119], v[118:119], v[60:61], v[108:109] op_sel_hi:[1,0,1]
	v_fma_f32 v120, v120, v60, v121
	v_readfirstlane_b32 s54, v38
	v_add_f32_e32 v39, s22, v38
	v_readlane_b32 s34, v174, 31
	v_max_f32_e32 v40, s32, v39
	v_readlane_b32 s40, v176, 31
	v_sub_f32_e32 v58, v39, v40
	v_sub_f32_e32 v59, s32, v40
	v_mul_f32_e32 v58, 0x3fb8aa3b, v58
; __device__ __forceinline__ unsigned pk2(float lo, float hi) { f32x2_t v = {lo, hi}; bf16x2_t b = __builtin_convertvector(v, bf16x2_t); return __builtin_bit_cast(unsigned, b); }
; __device__ __forceinline__ float bflo(unsigned w) { return __uint_as_float(w << 16); }
; __device__ __forceinline__ float bfhi(unsigned w) { return __uint_as_float(w & 0xffff0000u); }
; __device__ __forceinline__ float fexp(float x) { return __builtin_amdgcn_exp2f(x * LOG2E); }
;     __device__ __forceinline__ float* MBM() const { return (float*)(ws + WS_MB); }
;     __device__ __forceinline__ float* MBB() const { return (float*)(ws + WS_MB) + (NSLOT_P + NSLOT_S); }
;     __device__ __forceinline__ float* MST() const { return (float*)(ws + WS_MB) + 2 * (NSLOT_P + NSLOT_S); }
; __device__ __forceinline__ void phase_scan(Ctx& C, int l, const bool st, LAS unsigned char* lds) {
;     ...
;         for (int cg0 = 0; cg0 < NPC; cg0 += 16) {
;             if (cg0 + 16 < NPC) {
; #pragma unroll
;                 for (int j = 0; j < 16; ++j) { nb[j] = base[(size_t)((b * NPC + cg0 + 16 + j) * 4 + h) * 8192]; fnb[j] = hn ? dnb[(size_t)((b * NPC + cg0 + 16 + j) * 4 + h) * 128] : 0.f; }
;             }
; #pragma unroll
;             for (int j = 0; j < 16; ++j) { const int slot = (b * NPC + cg0 + j) * 4 + h;
;                 const float Bc = C.MBB()[slot], Mc = C.MBM()[slot];
;                 const float mn = fmaxf(Bc + m, Mc), g = fexp(Bc + m - mn), f = fexp(Mc - mn);
;                 if (st) { base[(size_t)slot * 8192] = pk2(c0, c1); if (hn) { dnb[(size_t)slot * 128] = nn; if (p == 0) C.MST()[slot] = m; } }
;                 c0 = g * c0 + f * bflo(buf[j]); c1 = g * c1 + f * bfhi(buf[j]); nn = g * nn + f * fb[j]; m = mn; }
; #pragma unroll
;             for (int j = 0; j < 16; ++j) { buf[j] = nb[j]; fb[j] = fnb[j]; }
	v_mul_f32_e32 v59, 0x3fb8aa3b, v59
	v_exp_f32_e32 v60, v58
	v_exp_f32_e32 v62, v59
	v_cvt_pk_bf16_f32 v122, v118, v119
	v_writelane_b32 v178, s54, 30
	global_store_dword v36, v122, s[6:7]
	s_add_u32 s6, s6, 0x20000
	s_addc_u32 s7, s7, 0
	global_store_dword v36, v120, s[10:11]
	s_add_u32 s10, s10, 0x800
	s_addc_u32 s11, s11, 0
	v_lshlrev_b32_e32 v108, 16, v156
	v_and_b32_e32 v109, 0xffff0000, v156
	v_pk_mul_f32 v[108:109], v[62:63], v[108:109] op_sel_hi:[0,1]
	v_mul_f32_e32 v121, v56, v62
	v_pk_fma_f32 v[118:119], v[118:119], v[60:61], v[108:109] op_sel_hi:[1,0,1]
	v_fma_f32 v120, v120, v60, v121
	v_readfirstlane_b32 s54, v40
	v_add_f32_e32 v39, s34, v40
	v_readlane_b32 s22, v174, 32
	v_max_f32_e32 v38, s40, v39
	v_readlane_b32 s32, v176, 32
	v_sub_f32_e32 v58, v39, v38
	v_sub_f32_e32 v59, s40, v38
	v_mul_f32_e32 v58, 0x3fb8aa3b, v58
	v_mul_f32_e32 v59, 0x3fb8aa3b, v59
	v_exp_f32_e32 v60, v58
	v_exp_f32_e32 v62, v59
	v_cvt_pk_bf16_f32 v122, v118, v119
	v_writelane_b32 v178, s54, 31
	global_store_dword v36, v122, s[6:7]
	s_add_u32 s6, s6, 0x20000
	s_addc_u32 s7, s7, 0
	global_store_dword v36, v120, s[10:11]
	s_add_u32 s10, s10, 0x800
	s_addc_u32 s11, s11, 0
	v_lshlrev_b32_e32 v108, 16, v157
	v_and_b32_e32 v109, 0xffff0000, v157
	v_pk_mul_f32 v[108:109], v[62:63], v[108:109] op_sel_hi:[0,1]
	v_mul_f32_e32 v121, v57, v62
	v_pk_fma_f32 v[118:119], v[118:119], v[60:61], v[108:109] op_sel_hi:[1,0,1]
	v_fma_f32 v120, v120, v60, v121
.Lscan_hn_b2:
	s_waitcnt vmcnt(32)
	global_load_dword v126, v36, s[4:5]
	s_add_u32 s4, s4, 0x20000
	s_addc_u32 s5, s5, 0
	global_load_dword v127, v36, s[4:5]
	s_add_u32 s4, s4, 0x20000
	s_addc_u32 s5, s5, 0
	global_load_dword v128, v36, s[4:5]
	s_add_u32 s4, s4, 0x20000
	s_addc_u32 s5, s5, 0
	global_load_dword v129, v36, s[4:5]
	s_add_u32 s4, s4, 0x20000
	s_addc_u32 s5, s5, 0
	global_load_dword v130, v36, s[4:5]
	s_add_u32 s4, s4, 0x20000
	s_addc_u32 s5, s5, 0
	global_load_dword v131, v36, s[4:5]
	s_add_u32 s4, s4, 0x20000
	s_addc_u32 s5, s5, 0
	global_load_dword v132, v36, s[4:5]
	s_add_u32 s4, s4, 0x20000
	s_addc_u32 s5, s5, 0
	global_load_dword v133, v36, s[4:5]
	s_add_u32 s4, s4, 0x20000
	s_addc_u32 s5, s5, 0
	global_load_dword v134, v36, s[4:5]
	s_add_u32 s4, s4, 0x20000
	s_addc_u32 s5, s5, 0
	global_load_dword v135, v36, s[4:5]
	s_add_u32 s4, s4, 0x20000
	s_addc_u32 s5, s5, 0
	global_load_dword v136, v36, s[4:5]
	s_add_u32 s4, s4, 0x20000
	s_addc_u32 s5, s5, 0
	global_load_dword v137, v36, s[4:5]
	s_add_u32 s4, s4, 0x20000
	s_addc_u32 s5, s5, 0
	global_load_dword v138, v36, s[4:5]
	s_add_u32 s4, s4, 0x20000
	s_addc_u32 s5, s5, 0
	global_load_dword v139, v36, s[4:5]
	s_add_u32 s4, s4, 0x20000
	s_addc_u32 s5, s5, 0
	global_load_dword v140, v36, s[4:5]
	s_add_u32 s4, s4, 0x20000
	s_addc_u32 s5, s5, 0
	global_load_dword v141, v36, s[4:5]
	s_add_u32 s4, s4, 0x20000
	s_addc_u32 s5, s5, 0
	global_load_dword v16, v36, s[8:9]
	s_add_u32 s8, s8, 0x800
	s_addc_u32 s9, s9, 0
	global_load_dword v17, v36, s[8:9]
	s_add_u32 s8, s8, 0x800
	s_addc_u32 s9, s9, 0
	global_load_dword v18, v36, s[8:9]
	s_add_u32 s8, s8, 0x800
	s_addc_u32 s9, s9, 0
	global_load_dword v19, v36, s[8:9]
	s_add_u32 s8, s8, 0x800
	s_addc_u32 s9, s9, 0
	global_load_dword v20, v36, s[8:9]
	s_add_u32 s8, s8, 0x800
	s_addc_u32 s9, s9, 0
	global_load_dword v21, v36, s[8:9]
	s_add_u32 s8, s8, 0x800
	s_addc_u32 s9, s9, 0
	global_load_dword v22, v36, s[8:9]
	s_add_u32 s8, s8, 0x800
	s_addc_u32 s9, s9, 0
	global_load_dword v23, v36, s[8:9]
	s_add_u32 s8, s8, 0x800
	s_addc_u32 s9, s9, 0
	global_load_dword v24, v36, s[8:9]
	s_add_u32 s8, s8, 0x800
	s_addc_u32 s9, s9, 0
	global_load_dword v25, v36, s[8:9]
	s_add_u32 s8, s8, 0x800
	s_addc_u32 s9, s9, 0
	global_load_dword v26, v36, s[8:9]
	s_add_u32 s8, s8, 0x800
	s_addc_u32 s9, s9, 0
	global_load_dword v27, v36, s[8:9]
	s_add_u32 s8, s8, 0x800
	s_addc_u32 s9, s9, 0
	global_load_dword v28, v36, s[8:9]
	s_add_u32 s8, s8, 0x800
	s_addc_u32 s9, s9, 0
	global_load_dword v29, v36, s[8:9]
	s_add_u32 s8, s8, 0x800
	s_addc_u32 s9, s9, 0
	global_load_dword v30, v36, s[8:9]
	s_add_u32 s8, s8, 0x800
	s_addc_u32 s9, s9, 0
	global_load_dword v31, v36, s[8:9]
	s_add_u32 s8, s8, 0x800
	s_addc_u32 s9, s9, 0
	v_readfirstlane_b32 s54, v38
	v_add_f32_e32 v39, s22, v38
	v_readlane_b32 s34, v174, 33
	v_max_f32_e32 v40, s32, v39
	v_readlane_b32 s40, v176, 33
	v_sub_f32_e32 v58, v39, v40
	v_sub_f32_e32 v59, s32, v40
	v_mul_f32_e32 v58, 0x3fb8aa3b, v58
	v_mul_f32_e32 v59, 0x3fb8aa3b, v59
	v_exp_f32_e32 v60, v58
	v_exp_f32_e32 v62, v59
	v_cvt_pk_bf16_f32 v122, v118, v119
	v_writelane_b32 v178, s54, 32
	global_store_dword v36, v122, s[6:7]
	s_add_u32 s6, s6, 0x20000
	s_addc_u32 s7, s7, 0
	global_store_dword v36, v120, s[10:11]
	s_add_u32 s10, s10, 0x800
	s_addc_u32 s11, s11, 0
	v_lshlrev_b32_e32 v108, 16, v158
	v_and_b32_e32 v109, 0xffff0000, v158
	v_pk_mul_f32 v[108:109], v[62:63], v[108:109] op_sel_hi:[0,1]
	v_mul_f32_e32 v121, v92, v62
	v_pk_fma_f32 v[118:119], v[118:119], v[60:61], v[108:109] op_sel_hi:[1,0,1]
	v_fma_f32 v120, v120, v60, v121
	v_readfirstlane_b32 s54, v40
	v_add_f32_e32 v39, s34, v40
	v_readlane_b32 s22, v174, 34
	v_max_f32_e32 v38, s40, v39
	v_readlane_b32 s32, v176, 34
	v_sub_f32_e32 v58, v39, v38
	v_sub_f32_e32 v59, s40, v38
	v_mul_f32_e32 v58, 0x3fb8aa3b, v58
	v_mul_f32_e32 v59, 0x3fb8aa3b, v59
	v_exp_f32_e32 v60, v58
	v_exp_f32_e32 v62, v59
	v_cvt_pk_bf16_f32 v122, v118, v119
	v_writelane_b32 v178, s54, 33
	global_store_dword v36, v122, s[6:7]
	s_add_u32 s6, s6, 0x20000
	s_addc_u32 s7, s7, 0
	global_store_dword v36, v120, s[10:11]
	s_add_u32 s10, s10, 0x800
	s_addc_u32 s11, s11, 0
	v_lshlrev_b32_e32 v108, 16, v159
; __device__ __forceinline__ unsigned pk2(float lo, float hi) { f32x2_t v = {lo, hi}; bf16x2_t b = __builtin_convertvector(v, bf16x2_t); return __builtin_bit_cast(unsigned, b); }
; __device__ __forceinline__ float bflo(unsigned w) { return __uint_as_float(w << 16); }
; __device__ __forceinline__ float bfhi(unsigned w) { return __uint_as_float(w & 0xffff0000u); }
; __device__ __forceinline__ float fexp(float x) { return __builtin_amdgcn_exp2f(x * LOG2E); }
;     __device__ __forceinline__ float* MBM() const { return (float*)(ws + WS_MB); }
;     __device__ __forceinline__ float* MBB() const { return (float*)(ws + WS_MB) + (NSLOT_P + NSLOT_S); }
;     __device__ __forceinline__ float* MST() const { return (float*)(ws + WS_MB) + 2 * (NSLOT_P + NSLOT_S); }
; __device__ __forceinline__ void phase_scan(Ctx& C, int l, const bool st, LAS unsigned char* lds) {
;     ...
;         for (int cg0 = 0; cg0 < NPC; cg0 += 16) {
;             if (cg0 + 16 < NPC) {
; #pragma unroll
;                 for (int j = 0; j < 16; ++j) { nb[j] = base[(size_t)((b * NPC + cg0 + 16 + j) * 4 + h) * 8192]; fnb[j] = hn ? dnb[(size_t)((b * NPC + cg0 + 16 + j) * 4 + h) * 128] : 0.f; }
;             }
; #pragma unroll
;             for (int j = 0; j < 16; ++j) { const int slot = (b * NPC + cg0 + j) * 4 + h;
;                 const float Bc = C.MBB()[slot], Mc = C.MBM()[slot];
;                 const float mn = fmaxf(Bc + m, Mc), g = fexp(Bc + m - mn), f = fexp(Mc - mn);
;                 if (st) { base[(size_t)slot * 8192] = pk2(c0, c1); if (hn) { dnb[(size_t)slot * 128] = nn; if (p == 0) C.MST()[slot] = m; } }
;                 c0 = g * c0 + f * bflo(buf[j]); c1 = g * c1 + f * bfhi(buf[j]); nn = g * nn + f * fb[j]; m = mn; }
; #pragma unroll
;             for (int j = 0; j < 16; ++j) { buf[j] = nb[j]; fb[j] = fnb[j]; }
	v_and_b32_e32 v109, 0xffff0000, v159
	v_pk_mul_f32 v[108:109], v[62:63], v[108:109] op_sel_hi:[0,1]
	v_mul_f32_e32 v121, v93, v62
	v_pk_fma_f32 v[118:119], v[118:119], v[60:61], v[108:109] op_sel_hi:[1,0,1]
	v_fma_f32 v120, v120, v60, v121
	v_readfirstlane_b32 s54, v38
	v_add_f32_e32 v39, s22, v38
	v_readlane_b32 s34, v174, 35
	v_max_f32_e32 v40, s32, v39
	v_readlane_b32 s40, v176, 35
	v_sub_f32_e32 v58, v39, v40
	v_sub_f32_e32 v59, s32, v40
	v_mul_f32_e32 v58, 0x3fb8aa3b, v58
	v_mul_f32_e32 v59, 0x3fb8aa3b, v59
	v_exp_f32_e32 v60, v58
	v_exp_f32_e32 v62, v59
	v_cvt_pk_bf16_f32 v122, v118, v119
	v_writelane_b32 v178, s54, 34
	global_store_dword v36, v122, s[6:7]
	s_add_u32 s6, s6, 0x20000
	s_addc_u32 s7, s7, 0
	global_store_dword v36, v120, s[10:11]
	s_add_u32 s10, s10, 0x800
	s_addc_u32 s11, s11, 0
	v_lshlrev_b32_e32 v108, 16, v160
	v_and_b32_e32 v109, 0xffff0000, v160
	v_pk_mul_f32 v[108:109], v[62:63], v[108:109] op_sel_hi:[0,1]
	v_mul_f32_e32 v121, v94, v62
	v_pk_fma_f32 v[118:119], v[118:119], v[60:61], v[108:109] op_sel_hi:[1,0,1]
	v_fma_f32 v120, v120, v60, v121
	v_readfirstlane_b32 s54, v40
	v_add_f32_e32 v39, s34, v40
	v_readlane_b32 s22, v174, 36
	v_max_f32_e32 v38, s40, v39
	v_readlane_b32 s32, v176, 36
	v_sub_f32_e32 v58, v39, v38
	v_sub_f32_e32 v59, s40, v38
	v_mul_f32_e32 v58, 0x3fb8aa3b, v58
	v_mul_f32_e32 v59, 0x3fb8aa3b, v59
	v_exp_f32_e32 v60, v58
	v_exp_f32_e32 v62, v59
	v_cvt_pk_bf16_f32 v122, v118, v119
	v_writelane_b32 v178, s54, 35
	global_store_dword v36, v122, s[6:7]
	s_add_u32 s6, s6, 0x20000
	s_addc_u32 s7, s7, 0
	global_store_dword v36, v120, s[10:11]
	s_add_u32 s10, s10, 0x800
	s_addc_u32 s11, s11, 0
	v_lshlrev_b32_e32 v108, 16, v161
	v_and_b32_e32 v109, 0xffff0000, v161
	v_pk_mul_f32 v[108:109], v[62:63], v[108:109] op_sel_hi:[0,1]
	v_mul_f32_e32 v121, v95, v62
	v_pk_fma_f32 v[118:119], v[118:119], v[60:61], v[108:109] op_sel_hi:[1,0,1]
	v_fma_f32 v120, v120, v60, v121
	v_readfirstlane_b32 s54, v38
	v_add_f32_e32 v39, s22, v38
	v_readlane_b32 s34, v174, 37
	v_max_f32_e32 v40, s32, v39
	v_readlane_b32 s40, v176, 37
	v_sub_f32_e32 v58, v39, v40
	v_sub_f32_e32 v59, s32, v40
	v_mul_f32_e32 v58, 0x3fb8aa3b, v58
	v_mul_f32_e32 v59, 0x3fb8aa3b, v59
	v_exp_f32_e32 v60, v58
	v_exp_f32_e32 v62, v59
	v_cvt_pk_bf16_f32 v122, v118, v119
	v_writelane_b32 v178, s54, 36
	global_store_dword v36, v122, s[6:7]
	s_add_u32 s6, s6, 0x20000
	s_addc_u32 s7, s7, 0
	global_store_dword v36, v120, s[10:11]
	s_add_u32 s10, s10, 0x800
	s_addc_u32 s11, s11, 0
	v_lshlrev_b32_e32 v108, 16, v162
	v_and_b32_e32 v109, 0xffff0000, v162
	v_pk_mul_f32 v[108:109], v[62:63], v[108:109] op_sel_hi:[0,1]
	v_mul_f32_e32 v121, v96, v62
	v_pk_fma_f32 v[118:119], v[118:119], v[60:61], v[108:109] op_sel_hi:[1,0,1]
	v_fma_f32 v120, v120, v60, v121
	v_readfirstlane_b32 s54, v40
	v_add_f32_e32 v39, s34, v40
	v_readlane_b32 s22, v174, 38
	v_max_f32_e32 v38, s40, v39
	v_readlane_b32 s32, v176, 38
	v_sub_f32_e32 v58, v39, v38
	v_sub_f32_e32 v59, s40, v38
	v_mul_f32_e32 v58, 0x3fb8aa3b, v58
	v_mul_f32_e32 v59, 0x3fb8aa3b, v59
	v_exp_f32_e32 v60, v58
	v_exp_f32_e32 v62, v59
	v_cvt_pk_bf16_f32 v122, v118, v119
	v_writelane_b32 v178, s54, 37
	global_store_dword v36, v122, s[6:7]
	s_add_u32 s6, s6, 0x20000
	s_addc_u32 s7, s7, 0
	global_store_dword v36, v120, s[10:11]
	s_add_u32 s10, s10, 0x800
	s_addc_u32 s11, s11, 0
	v_lshlrev_b32_e32 v108, 16, v163
	v_and_b32_e32 v109, 0xffff0000, v163
	v_pk_mul_f32 v[108:109], v[62:63], v[108:109] op_sel_hi:[0,1]
	v_mul_f32_e32 v121, v97, v62
	v_pk_fma_f32 v[118:119], v[118:119], v[60:61], v[108:109] op_sel_hi:[1,0,1]
	v_fma_f32 v120, v120, v60, v121
	v_readfirstlane_b32 s54, v38
	v_add_f32_e32 v39, s22, v38
	v_readlane_b32 s34, v174, 39
	v_max_f32_e32 v40, s32, v39
	v_readlane_b32 s40, v176, 39
	v_sub_f32_e32 v58, v39, v40
	v_sub_f32_e32 v59, s32, v40
	v_mul_f32_e32 v58, 0x3fb8aa3b, v58
	v_mul_f32_e32 v59, 0x3fb8aa3b, v59
	v_exp_f32_e32 v60, v58
	v_exp_f32_e32 v62, v59
	v_cvt_pk_bf16_f32 v122, v118, v119
	v_writelane_b32 v178, s54, 38
	global_store_dword v36, v122, s[6:7]
	s_add_u32 s6, s6, 0x20000
	s_addc_u32 s7, s7, 0
	global_store_dword v36, v120, s[10:11]
	s_add_u32 s10, s10, 0x800
	s_addc_u32 s11, s11, 0
	v_lshlrev_b32_e32 v108, 16, v164
	v_and_b32_e32 v109, 0xffff0000, v164
	v_pk_mul_f32 v[108:109], v[62:63], v[108:109] op_sel_hi:[0,1]
	v_mul_f32_e32 v121, v98, v62
	v_pk_fma_f32 v[118:119], v[118:119], v[60:61], v[108:109] op_sel_hi:[1,0,1]
	v_fma_f32 v120, v120, v60, v121
	v_readfirstlane_b32 s54, v40
	v_add_f32_e32 v39, s34, v40
	v_readlane_b32 s22, v174, 40
	v_max_f32_e32 v38, s40, v39
	v_readlane_b32 s32, v176, 40
	v_sub_f32_e32 v58, v39, v38
	v_sub_f32_e32 v59, s40, v38
	v_mul_f32_e32 v58, 0x3fb8aa3b, v58
	v_mul_f32_e32 v59, 0x3fb8aa3b, v59
	v_exp_f32_e32 v60, v58
	v_exp_f32_e32 v62, v59
	v_cvt_pk_bf16_f32 v122, v118, v119
	v_writelane_b32 v178, s54, 39
	global_store_dword v36, v122, s[6:7]
	s_add_u32 s6, s6, 0x20000
	s_addc_u32 s7, s7, 0
	global_store_dword v36, v120, s[10:11]
	s_add_u32 s10, s10, 0x800
	s_addc_u32 s11, s11, 0
	v_lshlrev_b32_e32 v108, 16, v165
	v_and_b32_e32 v109, 0xffff0000, v165
	v_pk_mul_f32 v[108:109], v[62:63], v[108:109] op_sel_hi:[0,1]
	v_mul_f32_e32 v121, v99, v62
	v_pk_fma_f32 v[118:119], v[118:119], v[60:61], v[108:109] op_sel_hi:[1,0,1]
	v_fma_f32 v120, v120, v60, v121
	v_readfirstlane_b32 s54, v38
	v_add_f32_e32 v39, s22, v38
	v_readlane_b32 s34, v174, 41
	v_max_f32_e32 v40, s32, v39
	v_readlane_b32 s40, v176, 41
	v_sub_f32_e32 v58, v39, v40
	v_sub_f32_e32 v59, s32, v40
	v_mul_f32_e32 v58, 0x3fb8aa3b, v58
	v_mul_f32_e32 v59, 0x3fb8aa3b, v59
	v_exp_f32_e32 v60, v58
	v_exp_f32_e32 v62, v59
; __device__ __forceinline__ unsigned pk2(float lo, float hi) { f32x2_t v = {lo, hi}; bf16x2_t b = __builtin_convertvector(v, bf16x2_t); return __builtin_bit_cast(unsigned, b); }
; __device__ __forceinline__ float bflo(unsigned w) { return __uint_as_float(w << 16); }
; __device__ __forceinline__ float bfhi(unsigned w) { return __uint_as_float(w & 0xffff0000u); }
; __device__ __forceinline__ float fexp(float x) { return __builtin_amdgcn_exp2f(x * LOG2E); }
;     __device__ __forceinline__ float* MBM() const { return (float*)(ws + WS_MB); }
;     __device__ __forceinline__ float* MBB() const { return (float*)(ws + WS_MB) + (NSLOT_P + NSLOT_S); }
;     __device__ __forceinline__ float* MST() const { return (float*)(ws + WS_MB) + 2 * (NSLOT_P + NSLOT_S); }
; __device__ __forceinline__ void phase_scan(Ctx& C, int l, const bool st, LAS unsigned char* lds) {
;     ...
;         for (int cg0 = 0; cg0 < NPC; cg0 += 16) {
;             if (cg0 + 16 < NPC) {
; #pragma unroll
;                 for (int j = 0; j < 16; ++j) { nb[j] = base[(size_t)((b * NPC + cg0 + 16 + j) * 4 + h) * 8192]; fnb[j] = hn ? dnb[(size_t)((b * NPC + cg0 + 16 + j) * 4 + h) * 128] : 0.f; }
;             }
; #pragma unroll
;             for (int j = 0; j < 16; ++j) { const int slot = (b * NPC + cg0 + j) * 4 + h;
;                 const float Bc = C.MBB()[slot], Mc = C.MBM()[slot];
;                 const float mn = fmaxf(Bc + m, Mc), g = fexp(Bc + m - mn), f = fexp(Mc - mn);
;                 if (st) { base[(size_t)slot * 8192] = pk2(c0, c1); if (hn) { dnb[(size_t)slot * 128] = nn; if (p == 0) C.MST()[slot] = m; } }
;                 c0 = g * c0 + f * bflo(buf[j]); c1 = g * c1 + f * bfhi(buf[j]); nn = g * nn + f * fb[j]; m = mn; }
; #pragma unroll
;             for (int j = 0; j < 16; ++j) { buf[j] = nb[j]; fb[j] = fnb[j]; }
	v_cvt_pk_bf16_f32 v122, v118, v119
	v_writelane_b32 v178, s54, 40
	global_store_dword v36, v122, s[6:7]
	s_add_u32 s6, s6, 0x20000
	s_addc_u32 s7, s7, 0
	global_store_dword v36, v120, s[10:11]
	s_add_u32 s10, s10, 0x800
	s_addc_u32 s11, s11, 0
	v_lshlrev_b32_e32 v108, 16, v166
	v_and_b32_e32 v109, 0xffff0000, v166
	v_pk_mul_f32 v[108:109], v[62:63], v[108:109] op_sel_hi:[0,1]
	v_mul_f32_e32 v121, v100, v62
	v_pk_fma_f32 v[118:119], v[118:119], v[60:61], v[108:109] op_sel_hi:[1,0,1]
	v_fma_f32 v120, v120, v60, v121
	v_readfirstlane_b32 s54, v40
	v_add_f32_e32 v39, s34, v40
	v_readlane_b32 s22, v174, 42
	v_max_f32_e32 v38, s40, v39
	v_readlane_b32 s32, v176, 42
	v_sub_f32_e32 v58, v39, v38
	v_sub_f32_e32 v59, s40, v38
	v_mul_f32_e32 v58, 0x3fb8aa3b, v58
	v_mul_f32_e32 v59, 0x3fb8aa3b, v59
	v_exp_f32_e32 v60, v58
	v_exp_f32_e32 v62, v59
	v_cvt_pk_bf16_f32 v122, v118, v119
	v_writelane_b32 v178, s54, 41
	global_store_dword v36, v122, s[6:7]
	s_add_u32 s6, s6, 0x20000
	s_addc_u32 s7, s7, 0
	global_store_dword v36, v120, s[10:11]
	s_add_u32 s10, s10, 0x800
	s_addc_u32 s11, s11, 0
	v_lshlrev_b32_e32 v108, 16, v167
	v_and_b32_e32 v109, 0xffff0000, v167
	v_pk_mul_f32 v[108:109], v[62:63], v[108:109] op_sel_hi:[0,1]
	v_mul_f32_e32 v121, v101, v62
	v_pk_fma_f32 v[118:119], v[118:119], v[60:61], v[108:109] op_sel_hi:[1,0,1]
	v_fma_f32 v120, v120, v60, v121
	v_readfirstlane_b32 s54, v38
	v_add_f32_e32 v39, s22, v38
	v_readlane_b32 s34, v174, 43
	v_max_f32_e32 v40, s32, v39
	v_readlane_b32 s40, v176, 43
	v_sub_f32_e32 v58, v39, v40
	v_sub_f32_e32 v59, s32, v40
	v_mul_f32_e32 v58, 0x3fb8aa3b, v58
	v_mul_f32_e32 v59, 0x3fb8aa3b, v59
	v_exp_f32_e32 v60, v58
	v_exp_f32_e32 v62, v59
	v_cvt_pk_bf16_f32 v122, v118, v119
	v_writelane_b32 v178, s54, 42
	global_store_dword v36, v122, s[6:7]
	s_add_u32 s6, s6, 0x20000
	s_addc_u32 s7, s7, 0
	global_store_dword v36, v120, s[10:11]
	s_add_u32 s10, s10, 0x800
	s_addc_u32 s11, s11, 0
	v_lshlrev_b32_e32 v108, 16, v168
	v_and_b32_e32 v109, 0xffff0000, v168
	v_pk_mul_f32 v[108:109], v[62:63], v[108:109] op_sel_hi:[0,1]
	v_mul_f32_e32 v121, v102, v62
	v_pk_fma_f32 v[118:119], v[118:119], v[60:61], v[108:109] op_sel_hi:[1,0,1]
	v_fma_f32 v120, v120, v60, v121
	v_readfirstlane_b32 s54, v40
	v_add_f32_e32 v39, s34, v40
	v_readlane_b32 s22, v174, 44
	v_max_f32_e32 v38, s40, v39
	v_readlane_b32 s32, v176, 44
	v_sub_f32_e32 v58, v39, v38
	v_sub_f32_e32 v59, s40, v38
	v_mul_f32_e32 v58, 0x3fb8aa3b, v58
	v_mul_f32_e32 v59, 0x3fb8aa3b, v59
	v_exp_f32_e32 v60, v58
	v_exp_f32_e32 v62, v59
	v_cvt_pk_bf16_f32 v122, v118, v119
	v_writelane_b32 v178, s54, 43
	global_store_dword v36, v122, s[6:7]
	s_add_u32 s6, s6, 0x20000
	s_addc_u32 s7, s7, 0
	global_store_dword v36, v120, s[10:11]
	s_add_u32 s10, s10, 0x800
	s_addc_u32 s11, s11, 0
	v_lshlrev_b32_e32 v108, 16, v169
	v_and_b32_e32 v109, 0xffff0000, v169
	v_pk_mul_f32 v[108:109], v[62:63], v[108:109] op_sel_hi:[0,1]
	v_mul_f32_e32 v121, v103, v62
	v_pk_fma_f32 v[118:119], v[118:119], v[60:61], v[108:109] op_sel_hi:[1,0,1]
	v_fma_f32 v120, v120, v60, v121
	v_readfirstlane_b32 s54, v38
	v_add_f32_e32 v39, s22, v38
	v_readlane_b32 s34, v174, 45
	v_max_f32_e32 v40, s32, v39
	v_readlane_b32 s40, v176, 45
	v_sub_f32_e32 v58, v39, v40
	v_sub_f32_e32 v59, s32, v40
	v_mul_f32_e32 v58, 0x3fb8aa3b, v58
	v_mul_f32_e32 v59, 0x3fb8aa3b, v59
	v_exp_f32_e32 v60, v58
	v_exp_f32_e32 v62, v59
	v_cvt_pk_bf16_f32 v122, v118, v119
	v_writelane_b32 v178, s54, 44
	global_store_dword v36, v122, s[6:7]
	s_add_u32 s6, s6, 0x20000
	s_addc_u32 s7, s7, 0
	global_store_dword v36, v120, s[10:11]
	s_add_u32 s10, s10, 0x800
	s_addc_u32 s11, s11, 0
	v_lshlrev_b32_e32 v108, 16, v170
	v_and_b32_e32 v109, 0xffff0000, v170
	v_pk_mul_f32 v[108:109], v[62:63], v[108:109] op_sel_hi:[0,1]
	v_mul_f32_e32 v121, v104, v62
	v_pk_fma_f32 v[118:119], v[118:119], v[60:61], v[108:109] op_sel_hi:[1,0,1]
	v_fma_f32 v120, v120, v60, v121
	v_readfirstlane_b32 s54, v40
	v_add_f32_e32 v39, s34, v40
	v_readlane_b32 s22, v174, 46
	v_max_f32_e32 v38, s40, v39
	v_readlane_b32 s32, v176, 46
	v_sub_f32_e32 v58, v39, v38
	v_sub_f32_e32 v59, s40, v38
	v_mul_f32_e32 v58, 0x3fb8aa3b, v58
	v_mul_f32_e32 v59, 0x3fb8aa3b, v59
	v_exp_f32_e32 v60, v58
	v_exp_f32_e32 v62, v59
	v_cvt_pk_bf16_f32 v122, v118, v119
	v_writelane_b32 v178, s54, 45
	global_store_dword v36, v122, s[6:7]
	s_add_u32 s6, s6, 0x20000
	s_addc_u32 s7, s7, 0
	global_store_dword v36, v120, s[10:11]
	s_add_u32 s10, s10, 0x800
	s_addc_u32 s11, s11, 0
	v_lshlrev_b32_e32 v108, 16, v171
	v_and_b32_e32 v109, 0xffff0000, v171
	v_pk_mul_f32 v[108:109], v[62:63], v[108:109] op_sel_hi:[0,1]
	v_mul_f32_e32 v121, v105, v62
	v_pk_fma_f32 v[118:119], v[118:119], v[60:61], v[108:109] op_sel_hi:[1,0,1]
	v_fma_f32 v120, v120, v60, v121
	v_readfirstlane_b32 s54, v38
	v_add_f32_e32 v39, s22, v38
	v_readlane_b32 s34, v174, 47
	v_max_f32_e32 v40, s32, v39
	v_readlane_b32 s40, v176, 47
	v_sub_f32_e32 v58, v39, v40
	v_sub_f32_e32 v59, s32, v40
	v_mul_f32_e32 v58, 0x3fb8aa3b, v58
	v_mul_f32_e32 v59, 0x3fb8aa3b, v59
	v_exp_f32_e32 v60, v58
	v_exp_f32_e32 v62, v59
	v_cvt_pk_bf16_f32 v122, v118, v119
	v_writelane_b32 v178, s54, 46
	global_store_dword v36, v122, s[6:7]
	s_add_u32 s6, s6, 0x20000
	s_addc_u32 s7, s7, 0
	global_store_dword v36, v120, s[10:11]
	s_add_u32 s10, s10, 0x800
	s_addc_u32 s11, s11, 0
	v_lshlrev_b32_e32 v108, 16, v172
	v_and_b32_e32 v109, 0xffff0000, v172
	v_pk_mul_f32 v[108:109], v[62:63], v[108:109] op_sel_hi:[0,1]
	v_mul_f32_e32 v121, v106, v62
	v_pk_fma_f32 v[118:119], v[118:119], v[60:61], v[108:109] op_sel_hi:[1,0,1]
	v_fma_f32 v120, v120, v60, v121
	v_readfirstlane_b32 s54, v40
	v_add_f32_e32 v39, s34, v40
	v_readlane_b32 s22, v174, 48
	v_max_f32_e32 v38, s40, v39
	v_readlane_b32 s32, v176, 48
	v_sub_f32_e32 v58, v39, v38
	v_sub_f32_e32 v59, s40, v38
	v_mul_f32_e32 v58, 0x3fb8aa3b, v58
	v_mul_f32_e32 v59, 0x3fb8aa3b, v59
	v_exp_f32_e32 v60, v58
	v_exp_f32_e32 v62, v59
	v_cvt_pk_bf16_f32 v122, v118, v119
	v_writelane_b32 v178, s54, 47
	global_store_dword v36, v122, s[6:7]
	s_add_u32 s6, s6, 0x20000
	s_addc_u32 s7, s7, 0
	global_store_dword v36, v120, s[10:11]
	s_add_u32 s10, s10, 0x800
	s_addc_u32 s11, s11, 0
	v_lshlrev_b32_e32 v108, 16, v173
	v_and_b32_e32 v109, 0xffff0000, v173
	v_pk_mul_f32 v[108:109], v[62:63], v[108:109] op_sel_hi:[0,1]
	v_mul_f32_e32 v121, v107, v62
	v_pk_fma_f32 v[118:119], v[118:119], v[60:61], v[108:109] op_sel_hi:[1,0,1]
	v_fma_f32 v120, v120, v60, v121
; __device__ __forceinline__ unsigned pk2(float lo, float hi) { f32x2_t v = {lo, hi}; bf16x2_t b = __builtin_convertvector(v, bf16x2_t); return __builtin_bit_cast(unsigned, b); }
; __device__ __forceinline__ float bflo(unsigned w) { return __uint_as_float(w << 16); }
; __device__ __forceinline__ float bfhi(unsigned w) { return __uint_as_float(w & 0xffff0000u); }
; __device__ __forceinline__ float fexp(float x) { return __builtin_amdgcn_exp2f(x * LOG2E); }
;     __device__ __forceinline__ float* MBM() const { return (float*)(ws + WS_MB); }
;     __device__ __forceinline__ float* MBB() const { return (float*)(ws + WS_MB) + (NSLOT_P + NSLOT_S); }
;     __device__ __forceinline__ float* MST() const { return (float*)(ws + WS_MB) + 2 * (NSLOT_P + NSLOT_S); }
; __device__ __forceinline__ void phase_scan(Ctx& C, int l, const bool st, LAS unsigned char* lds) {
;     ...
;         for (int cg0 = 0; cg0 < NPC; cg0 += 16) {
;             if (cg0 + 16 < NPC) {
; #pragma unroll
;                 for (int j = 0; j < 16; ++j) { nb[j] = base[(size_t)((b * NPC + cg0 + 16 + j) * 4 + h) * 8192]; fnb[j] = hn ? dnb[(size_t)((b * NPC + cg0 + 16 + j) * 4 + h) * 128] : 0.f; }
;             }
; #pragma unroll
;             for (int j = 0; j < 16; ++j) { const int slot = (b * NPC + cg0 + j) * 4 + h;
;                 const float Bc = C.MBB()[slot], Mc = C.MBM()[slot];
;                 const float mn = fmaxf(Bc + m, Mc), g = fexp(Bc + m - mn), f = fexp(Mc - mn);
;                 if (st) { base[(size_t)slot * 8192] = pk2(c0, c1); if (hn) { dnb[(size_t)slot * 128] = nn; if (p == 0) C.MST()[slot] = m; } }
;                 c0 = g * c0 + f * bflo(buf[j]); c1 = g * c1 + f * bfhi(buf[j]); nn = g * nn + f * fb[j]; m = mn; }
; #pragma unroll
;             for (int j = 0; j < 16; ++j) { buf[j] = nb[j]; fb[j] = fnb[j]; }
.Lscan_hn_b3:
	s_waitcnt vmcnt(32)
	global_load_dword v142, v36, s[4:5]
	s_add_u32 s4, s4, 0x20000
	s_addc_u32 s5, s5, 0
	global_load_dword v143, v36, s[4:5]
	s_add_u32 s4, s4, 0x20000
	s_addc_u32 s5, s5, 0
	global_load_dword v144, v36, s[4:5]
	s_add_u32 s4, s4, 0x20000
	s_addc_u32 s5, s5, 0
	global_load_dword v145, v36, s[4:5]
	s_add_u32 s4, s4, 0x20000
	s_addc_u32 s5, s5, 0
	global_load_dword v146, v36, s[4:5]
	s_add_u32 s4, s4, 0x20000
	s_addc_u32 s5, s5, 0
	global_load_dword v147, v36, s[4:5]
	s_add_u32 s4, s4, 0x20000
	s_addc_u32 s5, s5, 0
	global_load_dword v148, v36, s[4:5]
	s_add_u32 s4, s4, 0x20000
	s_addc_u32 s5, s5, 0
	global_load_dword v149, v36, s[4:5]
	s_add_u32 s4, s4, 0x20000
	s_addc_u32 s5, s5, 0
	global_load_dword v150, v36, s[4:5]
	s_add_u32 s4, s4, 0x20000
	s_addc_u32 s5, s5, 0
	global_load_dword v151, v36, s[4:5]
	s_add_u32 s4, s4, 0x20000
	s_addc_u32 s5, s5, 0
	global_load_dword v152, v36, s[4:5]
	s_add_u32 s4, s4, 0x20000
	s_addc_u32 s5, s5, 0
	global_load_dword v153, v36, s[4:5]
	s_add_u32 s4, s4, 0x20000
	s_addc_u32 s5, s5, 0
	global_load_dword v154, v36, s[4:5]
	s_add_u32 s4, s4, 0x20000
	s_addc_u32 s5, s5, 0
	global_load_dword v155, v36, s[4:5]
	s_add_u32 s4, s4, 0x20000
	s_addc_u32 s5, s5, 0
	global_load_dword v156, v36, s[4:5]
	s_add_u32 s4, s4, 0x20000
	s_addc_u32 s5, s5, 0
	global_load_dword v157, v36, s[4:5]
	s_add_u32 s4, s4, 0x20000
	s_addc_u32 s5, s5, 0
	global_load_dword v42, v36, s[8:9]
	s_add_u32 s8, s8, 0x800
	s_addc_u32 s9, s9, 0
	global_load_dword v43, v36, s[8:9]
	s_add_u32 s8, s8, 0x800
	s_addc_u32 s9, s9, 0
	global_load_dword v44, v36, s[8:9]
	s_add_u32 s8, s8, 0x800
	s_addc_u32 s9, s9, 0
	global_load_dword v45, v36, s[8:9]
	s_add_u32 s8, s8, 0x800
	s_addc_u32 s9, s9, 0
	global_load_dword v46, v36, s[8:9]
	s_add_u32 s8, s8, 0x800
	s_addc_u32 s9, s9, 0
	global_load_dword v47, v36, s[8:9]
	s_add_u32 s8, s8, 0x800
	s_addc_u32 s9, s9, 0
	global_load_dword v48, v36, s[8:9]
	s_add_u32 s8, s8, 0x800
	s_addc_u32 s9, s9, 0
	global_load_dword v49, v36, s[8:9]
	s_add_u32 s8, s8, 0x800
	s_addc_u32 s9, s9, 0
	global_load_dword v50, v36, s[8:9]
	s_add_u32 s8, s8, 0x800
	s_addc_u32 s9, s9, 0
	global_load_dword v51, v36, s[8:9]
	s_add_u32 s8, s8, 0x800
	s_addc_u32 s9, s9, 0
	global_load_dword v52, v36, s[8:9]
	s_add_u32 s8, s8, 0x800
	s_addc_u32 s9, s9, 0
	global_load_dword v53, v36, s[8:9]
	s_add_u32 s8, s8, 0x800
	s_addc_u32 s9, s9, 0
	global_load_dword v54, v36, s[8:9]
	s_add_u32 s8, s8, 0x800
	s_addc_u32 s9, s9, 0
	global_load_dword v55, v36, s[8:9]
	s_add_u32 s8, s8, 0x800
	s_addc_u32 s9, s9, 0
	global_load_dword v56, v36, s[8:9]
	s_add_u32 s8, s8, 0x800
	s_addc_u32 s9, s9, 0
	global_load_dword v57, v36, s[8:9]
	s_add_u32 s8, s8, 0x800
	s_addc_u32 s9, s9, 0
	v_readfirstlane_b32 s54, v38
	v_add_f32_e32 v39, s22, v38
	v_readlane_b32 s34, v174, 49
	v_max_f32_e32 v40, s32, v39
	v_readlane_b32 s40, v176, 49
	v_sub_f32_e32 v58, v39, v40
	v_sub_f32_e32 v59, s32, v40
	v_mul_f32_e32 v58, 0x3fb8aa3b, v58
	v_mul_f32_e32 v59, 0x3fb8aa3b, v59
	v_exp_f32_e32 v60, v58
	v_exp_f32_e32 v62, v59
	v_cvt_pk_bf16_f32 v122, v118, v119
	v_writelane_b32 v178, s54, 48
	global_store_dword v36, v122, s[6:7]
	s_add_u32 s6, s6, 0x20000
	s_addc_u32 s7, s7, 0
	global_store_dword v36, v120, s[10:11]
	s_add_u32 s10, s10, 0x800
	s_addc_u32 s11, s11, 0
	v_lshlrev_b32_e32 v108, 16, v126
	v_and_b32_e32 v109, 0xffff0000, v126
	v_pk_mul_f32 v[108:109], v[62:63], v[108:109] op_sel_hi:[0,1]
	v_mul_f32_e32 v121, v16, v62
	v_pk_fma_f32 v[118:119], v[118:119], v[60:61], v[108:109] op_sel_hi:[1,0,1]
	v_fma_f32 v120, v120, v60, v121
	v_readfirstlane_b32 s54, v40
	v_add_f32_e32 v39, s34, v40
	v_readlane_b32 s22, v174, 50
	v_max_f32_e32 v38, s40, v39
	v_readlane_b32 s32, v176, 50
	v_sub_f32_e32 v58, v39, v38
	v_sub_f32_e32 v59, s40, v38
	v_mul_f32_e32 v58, 0x3fb8aa3b, v58
	v_mul_f32_e32 v59, 0x3fb8aa3b, v59
	v_exp_f32_e32 v60, v58
	v_exp_f32_e32 v62, v59
	v_cvt_pk_bf16_f32 v122, v118, v119
	v_writelane_b32 v178, s54, 49
	global_store_dword v36, v122, s[6:7]
	s_add_u32 s6, s6, 0x20000
	s_addc_u32 s7, s7, 0
	global_store_dword v36, v120, s[10:11]
	s_add_u32 s10, s10, 0x800
	s_addc_u32 s11, s11, 0
	v_lshlrev_b32_e32 v108, 16, v127
	v_and_b32_e32 v109, 0xffff0000, v127
	v_pk_mul_f32 v[108:109], v[62:63], v[108:109] op_sel_hi:[0,1]
	v_mul_f32_e32 v121, v17, v62
	v_pk_fma_f32 v[118:119], v[118:119], v[60:61], v[108:109] op_sel_hi:[1,0,1]
	v_fma_f32 v120, v120, v60, v121
	v_readfirstlane_b32 s54, v38
	v_add_f32_e32 v39, s22, v38
	v_readlane_b32 s34, v174, 51
	v_max_f32_e32 v40, s32, v39
	v_readlane_b32 s40, v176, 51
	v_sub_f32_e32 v58, v39, v40
	v_sub_f32_e32 v59, s32, v40
	v_mul_f32_e32 v58, 0x3fb8aa3b, v58
	v_mul_f32_e32 v59, 0x3fb8aa3b, v59
	v_exp_f32_e32 v60, v58
	v_exp_f32_e32 v62, v59
	v_cvt_pk_bf16_f32 v122, v118, v119
	v_writelane_b32 v178, s54, 50
	global_store_dword v36, v122, s[6:7]
	s_add_u32 s6, s6, 0x20000
	s_addc_u32 s7, s7, 0
	global_store_dword v36, v120, s[10:11]
	s_add_u32 s10, s10, 0x800
	s_addc_u32 s11, s11, 0
	v_lshlrev_b32_e32 v108, 16, v128
	v_and_b32_e32 v109, 0xffff0000, v128
	v_pk_mul_f32 v[108:109], v[62:63], v[108:109] op_sel_hi:[0,1]
	v_mul_f32_e32 v121, v18, v62
	v_pk_fma_f32 v[118:119], v[118:119], v[60:61], v[108:109] op_sel_hi:[1,0,1]
	v_fma_f32 v120, v120, v60, v121
	v_readfirstlane_b32 s54, v40
	v_add_f32_e32 v39, s34, v40
	v_readlane_b32 s22, v174, 52
	v_max_f32_e32 v38, s40, v39
	v_readlane_b32 s32, v176, 52
	v_sub_f32_e32 v58, v39, v38
	v_sub_f32_e32 v59, s40, v38
	v_mul_f32_e32 v58, 0x3fb8aa3b, v58
	v_mul_f32_e32 v59, 0x3fb8aa3b, v59
	v_exp_f32_e32 v60, v58
	v_exp_f32_e32 v62, v59
	v_cvt_pk_bf16_f32 v122, v118, v119
; __device__ __forceinline__ unsigned pk2(float lo, float hi) { f32x2_t v = {lo, hi}; bf16x2_t b = __builtin_convertvector(v, bf16x2_t); return __builtin_bit_cast(unsigned, b); }
; __device__ __forceinline__ float bflo(unsigned w) { return __uint_as_float(w << 16); }
; __device__ __forceinline__ float bfhi(unsigned w) { return __uint_as_float(w & 0xffff0000u); }
; __device__ __forceinline__ float fexp(float x) { return __builtin_amdgcn_exp2f(x * LOG2E); }
;     __device__ __forceinline__ float* MBM() const { return (float*)(ws + WS_MB); }
;     __device__ __forceinline__ float* MBB() const { return (float*)(ws + WS_MB) + (NSLOT_P + NSLOT_S); }
;     __device__ __forceinline__ float* MST() const { return (float*)(ws + WS_MB) + 2 * (NSLOT_P + NSLOT_S); }
; __device__ __forceinline__ void phase_scan(Ctx& C, int l, const bool st, LAS unsigned char* lds) {
;     ...
;         for (int cg0 = 0; cg0 < NPC; cg0 += 16) {
;             if (cg0 + 16 < NPC) {
; #pragma unroll
;                 for (int j = 0; j < 16; ++j) { nb[j] = base[(size_t)((b * NPC + cg0 + 16 + j) * 4 + h) * 8192]; fnb[j] = hn ? dnb[(size_t)((b * NPC + cg0 + 16 + j) * 4 + h) * 128] : 0.f; }
;             }
; #pragma unroll
;             for (int j = 0; j < 16; ++j) { const int slot = (b * NPC + cg0 + j) * 4 + h;
;                 const float Bc = C.MBB()[slot], Mc = C.MBM()[slot];
;                 const float mn = fmaxf(Bc + m, Mc), g = fexp(Bc + m - mn), f = fexp(Mc - mn);
;                 if (st) { base[(size_t)slot * 8192] = pk2(c0, c1); if (hn) { dnb[(size_t)slot * 128] = nn; if (p == 0) C.MST()[slot] = m; } }
;                 c0 = g * c0 + f * bflo(buf[j]); c1 = g * c1 + f * bfhi(buf[j]); nn = g * nn + f * fb[j]; m = mn; }
; #pragma unroll
;             for (int j = 0; j < 16; ++j) { buf[j] = nb[j]; fb[j] = fnb[j]; }
	v_writelane_b32 v178, s54, 51
	global_store_dword v36, v122, s[6:7]
	s_add_u32 s6, s6, 0x20000
	s_addc_u32 s7, s7, 0
	global_store_dword v36, v120, s[10:11]
	s_add_u32 s10, s10, 0x800
	s_addc_u32 s11, s11, 0
	v_lshlrev_b32_e32 v108, 16, v129
	v_and_b32_e32 v109, 0xffff0000, v129
	v_pk_mul_f32 v[108:109], v[62:63], v[108:109] op_sel_hi:[0,1]
	v_mul_f32_e32 v121, v19, v62
	v_pk_fma_f32 v[118:119], v[118:119], v[60:61], v[108:109] op_sel_hi:[1,0,1]
	v_fma_f32 v120, v120, v60, v121
	v_readfirstlane_b32 s54, v38
	v_add_f32_e32 v39, s22, v38
	v_readlane_b32 s34, v174, 53
	v_max_f32_e32 v40, s32, v39
	v_readlane_b32 s40, v176, 53
	v_sub_f32_e32 v58, v39, v40
	v_sub_f32_e32 v59, s32, v40
	v_mul_f32_e32 v58, 0x3fb8aa3b, v58
	v_mul_f32_e32 v59, 0x3fb8aa3b, v59
	v_exp_f32_e32 v60, v58
	v_exp_f32_e32 v62, v59
	v_cvt_pk_bf16_f32 v122, v118, v119
	v_writelane_b32 v178, s54, 52
	global_store_dword v36, v122, s[6:7]
	s_add_u32 s6, s6, 0x20000
	s_addc_u32 s7, s7, 0
	global_store_dword v36, v120, s[10:11]
	s_add_u32 s10, s10, 0x800
	s_addc_u32 s11, s11, 0
	v_lshlrev_b32_e32 v108, 16, v130
	v_and_b32_e32 v109, 0xffff0000, v130
	v_pk_mul_f32 v[108:109], v[62:63], v[108:109] op_sel_hi:[0,1]
	v_mul_f32_e32 v121, v20, v62
	v_pk_fma_f32 v[118:119], v[118:119], v[60:61], v[108:109] op_sel_hi:[1,0,1]
	v_fma_f32 v120, v120, v60, v121
	v_readfirstlane_b32 s54, v40
	v_add_f32_e32 v39, s34, v40
	v_readlane_b32 s22, v174, 54
	v_max_f32_e32 v38, s40, v39
	v_readlane_b32 s32, v176, 54
	v_sub_f32_e32 v58, v39, v38
	v_sub_f32_e32 v59, s40, v38
	v_mul_f32_e32 v58, 0x3fb8aa3b, v58
	v_mul_f32_e32 v59, 0x3fb8aa3b, v59
	v_exp_f32_e32 v60, v58
	v_exp_f32_e32 v62, v59
	v_cvt_pk_bf16_f32 v122, v118, v119
	v_writelane_b32 v178, s54, 53
	global_store_dword v36, v122, s[6:7]
	s_add_u32 s6, s6, 0x20000
	s_addc_u32 s7, s7, 0
	global_store_dword v36, v120, s[10:11]
	s_add_u32 s10, s10, 0x800
	s_addc_u32 s11, s11, 0
	v_lshlrev_b32_e32 v108, 16, v131
	v_and_b32_e32 v109, 0xffff0000, v131
	v_pk_mul_f32 v[108:109], v[62:63], v[108:109] op_sel_hi:[0,1]
	v_mul_f32_e32 v121, v21, v62
	v_pk_fma_f32 v[118:119], v[118:119], v[60:61], v[108:109] op_sel_hi:[1,0,1]
	v_fma_f32 v120, v120, v60, v121
	v_readfirstlane_b32 s54, v38
	v_add_f32_e32 v39, s22, v38
	v_readlane_b32 s34, v174, 55
	v_max_f32_e32 v40, s32, v39
	v_readlane_b32 s40, v176, 55
	v_sub_f32_e32 v58, v39, v40
	v_sub_f32_e32 v59, s32, v40
	v_mul_f32_e32 v58, 0x3fb8aa3b, v58
	v_mul_f32_e32 v59, 0x3fb8aa3b, v59
	v_exp_f32_e32 v60, v58
	v_exp_f32_e32 v62, v59
	v_cvt_pk_bf16_f32 v122, v118, v119
	v_writelane_b32 v178, s54, 54
	global_store_dword v36, v122, s[6:7]
	s_add_u32 s6, s6, 0x20000
	s_addc_u32 s7, s7, 0
	global_store_dword v36, v120, s[10:11]
	s_add_u32 s10, s10, 0x800
	s_addc_u32 s11, s11, 0
	v_lshlrev_b32_e32 v108, 16, v132
	v_and_b32_e32 v109, 0xffff0000, v132
	v_pk_mul_f32 v[108:109], v[62:63], v[108:109] op_sel_hi:[0,1]
	v_mul_f32_e32 v121, v22, v62
	v_pk_fma_f32 v[118:119], v[118:119], v[60:61], v[108:109] op_sel_hi:[1,0,1]
	v_fma_f32 v120, v120, v60, v121
	v_readfirstlane_b32 s54, v40
	v_add_f32_e32 v39, s34, v40
	v_readlane_b32 s22, v174, 56
	v_max_f32_e32 v38, s40, v39
	v_readlane_b32 s32, v176, 56
	v_sub_f32_e32 v58, v39, v38
	v_sub_f32_e32 v59, s40, v38
	v_mul_f32_e32 v58, 0x3fb8aa3b, v58
	v_mul_f32_e32 v59, 0x3fb8aa3b, v59
	v_exp_f32_e32 v60, v58
	v_exp_f32_e32 v62, v59
	v_cvt_pk_bf16_f32 v122, v118, v119
	v_writelane_b32 v178, s54, 55
	global_store_dword v36, v122, s[6:7]
	s_add_u32 s6, s6, 0x20000
	s_addc_u32 s7, s7, 0
	global_store_dword v36, v120, s[10:11]
	s_add_u32 s10, s10, 0x800
	s_addc_u32 s11, s11, 0
	v_lshlrev_b32_e32 v108, 16, v133
	v_and_b32_e32 v109, 0xffff0000, v133
	v_pk_mul_f32 v[108:109], v[62:63], v[108:109] op_sel_hi:[0,1]
	v_mul_f32_e32 v121, v23, v62
	v_pk_fma_f32 v[118:119], v[118:119], v[60:61], v[108:109] op_sel_hi:[1,0,1]
	v_fma_f32 v120, v120, v60, v121
	v_readfirstlane_b32 s54, v38
	v_add_f32_e32 v39, s22, v38
	v_readlane_b32 s34, v174, 57
	v_max_f32_e32 v40, s32, v39
	v_readlane_b32 s40, v176, 57
	v_sub_f32_e32 v58, v39, v40
	v_sub_f32_e32 v59, s32, v40
	v_mul_f32_e32 v58, 0x3fb8aa3b, v58
	v_mul_f32_e32 v59, 0x3fb8aa3b, v59
	v_exp_f32_e32 v60, v58
	v_exp_f32_e32 v62, v59
	v_cvt_pk_bf16_f32 v122, v118, v119
	v_writelane_b32 v178, s54, 56
	global_store_dword v36, v122, s[6:7]
	s_add_u32 s6, s6, 0x20000
	s_addc_u32 s7, s7, 0
	global_store_dword v36, v120, s[10:11]
	s_add_u32 s10, s10, 0x800
	s_addc_u32 s11, s11, 0
	v_lshlrev_b32_e32 v108, 16, v134
	v_and_b32_e32 v109, 0xffff0000, v134
	v_pk_mul_f32 v[108:109], v[62:63], v[108:109] op_sel_hi:[0,1]
	v_mul_f32_e32 v121, v24, v62
	v_pk_fma_f32 v[118:119], v[118:119], v[60:61], v[108:109] op_sel_hi:[1,0,1]
	v_fma_f32 v120, v120, v60, v121
	v_readfirstlane_b32 s54, v40
	v_add_f32_e32 v39, s34, v40
	v_readlane_b32 s22, v174, 58
	v_max_f32_e32 v38, s40, v39
	v_readlane_b32 s32, v176, 58
	v_sub_f32_e32 v58, v39, v38
	v_sub_f32_e32 v59, s40, v38
	v_mul_f32_e32 v58, 0x3fb8aa3b, v58
	v_mul_f32_e32 v59, 0x3fb8aa3b, v59
	v_exp_f32_e32 v60, v58
	v_exp_f32_e32 v62, v59
	v_cvt_pk_bf16_f32 v122, v118, v119
	v_writelane_b32 v178, s54, 57
	global_store_dword v36, v122, s[6:7]
	s_add_u32 s6, s6, 0x20000
	s_addc_u32 s7, s7, 0
	global_store_dword v36, v120, s[10:11]
	s_add_u32 s10, s10, 0x800
	s_addc_u32 s11, s11, 0
	v_lshlrev_b32_e32 v108, 16, v135
	v_and_b32_e32 v109, 0xffff0000, v135
	v_pk_mul_f32 v[108:109], v[62:63], v[108:109] op_sel_hi:[0,1]
	v_mul_f32_e32 v121, v25, v62
	v_pk_fma_f32 v[118:119], v[118:119], v[60:61], v[108:109] op_sel_hi:[1,0,1]
	v_fma_f32 v120, v120, v60, v121
	v_readfirstlane_b32 s54, v38
	v_add_f32_e32 v39, s22, v38
	v_readlane_b32 s34, v174, 59
; __device__ __forceinline__ unsigned pk2(float lo, float hi) { f32x2_t v = {lo, hi}; bf16x2_t b = __builtin_convertvector(v, bf16x2_t); return __builtin_bit_cast(unsigned, b); }
; __device__ __forceinline__ float bflo(unsigned w) { return __uint_as_float(w << 16); }
; __device__ __forceinline__ float bfhi(unsigned w) { return __uint_as_float(w & 0xffff0000u); }
; __device__ __forceinline__ float fexp(float x) { return __builtin_amdgcn_exp2f(x * LOG2E); }
;     __device__ __forceinline__ float* MBM() const { return (float*)(ws + WS_MB); }
;     __device__ __forceinline__ float* MBB() const { return (float*)(ws + WS_MB) + (NSLOT_P + NSLOT_S); }
;     __device__ __forceinline__ float* MST() const { return (float*)(ws + WS_MB) + 2 * (NSLOT_P + NSLOT_S); }
; __device__ __forceinline__ void phase_scan(Ctx& C, int l, const bool st, LAS unsigned char* lds) {
;     ...
;         for (int cg0 = 0; cg0 < NPC; cg0 += 16) {
;             if (cg0 + 16 < NPC) {
; #pragma unroll
;                 for (int j = 0; j < 16; ++j) { nb[j] = base[(size_t)((b * NPC + cg0 + 16 + j) * 4 + h) * 8192]; fnb[j] = hn ? dnb[(size_t)((b * NPC + cg0 + 16 + j) * 4 + h) * 128] : 0.f; }
;             }
; #pragma unroll
;             for (int j = 0; j < 16; ++j) { const int slot = (b * NPC + cg0 + j) * 4 + h;
;                 const float Bc = C.MBB()[slot], Mc = C.MBM()[slot];
;                 const float mn = fmaxf(Bc + m, Mc), g = fexp(Bc + m - mn), f = fexp(Mc - mn);
;                 if (st) { base[(size_t)slot * 8192] = pk2(c0, c1); if (hn) { dnb[(size_t)slot * 128] = nn; if (p == 0) C.MST()[slot] = m; } }
;                 c0 = g * c0 + f * bflo(buf[j]); c1 = g * c1 + f * bfhi(buf[j]); nn = g * nn + f * fb[j]; m = mn; }
; #pragma unroll
;             for (int j = 0; j < 16; ++j) { buf[j] = nb[j]; fb[j] = fnb[j]; }
	v_max_f32_e32 v40, s32, v39
	v_readlane_b32 s40, v176, 59
	v_sub_f32_e32 v58, v39, v40
	v_sub_f32_e32 v59, s32, v40
	v_mul_f32_e32 v58, 0x3fb8aa3b, v58
	v_mul_f32_e32 v59, 0x3fb8aa3b, v59
	v_exp_f32_e32 v60, v58
	v_exp_f32_e32 v62, v59
	v_cvt_pk_bf16_f32 v122, v118, v119
	v_writelane_b32 v178, s54, 58
	global_store_dword v36, v122, s[6:7]
	s_add_u32 s6, s6, 0x20000
	s_addc_u32 s7, s7, 0
	global_store_dword v36, v120, s[10:11]
	s_add_u32 s10, s10, 0x800
	s_addc_u32 s11, s11, 0
	v_lshlrev_b32_e32 v108, 16, v136
	v_and_b32_e32 v109, 0xffff0000, v136
	v_pk_mul_f32 v[108:109], v[62:63], v[108:109] op_sel_hi:[0,1]
	v_mul_f32_e32 v121, v26, v62
	v_pk_fma_f32 v[118:119], v[118:119], v[60:61], v[108:109] op_sel_hi:[1,0,1]
	v_fma_f32 v120, v120, v60, v121
	v_readfirstlane_b32 s54, v40
	v_add_f32_e32 v39, s34, v40
	v_readlane_b32 s22, v174, 60
	v_max_f32_e32 v38, s40, v39
	v_readlane_b32 s32, v176, 60
	v_sub_f32_e32 v58, v39, v38
	v_sub_f32_e32 v59, s40, v38
	v_mul_f32_e32 v58, 0x3fb8aa3b, v58
	v_mul_f32_e32 v59, 0x3fb8aa3b, v59
	v_exp_f32_e32 v60, v58
	v_exp_f32_e32 v62, v59
	v_cvt_pk_bf16_f32 v122, v118, v119
	v_writelane_b32 v178, s54, 59
	global_store_dword v36, v122, s[6:7]
	s_add_u32 s6, s6, 0x20000
	s_addc_u32 s7, s7, 0
	global_store_dword v36, v120, s[10:11]
	s_add_u32 s10, s10, 0x800
	s_addc_u32 s11, s11, 0
	v_lshlrev_b32_e32 v108, 16, v137
	v_and_b32_e32 v109, 0xffff0000, v137
	v_pk_mul_f32 v[108:109], v[62:63], v[108:109] op_sel_hi:[0,1]
	v_mul_f32_e32 v121, v27, v62
	v_pk_fma_f32 v[118:119], v[118:119], v[60:61], v[108:109] op_sel_hi:[1,0,1]
	v_fma_f32 v120, v120, v60, v121
	v_readfirstlane_b32 s54, v38
	v_add_f32_e32 v39, s22, v38
	v_readlane_b32 s34, v174, 61
	v_max_f32_e32 v40, s32, v39
	v_readlane_b32 s40, v176, 61
	v_sub_f32_e32 v58, v39, v40
	v_sub_f32_e32 v59, s32, v40
	v_mul_f32_e32 v58, 0x3fb8aa3b, v58
	v_mul_f32_e32 v59, 0x3fb8aa3b, v59
	v_exp_f32_e32 v60, v58
	v_exp_f32_e32 v62, v59
	v_cvt_pk_bf16_f32 v122, v118, v119
	v_writelane_b32 v178, s54, 60
	global_store_dword v36, v122, s[6:7]
	s_add_u32 s6, s6, 0x20000
	s_addc_u32 s7, s7, 0
	global_store_dword v36, v120, s[10:11]
	s_add_u32 s10, s10, 0x800
	s_addc_u32 s11, s11, 0
	v_lshlrev_b32_e32 v108, 16, v138
	v_and_b32_e32 v109, 0xffff0000, v138
	v_pk_mul_f32 v[108:109], v[62:63], v[108:109] op_sel_hi:[0,1]
	v_mul_f32_e32 v121, v28, v62
	v_pk_fma_f32 v[118:119], v[118:119], v[60:61], v[108:109] op_sel_hi:[1,0,1]
	v_fma_f32 v120, v120, v60, v121
	v_readfirstlane_b32 s54, v40
	v_add_f32_e32 v39, s34, v40
	v_readlane_b32 s22, v174, 62
	v_max_f32_e32 v38, s40, v39
	v_readlane_b32 s32, v176, 62
	v_sub_f32_e32 v58, v39, v38
	v_sub_f32_e32 v59, s40, v38
	v_mul_f32_e32 v58, 0x3fb8aa3b, v58
	v_mul_f32_e32 v59, 0x3fb8aa3b, v59
	v_exp_f32_e32 v60, v58
	v_exp_f32_e32 v62, v59
	v_cvt_pk_bf16_f32 v122, v118, v119
	v_writelane_b32 v178, s54, 61
	global_store_dword v36, v122, s[6:7]
	s_add_u32 s6, s6, 0x20000
	s_addc_u32 s7, s7, 0
	global_store_dword v36, v120, s[10:11]
	s_add_u32 s10, s10, 0x800
	s_addc_u32 s11, s11, 0
	v_lshlrev_b32_e32 v108, 16, v139
	v_and_b32_e32 v109, 0xffff0000, v139
	v_pk_mul_f32 v[108:109], v[62:63], v[108:109] op_sel_hi:[0,1]
	v_mul_f32_e32 v121, v29, v62
	v_pk_fma_f32 v[118:119], v[118:119], v[60:61], v[108:109] op_sel_hi:[1,0,1]
	v_fma_f32 v120, v120, v60, v121
	v_readfirstlane_b32 s54, v38
	v_add_f32_e32 v39, s22, v38
	v_readlane_b32 s34, v174, 63
	v_max_f32_e32 v40, s32, v39
	v_readlane_b32 s40, v176, 63
	v_sub_f32_e32 v58, v39, v40
	v_sub_f32_e32 v59, s32, v40
	v_mul_f32_e32 v58, 0x3fb8aa3b, v58
	v_mul_f32_e32 v59, 0x3fb8aa3b, v59
	v_exp_f32_e32 v60, v58
	v_exp_f32_e32 v62, v59
	v_cvt_pk_bf16_f32 v122, v118, v119
	v_writelane_b32 v178, s54, 62
	global_store_dword v36, v122, s[6:7]
	s_add_u32 s6, s6, 0x20000
	s_addc_u32 s7, s7, 0
	global_store_dword v36, v120, s[10:11]
	s_add_u32 s10, s10, 0x800
	s_addc_u32 s11, s11, 0
	v_lshlrev_b32_e32 v108, 16, v140
	v_and_b32_e32 v109, 0xffff0000, v140
	v_pk_mul_f32 v[108:109], v[62:63], v[108:109] op_sel_hi:[0,1]
	v_mul_f32_e32 v121, v30, v62
	v_pk_fma_f32 v[118:119], v[118:119], v[60:61], v[108:109] op_sel_hi:[1,0,1]
	v_fma_f32 v120, v120, v60, v121
	v_readfirstlane_b32 s54, v40
	v_add_f32_e32 v39, s34, v40
	v_readlane_b32 s22, v175, 0
	v_max_f32_e32 v38, s40, v39
	v_readlane_b32 s32, v177, 0
	v_sub_f32_e32 v58, v39, v38
	v_sub_f32_e32 v59, s40, v38
	v_mul_f32_e32 v58, 0x3fb8aa3b, v58
	v_mul_f32_e32 v59, 0x3fb8aa3b, v59
	v_exp_f32_e32 v60, v58
	v_exp_f32_e32 v62, v59
	v_cvt_pk_bf16_f32 v122, v118, v119
	v_writelane_b32 v178, s54, 63
	global_store_dword v36, v122, s[6:7]
	s_add_u32 s6, s6, 0x20000
	s_addc_u32 s7, s7, 0
	global_store_dword v36, v120, s[10:11]
	s_add_u32 s10, s10, 0x800
	s_addc_u32 s11, s11, 0
	v_lshlrev_b32_e32 v108, 16, v141
	v_and_b32_e32 v109, 0xffff0000, v141
	v_pk_mul_f32 v[108:109], v[62:63], v[108:109] op_sel_hi:[0,1]
	v_mul_f32_e32 v121, v31, v62
	v_pk_fma_f32 v[118:119], v[118:119], v[60:61], v[108:109] op_sel_hi:[1,0,1]
	v_fma_f32 v120, v120, v60, v121
; __device__ __forceinline__ unsigned pk2(float lo, float hi) { f32x2_t v = {lo, hi}; bf16x2_t b = __builtin_convertvector(v, bf16x2_t); return __builtin_bit_cast(unsigned, b); }
; __device__ __forceinline__ float bflo(unsigned w) { return __uint_as_float(w << 16); }
; __device__ __forceinline__ float bfhi(unsigned w) { return __uint_as_float(w & 0xffff0000u); }
; __device__ __forceinline__ float fexp(float x) { return __builtin_amdgcn_exp2f(x * LOG2E); }
;     __device__ __forceinline__ float* MBM() const { return (float*)(ws + WS_MB); }
;     __device__ __forceinline__ float* MBB() const { return (float*)(ws + WS_MB) + (NSLOT_P + NSLOT_S); }
;     __device__ __forceinline__ float* MST() const { return (float*)(ws + WS_MB) + 2 * (NSLOT_P + NSLOT_S); }
; __device__ __forceinline__ void phase_scan(Ctx& C, int l, const bool st, LAS unsigned char* lds) {
;     ...
;         for (int cg0 = 0; cg0 < NPC; cg0 += 16) {
;             if (cg0 + 16 < NPC) {
; #pragma unroll
;                 for (int j = 0; j < 16; ++j) { nb[j] = base[(size_t)((b * NPC + cg0 + 16 + j) * 4 + h) * 8192]; fnb[j] = hn ? dnb[(size_t)((b * NPC + cg0 + 16 + j) * 4 + h) * 128] : 0.f; }
;             }
; #pragma unroll
;             for (int j = 0; j < 16; ++j) { const int slot = (b * NPC + cg0 + j) * 4 + h;
;                 const float Bc = C.MBB()[slot], Mc = C.MBM()[slot];
;                 const float mn = fmaxf(Bc + m, Mc), g = fexp(Bc + m - mn), f = fexp(Mc - mn);
;                 if (st) { base[(size_t)slot * 8192] = pk2(c0, c1); if (hn) { dnb[(size_t)slot * 128] = nn; if (p == 0) C.MST()[slot] = m; } }
;                 c0 = g * c0 + f * bflo(buf[j]); c1 = g * c1 + f * bfhi(buf[j]); nn = g * nn + f * fb[j]; m = mn; }
; #pragma unroll
;             for (int j = 0; j < 16; ++j) { buf[j] = nb[j]; fb[j] = fnb[j]; }
.Lscan_hn_b4:
	s_waitcnt vmcnt(32)
	global_load_dword v158, v36, s[4:5]
	s_add_u32 s4, s4, 0x20000
	s_addc_u32 s5, s5, 0
	global_load_dword v159, v36, s[4:5]
	s_add_u32 s4, s4, 0x20000
	s_addc_u32 s5, s5, 0
	global_load_dword v160, v36, s[4:5]
	s_add_u32 s4, s4, 0x20000
	s_addc_u32 s5, s5, 0
	global_load_dword v161, v36, s[4:5]
	s_add_u32 s4, s4, 0x20000
	s_addc_u32 s5, s5, 0
	global_load_dword v162, v36, s[4:5]
	s_add_u32 s4, s4, 0x20000
	s_addc_u32 s5, s5, 0
	global_load_dword v163, v36, s[4:5]
	s_add_u32 s4, s4, 0x20000
	s_addc_u32 s5, s5, 0
	global_load_dword v164, v36, s[4:5]
	s_add_u32 s4, s4, 0x20000
	s_addc_u32 s5, s5, 0
	global_load_dword v165, v36, s[4:5]
	s_add_u32 s4, s4, 0x20000
	s_addc_u32 s5, s5, 0
	global_load_dword v166, v36, s[4:5]
	s_add_u32 s4, s4, 0x20000
	s_addc_u32 s5, s5, 0
	global_load_dword v167, v36, s[4:5]
	s_add_u32 s4, s4, 0x20000
	s_addc_u32 s5, s5, 0
	global_load_dword v168, v36, s[4:5]
	s_add_u32 s4, s4, 0x20000
	s_addc_u32 s5, s5, 0
	global_load_dword v169, v36, s[4:5]
	s_add_u32 s4, s4, 0x20000
	s_addc_u32 s5, s5, 0
	global_load_dword v170, v36, s[4:5]
	s_add_u32 s4, s4, 0x20000
	s_addc_u32 s5, s5, 0
	global_load_dword v171, v36, s[4:5]
	s_add_u32 s4, s4, 0x20000
	s_addc_u32 s5, s5, 0
	global_load_dword v172, v36, s[4:5]
	s_add_u32 s4, s4, 0x20000
	s_addc_u32 s5, s5, 0
	global_load_dword v173, v36, s[4:5]
	s_add_u32 s4, s4, 0x20000
	s_addc_u32 s5, s5, 0
	global_load_dword v92, v36, s[8:9]
	s_add_u32 s8, s8, 0x800
	s_addc_u32 s9, s9, 0
	global_load_dword v93, v36, s[8:9]
	s_add_u32 s8, s8, 0x800
	s_addc_u32 s9, s9, 0
	global_load_dword v94, v36, s[8:9]
	s_add_u32 s8, s8, 0x800
	s_addc_u32 s9, s9, 0
	global_load_dword v95, v36, s[8:9]
	s_add_u32 s8, s8, 0x800
	s_addc_u32 s9, s9, 0
	global_load_dword v96, v36, s[8:9]
	s_add_u32 s8, s8, 0x800
	s_addc_u32 s9, s9, 0
	global_load_dword v97, v36, s[8:9]
	s_add_u32 s8, s8, 0x800
	s_addc_u32 s9, s9, 0
	global_load_dword v98, v36, s[8:9]
	s_add_u32 s8, s8, 0x800
	s_addc_u32 s9, s9, 0
	global_load_dword v99, v36, s[8:9]
	s_add_u32 s8, s8, 0x800
	s_addc_u32 s9, s9, 0
	global_load_dword v100, v36, s[8:9]
	s_add_u32 s8, s8, 0x800
	s_addc_u32 s9, s9, 0
	global_load_dword v101, v36, s[8:9]
	s_add_u32 s8, s8, 0x800
	s_addc_u32 s9, s9, 0
	global_load_dword v102, v36, s[8:9]
	s_add_u32 s8, s8, 0x800
	s_addc_u32 s9, s9, 0
	global_load_dword v103, v36, s[8:9]
	s_add_u32 s8, s8, 0x800
	s_addc_u32 s9, s9, 0
	global_load_dword v104, v36, s[8:9]
	s_add_u32 s8, s8, 0x800
	s_addc_u32 s9, s9, 0
	global_load_dword v105, v36, s[8:9]
	s_add_u32 s8, s8, 0x800
	s_addc_u32 s9, s9, 0
	global_load_dword v106, v36, s[8:9]
	s_add_u32 s8, s8, 0x800
	s_addc_u32 s9, s9, 0
	global_load_dword v107, v36, s[8:9]
	s_add_u32 s8, s8, 0x800
	s_addc_u32 s9, s9, 0
	v_readfirstlane_b32 s54, v38
	v_add_f32_e32 v39, s22, v38
	v_readlane_b32 s34, v175, 1
	v_max_f32_e32 v40, s32, v39
	v_readlane_b32 s40, v177, 1
	v_sub_f32_e32 v58, v39, v40
	v_sub_f32_e32 v59, s32, v40
	v_mul_f32_e32 v58, 0x3fb8aa3b, v58
	v_mul_f32_e32 v59, 0x3fb8aa3b, v59
	v_exp_f32_e32 v60, v58
	v_exp_f32_e32 v62, v59
	v_cvt_pk_bf16_f32 v122, v118, v119
	v_writelane_b32 v179, s54, 0
	global_store_dword v36, v122, s[6:7]
	s_add_u32 s6, s6, 0x20000
	s_addc_u32 s7, s7, 0
	global_store_dword v36, v120, s[10:11]
	s_add_u32 s10, s10, 0x800
	s_addc_u32 s11, s11, 0
	v_lshlrev_b32_e32 v108, 16, v142
	v_and_b32_e32 v109, 0xffff0000, v142
	v_pk_mul_f32 v[108:109], v[62:63], v[108:109] op_sel_hi:[0,1]
	v_mul_f32_e32 v121, v42, v62
	v_pk_fma_f32 v[118:119], v[118:119], v[60:61], v[108:109] op_sel_hi:[1,0,1]
	v_fma_f32 v120, v120, v60, v121
	v_readfirstlane_b32 s54, v40
	v_add_f32_e32 v39, s34, v40
	v_readlane_b32 s22, v175, 2
	v_max_f32_e32 v38, s40, v39
	v_readlane_b32 s32, v177, 2
	v_sub_f32_e32 v58, v39, v38
	v_sub_f32_e32 v59, s40, v38
	v_mul_f32_e32 v58, 0x3fb8aa3b, v58
	v_mul_f32_e32 v59, 0x3fb8aa3b, v59
	v_exp_f32_e32 v60, v58
	v_exp_f32_e32 v62, v59
	v_cvt_pk_bf16_f32 v122, v118, v119
	v_writelane_b32 v179, s54, 1
	global_store_dword v36, v122, s[6:7]
	s_add_u32 s6, s6, 0x20000
	s_addc_u32 s7, s7, 0
	global_store_dword v36, v120, s[10:11]
	s_add_u32 s10, s10, 0x800
	s_addc_u32 s11, s11, 0
	v_lshlrev_b32_e32 v108, 16, v143
	v_and_b32_e32 v109, 0xffff0000, v143
	v_pk_mul_f32 v[108:109], v[62:63], v[108:109] op_sel_hi:[0,1]
	v_mul_f32_e32 v121, v43, v62
	v_pk_fma_f32 v[118:119], v[118:119], v[60:61], v[108:109] op_sel_hi:[1,0,1]
	v_fma_f32 v120, v120, v60, v121
	v_readfirstlane_b32 s54, v38
	v_add_f32_e32 v39, s22, v38
	v_readlane_b32 s34, v175, 3
	v_max_f32_e32 v40, s32, v39
	v_readlane_b32 s40, v177, 3
	v_sub_f32_e32 v58, v39, v40
	v_sub_f32_e32 v59, s32, v40
	v_mul_f32_e32 v58, 0x3fb8aa3b, v58
	v_mul_f32_e32 v59, 0x3fb8aa3b, v59
	v_exp_f32_e32 v60, v58
	v_exp_f32_e32 v62, v59
	v_cvt_pk_bf16_f32 v122, v118, v119
	v_writelane_b32 v179, s54, 2
	global_store_dword v36, v122, s[6:7]
	s_add_u32 s6, s6, 0x20000
	s_addc_u32 s7, s7, 0
	global_store_dword v36, v120, s[10:11]
	s_add_u32 s10, s10, 0x800
	s_addc_u32 s11, s11, 0
	v_lshlrev_b32_e32 v108, 16, v144
	v_and_b32_e32 v109, 0xffff0000, v144
	v_pk_mul_f32 v[108:109], v[62:63], v[108:109] op_sel_hi:[0,1]
	v_mul_f32_e32 v121, v44, v62
	v_pk_fma_f32 v[118:119], v[118:119], v[60:61], v[108:109] op_sel_hi:[1,0,1]
	v_fma_f32 v120, v120, v60, v121
	v_readfirstlane_b32 s54, v40
	v_add_f32_e32 v39, s34, v40
	v_readlane_b32 s22, v175, 4
	v_max_f32_e32 v38, s40, v39
	v_readlane_b32 s32, v177, 4
	v_sub_f32_e32 v58, v39, v38
	v_sub_f32_e32 v59, s40, v38
	v_mul_f32_e32 v58, 0x3fb8aa3b, v58
	v_mul_f32_e32 v59, 0x3fb8aa3b, v59
	v_exp_f32_e32 v60, v58
	v_exp_f32_e32 v62, v59
	v_cvt_pk_bf16_f32 v122, v118, v119
; __device__ __forceinline__ unsigned pk2(float lo, float hi) { f32x2_t v = {lo, hi}; bf16x2_t b = __builtin_convertvector(v, bf16x2_t); return __builtin_bit_cast(unsigned, b); }
; __device__ __forceinline__ float bflo(unsigned w) { return __uint_as_float(w << 16); }
; __device__ __forceinline__ float bfhi(unsigned w) { return __uint_as_float(w & 0xffff0000u); }
; __device__ __forceinline__ float fexp(float x) { return __builtin_amdgcn_exp2f(x * LOG2E); }
;     __device__ __forceinline__ float* MBM() const { return (float*)(ws + WS_MB); }
;     __device__ __forceinline__ float* MBB() const { return (float*)(ws + WS_MB) + (NSLOT_P + NSLOT_S); }
;     __device__ __forceinline__ float* MST() const { return (float*)(ws + WS_MB) + 2 * (NSLOT_P + NSLOT_S); }
; __device__ __forceinline__ void phase_scan(Ctx& C, int l, const bool st, LAS unsigned char* lds) {
;     ...
;         for (int cg0 = 0; cg0 < NPC; cg0 += 16) {
;             if (cg0 + 16 < NPC) {
; #pragma unroll
;                 for (int j = 0; j < 16; ++j) { nb[j] = base[(size_t)((b * NPC + cg0 + 16 + j) * 4 + h) * 8192]; fnb[j] = hn ? dnb[(size_t)((b * NPC + cg0 + 16 + j) * 4 + h) * 128] : 0.f; }
;             }
; #pragma unroll
;             for (int j = 0; j < 16; ++j) { const int slot = (b * NPC + cg0 + j) * 4 + h;
;                 const float Bc = C.MBB()[slot], Mc = C.MBM()[slot];
;                 const float mn = fmaxf(Bc + m, Mc), g = fexp(Bc + m - mn), f = fexp(Mc - mn);
;                 if (st) { base[(size_t)slot * 8192] = pk2(c0, c1); if (hn) { dnb[(size_t)slot * 128] = nn; if (p == 0) C.MST()[slot] = m; } }
;                 c0 = g * c0 + f * bflo(buf[j]); c1 = g * c1 + f * bfhi(buf[j]); nn = g * nn + f * fb[j]; m = mn; }
; #pragma unroll
;             for (int j = 0; j < 16; ++j) { buf[j] = nb[j]; fb[j] = fnb[j]; }
	v_writelane_b32 v179, s54, 3
	global_store_dword v36, v122, s[6:7]
	s_add_u32 s6, s6, 0x20000
	s_addc_u32 s7, s7, 0
	global_store_dword v36, v120, s[10:11]
	s_add_u32 s10, s10, 0x800
	s_addc_u32 s11, s11, 0
	v_lshlrev_b32_e32 v108, 16, v145
	v_and_b32_e32 v109, 0xffff0000, v145
	v_pk_mul_f32 v[108:109], v[62:63], v[108:109] op_sel_hi:[0,1]
	v_mul_f32_e32 v121, v45, v62
	v_pk_fma_f32 v[118:119], v[118:119], v[60:61], v[108:109] op_sel_hi:[1,0,1]
	v_fma_f32 v120, v120, v60, v121
	v_readfirstlane_b32 s54, v38
	v_add_f32_e32 v39, s22, v38
	v_readlane_b32 s34, v175, 5
	v_max_f32_e32 v40, s32, v39
	v_readlane_b32 s40, v177, 5
	v_sub_f32_e32 v58, v39, v40
	v_sub_f32_e32 v59, s32, v40
	v_mul_f32_e32 v58, 0x3fb8aa3b, v58
	v_mul_f32_e32 v59, 0x3fb8aa3b, v59
	v_exp_f32_e32 v60, v58
	v_exp_f32_e32 v62, v59
	v_cvt_pk_bf16_f32 v122, v118, v119
	v_writelane_b32 v179, s54, 4
	global_store_dword v36, v122, s[6:7]
	s_add_u32 s6, s6, 0x20000
	s_addc_u32 s7, s7, 0
	global_store_dword v36, v120, s[10:11]
	s_add_u32 s10, s10, 0x800
	s_addc_u32 s11, s11, 0
	v_lshlrev_b32_e32 v108, 16, v146
	v_and_b32_e32 v109, 0xffff0000, v146
	v_pk_mul_f32 v[108:109], v[62:63], v[108:109] op_sel_hi:[0,1]
	v_mul_f32_e32 v121, v46, v62
	v_pk_fma_f32 v[118:119], v[118:119], v[60:61], v[108:109] op_sel_hi:[1,0,1]
	v_fma_f32 v120, v120, v60, v121
	v_readfirstlane_b32 s54, v40
	v_add_f32_e32 v39, s34, v40
	v_readlane_b32 s22, v175, 6
	v_max_f32_e32 v38, s40, v39
	v_readlane_b32 s32, v177, 6
	v_sub_f32_e32 v58, v39, v38
	v_sub_f32_e32 v59, s40, v38
	v_mul_f32_e32 v58, 0x3fb8aa3b, v58
	v_mul_f32_e32 v59, 0x3fb8aa3b, v59
	v_exp_f32_e32 v60, v58
	v_exp_f32_e32 v62, v59
	v_cvt_pk_bf16_f32 v122, v118, v119
	v_writelane_b32 v179, s54, 5
	global_store_dword v36, v122, s[6:7]
	s_add_u32 s6, s6, 0x20000
	s_addc_u32 s7, s7, 0
	global_store_dword v36, v120, s[10:11]
	s_add_u32 s10, s10, 0x800
	s_addc_u32 s11, s11, 0
	v_lshlrev_b32_e32 v108, 16, v147
	v_and_b32_e32 v109, 0xffff0000, v147
	v_pk_mul_f32 v[108:109], v[62:63], v[108:109] op_sel_hi:[0,1]
	v_mul_f32_e32 v121, v47, v62
	v_pk_fma_f32 v[118:119], v[118:119], v[60:61], v[108:109] op_sel_hi:[1,0,1]
	v_fma_f32 v120, v120, v60, v121
	v_readfirstlane_b32 s54, v38
	v_add_f32_e32 v39, s22, v38
	v_readlane_b32 s34, v175, 7
	v_max_f32_e32 v40, s32, v39
	v_readlane_b32 s40, v177, 7
	v_sub_f32_e32 v58, v39, v40
	v_sub_f32_e32 v59, s32, v40
	v_mul_f32_e32 v58, 0x3fb8aa3b, v58
	v_mul_f32_e32 v59, 0x3fb8aa3b, v59
	v_exp_f32_e32 v60, v58
	v_exp_f32_e32 v62, v59
	v_cvt_pk_bf16_f32 v122, v118, v119
	v_writelane_b32 v179, s54, 6
	global_store_dword v36, v122, s[6:7]
	s_add_u32 s6, s6, 0x20000
	s_addc_u32 s7, s7, 0
	global_store_dword v36, v120, s[10:11]
	s_add_u32 s10, s10, 0x800
	s_addc_u32 s11, s11, 0
	v_lshlrev_b32_e32 v108, 16, v148
	v_and_b32_e32 v109, 0xffff0000, v148
	v_pk_mul_f32 v[108:109], v[62:63], v[108:109] op_sel_hi:[0,1]
	v_mul_f32_e32 v121, v48, v62
	v_pk_fma_f32 v[118:119], v[118:119], v[60:61], v[108:109] op_sel_hi:[1,0,1]
	v_fma_f32 v120, v120, v60, v121
	v_readfirstlane_b32 s54, v40
	v_add_f32_e32 v39, s34, v40
	v_readlane_b32 s22, v175, 8
	v_max_f32_e32 v38, s40, v39
	v_readlane_b32 s32, v177, 8
	v_sub_f32_e32 v58, v39, v38
	v_sub_f32_e32 v59, s40, v38
	v_mul_f32_e32 v58, 0x3fb8aa3b, v58
	v_mul_f32_e32 v59, 0x3fb8aa3b, v59
	v_exp_f32_e32 v60, v58
	v_exp_f32_e32 v62, v59
	v_cvt_pk_bf16_f32 v122, v118, v119
	v_writelane_b32 v179, s54, 7
	global_store_dword v36, v122, s[6:7]
	s_add_u32 s6, s6, 0x20000
	s_addc_u32 s7, s7, 0
	global_store_dword v36, v120, s[10:11]
	s_add_u32 s10, s10, 0x800
	s_addc_u32 s11, s11, 0
	v_lshlrev_b32_e32 v108, 16, v149
	v_and_b32_e32 v109, 0xffff0000, v149
	v_pk_mul_f32 v[108:109], v[62:63], v[108:109] op_sel_hi:[0,1]
	v_mul_f32_e32 v121, v49, v62
	v_pk_fma_f32 v[118:119], v[118:119], v[60:61], v[108:109] op_sel_hi:[1,0,1]
	v_fma_f32 v120, v120, v60, v121
	v_readfirstlane_b32 s54, v38
	v_add_f32_e32 v39, s22, v38
	v_readlane_b32 s34, v175, 9
	v_max_f32_e32 v40, s32, v39
	v_readlane_b32 s40, v177, 9
	v_sub_f32_e32 v58, v39, v40
	v_sub_f32_e32 v59, s32, v40
	v_mul_f32_e32 v58, 0x3fb8aa3b, v58
	v_mul_f32_e32 v59, 0x3fb8aa3b, v59
	v_exp_f32_e32 v60, v58
	v_exp_f32_e32 v62, v59
	v_cvt_pk_bf16_f32 v122, v118, v119
	v_writelane_b32 v179, s54, 8
	global_store_dword v36, v122, s[6:7]
	s_add_u32 s6, s6, 0x20000
	s_addc_u32 s7, s7, 0
	global_store_dword v36, v120, s[10:11]
	s_add_u32 s10, s10, 0x800
	s_addc_u32 s11, s11, 0
	v_lshlrev_b32_e32 v108, 16, v150
	v_and_b32_e32 v109, 0xffff0000, v150
	v_pk_mul_f32 v[108:109], v[62:63], v[108:109] op_sel_hi:[0,1]
	v_mul_f32_e32 v121, v50, v62
	v_pk_fma_f32 v[118:119], v[118:119], v[60:61], v[108:109] op_sel_hi:[1,0,1]
	v_fma_f32 v120, v120, v60, v121
	v_readfirstlane_b32 s54, v40
	v_add_f32_e32 v39, s34, v40
	v_readlane_b32 s22, v175, 10
	v_max_f32_e32 v38, s40, v39
	v_readlane_b32 s32, v177, 10
	v_sub_f32_e32 v58, v39, v38
	v_sub_f32_e32 v59, s40, v38
	v_mul_f32_e32 v58, 0x3fb8aa3b, v58
	v_mul_f32_e32 v59, 0x3fb8aa3b, v59
	v_exp_f32_e32 v60, v58
	v_exp_f32_e32 v62, v59
	v_cvt_pk_bf16_f32 v122, v118, v119
	v_writelane_b32 v179, s54, 9
	global_store_dword v36, v122, s[6:7]
	s_add_u32 s6, s6, 0x20000
	s_addc_u32 s7, s7, 0
	global_store_dword v36, v120, s[10:11]
	s_add_u32 s10, s10, 0x800
	s_addc_u32 s11, s11, 0
	v_lshlrev_b32_e32 v108, 16, v151
	v_and_b32_e32 v109, 0xffff0000, v151
	v_pk_mul_f32 v[108:109], v[62:63], v[108:109] op_sel_hi:[0,1]
	v_mul_f32_e32 v121, v51, v62
	v_pk_fma_f32 v[118:119], v[118:119], v[60:61], v[108:109] op_sel_hi:[1,0,1]
	v_fma_f32 v120, v120, v60, v121
	v_readfirstlane_b32 s54, v38
	v_add_f32_e32 v39, s22, v38
	v_readlane_b32 s34, v175, 11
; __device__ __forceinline__ unsigned pk2(float lo, float hi) { f32x2_t v = {lo, hi}; bf16x2_t b = __builtin_convertvector(v, bf16x2_t); return __builtin_bit_cast(unsigned, b); }
; __device__ __forceinline__ float bflo(unsigned w) { return __uint_as_float(w << 16); }
; __device__ __forceinline__ float bfhi(unsigned w) { return __uint_as_float(w & 0xffff0000u); }
; __device__ __forceinline__ float fexp(float x) { return __builtin_amdgcn_exp2f(x * LOG2E); }
;     __device__ __forceinline__ float* MBM() const { return (float*)(ws + WS_MB); }
;     __device__ __forceinline__ float* MBB() const { return (float*)(ws + WS_MB) + (NSLOT_P + NSLOT_S); }
;     __device__ __forceinline__ float* MST() const { return (float*)(ws + WS_MB) + 2 * (NSLOT_P + NSLOT_S); }
; __device__ __forceinline__ void phase_scan(Ctx& C, int l, const bool st, LAS unsigned char* lds) {
;     ...
;         for (int cg0 = 0; cg0 < NPC; cg0 += 16) {
;             if (cg0 + 16 < NPC) {
; #pragma unroll
;                 for (int j = 0; j < 16; ++j) { nb[j] = base[(size_t)((b * NPC + cg0 + 16 + j) * 4 + h) * 8192]; fnb[j] = hn ? dnb[(size_t)((b * NPC + cg0 + 16 + j) * 4 + h) * 128] : 0.f; }
;             }
; #pragma unroll
;             for (int j = 0; j < 16; ++j) { const int slot = (b * NPC + cg0 + j) * 4 + h;
;                 const float Bc = C.MBB()[slot], Mc = C.MBM()[slot];
;                 const float mn = fmaxf(Bc + m, Mc), g = fexp(Bc + m - mn), f = fexp(Mc - mn);
;                 if (st) { base[(size_t)slot * 8192] = pk2(c0, c1); if (hn) { dnb[(size_t)slot * 128] = nn; if (p == 0) C.MST()[slot] = m; } }
;                 c0 = g * c0 + f * bflo(buf[j]); c1 = g * c1 + f * bfhi(buf[j]); nn = g * nn + f * fb[j]; m = mn; }
; #pragma unroll
;             for (int j = 0; j < 16; ++j) { buf[j] = nb[j]; fb[j] = fnb[j]; }
	v_max_f32_e32 v40, s32, v39
	v_readlane_b32 s40, v177, 11
	v_sub_f32_e32 v58, v39, v40
	v_sub_f32_e32 v59, s32, v40
	v_mul_f32_e32 v58, 0x3fb8aa3b, v58
	v_mul_f32_e32 v59, 0x3fb8aa3b, v59
	v_exp_f32_e32 v60, v58
	v_exp_f32_e32 v62, v59
	v_cvt_pk_bf16_f32 v122, v118, v119
	v_writelane_b32 v179, s54, 10
	global_store_dword v36, v122, s[6:7]
	s_add_u32 s6, s6, 0x20000
	s_addc_u32 s7, s7, 0
	global_store_dword v36, v120, s[10:11]
	s_add_u32 s10, s10, 0x800
	s_addc_u32 s11, s11, 0
	v_lshlrev_b32_e32 v108, 16, v152
	v_and_b32_e32 v109, 0xffff0000, v152
	v_pk_mul_f32 v[108:109], v[62:63], v[108:109] op_sel_hi:[0,1]
	v_mul_f32_e32 v121, v52, v62
	v_pk_fma_f32 v[118:119], v[118:119], v[60:61], v[108:109] op_sel_hi:[1,0,1]
	v_fma_f32 v120, v120, v60, v121
	v_readfirstlane_b32 s54, v40
	v_add_f32_e32 v39, s34, v40
	v_readlane_b32 s22, v175, 12
	v_max_f32_e32 v38, s40, v39
	v_readlane_b32 s32, v177, 12
	v_sub_f32_e32 v58, v39, v38
	v_sub_f32_e32 v59, s40, v38
	v_mul_f32_e32 v58, 0x3fb8aa3b, v58
	v_mul_f32_e32 v59, 0x3fb8aa3b, v59
	v_exp_f32_e32 v60, v58
	v_exp_f32_e32 v62, v59
	v_cvt_pk_bf16_f32 v122, v118, v119
	v_writelane_b32 v179, s54, 11
	global_store_dword v36, v122, s[6:7]
	s_add_u32 s6, s6, 0x20000
	s_addc_u32 s7, s7, 0
	global_store_dword v36, v120, s[10:11]
	s_add_u32 s10, s10, 0x800
	s_addc_u32 s11, s11, 0
	v_lshlrev_b32_e32 v108, 16, v153
	v_and_b32_e32 v109, 0xffff0000, v153
	v_pk_mul_f32 v[108:109], v[62:63], v[108:109] op_sel_hi:[0,1]
	v_mul_f32_e32 v121, v53, v62
	v_pk_fma_f32 v[118:119], v[118:119], v[60:61], v[108:109] op_sel_hi:[1,0,1]
	v_fma_f32 v120, v120, v60, v121
	v_readfirstlane_b32 s54, v38
	v_add_f32_e32 v39, s22, v38
	v_readlane_b32 s34, v175, 13
	v_max_f32_e32 v40, s32, v39
	v_readlane_b32 s40, v177, 13
	v_sub_f32_e32 v58, v39, v40
	v_sub_f32_e32 v59, s32, v40
	v_mul_f32_e32 v58, 0x3fb8aa3b, v58
	v_mul_f32_e32 v59, 0x3fb8aa3b, v59
	v_exp_f32_e32 v60, v58
	v_exp_f32_e32 v62, v59
	v_cvt_pk_bf16_f32 v122, v118, v119
	v_writelane_b32 v179, s54, 12
	global_store_dword v36, v122, s[6:7]
	s_add_u32 s6, s6, 0x20000
	s_addc_u32 s7, s7, 0
	global_store_dword v36, v120, s[10:11]
	s_add_u32 s10, s10, 0x800
	s_addc_u32 s11, s11, 0
	v_lshlrev_b32_e32 v108, 16, v154
	v_and_b32_e32 v109, 0xffff0000, v154
	v_pk_mul_f32 v[108:109], v[62:63], v[108:109] op_sel_hi:[0,1]
	v_mul_f32_e32 v121, v54, v62
	v_pk_fma_f32 v[118:119], v[118:119], v[60:61], v[108:109] op_sel_hi:[1,0,1]
	v_fma_f32 v120, v120, v60, v121
	v_readfirstlane_b32 s54, v40
	v_add_f32_e32 v39, s34, v40
	v_readlane_b32 s22, v175, 14
	v_max_f32_e32 v38, s40, v39
	v_readlane_b32 s32, v177, 14
	v_sub_f32_e32 v58, v39, v38
	v_sub_f32_e32 v59, s40, v38
	v_mul_f32_e32 v58, 0x3fb8aa3b, v58
	v_mul_f32_e32 v59, 0x3fb8aa3b, v59
	v_exp_f32_e32 v60, v58
	v_exp_f32_e32 v62, v59
	v_cvt_pk_bf16_f32 v122, v118, v119
	v_writelane_b32 v179, s54, 13
	global_store_dword v36, v122, s[6:7]
	s_add_u32 s6, s6, 0x20000
	s_addc_u32 s7, s7, 0
	global_store_dword v36, v120, s[10:11]
	s_add_u32 s10, s10, 0x800
	s_addc_u32 s11, s11, 0
	v_lshlrev_b32_e32 v108, 16, v155
	v_and_b32_e32 v109, 0xffff0000, v155
	v_pk_mul_f32 v[108:109], v[62:63], v[108:109] op_sel_hi:[0,1]
	v_mul_f32_e32 v121, v55, v62
	v_pk_fma_f32 v[118:119], v[118:119], v[60:61], v[108:109] op_sel_hi:[1,0,1]
	v_fma_f32 v120, v120, v60, v121
	v_readfirstlane_b32 s54, v38
	v_add_f32_e32 v39, s22, v38
	v_readlane_b32 s34, v175, 15
	v_max_f32_e32 v40, s32, v39
	v_readlane_b32 s40, v177, 15
	v_sub_f32_e32 v58, v39, v40
	v_sub_f32_e32 v59, s32, v40
	v_mul_f32_e32 v58, 0x3fb8aa3b, v58
	v_mul_f32_e32 v59, 0x3fb8aa3b, v59
	v_exp_f32_e32 v60, v58
	v_exp_f32_e32 v62, v59
	v_cvt_pk_bf16_f32 v122, v118, v119
	v_writelane_b32 v179, s54, 14
	global_store_dword v36, v122, s[6:7]
	s_add_u32 s6, s6, 0x20000
	s_addc_u32 s7, s7, 0
	global_store_dword v36, v120, s[10:11]
	s_add_u32 s10, s10, 0x800
	s_addc_u32 s11, s11, 0
	v_lshlrev_b32_e32 v108, 16, v156
	v_and_b32_e32 v109, 0xffff0000, v156
	v_pk_mul_f32 v[108:109], v[62:63], v[108:109] op_sel_hi:[0,1]
	v_mul_f32_e32 v121, v56, v62
	v_pk_fma_f32 v[118:119], v[118:119], v[60:61], v[108:109] op_sel_hi:[1,0,1]
	v_fma_f32 v120, v120, v60, v121
	v_readfirstlane_b32 s54, v40
	v_add_f32_e32 v39, s34, v40
	v_readlane_b32 s22, v175, 16
	v_max_f32_e32 v38, s40, v39
	v_readlane_b32 s32, v177, 16
	v_sub_f32_e32 v58, v39, v38
	v_sub_f32_e32 v59, s40, v38
	v_mul_f32_e32 v58, 0x3fb8aa3b, v58
	v_mul_f32_e32 v59, 0x3fb8aa3b, v59
	v_exp_f32_e32 v60, v58
	v_exp_f32_e32 v62, v59
	v_cvt_pk_bf16_f32 v122, v118, v119
	v_writelane_b32 v179, s54, 15
	global_store_dword v36, v122, s[6:7]
	s_add_u32 s6, s6, 0x20000
	s_addc_u32 s7, s7, 0
	global_store_dword v36, v120, s[10:11]
	s_add_u32 s10, s10, 0x800
	s_addc_u32 s11, s11, 0
	v_lshlrev_b32_e32 v108, 16, v157
	v_and_b32_e32 v109, 0xffff0000, v157
	v_pk_mul_f32 v[108:109], v[62:63], v[108:109] op_sel_hi:[0,1]
	v_mul_f32_e32 v121, v57, v62
	v_pk_fma_f32 v[118:119], v[118:119], v[60:61], v[108:109] op_sel_hi:[1,0,1]
	v_fma_f32 v120, v120, v60, v121
; __device__ __forceinline__ unsigned pk2(float lo, float hi) { f32x2_t v = {lo, hi}; bf16x2_t b = __builtin_convertvector(v, bf16x2_t); return __builtin_bit_cast(unsigned, b); }
; __device__ __forceinline__ float bflo(unsigned w) { return __uint_as_float(w << 16); }
; __device__ __forceinline__ float bfhi(unsigned w) { return __uint_as_float(w & 0xffff0000u); }
; __device__ __forceinline__ float fexp(float x) { return __builtin_amdgcn_exp2f(x * LOG2E); }
;     __device__ __forceinline__ float* MBM() const { return (float*)(ws + WS_MB); }
;     __device__ __forceinline__ float* MBB() const { return (float*)(ws + WS_MB) + (NSLOT_P + NSLOT_S); }
;     __device__ __forceinline__ float* MST() const { return (float*)(ws + WS_MB) + 2 * (NSLOT_P + NSLOT_S); }
; __device__ __forceinline__ void phase_scan(Ctx& C, int l, const bool st, LAS unsigned char* lds) {
;     ...
;         for (int cg0 = 0; cg0 < NPC; cg0 += 16) {
;             if (cg0 + 16 < NPC) {
; #pragma unroll
;                 for (int j = 0; j < 16; ++j) { nb[j] = base[(size_t)((b * NPC + cg0 + 16 + j) * 4 + h) * 8192]; fnb[j] = hn ? dnb[(size_t)((b * NPC + cg0 + 16 + j) * 4 + h) * 128] : 0.f; }
;             }
; #pragma unroll
;             for (int j = 0; j < 16; ++j) { const int slot = (b * NPC + cg0 + j) * 4 + h;
;                 const float Bc = C.MBB()[slot], Mc = C.MBM()[slot];
;                 const float mn = fmaxf(Bc + m, Mc), g = fexp(Bc + m - mn), f = fexp(Mc - mn);
;                 if (st) { base[(size_t)slot * 8192] = pk2(c0, c1); if (hn) { dnb[(size_t)slot * 128] = nn; if (p == 0) C.MST()[slot] = m; } }
;                 c0 = g * c0 + f * bflo(buf[j]); c1 = g * c1 + f * bfhi(buf[j]); nn = g * nn + f * fb[j]; m = mn; }
; #pragma unroll
;             for (int j = 0; j < 16; ++j) { buf[j] = nb[j]; fb[j] = fnb[j]; }
.Lscan_hn_b5:
	s_waitcnt vmcnt(32)
	global_load_dword v126, v36, s[4:5]
	s_add_u32 s4, s4, 0x20000
	s_addc_u32 s5, s5, 0
	global_load_dword v127, v36, s[4:5]
	s_add_u32 s4, s4, 0x20000
	s_addc_u32 s5, s5, 0
	global_load_dword v128, v36, s[4:5]
	s_add_u32 s4, s4, 0x20000
	s_addc_u32 s5, s5, 0
	global_load_dword v129, v36, s[4:5]
	s_add_u32 s4, s4, 0x20000
	s_addc_u32 s5, s5, 0
	global_load_dword v130, v36, s[4:5]
	s_add_u32 s4, s4, 0x20000
	s_addc_u32 s5, s5, 0
	global_load_dword v131, v36, s[4:5]
	s_add_u32 s4, s4, 0x20000
	s_addc_u32 s5, s5, 0
	global_load_dword v132, v36, s[4:5]
	s_add_u32 s4, s4, 0x20000
	s_addc_u32 s5, s5, 0
	global_load_dword v133, v36, s[4:5]
	s_add_u32 s4, s4, 0x20000
	s_addc_u32 s5, s5, 0
	global_load_dword v134, v36, s[4:5]
	s_add_u32 s4, s4, 0x20000
	s_addc_u32 s5, s5, 0
	global_load_dword v135, v36, s[4:5]
	s_add_u32 s4, s4, 0x20000
	s_addc_u32 s5, s5, 0
	global_load_dword v136, v36, s[4:5]
	s_add_u32 s4, s4, 0x20000
	s_addc_u32 s5, s5, 0
	global_load_dword v137, v36, s[4:5]
	s_add_u32 s4, s4, 0x20000
	s_addc_u32 s5, s5, 0
	global_load_dword v138, v36, s[4:5]
	s_add_u32 s4, s4, 0x20000
	s_addc_u32 s5, s5, 0
	global_load_dword v139, v36, s[4:5]
	s_add_u32 s4, s4, 0x20000
	s_addc_u32 s5, s5, 0
	global_load_dword v140, v36, s[4:5]
	s_add_u32 s4, s4, 0x20000
	s_addc_u32 s5, s5, 0
	global_load_dword v141, v36, s[4:5]
	s_add_u32 s4, s4, 0x20000
	s_addc_u32 s5, s5, 0
	global_load_dword v16, v36, s[8:9]
	s_add_u32 s8, s8, 0x800
	s_addc_u32 s9, s9, 0
	global_load_dword v17, v36, s[8:9]
	s_add_u32 s8, s8, 0x800
	s_addc_u32 s9, s9, 0
	global_load_dword v18, v36, s[8:9]
	s_add_u32 s8, s8, 0x800
	s_addc_u32 s9, s9, 0
	global_load_dword v19, v36, s[8:9]
	s_add_u32 s8, s8, 0x800
	s_addc_u32 s9, s9, 0
	global_load_dword v20, v36, s[8:9]
	s_add_u32 s8, s8, 0x800
	s_addc_u32 s9, s9, 0
	global_load_dword v21, v36, s[8:9]
	s_add_u32 s8, s8, 0x800
	s_addc_u32 s9, s9, 0
	global_load_dword v22, v36, s[8:9]
	s_add_u32 s8, s8, 0x800
	s_addc_u32 s9, s9, 0
	global_load_dword v23, v36, s[8:9]
	s_add_u32 s8, s8, 0x800
	s_addc_u32 s9, s9, 0
	global_load_dword v24, v36, s[8:9]
	s_add_u32 s8, s8, 0x800
	s_addc_u32 s9, s9, 0
	global_load_dword v25, v36, s[8:9]
	s_add_u32 s8, s8, 0x800
	s_addc_u32 s9, s9, 0
	global_load_dword v26, v36, s[8:9]
	s_add_u32 s8, s8, 0x800
	s_addc_u32 s9, s9, 0
	global_load_dword v27, v36, s[8:9]
	s_add_u32 s8, s8, 0x800
	s_addc_u32 s9, s9, 0
	global_load_dword v28, v36, s[8:9]
	s_add_u32 s8, s8, 0x800
	s_addc_u32 s9, s9, 0
	global_load_dword v29, v36, s[8:9]
	s_add_u32 s8, s8, 0x800
	s_addc_u32 s9, s9, 0
	global_load_dword v30, v36, s[8:9]
	s_add_u32 s8, s8, 0x800
	s_addc_u32 s9, s9, 0
	global_load_dword v31, v36, s[8:9]
	s_add_u32 s8, s8, 0x800
	s_addc_u32 s9, s9, 0
	v_readfirstlane_b32 s54, v38
	v_add_f32_e32 v39, s22, v38
	v_readlane_b32 s34, v175, 17
	v_max_f32_e32 v40, s32, v39
	v_readlane_b32 s40, v177, 17
	v_sub_f32_e32 v58, v39, v40
	v_sub_f32_e32 v59, s32, v40
	v_mul_f32_e32 v58, 0x3fb8aa3b, v58
	v_mul_f32_e32 v59, 0x3fb8aa3b, v59
	v_exp_f32_e32 v60, v58
	v_exp_f32_e32 v62, v59
	v_cvt_pk_bf16_f32 v122, v118, v119
	v_writelane_b32 v179, s54, 16
	global_store_dword v36, v122, s[6:7]
	s_add_u32 s6, s6, 0x20000
	s_addc_u32 s7, s7, 0
	global_store_dword v36, v120, s[10:11]
	s_add_u32 s10, s10, 0x800
	s_addc_u32 s11, s11, 0
	v_lshlrev_b32_e32 v108, 16, v158
	v_and_b32_e32 v109, 0xffff0000, v158
	v_pk_mul_f32 v[108:109], v[62:63], v[108:109] op_sel_hi:[0,1]
	v_mul_f32_e32 v121, v92, v62
	v_pk_fma_f32 v[118:119], v[118:119], v[60:61], v[108:109] op_sel_hi:[1,0,1]
	v_fma_f32 v120, v120, v60, v121
	v_readfirstlane_b32 s54, v40
	v_add_f32_e32 v39, s34, v40
	v_readlane_b32 s22, v175, 18
	v_max_f32_e32 v38, s40, v39
	v_readlane_b32 s32, v177, 18
	v_sub_f32_e32 v58, v39, v38
	v_sub_f32_e32 v59, s40, v38
	v_mul_f32_e32 v58, 0x3fb8aa3b, v58
	v_mul_f32_e32 v59, 0x3fb8aa3b, v59
	v_exp_f32_e32 v60, v58
	v_exp_f32_e32 v62, v59
	v_cvt_pk_bf16_f32 v122, v118, v119
	v_writelane_b32 v179, s54, 17
	global_store_dword v36, v122, s[6:7]
	s_add_u32 s6, s6, 0x20000
	s_addc_u32 s7, s7, 0
	global_store_dword v36, v120, s[10:11]
	s_add_u32 s10, s10, 0x800
	s_addc_u32 s11, s11, 0
	v_lshlrev_b32_e32 v108, 16, v159
	v_and_b32_e32 v109, 0xffff0000, v159
	v_pk_mul_f32 v[108:109], v[62:63], v[108:109] op_sel_hi:[0,1]
	v_mul_f32_e32 v121, v93, v62
	v_pk_fma_f32 v[118:119], v[118:119], v[60:61], v[108:109] op_sel_hi:[1,0,1]
	v_fma_f32 v120, v120, v60, v121
	v_readfirstlane_b32 s54, v38
	v_add_f32_e32 v39, s22, v38
	v_readlane_b32 s34, v175, 19
	v_max_f32_e32 v40, s32, v39
	v_readlane_b32 s40, v177, 19
	v_sub_f32_e32 v58, v39, v40
	v_sub_f32_e32 v59, s32, v40
	v_mul_f32_e32 v58, 0x3fb8aa3b, v58
	v_mul_f32_e32 v59, 0x3fb8aa3b, v59
	v_exp_f32_e32 v60, v58
	v_exp_f32_e32 v62, v59
	v_cvt_pk_bf16_f32 v122, v118, v119
	v_writelane_b32 v179, s54, 18
	global_store_dword v36, v122, s[6:7]
	s_add_u32 s6, s6, 0x20000
	s_addc_u32 s7, s7, 0
	global_store_dword v36, v120, s[10:11]
	s_add_u32 s10, s10, 0x800
	s_addc_u32 s11, s11, 0
	v_lshlrev_b32_e32 v108, 16, v160
	v_and_b32_e32 v109, 0xffff0000, v160
	v_pk_mul_f32 v[108:109], v[62:63], v[108:109] op_sel_hi:[0,1]
	v_mul_f32_e32 v121, v94, v62
	v_pk_fma_f32 v[118:119], v[118:119], v[60:61], v[108:109] op_sel_hi:[1,0,1]
	v_fma_f32 v120, v120, v60, v121
	v_readfirstlane_b32 s54, v40
	v_add_f32_e32 v39, s34, v40
	v_readlane_b32 s22, v175, 20
	v_max_f32_e32 v38, s40, v39
	v_readlane_b32 s32, v177, 20
	v_sub_f32_e32 v58, v39, v38
	v_sub_f32_e32 v59, s40, v38
	v_mul_f32_e32 v58, 0x3fb8aa3b, v58
	v_mul_f32_e32 v59, 0x3fb8aa3b, v59
	v_exp_f32_e32 v60, v58
	v_exp_f32_e32 v62, v59
	v_cvt_pk_bf16_f32 v122, v118, v119
; __device__ __forceinline__ unsigned pk2(float lo, float hi) { f32x2_t v = {lo, hi}; bf16x2_t b = __builtin_convertvector(v, bf16x2_t); return __builtin_bit_cast(unsigned, b); }
; __device__ __forceinline__ float bflo(unsigned w) { return __uint_as_float(w << 16); }
; __device__ __forceinline__ float bfhi(unsigned w) { return __uint_as_float(w & 0xffff0000u); }
; __device__ __forceinline__ float fexp(float x) { return __builtin_amdgcn_exp2f(x * LOG2E); }
;     __device__ __forceinline__ float* MBM() const { return (float*)(ws + WS_MB); }
;     __device__ __forceinline__ float* MBB() const { return (float*)(ws + WS_MB) + (NSLOT_P + NSLOT_S); }
;     __device__ __forceinline__ float* MST() const { return (float*)(ws + WS_MB) + 2 * (NSLOT_P + NSLOT_S); }
; __device__ __forceinline__ void phase_scan(Ctx& C, int l, const bool st, LAS unsigned char* lds) {
;     ...
;         for (int cg0 = 0; cg0 < NPC; cg0 += 16) {
;             if (cg0 + 16 < NPC) {
; #pragma unroll
;                 for (int j = 0; j < 16; ++j) { nb[j] = base[(size_t)((b * NPC + cg0 + 16 + j) * 4 + h) * 8192]; fnb[j] = hn ? dnb[(size_t)((b * NPC + cg0 + 16 + j) * 4 + h) * 128] : 0.f; }
;             }
; #pragma unroll
;             for (int j = 0; j < 16; ++j) { const int slot = (b * NPC + cg0 + j) * 4 + h;
;                 const float Bc = C.MBB()[slot], Mc = C.MBM()[slot];
;                 const float mn = fmaxf(Bc + m, Mc), g = fexp(Bc + m - mn), f = fexp(Mc - mn);
;                 if (st) { base[(size_t)slot * 8192] = pk2(c0, c1); if (hn) { dnb[(size_t)slot * 128] = nn; if (p == 0) C.MST()[slot] = m; } }
;                 c0 = g * c0 + f * bflo(buf[j]); c1 = g * c1 + f * bfhi(buf[j]); nn = g * nn + f * fb[j]; m = mn; }
; #pragma unroll
;             for (int j = 0; j < 16; ++j) { buf[j] = nb[j]; fb[j] = fnb[j]; }
	v_writelane_b32 v179, s54, 19
	global_store_dword v36, v122, s[6:7]
	s_add_u32 s6, s6, 0x20000
	s_addc_u32 s7, s7, 0
	global_store_dword v36, v120, s[10:11]
	s_add_u32 s10, s10, 0x800
	s_addc_u32 s11, s11, 0
	v_lshlrev_b32_e32 v108, 16, v161
	v_and_b32_e32 v109, 0xffff0000, v161
	v_pk_mul_f32 v[108:109], v[62:63], v[108:109] op_sel_hi:[0,1]
	v_mul_f32_e32 v121, v95, v62
	v_pk_fma_f32 v[118:119], v[118:119], v[60:61], v[108:109] op_sel_hi:[1,0,1]
	v_fma_f32 v120, v120, v60, v121
	v_readfirstlane_b32 s54, v38
	v_add_f32_e32 v39, s22, v38
	v_readlane_b32 s34, v175, 21
	v_max_f32_e32 v40, s32, v39
	v_readlane_b32 s40, v177, 21
	v_sub_f32_e32 v58, v39, v40
	v_sub_f32_e32 v59, s32, v40
	v_mul_f32_e32 v58, 0x3fb8aa3b, v58
	v_mul_f32_e32 v59, 0x3fb8aa3b, v59
	v_exp_f32_e32 v60, v58
	v_exp_f32_e32 v62, v59
	v_cvt_pk_bf16_f32 v122, v118, v119
	v_writelane_b32 v179, s54, 20
	global_store_dword v36, v122, s[6:7]
	s_add_u32 s6, s6, 0x20000
	s_addc_u32 s7, s7, 0
	global_store_dword v36, v120, s[10:11]
	s_add_u32 s10, s10, 0x800
	s_addc_u32 s11, s11, 0
	v_lshlrev_b32_e32 v108, 16, v162
	v_and_b32_e32 v109, 0xffff0000, v162
	v_pk_mul_f32 v[108:109], v[62:63], v[108:109] op_sel_hi:[0,1]
	v_mul_f32_e32 v121, v96, v62
	v_pk_fma_f32 v[118:119], v[118:119], v[60:61], v[108:109] op_sel_hi:[1,0,1]
	v_fma_f32 v120, v120, v60, v121
	v_readfirstlane_b32 s54, v40
	v_add_f32_e32 v39, s34, v40
	v_readlane_b32 s22, v175, 22
	v_max_f32_e32 v38, s40, v39
	v_readlane_b32 s32, v177, 22
	v_sub_f32_e32 v58, v39, v38
	v_sub_f32_e32 v59, s40, v38
	v_mul_f32_e32 v58, 0x3fb8aa3b, v58
	v_mul_f32_e32 v59, 0x3fb8aa3b, v59
	v_exp_f32_e32 v60, v58
	v_exp_f32_e32 v62, v59
	v_cvt_pk_bf16_f32 v122, v118, v119
	v_writelane_b32 v179, s54, 21
	global_store_dword v36, v122, s[6:7]
	s_add_u32 s6, s6, 0x20000
	s_addc_u32 s7, s7, 0
	global_store_dword v36, v120, s[10:11]
	s_add_u32 s10, s10, 0x800
	s_addc_u32 s11, s11, 0
	v_lshlrev_b32_e32 v108, 16, v163
	v_and_b32_e32 v109, 0xffff0000, v163
	v_pk_mul_f32 v[108:109], v[62:63], v[108:109] op_sel_hi:[0,1]
	v_mul_f32_e32 v121, v97, v62
	v_pk_fma_f32 v[118:119], v[118:119], v[60:61], v[108:109] op_sel_hi:[1,0,1]
	v_fma_f32 v120, v120, v60, v121
	v_readfirstlane_b32 s54, v38
	v_add_f32_e32 v39, s22, v38
	v_readlane_b32 s34, v175, 23
	v_max_f32_e32 v40, s32, v39
	v_readlane_b32 s40, v177, 23
	v_sub_f32_e32 v58, v39, v40
	v_sub_f32_e32 v59, s32, v40
	v_mul_f32_e32 v58, 0x3fb8aa3b, v58
	v_mul_f32_e32 v59, 0x3fb8aa3b, v59
	v_exp_f32_e32 v60, v58
	v_exp_f32_e32 v62, v59
	v_cvt_pk_bf16_f32 v122, v118, v119
	v_writelane_b32 v179, s54, 22
	global_store_dword v36, v122, s[6:7]
	s_add_u32 s6, s6, 0x20000
	s_addc_u32 s7, s7, 0
	global_store_dword v36, v120, s[10:11]
	s_add_u32 s10, s10, 0x800
	s_addc_u32 s11, s11, 0
	v_lshlrev_b32_e32 v108, 16, v164
	v_and_b32_e32 v109, 0xffff0000, v164
	v_pk_mul_f32 v[108:109], v[62:63], v[108:109] op_sel_hi:[0,1]
	v_mul_f32_e32 v121, v98, v62
	v_pk_fma_f32 v[118:119], v[118:119], v[60:61], v[108:109] op_sel_hi:[1,0,1]
	v_fma_f32 v120, v120, v60, v121
	v_readfirstlane_b32 s54, v40
	v_add_f32_e32 v39, s34, v40
	v_readlane_b32 s22, v175, 24
	v_max_f32_e32 v38, s40, v39
	v_readlane_b32 s32, v177, 24
	v_sub_f32_e32 v58, v39, v38
	v_sub_f32_e32 v59, s40, v38
	v_mul_f32_e32 v58, 0x3fb8aa3b, v58
	v_mul_f32_e32 v59, 0x3fb8aa3b, v59
	v_exp_f32_e32 v60, v58
	v_exp_f32_e32 v62, v59
	v_cvt_pk_bf16_f32 v122, v118, v119
	v_writelane_b32 v179, s54, 23
	global_store_dword v36, v122, s[6:7]
	s_add_u32 s6, s6, 0x20000
	s_addc_u32 s7, s7, 0
	global_store_dword v36, v120, s[10:11]
	s_add_u32 s10, s10, 0x800
	s_addc_u32 s11, s11, 0
	v_lshlrev_b32_e32 v108, 16, v165
	v_and_b32_e32 v109, 0xffff0000, v165
	v_pk_mul_f32 v[108:109], v[62:63], v[108:109] op_sel_hi:[0,1]
	v_mul_f32_e32 v121, v99, v62
	v_pk_fma_f32 v[118:119], v[118:119], v[60:61], v[108:109] op_sel_hi:[1,0,1]
	v_fma_f32 v120, v120, v60, v121
	v_readfirstlane_b32 s54, v38
	v_add_f32_e32 v39, s22, v38
	v_readlane_b32 s34, v175, 25
	v_max_f32_e32 v40, s32, v39
	v_readlane_b32 s40, v177, 25
	v_sub_f32_e32 v58, v39, v40
	v_sub_f32_e32 v59, s32, v40
	v_mul_f32_e32 v58, 0x3fb8aa3b, v58
	v_mul_f32_e32 v59, 0x3fb8aa3b, v59
	v_exp_f32_e32 v60, v58
	v_exp_f32_e32 v62, v59
	v_cvt_pk_bf16_f32 v122, v118, v119
	v_writelane_b32 v179, s54, 24
	global_store_dword v36, v122, s[6:7]
	s_add_u32 s6, s6, 0x20000
	s_addc_u32 s7, s7, 0
	global_store_dword v36, v120, s[10:11]
	s_add_u32 s10, s10, 0x800
	s_addc_u32 s11, s11, 0
	v_lshlrev_b32_e32 v108, 16, v166
	v_and_b32_e32 v109, 0xffff0000, v166
	v_pk_mul_f32 v[108:109], v[62:63], v[108:109] op_sel_hi:[0,1]
	v_mul_f32_e32 v121, v100, v62
	v_pk_fma_f32 v[118:119], v[118:119], v[60:61], v[108:109] op_sel_hi:[1,0,1]
	v_fma_f32 v120, v120, v60, v121
	v_readfirstlane_b32 s54, v40
	v_add_f32_e32 v39, s34, v40
	v_readlane_b32 s22, v175, 26
	v_max_f32_e32 v38, s40, v39
	v_readlane_b32 s32, v177, 26
	v_sub_f32_e32 v58, v39, v38
	v_sub_f32_e32 v59, s40, v38
	v_mul_f32_e32 v58, 0x3fb8aa3b, v58
	v_mul_f32_e32 v59, 0x3fb8aa3b, v59
	v_exp_f32_e32 v60, v58
	v_exp_f32_e32 v62, v59
	v_cvt_pk_bf16_f32 v122, v118, v119
	v_writelane_b32 v179, s54, 25
	global_store_dword v36, v122, s[6:7]
	s_add_u32 s6, s6, 0x20000
	s_addc_u32 s7, s7, 0
	global_store_dword v36, v120, s[10:11]
	s_add_u32 s10, s10, 0x800
	s_addc_u32 s11, s11, 0
	v_lshlrev_b32_e32 v108, 16, v167
	v_and_b32_e32 v109, 0xffff0000, v167
	v_pk_mul_f32 v[108:109], v[62:63], v[108:109] op_sel_hi:[0,1]
	v_mul_f32_e32 v121, v101, v62
	v_pk_fma_f32 v[118:119], v[118:119], v[60:61], v[108:109] op_sel_hi:[1,0,1]
	v_fma_f32 v120, v120, v60, v121
	v_readfirstlane_b32 s54, v38
	v_add_f32_e32 v39, s22, v38
	v_readlane_b32 s34, v175, 27
; __device__ __forceinline__ unsigned pk2(float lo, float hi) { f32x2_t v = {lo, hi}; bf16x2_t b = __builtin_convertvector(v, bf16x2_t); return __builtin_bit_cast(unsigned, b); }
; __device__ __forceinline__ float bflo(unsigned w) { return __uint_as_float(w << 16); }
; __device__ __forceinline__ float bfhi(unsigned w) { return __uint_as_float(w & 0xffff0000u); }
; __device__ __forceinline__ float fexp(float x) { return __builtin_amdgcn_exp2f(x * LOG2E); }
;     __device__ __forceinline__ float* MBM() const { return (float*)(ws + WS_MB); }
;     __device__ __forceinline__ float* MBB() const { return (float*)(ws + WS_MB) + (NSLOT_P + NSLOT_S); }
;     __device__ __forceinline__ float* MST() const { return (float*)(ws + WS_MB) + 2 * (NSLOT_P + NSLOT_S); }
; __device__ __forceinline__ void phase_scan(Ctx& C, int l, const bool st, LAS unsigned char* lds) {
;     ...
;         for (int cg0 = 0; cg0 < NPC; cg0 += 16) {
;             if (cg0 + 16 < NPC) {
; #pragma unroll
;                 for (int j = 0; j < 16; ++j) { nb[j] = base[(size_t)((b * NPC + cg0 + 16 + j) * 4 + h) * 8192]; fnb[j] = hn ? dnb[(size_t)((b * NPC + cg0 + 16 + j) * 4 + h) * 128] : 0.f; }
;             }
; #pragma unroll
;             for (int j = 0; j < 16; ++j) { const int slot = (b * NPC + cg0 + j) * 4 + h;
;                 const float Bc = C.MBB()[slot], Mc = C.MBM()[slot];
;                 const float mn = fmaxf(Bc + m, Mc), g = fexp(Bc + m - mn), f = fexp(Mc - mn);
;                 if (st) { base[(size_t)slot * 8192] = pk2(c0, c1); if (hn) { dnb[(size_t)slot * 128] = nn; if (p == 0) C.MST()[slot] = m; } }
;                 c0 = g * c0 + f * bflo(buf[j]); c1 = g * c1 + f * bfhi(buf[j]); nn = g * nn + f * fb[j]; m = mn; }
; #pragma unroll
;             for (int j = 0; j < 16; ++j) { buf[j] = nb[j]; fb[j] = fnb[j]; }
	v_max_f32_e32 v40, s32, v39
	v_readlane_b32 s40, v177, 27
	v_sub_f32_e32 v58, v39, v40
	v_sub_f32_e32 v59, s32, v40
	v_mul_f32_e32 v58, 0x3fb8aa3b, v58
	v_mul_f32_e32 v59, 0x3fb8aa3b, v59
	v_exp_f32_e32 v60, v58
	v_exp_f32_e32 v62, v59
	v_cvt_pk_bf16_f32 v122, v118, v119
	v_writelane_b32 v179, s54, 26
	global_store_dword v36, v122, s[6:7]
	s_add_u32 s6, s6, 0x20000
	s_addc_u32 s7, s7, 0
	global_store_dword v36, v120, s[10:11]
	s_add_u32 s10, s10, 0x800
	s_addc_u32 s11, s11, 0
	v_lshlrev_b32_e32 v108, 16, v168
	v_and_b32_e32 v109, 0xffff0000, v168
	v_pk_mul_f32 v[108:109], v[62:63], v[108:109] op_sel_hi:[0,1]
	v_mul_f32_e32 v121, v102, v62
	v_pk_fma_f32 v[118:119], v[118:119], v[60:61], v[108:109] op_sel_hi:[1,0,1]
	v_fma_f32 v120, v120, v60, v121
	v_readfirstlane_b32 s54, v40
	v_add_f32_e32 v39, s34, v40
	v_readlane_b32 s22, v175, 28
	v_max_f32_e32 v38, s40, v39
	v_readlane_b32 s32, v177, 28
	v_sub_f32_e32 v58, v39, v38
	v_sub_f32_e32 v59, s40, v38
	v_mul_f32_e32 v58, 0x3fb8aa3b, v58
	v_mul_f32_e32 v59, 0x3fb8aa3b, v59
	v_exp_f32_e32 v60, v58
	v_exp_f32_e32 v62, v59
	v_cvt_pk_bf16_f32 v122, v118, v119
	v_writelane_b32 v179, s54, 27
	global_store_dword v36, v122, s[6:7]
	s_add_u32 s6, s6, 0x20000
	s_addc_u32 s7, s7, 0
	global_store_dword v36, v120, s[10:11]
	s_add_u32 s10, s10, 0x800
	s_addc_u32 s11, s11, 0
	v_lshlrev_b32_e32 v108, 16, v169
	v_and_b32_e32 v109, 0xffff0000, v169
	v_pk_mul_f32 v[108:109], v[62:63], v[108:109] op_sel_hi:[0,1]
	v_mul_f32_e32 v121, v103, v62
	v_pk_fma_f32 v[118:119], v[118:119], v[60:61], v[108:109] op_sel_hi:[1,0,1]
	v_fma_f32 v120, v120, v60, v121
	v_readfirstlane_b32 s54, v38
	v_add_f32_e32 v39, s22, v38
	v_readlane_b32 s34, v175, 29
	v_max_f32_e32 v40, s32, v39
	v_readlane_b32 s40, v177, 29
	v_sub_f32_e32 v58, v39, v40
	v_sub_f32_e32 v59, s32, v40
	v_mul_f32_e32 v58, 0x3fb8aa3b, v58
	v_mul_f32_e32 v59, 0x3fb8aa3b, v59
	v_exp_f32_e32 v60, v58
	v_exp_f32_e32 v62, v59
	v_cvt_pk_bf16_f32 v122, v118, v119
	v_writelane_b32 v179, s54, 28
	global_store_dword v36, v122, s[6:7]
	s_add_u32 s6, s6, 0x20000
	s_addc_u32 s7, s7, 0
	global_store_dword v36, v120, s[10:11]
	s_add_u32 s10, s10, 0x800
	s_addc_u32 s11, s11, 0
	v_lshlrev_b32_e32 v108, 16, v170
	v_and_b32_e32 v109, 0xffff0000, v170
	v_pk_mul_f32 v[108:109], v[62:63], v[108:109] op_sel_hi:[0,1]
	v_mul_f32_e32 v121, v104, v62
	v_pk_fma_f32 v[118:119], v[118:119], v[60:61], v[108:109] op_sel_hi:[1,0,1]
	v_fma_f32 v120, v120, v60, v121
	v_readfirstlane_b32 s54, v40
	v_add_f32_e32 v39, s34, v40
	v_readlane_b32 s22, v175, 30
	v_max_f32_e32 v38, s40, v39
	v_readlane_b32 s32, v177, 30
	v_sub_f32_e32 v58, v39, v38
	v_sub_f32_e32 v59, s40, v38
	v_mul_f32_e32 v58, 0x3fb8aa3b, v58
	v_mul_f32_e32 v59, 0x3fb8aa3b, v59
	v_exp_f32_e32 v60, v58
	v_exp_f32_e32 v62, v59
	v_cvt_pk_bf16_f32 v122, v118, v119
	v_writelane_b32 v179, s54, 29
	global_store_dword v36, v122, s[6:7]
	s_add_u32 s6, s6, 0x20000
	s_addc_u32 s7, s7, 0
	global_store_dword v36, v120, s[10:11]
	s_add_u32 s10, s10, 0x800
	s_addc_u32 s11, s11, 0
	v_lshlrev_b32_e32 v108, 16, v171
	v_and_b32_e32 v109, 0xffff0000, v171
	v_pk_mul_f32 v[108:109], v[62:63], v[108:109] op_sel_hi:[0,1]
	v_mul_f32_e32 v121, v105, v62
	v_pk_fma_f32 v[118:119], v[118:119], v[60:61], v[108:109] op_sel_hi:[1,0,1]
	v_fma_f32 v120, v120, v60, v121
	v_readfirstlane_b32 s54, v38
	v_add_f32_e32 v39, s22, v38
	v_readlane_b32 s34, v175, 31
	v_max_f32_e32 v40, s32, v39
	v_readlane_b32 s40, v177, 31
	v_sub_f32_e32 v58, v39, v40
	v_sub_f32_e32 v59, s32, v40
	v_mul_f32_e32 v58, 0x3fb8aa3b, v58
	v_mul_f32_e32 v59, 0x3fb8aa3b, v59
	v_exp_f32_e32 v60, v58
	v_exp_f32_e32 v62, v59
	v_cvt_pk_bf16_f32 v122, v118, v119
	v_writelane_b32 v179, s54, 30
	global_store_dword v36, v122, s[6:7]
	s_add_u32 s6, s6, 0x20000
	s_addc_u32 s7, s7, 0
	global_store_dword v36, v120, s[10:11]
	s_add_u32 s10, s10, 0x800
	s_addc_u32 s11, s11, 0
	v_lshlrev_b32_e32 v108, 16, v172
	v_and_b32_e32 v109, 0xffff0000, v172
	v_pk_mul_f32 v[108:109], v[62:63], v[108:109] op_sel_hi:[0,1]
	v_mul_f32_e32 v121, v106, v62
	v_pk_fma_f32 v[118:119], v[118:119], v[60:61], v[108:109] op_sel_hi:[1,0,1]
	v_fma_f32 v120, v120, v60, v121
	v_readfirstlane_b32 s54, v40
	v_add_f32_e32 v39, s34, v40
	v_readlane_b32 s22, v175, 32
	v_max_f32_e32 v38, s40, v39
	v_readlane_b32 s32, v177, 32
	v_sub_f32_e32 v58, v39, v38
	v_sub_f32_e32 v59, s40, v38
	v_mul_f32_e32 v58, 0x3fb8aa3b, v58
	v_mul_f32_e32 v59, 0x3fb8aa3b, v59
	v_exp_f32_e32 v60, v58
	v_exp_f32_e32 v62, v59
	v_cvt_pk_bf16_f32 v122, v118, v119
	v_writelane_b32 v179, s54, 31
	global_store_dword v36, v122, s[6:7]
	s_add_u32 s6, s6, 0x20000
	s_addc_u32 s7, s7, 0
	global_store_dword v36, v120, s[10:11]
	s_add_u32 s10, s10, 0x800
	s_addc_u32 s11, s11, 0
	v_lshlrev_b32_e32 v108, 16, v173
	v_and_b32_e32 v109, 0xffff0000, v173
	v_pk_mul_f32 v[108:109], v[62:63], v[108:109] op_sel_hi:[0,1]
	v_mul_f32_e32 v121, v107, v62
	v_pk_fma_f32 v[118:119], v[118:119], v[60:61], v[108:109] op_sel_hi:[1,0,1]
	v_fma_f32 v120, v120, v60, v121
; __device__ __forceinline__ unsigned pk2(float lo, float hi) { f32x2_t v = {lo, hi}; bf16x2_t b = __builtin_convertvector(v, bf16x2_t); return __builtin_bit_cast(unsigned, b); }
; __device__ __forceinline__ float bflo(unsigned w) { return __uint_as_float(w << 16); }
; __device__ __forceinline__ float bfhi(unsigned w) { return __uint_as_float(w & 0xffff0000u); }
; __device__ __forceinline__ float fexp(float x) { return __builtin_amdgcn_exp2f(x * LOG2E); }
;     __device__ __forceinline__ float* MBM() const { return (float*)(ws + WS_MB); }
;     __device__ __forceinline__ float* MBB() const { return (float*)(ws + WS_MB) + (NSLOT_P + NSLOT_S); }
;     __device__ __forceinline__ float* MST() const { return (float*)(ws + WS_MB) + 2 * (NSLOT_P + NSLOT_S); }
; __device__ __forceinline__ void phase_scan(Ctx& C, int l, const bool st, LAS unsigned char* lds) {
;     ...
;         for (int cg0 = 0; cg0 < NPC; cg0 += 16) {
;             if (cg0 + 16 < NPC) {
; #pragma unroll
;                 for (int j = 0; j < 16; ++j) { nb[j] = base[(size_t)((b * NPC + cg0 + 16 + j) * 4 + h) * 8192]; fnb[j] = hn ? dnb[(size_t)((b * NPC + cg0 + 16 + j) * 4 + h) * 128] : 0.f; }
;             }
; #pragma unroll
;             for (int j = 0; j < 16; ++j) { const int slot = (b * NPC + cg0 + j) * 4 + h;
;                 const float Bc = C.MBB()[slot], Mc = C.MBM()[slot];
;                 const float mn = fmaxf(Bc + m, Mc), g = fexp(Bc + m - mn), f = fexp(Mc - mn);
;                 if (st) { base[(size_t)slot * 8192] = pk2(c0, c1); if (hn) { dnb[(size_t)slot * 128] = nn; if (p == 0) C.MST()[slot] = m; } }
;                 c0 = g * c0 + f * bflo(buf[j]); c1 = g * c1 + f * bfhi(buf[j]); nn = g * nn + f * fb[j]; m = mn; }
; #pragma unroll
;             for (int j = 0; j < 16; ++j) { buf[j] = nb[j]; fb[j] = fnb[j]; }
.Lscan_hn_b6:
	s_waitcnt vmcnt(32)
	global_load_dword v142, v36, s[4:5]
	s_add_u32 s4, s4, 0x20000
	s_addc_u32 s5, s5, 0
	global_load_dword v143, v36, s[4:5]
	s_add_u32 s4, s4, 0x20000
	s_addc_u32 s5, s5, 0
	global_load_dword v144, v36, s[4:5]
	s_add_u32 s4, s4, 0x20000
	s_addc_u32 s5, s5, 0
	global_load_dword v145, v36, s[4:5]
	s_add_u32 s4, s4, 0x20000
	s_addc_u32 s5, s5, 0
	global_load_dword v146, v36, s[4:5]
	s_add_u32 s4, s4, 0x20000
	s_addc_u32 s5, s5, 0
	global_load_dword v147, v36, s[4:5]
	s_add_u32 s4, s4, 0x20000
	s_addc_u32 s5, s5, 0
	global_load_dword v148, v36, s[4:5]
	s_add_u32 s4, s4, 0x20000
	s_addc_u32 s5, s5, 0
	global_load_dword v149, v36, s[4:5]
	s_add_u32 s4, s4, 0x20000
	s_addc_u32 s5, s5, 0
	global_load_dword v150, v36, s[4:5]
	s_add_u32 s4, s4, 0x20000
	s_addc_u32 s5, s5, 0
	global_load_dword v151, v36, s[4:5]
	s_add_u32 s4, s4, 0x20000
	s_addc_u32 s5, s5, 0
	global_load_dword v152, v36, s[4:5]
	s_add_u32 s4, s4, 0x20000
	s_addc_u32 s5, s5, 0
	global_load_dword v153, v36, s[4:5]
	s_add_u32 s4, s4, 0x20000
	s_addc_u32 s5, s5, 0
	global_load_dword v154, v36, s[4:5]
	s_add_u32 s4, s4, 0x20000
	s_addc_u32 s5, s5, 0
	global_load_dword v155, v36, s[4:5]
	s_add_u32 s4, s4, 0x20000
	s_addc_u32 s5, s5, 0
	global_load_dword v156, v36, s[4:5]
	s_add_u32 s4, s4, 0x20000
	s_addc_u32 s5, s5, 0
	global_load_dword v157, v36, s[4:5]
	s_add_u32 s4, s4, 0x20000
	s_addc_u32 s5, s5, 0
	global_load_dword v42, v36, s[8:9]
	s_add_u32 s8, s8, 0x800
	s_addc_u32 s9, s9, 0
	global_load_dword v43, v36, s[8:9]
	s_add_u32 s8, s8, 0x800
	s_addc_u32 s9, s9, 0
	global_load_dword v44, v36, s[8:9]
	s_add_u32 s8, s8, 0x800
	s_addc_u32 s9, s9, 0
	global_load_dword v45, v36, s[8:9]
	s_add_u32 s8, s8, 0x800
	s_addc_u32 s9, s9, 0
	global_load_dword v46, v36, s[8:9]
	s_add_u32 s8, s8, 0x800
	s_addc_u32 s9, s9, 0
	global_load_dword v47, v36, s[8:9]
	s_add_u32 s8, s8, 0x800
	s_addc_u32 s9, s9, 0
	global_load_dword v48, v36, s[8:9]
	s_add_u32 s8, s8, 0x800
	s_addc_u32 s9, s9, 0
	global_load_dword v49, v36, s[8:9]
	s_add_u32 s8, s8, 0x800
	s_addc_u32 s9, s9, 0
	global_load_dword v50, v36, s[8:9]
	s_add_u32 s8, s8, 0x800
	s_addc_u32 s9, s9, 0
	global_load_dword v51, v36, s[8:9]
	s_add_u32 s8, s8, 0x800
	s_addc_u32 s9, s9, 0
	global_load_dword v52, v36, s[8:9]
	s_add_u32 s8, s8, 0x800
	s_addc_u32 s9, s9, 0
	global_load_dword v53, v36, s[8:9]
	s_add_u32 s8, s8, 0x800
	s_addc_u32 s9, s9, 0
	global_load_dword v54, v36, s[8:9]
	s_add_u32 s8, s8, 0x800
	s_addc_u32 s9, s9, 0
	global_load_dword v55, v36, s[8:9]
	s_add_u32 s8, s8, 0x800
	s_addc_u32 s9, s9, 0
	global_load_dword v56, v36, s[8:9]
	s_add_u32 s8, s8, 0x800
	s_addc_u32 s9, s9, 0
	global_load_dword v57, v36, s[8:9]
	s_add_u32 s8, s8, 0x800
	s_addc_u32 s9, s9, 0
	v_readfirstlane_b32 s54, v38
	v_add_f32_e32 v39, s22, v38
	v_readlane_b32 s34, v175, 33
	v_max_f32_e32 v40, s32, v39
	v_readlane_b32 s40, v177, 33
	v_sub_f32_e32 v58, v39, v40
	v_sub_f32_e32 v59, s32, v40
	v_mul_f32_e32 v58, 0x3fb8aa3b, v58
	v_mul_f32_e32 v59, 0x3fb8aa3b, v59
	v_exp_f32_e32 v60, v58
	v_exp_f32_e32 v62, v59
	v_cvt_pk_bf16_f32 v122, v118, v119
	v_writelane_b32 v179, s54, 32
	global_store_dword v36, v122, s[6:7]
	s_add_u32 s6, s6, 0x20000
	s_addc_u32 s7, s7, 0
	global_store_dword v36, v120, s[10:11]
	s_add_u32 s10, s10, 0x800
	s_addc_u32 s11, s11, 0
	v_lshlrev_b32_e32 v108, 16, v126
	v_and_b32_e32 v109, 0xffff0000, v126
	v_pk_mul_f32 v[108:109], v[62:63], v[108:109] op_sel_hi:[0,1]
	v_mul_f32_e32 v121, v16, v62
	v_pk_fma_f32 v[118:119], v[118:119], v[60:61], v[108:109] op_sel_hi:[1,0,1]
	v_fma_f32 v120, v120, v60, v121
	v_readfirstlane_b32 s54, v40
	v_add_f32_e32 v39, s34, v40
	v_readlane_b32 s22, v175, 34
	v_max_f32_e32 v38, s40, v39
	v_readlane_b32 s32, v177, 34
	v_sub_f32_e32 v58, v39, v38
	v_sub_f32_e32 v59, s40, v38
	v_mul_f32_e32 v58, 0x3fb8aa3b, v58
	v_mul_f32_e32 v59, 0x3fb8aa3b, v59
	v_exp_f32_e32 v60, v58
	v_exp_f32_e32 v62, v59
	v_cvt_pk_bf16_f32 v122, v118, v119
	v_writelane_b32 v179, s54, 33
	global_store_dword v36, v122, s[6:7]
	s_add_u32 s6, s6, 0x20000
	s_addc_u32 s7, s7, 0
	global_store_dword v36, v120, s[10:11]
	s_add_u32 s10, s10, 0x800
	s_addc_u32 s11, s11, 0
	v_lshlrev_b32_e32 v108, 16, v127
	v_and_b32_e32 v109, 0xffff0000, v127
	v_pk_mul_f32 v[108:109], v[62:63], v[108:109] op_sel_hi:[0,1]
	v_mul_f32_e32 v121, v17, v62
	v_pk_fma_f32 v[118:119], v[118:119], v[60:61], v[108:109] op_sel_hi:[1,0,1]
	v_fma_f32 v120, v120, v60, v121
	v_readfirstlane_b32 s54, v38
	v_add_f32_e32 v39, s22, v38
	v_readlane_b32 s34, v175, 35
	v_max_f32_e32 v40, s32, v39
	v_readlane_b32 s40, v177, 35
	v_sub_f32_e32 v58, v39, v40
	v_sub_f32_e32 v59, s32, v40
	v_mul_f32_e32 v58, 0x3fb8aa3b, v58
	v_mul_f32_e32 v59, 0x3fb8aa3b, v59
	v_exp_f32_e32 v60, v58
	v_exp_f32_e32 v62, v59
	v_cvt_pk_bf16_f32 v122, v118, v119
	v_writelane_b32 v179, s54, 34
	global_store_dword v36, v122, s[6:7]
	s_add_u32 s6, s6, 0x20000
	s_addc_u32 s7, s7, 0
	global_store_dword v36, v120, s[10:11]
	s_add_u32 s10, s10, 0x800
	s_addc_u32 s11, s11, 0
	v_lshlrev_b32_e32 v108, 16, v128
	v_and_b32_e32 v109, 0xffff0000, v128
	v_pk_mul_f32 v[108:109], v[62:63], v[108:109] op_sel_hi:[0,1]
	v_mul_f32_e32 v121, v18, v62
	v_pk_fma_f32 v[118:119], v[118:119], v[60:61], v[108:109] op_sel_hi:[1,0,1]
	v_fma_f32 v120, v120, v60, v121
	v_readfirstlane_b32 s54, v40
	v_add_f32_e32 v39, s34, v40
	v_readlane_b32 s22, v175, 36
	v_max_f32_e32 v38, s40, v39
	v_readlane_b32 s32, v177, 36
	v_sub_f32_e32 v58, v39, v38
	v_sub_f32_e32 v59, s40, v38
	v_mul_f32_e32 v58, 0x3fb8aa3b, v58
	v_mul_f32_e32 v59, 0x3fb8aa3b, v59
	v_exp_f32_e32 v60, v58
	v_exp_f32_e32 v62, v59
	v_cvt_pk_bf16_f32 v122, v118, v119
; __device__ __forceinline__ unsigned pk2(float lo, float hi) { f32x2_t v = {lo, hi}; bf16x2_t b = __builtin_convertvector(v, bf16x2_t); return __builtin_bit_cast(unsigned, b); }
; __device__ __forceinline__ float bflo(unsigned w) { return __uint_as_float(w << 16); }
; __device__ __forceinline__ float bfhi(unsigned w) { return __uint_as_float(w & 0xffff0000u); }
; __device__ __forceinline__ float fexp(float x) { return __builtin_amdgcn_exp2f(x * LOG2E); }
;     __device__ __forceinline__ float* MBM() const { return (float*)(ws + WS_MB); }
;     __device__ __forceinline__ float* MBB() const { return (float*)(ws + WS_MB) + (NSLOT_P + NSLOT_S); }
;     __device__ __forceinline__ float* MST() const { return (float*)(ws + WS_MB) + 2 * (NSLOT_P + NSLOT_S); }
; __device__ __forceinline__ void phase_scan(Ctx& C, int l, const bool st, LAS unsigned char* lds) {
;     ...
;         for (int cg0 = 0; cg0 < NPC; cg0 += 16) {
;             if (cg0 + 16 < NPC) {
; #pragma unroll
;                 for (int j = 0; j < 16; ++j) { nb[j] = base[(size_t)((b * NPC + cg0 + 16 + j) * 4 + h) * 8192]; fnb[j] = hn ? dnb[(size_t)((b * NPC + cg0 + 16 + j) * 4 + h) * 128] : 0.f; }
;             }
; #pragma unroll
;             for (int j = 0; j < 16; ++j) { const int slot = (b * NPC + cg0 + j) * 4 + h;
;                 const float Bc = C.MBB()[slot], Mc = C.MBM()[slot];
;                 const float mn = fmaxf(Bc + m, Mc), g = fexp(Bc + m - mn), f = fexp(Mc - mn);
;                 if (st) { base[(size_t)slot * 8192] = pk2(c0, c1); if (hn) { dnb[(size_t)slot * 128] = nn; if (p == 0) C.MST()[slot] = m; } }
;                 c0 = g * c0 + f * bflo(buf[j]); c1 = g * c1 + f * bfhi(buf[j]); nn = g * nn + f * fb[j]; m = mn; }
; #pragma unroll
;             for (int j = 0; j < 16; ++j) { buf[j] = nb[j]; fb[j] = fnb[j]; }
	v_writelane_b32 v179, s54, 35
	global_store_dword v36, v122, s[6:7]
	s_add_u32 s6, s6, 0x20000
	s_addc_u32 s7, s7, 0
	global_store_dword v36, v120, s[10:11]
	s_add_u32 s10, s10, 0x800
	s_addc_u32 s11, s11, 0
	v_lshlrev_b32_e32 v108, 16, v129
	v_and_b32_e32 v109, 0xffff0000, v129
	v_pk_mul_f32 v[108:109], v[62:63], v[108:109] op_sel_hi:[0,1]
	v_mul_f32_e32 v121, v19, v62
	v_pk_fma_f32 v[118:119], v[118:119], v[60:61], v[108:109] op_sel_hi:[1,0,1]
	v_fma_f32 v120, v120, v60, v121
	v_readfirstlane_b32 s54, v38
	v_add_f32_e32 v39, s22, v38
	v_readlane_b32 s34, v175, 37
	v_max_f32_e32 v40, s32, v39
	v_readlane_b32 s40, v177, 37
	v_sub_f32_e32 v58, v39, v40
	v_sub_f32_e32 v59, s32, v40
	v_mul_f32_e32 v58, 0x3fb8aa3b, v58
	v_mul_f32_e32 v59, 0x3fb8aa3b, v59
	v_exp_f32_e32 v60, v58
	v_exp_f32_e32 v62, v59
	v_cvt_pk_bf16_f32 v122, v118, v119
	v_writelane_b32 v179, s54, 36
	global_store_dword v36, v122, s[6:7]
	s_add_u32 s6, s6, 0x20000
	s_addc_u32 s7, s7, 0
	global_store_dword v36, v120, s[10:11]
	s_add_u32 s10, s10, 0x800
	s_addc_u32 s11, s11, 0
	v_lshlrev_b32_e32 v108, 16, v130
	v_and_b32_e32 v109, 0xffff0000, v130
	v_pk_mul_f32 v[108:109], v[62:63], v[108:109] op_sel_hi:[0,1]
	v_mul_f32_e32 v121, v20, v62
	v_pk_fma_f32 v[118:119], v[118:119], v[60:61], v[108:109] op_sel_hi:[1,0,1]
	v_fma_f32 v120, v120, v60, v121
	v_readfirstlane_b32 s54, v40
	v_add_f32_e32 v39, s34, v40
	v_readlane_b32 s22, v175, 38
	v_max_f32_e32 v38, s40, v39
	v_readlane_b32 s32, v177, 38
	v_sub_f32_e32 v58, v39, v38
	v_sub_f32_e32 v59, s40, v38
	v_mul_f32_e32 v58, 0x3fb8aa3b, v58
	v_mul_f32_e32 v59, 0x3fb8aa3b, v59
	v_exp_f32_e32 v60, v58
	v_exp_f32_e32 v62, v59
	v_cvt_pk_bf16_f32 v122, v118, v119
	v_writelane_b32 v179, s54, 37
	global_store_dword v36, v122, s[6:7]
	s_add_u32 s6, s6, 0x20000
	s_addc_u32 s7, s7, 0
	global_store_dword v36, v120, s[10:11]
	s_add_u32 s10, s10, 0x800
	s_addc_u32 s11, s11, 0
	v_lshlrev_b32_e32 v108, 16, v131
	v_and_b32_e32 v109, 0xffff0000, v131
	v_pk_mul_f32 v[108:109], v[62:63], v[108:109] op_sel_hi:[0,1]
	v_mul_f32_e32 v121, v21, v62
	v_pk_fma_f32 v[118:119], v[118:119], v[60:61], v[108:109] op_sel_hi:[1,0,1]
	v_fma_f32 v120, v120, v60, v121
	v_readfirstlane_b32 s54, v38
	v_add_f32_e32 v39, s22, v38
	v_readlane_b32 s34, v175, 39
	v_max_f32_e32 v40, s32, v39
	v_readlane_b32 s40, v177, 39
	v_sub_f32_e32 v58, v39, v40
	v_sub_f32_e32 v59, s32, v40
	v_mul_f32_e32 v58, 0x3fb8aa3b, v58
	v_mul_f32_e32 v59, 0x3fb8aa3b, v59
	v_exp_f32_e32 v60, v58
	v_exp_f32_e32 v62, v59
	v_cvt_pk_bf16_f32 v122, v118, v119
	v_writelane_b32 v179, s54, 38
	global_store_dword v36, v122, s[6:7]
	s_add_u32 s6, s6, 0x20000
	s_addc_u32 s7, s7, 0
	global_store_dword v36, v120, s[10:11]
	s_add_u32 s10, s10, 0x800
	s_addc_u32 s11, s11, 0
	v_lshlrev_b32_e32 v108, 16, v132
	v_and_b32_e32 v109, 0xffff0000, v132
	v_pk_mul_f32 v[108:109], v[62:63], v[108:109] op_sel_hi:[0,1]
	v_mul_f32_e32 v121, v22, v62
	v_pk_fma_f32 v[118:119], v[118:119], v[60:61], v[108:109] op_sel_hi:[1,0,1]
	v_fma_f32 v120, v120, v60, v121
	v_readfirstlane_b32 s54, v40
	v_add_f32_e32 v39, s34, v40
	v_readlane_b32 s22, v175, 40
	v_max_f32_e32 v38, s40, v39
	v_readlane_b32 s32, v177, 40
	v_sub_f32_e32 v58, v39, v38
	v_sub_f32_e32 v59, s40, v38
	v_mul_f32_e32 v58, 0x3fb8aa3b, v58
	v_mul_f32_e32 v59, 0x3fb8aa3b, v59
	v_exp_f32_e32 v60, v58
	v_exp_f32_e32 v62, v59
	v_cvt_pk_bf16_f32 v122, v118, v119
	v_writelane_b32 v179, s54, 39
	global_store_dword v36, v122, s[6:7]
	s_add_u32 s6, s6, 0x20000
	s_addc_u32 s7, s7, 0
	global_store_dword v36, v120, s[10:11]
	s_add_u32 s10, s10, 0x800
	s_addc_u32 s11, s11, 0
	v_lshlrev_b32_e32 v108, 16, v133
	v_and_b32_e32 v109, 0xffff0000, v133
	v_pk_mul_f32 v[108:109], v[62:63], v[108:109] op_sel_hi:[0,1]
	v_mul_f32_e32 v121, v23, v62
	v_pk_fma_f32 v[118:119], v[118:119], v[60:61], v[108:109] op_sel_hi:[1,0,1]
	v_fma_f32 v120, v120, v60, v121
	v_readfirstlane_b32 s54, v38
	v_add_f32_e32 v39, s22, v38
	v_readlane_b32 s34, v175, 41
	v_max_f32_e32 v40, s32, v39
	v_readlane_b32 s40, v177, 41
	v_sub_f32_e32 v58, v39, v40
	v_sub_f32_e32 v59, s32, v40
	v_mul_f32_e32 v58, 0x3fb8aa3b, v58
	v_mul_f32_e32 v59, 0x3fb8aa3b, v59
	v_exp_f32_e32 v60, v58
	v_exp_f32_e32 v62, v59
	v_cvt_pk_bf16_f32 v122, v118, v119
	v_writelane_b32 v179, s54, 40
	global_store_dword v36, v122, s[6:7]
	s_add_u32 s6, s6, 0x20000
	s_addc_u32 s7, s7, 0
	global_store_dword v36, v120, s[10:11]
	s_add_u32 s10, s10, 0x800
	s_addc_u32 s11, s11, 0
	v_lshlrev_b32_e32 v108, 16, v134
	v_and_b32_e32 v109, 0xffff0000, v134
	v_pk_mul_f32 v[108:109], v[62:63], v[108:109] op_sel_hi:[0,1]
	v_mul_f32_e32 v121, v24, v62
	v_pk_fma_f32 v[118:119], v[118:119], v[60:61], v[108:109] op_sel_hi:[1,0,1]
	v_fma_f32 v120, v120, v60, v121
	v_readfirstlane_b32 s54, v40
	v_add_f32_e32 v39, s34, v40
	v_readlane_b32 s22, v175, 42
	v_max_f32_e32 v38, s40, v39
	v_readlane_b32 s32, v177, 42
	v_sub_f32_e32 v58, v39, v38
	v_sub_f32_e32 v59, s40, v38
	v_mul_f32_e32 v58, 0x3fb8aa3b, v58
	v_mul_f32_e32 v59, 0x3fb8aa3b, v59
	v_exp_f32_e32 v60, v58
	v_exp_f32_e32 v62, v59
	v_cvt_pk_bf16_f32 v122, v118, v119
	v_writelane_b32 v179, s54, 41
	global_store_dword v36, v122, s[6:7]
	s_add_u32 s6, s6, 0x20000
	s_addc_u32 s7, s7, 0
	global_store_dword v36, v120, s[10:11]
	s_add_u32 s10, s10, 0x800
	s_addc_u32 s11, s11, 0
	v_lshlrev_b32_e32 v108, 16, v135
	v_and_b32_e32 v109, 0xffff0000, v135
	v_pk_mul_f32 v[108:109], v[62:63], v[108:109] op_sel_hi:[0,1]
	v_mul_f32_e32 v121, v25, v62
	v_pk_fma_f32 v[118:119], v[118:119], v[60:61], v[108:109] op_sel_hi:[1,0,1]
	v_fma_f32 v120, v120, v60, v121
	v_readfirstlane_b32 s54, v38
	v_add_f32_e32 v39, s22, v38
	v_readlane_b32 s34, v175, 43
; __device__ __forceinline__ unsigned pk2(float lo, float hi) { f32x2_t v = {lo, hi}; bf16x2_t b = __builtin_convertvector(v, bf16x2_t); return __builtin_bit_cast(unsigned, b); }
; __device__ __forceinline__ float bflo(unsigned w) { return __uint_as_float(w << 16); }
; __device__ __forceinline__ float bfhi(unsigned w) { return __uint_as_float(w & 0xffff0000u); }
; __device__ __forceinline__ float fexp(float x) { return __builtin_amdgcn_exp2f(x * LOG2E); }
;     __device__ __forceinline__ float* MBM() const { return (float*)(ws + WS_MB); }
;     __device__ __forceinline__ float* MBB() const { return (float*)(ws + WS_MB) + (NSLOT_P + NSLOT_S); }
;     __device__ __forceinline__ float* MST() const { return (float*)(ws + WS_MB) + 2 * (NSLOT_P + NSLOT_S); }
; __device__ __forceinline__ void phase_scan(Ctx& C, int l, const bool st, LAS unsigned char* lds) {
;     ...
;         for (int cg0 = 0; cg0 < NPC; cg0 += 16) {
;             if (cg0 + 16 < NPC) {
; #pragma unroll
;                 for (int j = 0; j < 16; ++j) { nb[j] = base[(size_t)((b * NPC + cg0 + 16 + j) * 4 + h) * 8192]; fnb[j] = hn ? dnb[(size_t)((b * NPC + cg0 + 16 + j) * 4 + h) * 128] : 0.f; }
;             }
; #pragma unroll
;             for (int j = 0; j < 16; ++j) { const int slot = (b * NPC + cg0 + j) * 4 + h;
;                 const float Bc = C.MBB()[slot], Mc = C.MBM()[slot];
;                 const float mn = fmaxf(Bc + m, Mc), g = fexp(Bc + m - mn), f = fexp(Mc - mn);
;                 if (st) { base[(size_t)slot * 8192] = pk2(c0, c1); if (hn) { dnb[(size_t)slot * 128] = nn; if (p == 0) C.MST()[slot] = m; } }
;                 c0 = g * c0 + f * bflo(buf[j]); c1 = g * c1 + f * bfhi(buf[j]); nn = g * nn + f * fb[j]; m = mn; }
; #pragma unroll
;             for (int j = 0; j < 16; ++j) { buf[j] = nb[j]; fb[j] = fnb[j]; }
	v_max_f32_e32 v40, s32, v39
	v_readlane_b32 s40, v177, 43
	v_sub_f32_e32 v58, v39, v40
	v_sub_f32_e32 v59, s32, v40
	v_mul_f32_e32 v58, 0x3fb8aa3b, v58
	v_mul_f32_e32 v59, 0x3fb8aa3b, v59
	v_exp_f32_e32 v60, v58
	v_exp_f32_e32 v62, v59
	v_cvt_pk_bf16_f32 v122, v118, v119
	v_writelane_b32 v179, s54, 42
	global_store_dword v36, v122, s[6:7]
	s_add_u32 s6, s6, 0x20000
	s_addc_u32 s7, s7, 0
	global_store_dword v36, v120, s[10:11]
	s_add_u32 s10, s10, 0x800
	s_addc_u32 s11, s11, 0
	v_lshlrev_b32_e32 v108, 16, v136
	v_and_b32_e32 v109, 0xffff0000, v136
	v_pk_mul_f32 v[108:109], v[62:63], v[108:109] op_sel_hi:[0,1]
	v_mul_f32_e32 v121, v26, v62
	v_pk_fma_f32 v[118:119], v[118:119], v[60:61], v[108:109] op_sel_hi:[1,0,1]
	v_fma_f32 v120, v120, v60, v121
	v_readfirstlane_b32 s54, v40
	v_add_f32_e32 v39, s34, v40
	v_readlane_b32 s22, v175, 44
	v_max_f32_e32 v38, s40, v39
	v_readlane_b32 s32, v177, 44
	v_sub_f32_e32 v58, v39, v38
	v_sub_f32_e32 v59, s40, v38
	v_mul_f32_e32 v58, 0x3fb8aa3b, v58
	v_mul_f32_e32 v59, 0x3fb8aa3b, v59
	v_exp_f32_e32 v60, v58
	v_exp_f32_e32 v62, v59
	v_cvt_pk_bf16_f32 v122, v118, v119
	v_writelane_b32 v179, s54, 43
	global_store_dword v36, v122, s[6:7]
	s_add_u32 s6, s6, 0x20000
	s_addc_u32 s7, s7, 0
	global_store_dword v36, v120, s[10:11]
	s_add_u32 s10, s10, 0x800
	s_addc_u32 s11, s11, 0
	v_lshlrev_b32_e32 v108, 16, v137
	v_and_b32_e32 v109, 0xffff0000, v137
	v_pk_mul_f32 v[108:109], v[62:63], v[108:109] op_sel_hi:[0,1]
	v_mul_f32_e32 v121, v27, v62
	v_pk_fma_f32 v[118:119], v[118:119], v[60:61], v[108:109] op_sel_hi:[1,0,1]
	v_fma_f32 v120, v120, v60, v121
	v_readfirstlane_b32 s54, v38
	v_add_f32_e32 v39, s22, v38
	v_readlane_b32 s34, v175, 45
	v_max_f32_e32 v40, s32, v39
	v_readlane_b32 s40, v177, 45
	v_sub_f32_e32 v58, v39, v40
	v_sub_f32_e32 v59, s32, v40
	v_mul_f32_e32 v58, 0x3fb8aa3b, v58
	v_mul_f32_e32 v59, 0x3fb8aa3b, v59
	v_exp_f32_e32 v60, v58
	v_exp_f32_e32 v62, v59
	v_cvt_pk_bf16_f32 v122, v118, v119
	v_writelane_b32 v179, s54, 44
	global_store_dword v36, v122, s[6:7]
	s_add_u32 s6, s6, 0x20000
	s_addc_u32 s7, s7, 0
	global_store_dword v36, v120, s[10:11]
	s_add_u32 s10, s10, 0x800
	s_addc_u32 s11, s11, 0
	v_lshlrev_b32_e32 v108, 16, v138
	v_and_b32_e32 v109, 0xffff0000, v138
	v_pk_mul_f32 v[108:109], v[62:63], v[108:109] op_sel_hi:[0,1]
	v_mul_f32_e32 v121, v28, v62
	v_pk_fma_f32 v[118:119], v[118:119], v[60:61], v[108:109] op_sel_hi:[1,0,1]
	v_fma_f32 v120, v120, v60, v121
	v_readfirstlane_b32 s54, v40
	v_add_f32_e32 v39, s34, v40
	v_readlane_b32 s22, v175, 46
	v_max_f32_e32 v38, s40, v39
	v_readlane_b32 s32, v177, 46
	v_sub_f32_e32 v58, v39, v38
	v_sub_f32_e32 v59, s40, v38
	v_mul_f32_e32 v58, 0x3fb8aa3b, v58
	v_mul_f32_e32 v59, 0x3fb8aa3b, v59
	v_exp_f32_e32 v60, v58
	v_exp_f32_e32 v62, v59
	v_cvt_pk_bf16_f32 v122, v118, v119
	v_writelane_b32 v179, s54, 45
	global_store_dword v36, v122, s[6:7]
	s_add_u32 s6, s6, 0x20000
	s_addc_u32 s7, s7, 0
	global_store_dword v36, v120, s[10:11]
	s_add_u32 s10, s10, 0x800
	s_addc_u32 s11, s11, 0
	v_lshlrev_b32_e32 v108, 16, v139
	v_and_b32_e32 v109, 0xffff0000, v139
	v_pk_mul_f32 v[108:109], v[62:63], v[108:109] op_sel_hi:[0,1]
	v_mul_f32_e32 v121, v29, v62
	v_pk_fma_f32 v[118:119], v[118:119], v[60:61], v[108:109] op_sel_hi:[1,0,1]
	v_fma_f32 v120, v120, v60, v121
	v_readfirstlane_b32 s54, v38
	v_add_f32_e32 v39, s22, v38
	v_readlane_b32 s34, v175, 47
	v_max_f32_e32 v40, s32, v39
	v_readlane_b32 s40, v177, 47
	v_sub_f32_e32 v58, v39, v40
	v_sub_f32_e32 v59, s32, v40
	v_mul_f32_e32 v58, 0x3fb8aa3b, v58
	v_mul_f32_e32 v59, 0x3fb8aa3b, v59
	v_exp_f32_e32 v60, v58
	v_exp_f32_e32 v62, v59
	v_cvt_pk_bf16_f32 v122, v118, v119
	v_writelane_b32 v179, s54, 46
	global_store_dword v36, v122, s[6:7]
	s_add_u32 s6, s6, 0x20000
	s_addc_u32 s7, s7, 0
	global_store_dword v36, v120, s[10:11]
	s_add_u32 s10, s10, 0x800
	s_addc_u32 s11, s11, 0
	v_lshlrev_b32_e32 v108, 16, v140
	v_and_b32_e32 v109, 0xffff0000, v140
	v_pk_mul_f32 v[108:109], v[62:63], v[108:109] op_sel_hi:[0,1]
	v_mul_f32_e32 v121, v30, v62
	v_pk_fma_f32 v[118:119], v[118:119], v[60:61], v[108:109] op_sel_hi:[1,0,1]
	v_fma_f32 v120, v120, v60, v121
	v_readfirstlane_b32 s54, v40
	v_add_f32_e32 v39, s34, v40
	v_readlane_b32 s22, v175, 48
	v_max_f32_e32 v38, s40, v39
	v_readlane_b32 s32, v177, 48
	v_sub_f32_e32 v58, v39, v38
	v_sub_f32_e32 v59, s40, v38
	v_mul_f32_e32 v58, 0x3fb8aa3b, v58
	v_mul_f32_e32 v59, 0x3fb8aa3b, v59
	v_exp_f32_e32 v60, v58
	v_exp_f32_e32 v62, v59
	v_cvt_pk_bf16_f32 v122, v118, v119
	v_writelane_b32 v179, s54, 47
	global_store_dword v36, v122, s[6:7]
	s_add_u32 s6, s6, 0x20000
	s_addc_u32 s7, s7, 0
	global_store_dword v36, v120, s[10:11]
	s_add_u32 s10, s10, 0x800
	s_addc_u32 s11, s11, 0
	v_lshlrev_b32_e32 v108, 16, v141
	v_and_b32_e32 v109, 0xffff0000, v141
	v_pk_mul_f32 v[108:109], v[62:63], v[108:109] op_sel_hi:[0,1]
	v_mul_f32_e32 v121, v31, v62
	v_pk_fma_f32 v[118:119], v[118:119], v[60:61], v[108:109] op_sel_hi:[1,0,1]
	v_fma_f32 v120, v120, v60, v121
; __device__ __forceinline__ unsigned pk2(float lo, float hi) { f32x2_t v = {lo, hi}; bf16x2_t b = __builtin_convertvector(v, bf16x2_t); return __builtin_bit_cast(unsigned, b); }
; __device__ __forceinline__ float bflo(unsigned w) { return __uint_as_float(w << 16); }
; __device__ __forceinline__ float bfhi(unsigned w) { return __uint_as_float(w & 0xffff0000u); }
; __device__ __forceinline__ float fexp(float x) { return __builtin_amdgcn_exp2f(x * LOG2E); }
;     __device__ __forceinline__ float* MBM() const { return (float*)(ws + WS_MB); }
;     __device__ __forceinline__ float* MBB() const { return (float*)(ws + WS_MB) + (NSLOT_P + NSLOT_S); }
;     __device__ __forceinline__ float* MST() const { return (float*)(ws + WS_MB) + 2 * (NSLOT_P + NSLOT_S); }
; __device__ __forceinline__ void phase_scan(Ctx& C, int l, const bool st, LAS unsigned char* lds) {
;     ...
;         for (int cg0 = 0; cg0 < NPC; cg0 += 16) {
;             if (cg0 + 16 < NPC) {
; #pragma unroll
;                 for (int j = 0; j < 16; ++j) { nb[j] = base[(size_t)((b * NPC + cg0 + 16 + j) * 4 + h) * 8192]; fnb[j] = hn ? dnb[(size_t)((b * NPC + cg0 + 16 + j) * 4 + h) * 128] : 0.f; }
;             }
; #pragma unroll
;             for (int j = 0; j < 16; ++j) { const int slot = (b * NPC + cg0 + j) * 4 + h;
;                 const float Bc = C.MBB()[slot], Mc = C.MBM()[slot];
;                 const float mn = fmaxf(Bc + m, Mc), g = fexp(Bc + m - mn), f = fexp(Mc - mn);
;                 if (st) { base[(size_t)slot * 8192] = pk2(c0, c1); if (hn) { dnb[(size_t)slot * 128] = nn; if (p == 0) C.MST()[slot] = m; } }
;                 c0 = g * c0 + f * bflo(buf[j]); c1 = g * c1 + f * bfhi(buf[j]); nn = g * nn + f * fb[j]; m = mn; }
; #pragma unroll
;             for (int j = 0; j < 16; ++j) { buf[j] = nb[j]; fb[j] = fnb[j]; }
.Lscan_hn_b7:
	s_waitcnt vmcnt(32)
	v_readfirstlane_b32 s54, v38
	v_add_f32_e32 v39, s22, v38
	v_readlane_b32 s34, v175, 49
	v_max_f32_e32 v40, s32, v39
	v_readlane_b32 s40, v177, 49
	v_sub_f32_e32 v58, v39, v40
	v_sub_f32_e32 v59, s32, v40
	v_mul_f32_e32 v58, 0x3fb8aa3b, v58
	v_mul_f32_e32 v59, 0x3fb8aa3b, v59
	v_exp_f32_e32 v60, v58
	v_exp_f32_e32 v62, v59
	v_cvt_pk_bf16_f32 v122, v118, v119
	v_writelane_b32 v179, s54, 48
	global_store_dword v36, v122, s[6:7]
	s_add_u32 s6, s6, 0x20000
	s_addc_u32 s7, s7, 0
	global_store_dword v36, v120, s[10:11]
	s_add_u32 s10, s10, 0x800
	s_addc_u32 s11, s11, 0
	v_lshlrev_b32_e32 v108, 16, v142
	v_and_b32_e32 v109, 0xffff0000, v142
	v_pk_mul_f32 v[108:109], v[62:63], v[108:109] op_sel_hi:[0,1]
	v_mul_f32_e32 v121, v42, v62
	v_pk_fma_f32 v[118:119], v[118:119], v[60:61], v[108:109] op_sel_hi:[1,0,1]
	v_fma_f32 v120, v120, v60, v121
	v_readfirstlane_b32 s54, v40
	v_add_f32_e32 v39, s34, v40
	v_readlane_b32 s22, v175, 50
	v_max_f32_e32 v38, s40, v39
	v_readlane_b32 s32, v177, 50
	v_sub_f32_e32 v58, v39, v38
	v_sub_f32_e32 v59, s40, v38
	v_mul_f32_e32 v58, 0x3fb8aa3b, v58
	v_mul_f32_e32 v59, 0x3fb8aa3b, v59
	v_exp_f32_e32 v60, v58
	v_exp_f32_e32 v62, v59
	v_cvt_pk_bf16_f32 v122, v118, v119
	v_writelane_b32 v179, s54, 49
	global_store_dword v36, v122, s[6:7]
	s_add_u32 s6, s6, 0x20000
	s_addc_u32 s7, s7, 0
	global_store_dword v36, v120, s[10:11]
	s_add_u32 s10, s10, 0x800
	s_addc_u32 s11, s11, 0
	v_lshlrev_b32_e32 v108, 16, v143
	v_and_b32_e32 v109, 0xffff0000, v143
	v_pk_mul_f32 v[108:109], v[62:63], v[108:109] op_sel_hi:[0,1]
	v_mul_f32_e32 v121, v43, v62
	v_pk_fma_f32 v[118:119], v[118:119], v[60:61], v[108:109] op_sel_hi:[1,0,1]
	v_fma_f32 v120, v120, v60, v121
	v_readfirstlane_b32 s54, v38
	v_add_f32_e32 v39, s22, v38
	v_readlane_b32 s34, v175, 51
	v_max_f32_e32 v40, s32, v39
	v_readlane_b32 s40, v177, 51
	v_sub_f32_e32 v58, v39, v40
	v_sub_f32_e32 v59, s32, v40
	v_mul_f32_e32 v58, 0x3fb8aa3b, v58
	v_mul_f32_e32 v59, 0x3fb8aa3b, v59
	v_exp_f32_e32 v60, v58
	v_exp_f32_e32 v62, v59
	v_cvt_pk_bf16_f32 v122, v118, v119
	v_writelane_b32 v179, s54, 50
	global_store_dword v36, v122, s[6:7]
	s_add_u32 s6, s6, 0x20000
	s_addc_u32 s7, s7, 0
	global_store_dword v36, v120, s[10:11]
	s_add_u32 s10, s10, 0x800
	s_addc_u32 s11, s11, 0
	v_lshlrev_b32_e32 v108, 16, v144
	v_and_b32_e32 v109, 0xffff0000, v144
	v_pk_mul_f32 v[108:109], v[62:63], v[108:109] op_sel_hi:[0,1]
	v_mul_f32_e32 v121, v44, v62
	v_pk_fma_f32 v[118:119], v[118:119], v[60:61], v[108:109] op_sel_hi:[1,0,1]
	v_fma_f32 v120, v120, v60, v121
	v_readfirstlane_b32 s54, v40
	v_add_f32_e32 v39, s34, v40
	v_readlane_b32 s22, v175, 52
	v_max_f32_e32 v38, s40, v39
	v_readlane_b32 s32, v177, 52
	v_sub_f32_e32 v58, v39, v38
	v_sub_f32_e32 v59, s40, v38
	v_mul_f32_e32 v58, 0x3fb8aa3b, v58
	v_mul_f32_e32 v59, 0x3fb8aa3b, v59
	v_exp_f32_e32 v60, v58
	v_exp_f32_e32 v62, v59
	v_cvt_pk_bf16_f32 v122, v118, v119
	v_writelane_b32 v179, s54, 51
	global_store_dword v36, v122, s[6:7]
	s_add_u32 s6, s6, 0x20000
	s_addc_u32 s7, s7, 0
	global_store_dword v36, v120, s[10:11]
	s_add_u32 s10, s10, 0x800
	s_addc_u32 s11, s11, 0
	v_lshlrev_b32_e32 v108, 16, v145
	v_and_b32_e32 v109, 0xffff0000, v145
	v_pk_mul_f32 v[108:109], v[62:63], v[108:109] op_sel_hi:[0,1]
	v_mul_f32_e32 v121, v45, v62
	v_pk_fma_f32 v[118:119], v[118:119], v[60:61], v[108:109] op_sel_hi:[1,0,1]
	v_fma_f32 v120, v120, v60, v121
	v_readfirstlane_b32 s54, v38
	v_add_f32_e32 v39, s22, v38
	v_readlane_b32 s34, v175, 53
	v_max_f32_e32 v40, s32, v39
	v_readlane_b32 s40, v177, 53
	v_sub_f32_e32 v58, v39, v40
	v_sub_f32_e32 v59, s32, v40
	v_mul_f32_e32 v58, 0x3fb8aa3b, v58
	v_mul_f32_e32 v59, 0x3fb8aa3b, v59
	v_exp_f32_e32 v60, v58
	v_exp_f32_e32 v62, v59
	v_cvt_pk_bf16_f32 v122, v118, v119
	v_writelane_b32 v179, s54, 52
	global_store_dword v36, v122, s[6:7]
	s_add_u32 s6, s6, 0x20000
	s_addc_u32 s7, s7, 0
	global_store_dword v36, v120, s[10:11]
	s_add_u32 s10, s10, 0x800
	s_addc_u32 s11, s11, 0
	v_lshlrev_b32_e32 v108, 16, v146
	v_and_b32_e32 v109, 0xffff0000, v146
	v_pk_mul_f32 v[108:109], v[62:63], v[108:109] op_sel_hi:[0,1]
	v_mul_f32_e32 v121, v46, v62
	v_pk_fma_f32 v[118:119], v[118:119], v[60:61], v[108:109] op_sel_hi:[1,0,1]
	v_fma_f32 v120, v120, v60, v121
	v_readfirstlane_b32 s54, v40
	v_add_f32_e32 v39, s34, v40
	v_readlane_b32 s22, v175, 54
	v_max_f32_e32 v38, s40, v39
	v_readlane_b32 s32, v177, 54
	v_sub_f32_e32 v58, v39, v38
	v_sub_f32_e32 v59, s40, v38
	v_mul_f32_e32 v58, 0x3fb8aa3b, v58
	v_mul_f32_e32 v59, 0x3fb8aa3b, v59
	v_exp_f32_e32 v60, v58
	v_exp_f32_e32 v62, v59
	v_cvt_pk_bf16_f32 v122, v118, v119
	v_writelane_b32 v179, s54, 53
	global_store_dword v36, v122, s[6:7]
	s_add_u32 s6, s6, 0x20000
	s_addc_u32 s7, s7, 0
	global_store_dword v36, v120, s[10:11]
	s_add_u32 s10, s10, 0x800
	s_addc_u32 s11, s11, 0
	v_lshlrev_b32_e32 v108, 16, v147
	v_and_b32_e32 v109, 0xffff0000, v147
	v_pk_mul_f32 v[108:109], v[62:63], v[108:109] op_sel_hi:[0,1]
	v_mul_f32_e32 v121, v47, v62
	v_pk_fma_f32 v[118:119], v[118:119], v[60:61], v[108:109] op_sel_hi:[1,0,1]
	v_fma_f32 v120, v120, v60, v121
	v_readfirstlane_b32 s54, v38
	v_add_f32_e32 v39, s22, v38
	v_readlane_b32 s34, v175, 55
	v_max_f32_e32 v40, s32, v39
	v_readlane_b32 s40, v177, 55
	v_sub_f32_e32 v58, v39, v40
	v_sub_f32_e32 v59, s32, v40
	v_mul_f32_e32 v58, 0x3fb8aa3b, v58
	v_mul_f32_e32 v59, 0x3fb8aa3b, v59
	v_exp_f32_e32 v60, v58
	v_exp_f32_e32 v62, v59
	v_cvt_pk_bf16_f32 v122, v118, v119
	v_writelane_b32 v179, s54, 54
	global_store_dword v36, v122, s[6:7]
	s_add_u32 s6, s6, 0x20000
	s_addc_u32 s7, s7, 0
	global_store_dword v36, v120, s[10:11]
; __device__ __forceinline__ unsigned pk2(float lo, float hi) { f32x2_t v = {lo, hi}; bf16x2_t b = __builtin_convertvector(v, bf16x2_t); return __builtin_bit_cast(unsigned, b); }
; __device__ __forceinline__ float bflo(unsigned w) { return __uint_as_float(w << 16); }
; __device__ __forceinline__ float bfhi(unsigned w) { return __uint_as_float(w & 0xffff0000u); }
; __device__ __forceinline__ float fexp(float x) { return __builtin_amdgcn_exp2f(x * LOG2E); }
;     __device__ __forceinline__ float* MBM() const { return (float*)(ws + WS_MB); }
;     __device__ __forceinline__ float* MBB() const { return (float*)(ws + WS_MB) + (NSLOT_P + NSLOT_S); }
;     __device__ __forceinline__ float* MST() const { return (float*)(ws + WS_MB) + 2 * (NSLOT_P + NSLOT_S); }
; __device__ __forceinline__ void phase_scan(Ctx& C, int l, const bool st, LAS unsigned char* lds) {
;     ...
;         for (int cg0 = 0; cg0 < NPC; cg0 += 16) {
;             if (cg0 + 16 < NPC) {
; #pragma unroll
;                 for (int j = 0; j < 16; ++j) { nb[j] = base[(size_t)((b * NPC + cg0 + 16 + j) * 4 + h) * 8192]; fnb[j] = hn ? dnb[(size_t)((b * NPC + cg0 + 16 + j) * 4 + h) * 128] : 0.f; }
;             }
; #pragma unroll
;             for (int j = 0; j < 16; ++j) { const int slot = (b * NPC + cg0 + j) * 4 + h;
;                 const float Bc = C.MBB()[slot], Mc = C.MBM()[slot];
;                 const float mn = fmaxf(Bc + m, Mc), g = fexp(Bc + m - mn), f = fexp(Mc - mn);
;                 if (st) { base[(size_t)slot * 8192] = pk2(c0, c1); if (hn) { dnb[(size_t)slot * 128] = nn; if (p == 0) C.MST()[slot] = m; } }
;                 c0 = g * c0 + f * bflo(buf[j]); c1 = g * c1 + f * bfhi(buf[j]); nn = g * nn + f * fb[j]; m = mn; }
; #pragma unroll
;             for (int j = 0; j < 16; ++j) { buf[j] = nb[j]; fb[j] = fnb[j]; }
	s_add_u32 s10, s10, 0x800
	s_addc_u32 s11, s11, 0
	v_lshlrev_b32_e32 v108, 16, v148
	v_and_b32_e32 v109, 0xffff0000, v148
	v_pk_mul_f32 v[108:109], v[62:63], v[108:109] op_sel_hi:[0,1]
	v_mul_f32_e32 v121, v48, v62
	v_pk_fma_f32 v[118:119], v[118:119], v[60:61], v[108:109] op_sel_hi:[1,0,1]
	v_fma_f32 v120, v120, v60, v121
	v_readfirstlane_b32 s54, v40
	v_add_f32_e32 v39, s34, v40
	v_readlane_b32 s22, v175, 56
	v_max_f32_e32 v38, s40, v39
	v_readlane_b32 s32, v177, 56
	v_sub_f32_e32 v58, v39, v38
	v_sub_f32_e32 v59, s40, v38
	v_mul_f32_e32 v58, 0x3fb8aa3b, v58
	v_mul_f32_e32 v59, 0x3fb8aa3b, v59
	v_exp_f32_e32 v60, v58
	v_exp_f32_e32 v62, v59
	v_cvt_pk_bf16_f32 v122, v118, v119
	v_writelane_b32 v179, s54, 55
	global_store_dword v36, v122, s[6:7]
	s_add_u32 s6, s6, 0x20000
	s_addc_u32 s7, s7, 0
	global_store_dword v36, v120, s[10:11]
	s_add_u32 s10, s10, 0x800
	s_addc_u32 s11, s11, 0
	v_lshlrev_b32_e32 v108, 16, v149
	v_and_b32_e32 v109, 0xffff0000, v149
	v_pk_mul_f32 v[108:109], v[62:63], v[108:109] op_sel_hi:[0,1]
	v_mul_f32_e32 v121, v49, v62
	v_pk_fma_f32 v[118:119], v[118:119], v[60:61], v[108:109] op_sel_hi:[1,0,1]
	v_fma_f32 v120, v120, v60, v121
	v_readfirstlane_b32 s54, v38
	v_add_f32_e32 v39, s22, v38
	v_readlane_b32 s34, v175, 57
	v_max_f32_e32 v40, s32, v39
	v_readlane_b32 s40, v177, 57
	v_sub_f32_e32 v58, v39, v40
	v_sub_f32_e32 v59, s32, v40
	v_mul_f32_e32 v58, 0x3fb8aa3b, v58
	v_mul_f32_e32 v59, 0x3fb8aa3b, v59
	v_exp_f32_e32 v60, v58
	v_exp_f32_e32 v62, v59
	v_cvt_pk_bf16_f32 v122, v118, v119
	v_writelane_b32 v179, s54, 56
	global_store_dword v36, v122, s[6:7]
	s_add_u32 s6, s6, 0x20000
	s_addc_u32 s7, s7, 0
	global_store_dword v36, v120, s[10:11]
	s_add_u32 s10, s10, 0x800
	s_addc_u32 s11, s11, 0
	v_lshlrev_b32_e32 v108, 16, v150
	v_and_b32_e32 v109, 0xffff0000, v150
	v_pk_mul_f32 v[108:109], v[62:63], v[108:109] op_sel_hi:[0,1]
	v_mul_f32_e32 v121, v50, v62
	v_pk_fma_f32 v[118:119], v[118:119], v[60:61], v[108:109] op_sel_hi:[1,0,1]
	v_fma_f32 v120, v120, v60, v121
	v_readfirstlane_b32 s54, v40
	v_add_f32_e32 v39, s34, v40
	v_readlane_b32 s22, v175, 58
	v_max_f32_e32 v38, s40, v39
	v_readlane_b32 s32, v177, 58
	v_sub_f32_e32 v58, v39, v38
	v_sub_f32_e32 v59, s40, v38
	v_mul_f32_e32 v58, 0x3fb8aa3b, v58
	v_mul_f32_e32 v59, 0x3fb8aa3b, v59
	v_exp_f32_e32 v60, v58
	v_exp_f32_e32 v62, v59
	v_cvt_pk_bf16_f32 v122, v118, v119
	v_writelane_b32 v179, s54, 57
	global_store_dword v36, v122, s[6:7]
	s_add_u32 s6, s6, 0x20000
	s_addc_u32 s7, s7, 0
	global_store_dword v36, v120, s[10:11]
	s_add_u32 s10, s10, 0x800
	s_addc_u32 s11, s11, 0
	v_lshlrev_b32_e32 v108, 16, v151
	v_and_b32_e32 v109, 0xffff0000, v151
	v_pk_mul_f32 v[108:109], v[62:63], v[108:109] op_sel_hi:[0,1]
	v_mul_f32_e32 v121, v51, v62
	v_pk_fma_f32 v[118:119], v[118:119], v[60:61], v[108:109] op_sel_hi:[1,0,1]
	v_fma_f32 v120, v120, v60, v121
	v_readfirstlane_b32 s54, v38
	v_add_f32_e32 v39, s22, v38
	v_readlane_b32 s34, v175, 59
	v_max_f32_e32 v40, s32, v39
	v_readlane_b32 s40, v177, 59
	v_sub_f32_e32 v58, v39, v40
	v_sub_f32_e32 v59, s32, v40
	v_mul_f32_e32 v58, 0x3fb8aa3b, v58
	v_mul_f32_e32 v59, 0x3fb8aa3b, v59
	v_exp_f32_e32 v60, v58
	v_exp_f32_e32 v62, v59
	v_cvt_pk_bf16_f32 v122, v118, v119
	v_writelane_b32 v179, s54, 58
	global_store_dword v36, v122, s[6:7]
	s_add_u32 s6, s6, 0x20000
	s_addc_u32 s7, s7, 0
	global_store_dword v36, v120, s[10:11]
	s_add_u32 s10, s10, 0x800
	s_addc_u32 s11, s11, 0
	v_lshlrev_b32_e32 v108, 16, v152
	v_and_b32_e32 v109, 0xffff0000, v152
	v_pk_mul_f32 v[108:109], v[62:63], v[108:109] op_sel_hi:[0,1]
	v_mul_f32_e32 v121, v52, v62
	v_pk_fma_f32 v[118:119], v[118:119], v[60:61], v[108:109] op_sel_hi:[1,0,1]
	v_fma_f32 v120, v120, v60, v121
	v_readfirstlane_b32 s54, v40
	v_add_f32_e32 v39, s34, v40
	v_readlane_b32 s22, v175, 60
	v_max_f32_e32 v38, s40, v39
	v_readlane_b32 s32, v177, 60
	v_sub_f32_e32 v58, v39, v38
	v_sub_f32_e32 v59, s40, v38
	v_mul_f32_e32 v58, 0x3fb8aa3b, v58
	v_mul_f32_e32 v59, 0x3fb8aa3b, v59
	v_exp_f32_e32 v60, v58
	v_exp_f32_e32 v62, v59
	v_cvt_pk_bf16_f32 v122, v118, v119
	v_writelane_b32 v179, s54, 59
	global_store_dword v36, v122, s[6:7]
	s_add_u32 s6, s6, 0x20000
	s_addc_u32 s7, s7, 0
	global_store_dword v36, v120, s[10:11]
	s_add_u32 s10, s10, 0x800
	s_addc_u32 s11, s11, 0
	v_lshlrev_b32_e32 v108, 16, v153
	v_and_b32_e32 v109, 0xffff0000, v153
	v_pk_mul_f32 v[108:109], v[62:63], v[108:109] op_sel_hi:[0,1]
	v_mul_f32_e32 v121, v53, v62
; __device__ __forceinline__ unsigned pk2(float lo, float hi) { f32x2_t v = {lo, hi}; bf16x2_t b = __builtin_convertvector(v, bf16x2_t); return __builtin_bit_cast(unsigned, b); }
; __device__ __forceinline__ float bflo(unsigned w) { return __uint_as_float(w << 16); }
; __device__ __forceinline__ float bfhi(unsigned w) { return __uint_as_float(w & 0xffff0000u); }
; __device__ __forceinline__ float fexp(float x) { return __builtin_amdgcn_exp2f(x * LOG2E); }
;     __device__ __forceinline__ float* MBM() const { return (float*)(ws + WS_MB); }
;     __device__ __forceinline__ float* MBB() const { return (float*)(ws + WS_MB) + (NSLOT_P + NSLOT_S); }
;     __device__ __forceinline__ float* MST() const { return (float*)(ws + WS_MB) + 2 * (NSLOT_P + NSLOT_S); }
; __device__ __forceinline__ void phase_scan(Ctx& C, int l, const bool st, LAS unsigned char* lds) {
;     ...
;             for (int j = 0; j < 16; ++j) { const int slot = (b * NPC + cg0 + j) * 4 + h;
;                 const float Bc = C.MBB()[slot], Mc = C.MBM()[slot];
;                 const float mn = fmaxf(Bc + m, Mc), g = fexp(Bc + m - mn), f = fexp(Mc - mn);
;                 if (st) { base[(size_t)slot * 8192] = pk2(c0, c1); if (hn) { dnb[(size_t)slot * 128] = nn; if (p == 0) C.MST()[slot] = m; } }
;                 c0 = g * c0 + f * bflo(buf[j]); c1 = g * c1 + f * bfhi(buf[j]); nn = g * nn + f * fb[j]; m = mn; }
; #pragma unroll
;             for (int j = 0; j < 16; ++j) { buf[j] = nb[j]; fb[j] = fnb[j]; }
;         }
;         const int v = p >> 6, d = (p & 63) * 2;
;         float* o = C.out + O_NCP + ((size_t)(l * NBP + b) * 4 + h) * 16384;
;         if (st) { o[d * 128 + v] = c0; o[(d + 1) * 128 + v] = c1;
;             if (hn) { C.out[O_NNP + ((size_t)(l * NBP + b) * 4 + h) * 128 + p] = nn; if (p == 0) C.out[O_NMP + (size_t)(l * NBP + b) * 4 + h] = m; } }
	v_pk_fma_f32 v[118:119], v[118:119], v[60:61], v[108:109] op_sel_hi:[1,0,1]
	v_fma_f32 v120, v120, v60, v121
	v_readfirstlane_b32 s54, v38
	v_add_f32_e32 v39, s22, v38
	v_readlane_b32 s34, v175, 61
	v_max_f32_e32 v40, s32, v39
	v_readlane_b32 s40, v177, 61
	v_sub_f32_e32 v58, v39, v40
	v_sub_f32_e32 v59, s32, v40
	v_mul_f32_e32 v58, 0x3fb8aa3b, v58
	v_mul_f32_e32 v59, 0x3fb8aa3b, v59
	v_exp_f32_e32 v60, v58
	v_exp_f32_e32 v62, v59
	v_cvt_pk_bf16_f32 v122, v118, v119
	v_writelane_b32 v179, s54, 60
	global_store_dword v36, v122, s[6:7]
	s_add_u32 s6, s6, 0x20000
	s_addc_u32 s7, s7, 0
	global_store_dword v36, v120, s[10:11]
	s_add_u32 s10, s10, 0x800
	s_addc_u32 s11, s11, 0
	v_lshlrev_b32_e32 v108, 16, v154
	v_and_b32_e32 v109, 0xffff0000, v154
	v_pk_mul_f32 v[108:109], v[62:63], v[108:109] op_sel_hi:[0,1]
	v_mul_f32_e32 v121, v54, v62
	v_pk_fma_f32 v[118:119], v[118:119], v[60:61], v[108:109] op_sel_hi:[1,0,1]
	v_fma_f32 v120, v120, v60, v121
	v_readfirstlane_b32 s54, v40
	v_add_f32_e32 v39, s34, v40
	v_readlane_b32 s22, v175, 62
	v_max_f32_e32 v38, s40, v39
	v_readlane_b32 s32, v177, 62
	v_sub_f32_e32 v58, v39, v38
	v_sub_f32_e32 v59, s40, v38
	v_mul_f32_e32 v58, 0x3fb8aa3b, v58
	v_mul_f32_e32 v59, 0x3fb8aa3b, v59
	v_exp_f32_e32 v60, v58
	v_exp_f32_e32 v62, v59
	v_cvt_pk_bf16_f32 v122, v118, v119
	v_writelane_b32 v179, s54, 61
	global_store_dword v36, v122, s[6:7]
	s_add_u32 s6, s6, 0x20000
	s_addc_u32 s7, s7, 0
	global_store_dword v36, v120, s[10:11]
	s_add_u32 s10, s10, 0x800
	s_addc_u32 s11, s11, 0
	v_lshlrev_b32_e32 v108, 16, v155
	v_and_b32_e32 v109, 0xffff0000, v155
	v_pk_mul_f32 v[108:109], v[62:63], v[108:109] op_sel_hi:[0,1]
	v_mul_f32_e32 v121, v55, v62
	v_pk_fma_f32 v[118:119], v[118:119], v[60:61], v[108:109] op_sel_hi:[1,0,1]
	v_fma_f32 v120, v120, v60, v121
	v_readfirstlane_b32 s54, v38
	v_add_f32_e32 v39, s22, v38
	v_readlane_b32 s34, v175, 63
	v_max_f32_e32 v40, s32, v39
	v_readlane_b32 s40, v177, 63
	v_sub_f32_e32 v58, v39, v40
	v_sub_f32_e32 v59, s32, v40
	v_mul_f32_e32 v58, 0x3fb8aa3b, v58
	v_mul_f32_e32 v59, 0x3fb8aa3b, v59
	v_exp_f32_e32 v60, v58
	v_exp_f32_e32 v62, v59
	v_cvt_pk_bf16_f32 v122, v118, v119
	v_writelane_b32 v179, s54, 62
	global_store_dword v36, v122, s[6:7]
	s_add_u32 s6, s6, 0x20000
	s_addc_u32 s7, s7, 0
	global_store_dword v36, v120, s[10:11]
	s_add_u32 s10, s10, 0x800
	s_addc_u32 s11, s11, 0
	v_lshlrev_b32_e32 v108, 16, v156
	v_and_b32_e32 v109, 0xffff0000, v156
	v_pk_mul_f32 v[108:109], v[62:63], v[108:109] op_sel_hi:[0,1]
	v_mul_f32_e32 v121, v56, v62
	v_pk_fma_f32 v[118:119], v[118:119], v[60:61], v[108:109] op_sel_hi:[1,0,1]
	v_fma_f32 v120, v120, v60, v121
	v_readfirstlane_b32 s54, v40
	v_add_f32_e32 v39, s34, v40
	v_max_f32_e32 v38, s40, v39
	v_sub_f32_e32 v58, v39, v38
	v_sub_f32_e32 v59, s40, v38
	v_mul_f32_e32 v58, 0x3fb8aa3b, v58
	v_mul_f32_e32 v59, 0x3fb8aa3b, v59
	v_exp_f32_e32 v60, v58
	v_exp_f32_e32 v62, v59
	v_cvt_pk_bf16_f32 v122, v118, v119
	v_writelane_b32 v179, s54, 63
	global_store_dword v36, v122, s[6:7]
	s_add_u32 s6, s6, 0x20000
	s_addc_u32 s7, s7, 0
	global_store_dword v36, v120, s[10:11]
	s_add_u32 s10, s10, 0x800
	s_addc_u32 s11, s11, 0
	v_lshlrev_b32_e32 v108, 16, v157
	v_and_b32_e32 v109, 0xffff0000, v157
	v_pk_mul_f32 v[108:109], v[62:63], v[108:109] op_sel_hi:[0,1]
	v_mul_f32_e32 v121, v57, v62
	v_pk_fma_f32 v[118:119], v[118:119], v[60:61], v[108:109] op_sel_hi:[1,0,1]
	v_fma_f32 v120, v120, v60, v121
.Lscan_fin:
	s_lshl_b32 s49, s14, 2
	s_add_u32 s49, s49, s46
	s_lshl_b32 s49, s49, 2
	s_add_u32 s49, s49, s47
	s_lshl_b32 s54, s49, 16
	s_lshr_b32 s55, s41, 6
	s_lshl_b32 s55, s55, 2
	s_add_u32 s54, s54, s55
	s_add_u32 s4, s88, s54
	s_addc_u32 s5, s89, 0
	s_add_u32 s4, s4, 0x9418000
	s_addc_u32 s5, s5, 0
	global_store_dword v180, v118, s[4:5]
	global_store_dword v180, v119, s[4:5] offset:512
	s_cmp_eq_u32 s52, 1
	s_cbranch_scc0 .Lscan_next
	s_lshl_b32 s54, s49, 9
	s_add_u32 s4, s88, s54
	s_addc_u32 s5, s89, 0
	s_add_u32 s4, s4, 0x9618000
	s_addc_u32 s5, s5, 0
	global_store_dword v36, v120, s[4:5]
	s_cmp_eq_u32 s53, 1
	s_cbranch_scc0 .Lscan_next
	global_store_dword v124, v178, s[50:51]
	global_store_dword v124, v179, s[50:51] offset:1024
	s_lshl_b32 s54, s49, 2
	s_add_u32 s4, s88, s54
	s_addc_u32 s5, s89, 0
	s_add_u32 s4, s4, 0x961c000
	s_addc_u32 s5, s5, 0
	s_mov_b64 exec, 1
	global_store_dword v123, v38, s[4:5]
	s_mov_b64 exec, s[2:3]
.Lscan_next:
	s_add_u32 s12, s12, s19
	s_branch .Lscan_outer
